# all packed f32 mul/add/fma in every phase unpacked into scalar pairs
# baseline (speedup 1.0000x reference)
.LBB0_196:
	s_and_b32 s30, s61, 1
	s_lshl_b32 s15, s30, 12
	s_add_i32 s19, s15, 0
	s_add_i32 s19, s19, 0x24010
	s_lshl_b32 s31, s49, 2
	s_add_i32 s31, s19, s31
	v_lshl_add_u32 v163, v155, 2, s31
	ds_read_b128 v[132:135], v163 offset:3072
	s_lshl_b32 s34, s30, 13
	s_add_i32 s35, s34, 0
	s_add_i32 s35, s35, 0x20000
	s_waitcnt lgkmcnt(0)
	v_mul_f32_e32 v124, v124, v134
	v_mul_f32_e32 v125, v125, v134
	v_mul_f32_e32 v108, v108, v134
	v_mul_f32_e32 v109, v109, v134
	v_mul_f32_e32 v128, v128, v134
	v_mul_f32_e32 v129, v129, v134
	v_mul_f32_e32 v108, v124, v108
	v_mul_f32_e32 v109, v125, v109
	v_mov_b32_e32 v124, v135
	v_mul_f32_e32 v120, v120, v124
	v_mul_f32_e32 v121, v121, v124
	v_mul_f32_e32 v122, v122, v124
	v_mul_f32_e32 v123, v123, v124
	v_mul_f32_e32 v104, v104, v124
	v_mul_f32_e32 v105, v105, v124
	v_mul_f32_e32 v106, v106, v124
	v_mul_f32_e32 v107, v107, v124
	v_mul_f32_e32 v120, v120, v104
	v_mul_f32_e32 v121, v121, v105
	v_mul_f32_e32 v122, v122, v106
	v_mul_f32_e32 v123, v123, v107
	v_mul_f32_e32 v104, v116, v124
	v_mul_f32_e32 v105, v117, v124
	v_mul_f32_e32 v106, v118, v124
	v_mul_f32_e32 v107, v119, v124
	v_mul_f32_e32 v100, v100, v124
	v_mul_f32_e32 v101, v101, v124
	v_mul_f32_e32 v102, v102, v124
	v_mul_f32_e32 v103, v103, v124
	v_mul_f32_e32 v104, v104, v100
	v_mul_f32_e32 v105, v105, v101
	v_mul_f32_e32 v106, v106, v102
	v_mul_f32_e32 v107, v107, v103
	ds_read_b128 v[100:103], v163 offset:3584
	v_mul_f32_e32 v130, v130, v134
	v_mul_f32_e32 v131, v131, v134
	v_mul_f32_e32 v112, v112, v134
	v_mul_f32_e32 v113, v113, v134
	v_mul_f32_e32 v114, v114, v134
	v_mul_f32_e32 v115, v115, v134
	v_mul_f32_e32 v126, v126, v134
	v_mul_f32_e32 v127, v127, v134
	s_waitcnt lgkmcnt(0)
	v_mul_f32_e32 v92, v92, v102
	v_mul_f32_e32 v93, v93, v102
	v_mul_f32_e32 v80, v80, v102
	v_mul_f32_e32 v81, v81, v102
	v_mul_f32_e32 v110, v110, v134
	v_mul_f32_e32 v111, v111, v134
	v_mul_f32_e32 v80, v92, v80
	v_mul_f32_e32 v81, v93, v81
	v_mov_b32_e32 v92, v103
	v_mul_f32_e32 v84, v84, v92
	v_mul_f32_e32 v85, v85, v92
	v_mul_f32_e32 v86, v86, v92
	v_mul_f32_e32 v87, v87, v92
	v_mul_f32_e32 v68, v68, v92
	v_mul_f32_e32 v69, v69, v92
	v_mul_f32_e32 v70, v70, v92
	v_mul_f32_e32 v71, v71, v92
	v_mul_f32_e32 v96, v96, v102
	v_mul_f32_e32 v97, v97, v102
	v_mul_f32_e32 v98, v98, v102
	v_mul_f32_e32 v99, v99, v102
	v_mul_f32_e32 v88, v88, v102
	v_mul_f32_e32 v89, v89, v102
	v_mul_f32_e32 v90, v90, v102
	v_mul_f32_e32 v91, v91, v102
	v_mul_f32_e32 v94, v94, v102
	v_mul_f32_e32 v95, v95, v102
	v_mul_f32_e32 v82, v82, v102
	v_mul_f32_e32 v83, v83, v102
	v_mul_f32_e32 v86, v86, v70
	v_mul_f32_e32 v87, v87, v71
	v_mul_f32_e32 v84, v84, v68
	v_mul_f32_e32 v85, v85, v69
	v_mul_f32_e32 v68, v76, v92
	v_mul_f32_e32 v69, v77, v92
	v_mul_f32_e32 v70, v78, v92
	v_mul_f32_e32 v71, v79, v92
	v_mul_f32_e32 v60, v60, v92
	v_mul_f32_e32 v61, v61, v92
	v_mul_f32_e32 v62, v62, v92
	v_mul_f32_e32 v63, v63, v92
	v_mul_f32_e32 v114, v130, v114
	v_mul_f32_e32 v115, v131, v115
	v_mul_f32_e32 v112, v128, v112
	v_mul_f32_e32 v113, v129, v113
	v_mul_f32_e32 v110, v126, v110
	v_mul_f32_e32 v111, v127, v111
	v_mul_f32_e32 v90, v98, v90
	v_mul_f32_e32 v91, v99, v91
	v_mul_f32_e32 v88, v96, v88
	v_mul_f32_e32 v89, v97, v89
	v_mul_f32_e32 v82, v94, v82
	v_mul_f32_e32 v83, v95, v83
	v_mul_f32_e32 v62, v70, v62
	v_mul_f32_e32 v63, v71, v63
	v_mul_f32_e32 v60, v68, v60
	v_mul_f32_e32 v61, v69, v61
	s_and_saveexec_b64 s[30:31], s[6:7]
	s_cbranch_execz .LBB0_198
	s_add_i32 s36, s53, s35
	v_lshl_add_u32 v68, v158, 2, s36
	ds_write_b128 v68, v[112:115]
	ds_write_b128 v68, v[108:111] offset:16
	ds_write_b128 v68, v[120:123] offset:1024
	ds_write_b128 v68, v[104:107] offset:1040
	ds_write_b128 v68, v[88:91] offset:4096
	ds_write_b128 v68, v[80:83] offset:4112
	ds_write_b128 v68, v[84:87] offset:5120
	ds_write_b128 v68, v[60:63] offset:5136

.LBB0_201:
	v_mul_f32_e32 v72, v72, v132
	v_mul_f32_e32 v73, v73, v132
	v_mul_f32_e32 v56, v56, v132
	v_mul_f32_e32 v57, v57, v132
	v_mul_f32_e32 v64, v64, v133
	v_mul_f32_e32 v65, v65, v133
	v_mul_f32_e32 v52, v52, v133
	v_mul_f32_e32 v53, v53, v133
	v_mul_f32_e32 v56, v72, v56
	v_mul_f32_e32 v57, v73, v57
	v_mul_f32_e32 v52, v64, v52
	v_mul_f32_e32 v53, v65, v53
	s_waitcnt lgkmcnt(0)
	v_mov_b32_dpp v68, v120 row_shr:1 row_mask:0xf bank_mask:0xf
	v_mul_f32_e32 v72, v112, v96
	v_mul_f32_e32 v64, v92, v68
	v_mul_f32_e32 v65, v52, v96
	v_fmac_f32_e32 v72, v52, v92
	v_fmac_f32_e32 v64, v56, v96
	v_fmac_f32_e32 v65, v56, v92
	v_fmac_f32_e32 v72, v56, v76
	v_mul_f32_e32 v56, v120, v96
	v_mul_f32_e32 v66, v66, v133
	v_mul_f32_e32 v67, v67, v133
	v_mul_f32_e32 v54, v54, v133
	v_mul_f32_e32 v55, v55, v133
	v_fmac_f32_e32 v56, v112, v92
	v_mov_b32_dpp v69, v121 row_shr:1 row_mask:0xf bank_mask:0xf
	v_mul_f32_e32 v73, v113, v97
	v_mul_f32_e32 v74, v74, v132
	v_mul_f32_e32 v75, v75, v132
	v_mul_f32_e32 v58, v58, v132
	v_mul_f32_e32 v59, v59, v132
	v_mul_f32_e32 v54, v66, v54
	v_mul_f32_e32 v55, v67, v55
	v_fmac_f32_e32 v56, v52, v76
	v_mul_f32_e32 v52, v93, v69
	v_mul_f32_e32 v66, v53, v97
	v_fmac_f32_e32 v73, v53, v93
	v_mul_f32_e32 v58, v74, v58
	v_mul_f32_e32 v59, v75, v59
	v_fmac_f32_e32 v52, v57, v97
	v_fmac_f32_e32 v66, v57, v93
	v_fmac_f32_e32 v73, v57, v77
	v_mul_f32_e32 v57, v121, v97
	v_mul_f32_e32 v67, v54, v98
	v_fmac_f32_e32 v57, v113, v93
	v_mov_b32_dpp v70, v122 row_shr:1 row_mask:0xf bank_mask:0xf
	v_fmac_f32_e32 v67, v58, v94
	v_fmac_f32_e32 v57, v53, v77
	v_mul_f32_e32 v53, v94, v70
	v_fmac_f32_e32 v67, v78, v70
	v_mul_f32_e32 v70, v114, v98
	v_fmac_f32_e32 v70, v54, v94
	v_fmac_f32_e32 v53, v58, v98
	v_fmac_f32_e32 v70, v58, v78
	v_mul_f32_e32 v58, v122, v98
	v_mul_f32_e32 v74, v55, v99
	v_fmac_f32_e32 v58, v114, v94
	v_mov_b32_dpp v71, v123 row_shr:1 row_mask:0xf bank_mask:0xf
	v_fmac_f32_e32 v74, v59, v95
	s_addk_i32 s19, 0x800
	v_fmac_f32_e32 v58, v54, v78
	v_mul_f32_e32 v54, v95, v71
	v_fmac_f32_e32 v74, v79, v71
	v_mul_f32_e32 v71, v115, v99
	s_and_b64 s[36:37], s[28:29], exec
	v_fmac_f32_e32 v71, v55, v95
	s_cselect_b32 s19, s19, s30
	v_mov_b32_dpp v116, v112 row_shr:1 row_mask:0xf bank_mask:0xf
	v_mov_b32_dpp v117, v113 row_shr:1 row_mask:0xf bank_mask:0xf
	v_mov_b32_dpp v118, v114 row_shr:1 row_mask:0xf bank_mask:0xf
	v_fmac_f32_e32 v54, v59, v99
	v_fmac_f32_e32 v71, v59, v79
	v_mul_f32_e32 v59, v123, v99
	s_cmp_lg_u32 s19, 0
	v_fmac_f32_e32 v64, v76, v116
	v_fmac_f32_e32 v65, v76, v68
	v_fmac_f32_e32 v52, v77, v117
	v_fmac_f32_e32 v66, v77, v69
	v_fmac_f32_e32 v53, v78, v118
	v_mov_b32_dpp v119, v115 row_shr:1 row_mask:0xf bank_mask:0xf
	v_fmac_f32_e32 v59, v115, v95
	s_cselect_b64 s[30:31], -1, 0
	s_cmp_eq_u32 s19, 0
	v_lshl_add_u32 v102, v158, 2, s19
	v_fmac_f32_e32 v54, v79, v119
	v_fmac_f32_e32 v59, v55, v79
	v_cvt_pk_bf16_f32 v68, v64, v52
	v_cvt_pk_bf16_f32 v69, v53, v54
	v_cvt_pk_bf16_f32 v66, v65, v66
	v_cvt_pk_bf16_f32 v67, v67, v74
	v_cvt_pk_bf16_f32 v64, v72, v73
	v_cvt_pk_bf16_f32 v65, v70, v71
	v_cvt_pk_bf16_f32 v52, v56, v57
	v_cvt_pk_bf16_f32 v53, v58, v59
	s_cbranch_scc1 .LBB0_203
	ds_read_b128 v[70:73], v102
	ds_read_b128 v[54:57], v102 offset:1024
	s_branch .LBB0_204

.LBB0_204:
	v_mul_f32_e32 v40, v40, v101
	v_mul_f32_e32 v41, v41, v101
	v_mul_f32_e32 v42, v42, v101
	v_mul_f32_e32 v43, v43, v101
	v_mul_f32_e32 v32, v32, v101
	v_mul_f32_e32 v33, v33, v101
	v_mul_f32_e32 v34, v34, v101
	v_mul_f32_e32 v35, v35, v101
	v_mul_f32_e32 v44, v44, v100
	v_mul_f32_e32 v45, v45, v100
	v_mul_f32_e32 v36, v36, v100
	v_mul_f32_e32 v37, v37, v100
	v_mul_f32_e32 v34, v42, v34
	v_mul_f32_e32 v35, v43, v35
	v_mul_f32_e32 v32, v40, v32
	v_mul_f32_e32 v33, v41, v33
	s_waitcnt lgkmcnt(0)
	v_mov_b32_dpp v54, v84 row_shr:1 row_mask:0xf bank_mask:0xf
	v_mul_f32_e32 v42, v88, v96
	v_mul_f32_e32 v43, v84, v96
	v_mul_f32_e32 v36, v44, v36
	v_mul_f32_e32 v37, v45, v37
	v_mul_f32_e32 v40, v92, v54
	v_mul_f32_e32 v41, v32, v96
	v_fmac_f32_e32 v42, v32, v92
	v_fmac_f32_e32 v43, v88, v92
	v_mov_b32_dpp v55, v85 row_shr:1 row_mask:0xf bank_mask:0xf
	v_mul_f32_e32 v44, v89, v97
	v_mul_f32_e32 v46, v46, v100
	v_mul_f32_e32 v47, v47, v100
	v_mul_f32_e32 v38, v38, v100
	v_mul_f32_e32 v39, v39, v100
	v_fmac_f32_e32 v40, v36, v96
	v_fmac_f32_e32 v41, v36, v92
	v_fmac_f32_e32 v42, v36, v76
	v_fmac_f32_e32 v43, v32, v76
	v_mul_f32_e32 v32, v93, v55
	v_mul_f32_e32 v36, v33, v97
	v_fmac_f32_e32 v44, v33, v93
	v_mul_f32_e32 v38, v46, v38
	v_mul_f32_e32 v39, v47, v39
	v_fmac_f32_e32 v32, v37, v97
	v_fmac_f32_e32 v36, v37, v93
	v_fmac_f32_e32 v44, v37, v77
	v_mul_f32_e32 v45, v85, v97
	v_mul_f32_e32 v37, v34, v98
	v_mul_f32_e32 v47, v86, v98
	v_fmac_f32_e32 v45, v89, v93
	v_mov_b32_dpp v56, v86 row_shr:1 row_mask:0xf bank_mask:0xf
	v_fmac_f32_e32 v37, v38, v94
	v_mul_f32_e32 v46, v90, v98
	v_fmac_f32_e32 v47, v90, v94
	v_mov_b32_dpp v57, v87 row_shr:1 row_mask:0xf bank_mask:0xf
	v_fmac_f32_e32 v41, v76, v54
	v_fmac_f32_e32 v36, v77, v55
	v_fmac_f32_e32 v45, v33, v77
	v_mul_f32_e32 v33, v94, v56
	v_fmac_f32_e32 v37, v78, v56
	v_fmac_f32_e32 v46, v34, v94
	v_fmac_f32_e32 v47, v34, v78
	v_mul_f32_e32 v34, v95, v57
	v_mul_f32_e32 v54, v35, v99
	v_mul_f32_e32 v55, v91, v99
	v_mul_f32_e32 v56, v87, v99
	v_mov_b32_dpp v70, v88 row_shr:1 row_mask:0xf bank_mask:0xf
	v_mov_b32_dpp v71, v89 row_shr:1 row_mask:0xf bank_mask:0xf
	v_mov_b32_dpp v72, v90 row_shr:1 row_mask:0xf bank_mask:0xf
	v_fmac_f32_e32 v33, v38, v98
	v_mov_b32_dpp v73, v91 row_shr:1 row_mask:0xf bank_mask:0xf
	v_fmac_f32_e32 v34, v39, v99
	v_fmac_f32_e32 v54, v39, v95
	v_fmac_f32_e32 v55, v35, v95
	v_fmac_f32_e32 v56, v91, v95
	v_fmac_f32_e32 v40, v76, v70
	v_fmac_f32_e32 v32, v77, v71
	v_fmac_f32_e32 v33, v78, v72
	v_fmac_f32_e32 v46, v38, v78
	v_fmac_f32_e32 v34, v79, v73
	v_fmac_f32_e32 v54, v79, v57
	v_fmac_f32_e32 v55, v39, v79
	v_fmac_f32_e32 v56, v35, v79
	v_cvt_pk_bf16_f32 v38, v40, v32
	v_cvt_pk_bf16_f32 v39, v33, v34
	v_cvt_pk_bf16_f32 v36, v41, v36
	v_cvt_pk_bf16_f32 v37, v37, v54
	v_cvt_pk_bf16_f32 v34, v42, v44
	v_cvt_pk_bf16_f32 v35, v46, v55
	v_cvt_pk_bf16_f32 v32, v43, v45
	v_cvt_pk_bf16_f32 v33, v47, v56
	ds_read_b128 v[44:47], v124 offset:16
	ds_read_b128 v[56:59], v124 offset:528
	ds_read_b128 v[40:43], v124 offset:1040
	v_mov_b32_e32 v77, 0
	s_andn2_b64 vcc, exec, s[34:35]
	v_mov_b32_e32 v79, 0
	v_mov_b32_e32 v71, 0
	v_mov_b32_e32 v55, 0
	v_mov_b32_e32 v73, 0
	v_mov_b32_e32 v78, 0
	v_mov_b32_e32 v70, 0
	v_mov_b32_e32 v54, 0
	v_mov_b32_e32 v72, 0
	s_cbranch_vccnz .LBB0_206
	ds_read_b128 v[70:73], v103 offset:1040
	ds_read_b128 v[84:87], v103 offset:16
	s_waitcnt lgkmcnt(0)
	v_mov_b32_e32 v79, v70
	v_mov_b32_e32 v55, v72
	v_mov_b32_e32 v78, v84
	v_mov_b32_e32 v70, v85
	v_mov_b32_e32 v54, v86
	v_mov_b32_e32 v72, v87
.LBB0_206:
	v_mov_b32_e32 v84, v132
	v_mov_b32_e32 v85, v132
	v_mov_b32_e32 v90, v132
	v_mov_b32_e32 v91, v132
	v_mul_f32_e32 v28, v28, v84
	v_mul_f32_e32 v29, v29, v85
	v_mul_f32_e32 v20, v20, v84
	v_mul_f32_e32 v21, v21, v85
	v_mov_b32_e32 v132, v133
	v_mov_b32_e32 v86, v133
	v_mov_b32_e32 v87, v133
	v_mul_f32_e32 v30, v30, v90
	v_mul_f32_e32 v31, v31, v91
	v_mul_f32_e32 v22, v22, v90
	v_mul_f32_e32 v23, v23, v91
	v_mul_f32_e32 v28, v28, v20
	v_mul_f32_e32 v29, v29, v21
	v_mul_f32_e32 v20, v26, v132
	v_mul_f32_e32 v21, v27, v133
	v_mul_f32_e32 v18, v18, v132
	v_mul_f32_e32 v19, v19, v133
	v_mul_f32_e32 v30, v30, v22
	v_mul_f32_e32 v31, v31, v23
	v_mul_f32_e32 v22, v24, v86
	v_mul_f32_e32 v23, v25, v87
	v_mul_f32_e32 v16, v16, v86
	v_mul_f32_e32 v17, v17, v87
	v_mul_f32_e32 v18, v20, v18
	v_mul_f32_e32 v19, v21, v19
	v_mov_b32_dpp v78, v108 row_shr:1 row_mask:0xf bank_mask:0xf
	v_mov_b32_dpp v79, v104 row_shr:1 row_mask:0xf bank_mask:0xf
	s_waitcnt lgkmcnt(0)
	v_mov_b32_e32 v20, v44
	v_mov_b32_e32 v21, v56
	v_mul_f32_e32 v16, v22, v16
	v_mul_f32_e32 v17, v23, v17
	v_mul_f32_e32 v22, v20, v78
	v_mul_f32_e32 v23, v21, v79
	v_mov_b32_e32 v78, v56
	v_fma_f32 v23, v28, v40, v23
	v_add_f32_e32 v76, v22, v23
	v_mov_b32_e32 v22, v28
	v_mov_b32_e32 v23, v44
	v_mul_f32_e32 v22, v22, v78
	v_mul_f32_e32 v23, v23, v79
	v_mov_b32_dpp v70, v109 row_shr:1 row_mask:0xf bank_mask:0xf
	v_fma_f32 v22, v16, v40, v22
	v_add_f32_e32 v78, v22, v23
	v_mov_b32_e32 v22, v28
	v_mov_b32_e32 v23, v16
	v_mul_f32_e32 v22, v22, v20
	v_mul_f32_e32 v23, v23, v21
	v_mov_b32_dpp v71, v105 row_shr:1 row_mask:0xf bank_mask:0xf
	v_fma_f32 v23, v108, v40, v23
	v_add_f32_e32 v79, v22, v23
	v_mov_b32_e32 v22, v16
	v_mov_b32_e32 v23, v108
	v_mul_f32_e32 v22, v22, v20
	v_mul_f32_e32 v23, v23, v21
	v_mov_b32_e32 v108, v17
	v_fma_f32 v16, v104, v40, v23
	v_add_f32_e32 v84, v22, v16
	v_mov_b32_e32 v22, v45
	v_mov_b32_e32 v23, v57
	v_mul_f32_e32 v24, v22, v70
	v_mul_f32_e32 v25, v23, v71
	v_mov_b32_e32 v70, v57
	v_fma_f32 v16, v29, v41, v25
	v_add_f32_e32 v28, v24, v16
	v_mov_b32_e32 v24, v29
	v_mov_b32_e32 v25, v45
	v_mul_f32_e32 v24, v24, v70
	v_mul_f32_e32 v25, v25, v71
	v_mov_b32_dpp v54, v110 row_shr:1 row_mask:0xf bank_mask:0xf
	v_fma_f32 v16, v17, v41, v24
	v_add_f32_e32 v85, v16, v25
	v_mov_b32_e32 v16, v29
	v_mul_f32_e32 v24, v16, v22
	v_mul_f32_e32 v25, v17, v23
	v_mov_b32_dpp v55, v106 row_shr:1 row_mask:0xf bank_mask:0xf
	v_fma_f32 v16, v109, v41, v25
	v_add_f32_e32 v86, v24, v16
	v_mul_f32_e32 v16, v108, v22
	v_mul_f32_e32 v17, v109, v23
	v_mov_b32_e32 v24, v46
	v_fma_f32 v17, v105, v41, v17
	v_mov_b32_e32 v25, v58
	v_add_f32_e32 v87, v16, v17
	v_mul_f32_e32 v16, v24, v54
	v_mul_f32_e32 v17, v25, v55
	v_mov_b32_e32 v54, v58
	v_fma_f32 v17, v30, v42, v17
	v_add_f32_e32 v29, v16, v17
	v_mov_b32_e32 v16, v30
	v_mov_b32_e32 v17, v46
	v_mul_f32_e32 v16, v16, v54
	v_mul_f32_e32 v17, v17, v55
	v_mov_b32_dpp v72, v111 row_shr:1 row_mask:0xf bank_mask:0xf
	v_fma_f32 v16, v18, v42, v16
	v_add_f32_e32 v54, v16, v17
	v_mov_b32_e32 v16, v30
	v_mov_b32_e32 v17, v18
	v_mul_f32_e32 v16, v16, v24
	v_mul_f32_e32 v17, v17, v25
	v_mov_b32_dpp v73, v107 row_shr:1 row_mask:0xf bank_mask:0xf
	v_fma_f32 v17, v110, v42, v17
	v_add_f32_e32 v30, v16, v17
	v_mov_b32_e32 v16, v18
	v_mov_b32_e32 v17, v110
	v_mul_f32_e32 v16, v16, v24
	v_mul_f32_e32 v17, v17, v25
	v_mov_b32_e32 v26, v47
	v_fma_f32 v17, v106, v42, v17
	v_mov_b32_e32 v27, v59
	v_add_f32_e32 v55, v16, v17
	v_mul_f32_e32 v16, v26, v72
	v_mul_f32_e32 v17, v27, v73
	v_mov_b32_e32 v72, v59
	v_fma_f32 v17, v31, v43, v17
	v_add_f32_e32 v71, v16, v17
	v_mov_b32_e32 v16, v31
	v_mov_b32_e32 v17, v47
	v_mul_f32_e32 v16, v16, v72
	v_mul_f32_e32 v17, v17, v73
	v_mov_b32_e32 v18, v31
	v_fma_f32 v16, v19, v43, v16
	v_add_f32_e32 v72, v16, v17
	v_mul_f32_e32 v16, v18, v26
	v_mul_f32_e32 v17, v19, v27
	v_mov_b32_e32 v110, v19
	v_fma_f32 v17, v111, v43, v17
	v_lshl_add_u32 v88, s60, 8, v157
	v_add_f32_e32 v31, v16, v17
	v_mul_f32_e32 v16, v110, v26
	v_mul_f32_e32 v17, v111, v27
	v_lshl_or_b32 v74, s59, 7, v158
	v_fma_f32 v17, v107, v43, v17
	v_ashrrev_i32_e32 v89, 31, v88
	v_ashrrev_i32_e32 v75, 31, v74
	v_add_f32_e32 v73, v16, v17
	v_lshlrev_b64 v[16:17], 11, v[88:89]
	v_cvt_pk_bf16_f32 v70, v76, v28
	v_cvt_pk_bf16_f32 v71, v29, v71
	v_lshl_add_u64 v[28:29], s[0:1], 0, v[16:17]
	v_lshlrev_b64 v[16:17], 1, v[74:75]
	v_lshl_add_u64 v[18:19], v[28:29], 0, v[16:17]
	global_store_dwordx4 v[18:19], v[68:71], off nt
	v_or_b32_e32 v18, 1, v88
	v_ashrrev_i32_e32 v19, 31, v18
	v_lshlrev_b64 v[18:19], 11, v[18:19]
	v_lshl_add_u64 v[18:19], s[0:1], 0, v[18:19]
	v_lshl_add_u64 v[18:19], v[18:19], 0, v[16:17]
	v_cvt_pk_bf16_f32 v68, v78, v85
	v_cvt_pk_bf16_f32 v69, v54, v72
	global_store_dwordx4 v[18:19], v[66:69], off nt
	v_or_b32_e32 v18, 2, v88
	v_ashrrev_i32_e32 v19, 31, v18
	v_lshlrev_b64 v[18:19], 11, v[18:19]
	v_lshl_add_u64 v[18:19], s[0:1], 0, v[18:19]
	v_lshl_add_u64 v[18:19], v[18:19], 0, v[16:17]
	v_cvt_pk_bf16_f32 v66, v79, v86
	v_cvt_pk_bf16_f32 v67, v30, v31
	global_store_dwordx4 v[18:19], v[64:67], off nt
	v_or_b32_e32 v18, 3, v88
	v_ashrrev_i32_e32 v19, 31, v18
	v_lshlrev_b64 v[18:19], 11, v[18:19]
	v_lshl_add_u64 v[18:19], s[0:1], 0, v[18:19]
	v_lshl_add_u64 v[16:17], v[18:19], 0, v[16:17]
	v_cvt_pk_bf16_f32 v54, v84, v87
	v_cvt_pk_bf16_f32 v55, v55, v73
	global_store_dwordx4 v[16:17], v[52:55], off nt
	s_andn2_b64 vcc, exec, s[30:31]
	v_mov_b32_e32 v17, 0
	v_mov_b32_e32 v31, 0
	v_mov_b32_e32 v19, 0
	v_mov_b32_e32 v76, 0
	v_mov_b32_e32 v16, 0
	v_mov_b32_e32 v30, 0
	v_mov_b32_e32 v18, 0
	s_cbranch_vccnz .LBB0_208
	ds_read_b128 v[16:19], v102 offset:1040
	ds_read_b128 v[52:55], v102 offset:16
	s_waitcnt lgkmcnt(0)
	v_mov_b32_e32 v77, v16
	v_mov_b32_e32 v31, v18
	v_mov_b32_e32 v76, v52
	v_mov_b32_e32 v16, v53
	v_mov_b32_e32 v30, v54
	v_mov_b32_e32 v18, v55
.LBB0_208:
	v_mov_b32_e32 v52, v100
	v_mov_b32_e32 v53, v100
	v_mov_b32_e32 v54, v101
	v_mov_b32_e32 v55, v101
	v_mul_f32_e32 v12, v12, v52
	v_mul_f32_e32 v13, v13, v53
	v_mul_f32_e32 v4, v4, v52
	v_mul_f32_e32 v5, v5, v53
	v_mul_f32_e32 v8, v8, v54
	v_mul_f32_e32 v9, v9, v55
	v_mul_f32_e32 v0, v0, v54
	v_mul_f32_e32 v1, v1, v55
	v_mov_b32_dpp v76, v80 row_shr:1 row_mask:0xf bank_mask:0xf
	v_mov_b32_dpp v77, v60 row_shr:1 row_mask:0xf bank_mask:0xf
	v_mov_b32_e32 v64, v100
	v_mov_b32_e32 v65, v100
	v_mul_f32_e32 v4, v12, v4
	v_mul_f32_e32 v5, v13, v5
	v_mov_b32_e32 v100, v101
	v_mul_f32_e32 v0, v8, v0
	v_mul_f32_e32 v1, v9, v1
	v_mul_f32_e32 v8, v20, v76
	v_mul_f32_e32 v9, v21, v77
	v_mul_f32_e32 v10, v10, v100
	v_mul_f32_e32 v11, v11, v101
	v_mul_f32_e32 v2, v2, v100
	v_mul_f32_e32 v3, v3, v101
	v_fma_f32 v9, v4, v40, v9
	v_mul_f32_e32 v2, v10, v2
	v_mul_f32_e32 v3, v11, v3
	v_add_f32_e32 v10, v8, v9
	v_mov_b32_e32 v8, v4
	v_mov_b32_e32 v9, v44
	v_mov_b32_e32 v76, v56
	v_mul_f32_e32 v8, v8, v76
	v_mul_f32_e32 v9, v9, v77
	v_mov_b32_dpp v16, v81 row_shr:1 row_mask:0xf bank_mask:0xf
	v_fma_f32 v8, v0, v40, v8
	v_add_f32_e32 v11, v8, v9
	v_mov_b32_e32 v8, v4
	v_mov_b32_e32 v9, v0
	v_mul_f32_e32 v8, v8, v20
	v_mul_f32_e32 v9, v9, v21
	v_mov_b32_dpp v17, v61 row_shr:1 row_mask:0xf bank_mask:0xf
	v_fma_f32 v4, v80, v40, v9
	v_add_f32_e32 v12, v8, v4
	v_mov_b32_e32 v8, v0
	v_mov_b32_e32 v9, v80
	v_mul_f32_e32 v8, v8, v20
	v_mul_f32_e32 v9, v9, v21
	v_mul_f32_e32 v14, v14, v64
	v_mul_f32_e32 v15, v15, v65
	v_fma_f32 v0, v60, v40, v9
	v_add_f32_e32 v13, v8, v0
	v_mul_f32_e32 v8, v22, v16
	v_mul_f32_e32 v9, v23, v17
	v_mul_f32_e32 v6, v6, v64
	v_mul_f32_e32 v7, v7, v65
	v_fma_f32 v0, v5, v41, v9
	v_mov_b32_e32 v44, v5
	v_mov_b32_e32 v16, v57
	v_mul_f32_e32 v6, v14, v6
	v_mul_f32_e32 v7, v15, v7
	v_add_f32_e32 v14, v8, v0
	v_mul_f32_e32 v8, v44, v16
	v_mul_f32_e32 v9, v45, v17
	v_mov_b32_e32 v80, v1
	v_fma_f32 v0, v1, v41, v8
	v_add_f32_e32 v8, v0, v9
	v_mov_b32_e32 v0, v5
	v_mul_f32_e32 v4, v0, v22
	v_mul_f32_e32 v5, v1, v23
	v_mov_b32_dpp v30, v82 row_shr:1 row_mask:0xf bank_mask:0xf
	v_fma_f32 v0, v81, v41, v5
	v_add_f32_e32 v4, v4, v0
	v_mul_f32_e32 v0, v80, v22
	v_mul_f32_e32 v1, v81, v23
	v_mov_b32_dpp v31, v62 row_shr:1 row_mask:0xf bank_mask:0xf
	v_fma_f32 v1, v61, v41, v1
	v_add_f32_e32 v5, v0, v1
	v_mul_f32_e32 v0, v24, v30
	v_mul_f32_e32 v1, v25, v31
	v_mov_b32_e32 v30, v58
	v_fma_f32 v1, v6, v42, v1
	v_add_f32_e32 v9, v0, v1
	v_mov_b32_e32 v0, v6
	v_mov_b32_e32 v1, v46
	v_mul_f32_e32 v0, v0, v30
	v_mul_f32_e32 v1, v1, v31
	v_mov_b32_dpp v18, v83 row_shr:1 row_mask:0xf bank_mask:0xf
	v_fma_f32 v0, v2, v42, v0
	v_add_f32_e32 v15, v0, v1
	v_mov_b32_e32 v0, v6
	v_mov_b32_e32 v1, v2
	v_mul_f32_e32 v0, v0, v24
	v_mul_f32_e32 v1, v1, v25
	v_mov_b32_dpp v19, v63 row_shr:1 row_mask:0xf bank_mask:0xf
	v_fma_f32 v1, v82, v42, v1
	v_add_f32_e32 v6, v0, v1
	v_mov_b32_e32 v0, v2
	v_mov_b32_e32 v1, v82
	v_mul_f32_e32 v0, v0, v24
	v_mul_f32_e32 v1, v1, v25
	v_mov_b32_e32 v46, v7
	v_fma_f32 v1, v62, v42, v1
	v_add_f32_e32 v16, v0, v1
	v_mul_f32_e32 v0, v26, v18
	v_mul_f32_e32 v1, v27, v19
	v_mov_b32_e32 v18, v59
	v_fma_f32 v1, v7, v43, v1
	v_add_f32_e32 v17, v0, v1
	v_mul_f32_e32 v0, v46, v18
	v_mul_f32_e32 v1, v47, v19
	v_mov_b32_e32 v2, v7
	v_fma_f32 v0, v3, v43, v0
	v_add_f32_e32 v18, v0, v1
	v_mul_f32_e32 v0, v2, v26
	v_mul_f32_e32 v1, v3, v27
	v_mov_b32_e32 v82, v3
	v_fma_f32 v1, v83, v43, v1
	v_add_f32_e32 v7, v0, v1
	v_mul_f32_e32 v0, v82, v26
	v_mul_f32_e32 v1, v83, v27
	v_cvt_pk_bf16_f32 v40, v10, v14
	v_cvt_pk_bf16_f32 v41, v9, v17
	s_nop 0
	v_fma_f32 v1, v63, v43, v1
	v_add_f32_e32 v19, v0, v1
	v_lshl_add_u64 v[0:1], v[74:75], 1, v[28:29]
	v_add_co_u32_e32 v2, vcc, s56, v0
	s_nop 1
	v_addc_co_u32_e32 v3, vcc, 0, v1, vcc
	v_add_co_u32_e32 v0, vcc, 0x41000, v0
	global_store_dwordx4 v[2:3], v[38:41], off nt
	s_nop 0
	v_addc_co_u32_e32 v1, vcc, 0, v1, vcc
	v_cvt_pk_bf16_f32 v38, v11, v8
	v_cvt_pk_bf16_f32 v39, v15, v18
	global_store_dwordx4 v[2:3], v[36:39], off offset:2048 nt
	s_nop 1
	v_cvt_pk_bf16_f32 v36, v12, v4
	v_cvt_pk_bf16_f32 v37, v6, v7
	global_store_dwordx4 v[0:1], v[34:37], off nt
	s_nop 1
	v_cvt_pk_bf16_f32 v34, v13, v5
	v_cvt_pk_bf16_f32 v35, v16, v19
	global_store_dwordx4 v[0:1], v[32:35], off offset:2048 nt
	s_and_b64 vcc, exec, s[8:9]
	s_mov_b64 s[8:9], -1
	s_cbranch_vccnz .LBB0_189
	s_xor_b32 s8, s15, 0x1000
	s_add_i32 s15, s8, 0
	s_add_i32 s15, s15, 0x24010
	s_and_saveexec_b64 s[8:9], s[2:3]
	s_cbranch_execz .LBB0_211
	v_add3_u32 v0, s15, v161, v146
	s_waitcnt vmcnt(8)
	ds_write_b128 v0, v[48:51]

.LBB0_286:
	ds_read_b128 v[128:131], v162
	ds_read_b128 v[148:151], v162 offset:1024
	ds_read_b128 v[152:155], v162 offset:2048
	ds_read_b128 v[166:169], v162 offset:3072
	s_add_u32 s36, s34, 0xfffc0080
	s_addc_u32 s37, s35, -1
	s_cmp_eq_u32 s59, 12
	s_cselect_b32 s39, s23, s37
	s_cselect_b32 s38, s55, s36
	s_cselect_b32 s37, s21, s58
	s_cselect_b32 s36, s56, s57
	v_lshl_add_u64 v[156:157], s[34:35], 0, v[140:141]
	s_add_i32 m0, s31, 0xc000
	ds_read_b128 v[170:173], v163
	ds_read_b128 v[174:177], v163 offset:1024
	ds_read_b128 v[178:181], v163 offset:2048
	ds_read_b128 v[182:185], v163 offset:3072
	ds_read_b128 v[190:193], v163 offset:4096
	ds_read_b128 v[194:197], v163 offset:5120
	ds_read_b128 v[198:201], v163 offset:6144
	ds_read_b128 v[202:205], v163 offset:7168
	global_load_lds_dwordx4 v[156:157], off
	v_lshl_add_u64 v[156:157], s[34:35], 0, v[142:143]
	s_add_i32 m0, s31, 0xe000
	s_nop 0
	global_load_lds_dwordx4 v[156:157], off
	s_waitcnt lgkmcnt(8)
	s_barrier
	s_waitcnt lgkmcnt(0)
	s_setprio 1
	s_waitcnt lgkmcnt(0)
	v_mfma_f32_16x16x32_bf16 v[124:127], v[128:131], v[170:173], v[124:127]
	v_mfma_f32_16x16x32_bf16 v[120:123], v[152:155], v[170:173], v[120:123]
	v_mfma_f32_16x16x32_bf16 v[108:111], v[128:131], v[178:181], v[108:111]
	v_mfma_f32_16x16x32_bf16 v[104:107], v[152:155], v[178:181], v[104:107]
	v_mfma_f32_16x16x32_bf16 v[92:95], v[128:131], v[190:193], v[92:95]
	v_mfma_f32_16x16x32_bf16 v[88:91], v[152:155], v[190:193], v[88:91]
	v_mfma_f32_16x16x32_bf16 v[76:79], v[128:131], v[198:201], v[76:79]
	v_mfma_f32_16x16x32_bf16 v[72:75], v[152:155], v[198:201], v[72:75]
	v_mfma_f32_16x16x32_bf16 v[124:127], v[148:151], v[174:177], v[124:127]
	v_mfma_f32_16x16x32_bf16 v[120:123], v[166:169], v[174:177], v[120:123]
	v_mfma_f32_16x16x32_bf16 v[108:111], v[148:151], v[182:185], v[108:111]
	v_mfma_f32_16x16x32_bf16 v[104:107], v[166:169], v[182:185], v[104:107]
	v_mfma_f32_16x16x32_bf16 v[92:95], v[148:151], v[194:197], v[92:95]
	v_mfma_f32_16x16x32_bf16 v[88:91], v[166:169], v[194:197], v[88:91]
	v_mfma_f32_16x16x32_bf16 v[76:79], v[148:151], v[202:205], v[76:79]
	v_mfma_f32_16x16x32_bf16 v[72:75], v[166:169], v[202:205], v[72:75]
	s_setprio 0
	s_barrier
	s_add_i32 s60, s52, s44
	v_lshl_add_u64 v[156:157], s[36:37], 0, v[134:135]
	s_mov_b32 m0, s60
	ds_read_b128 v[206:209], v164
	ds_read_b128 v[210:213], v164 offset:1024
	ds_read_b128 v[214:217], v164 offset:2048
	ds_read_b128 v[218:221], v164 offset:3072
	global_load_lds_dwordx4 v[156:157], off
	v_lshl_add_u64 v[186:187], s[36:37], 0, v[138:139]
	s_add_i32 m0, s60, 0x2000
	s_nop 0
	global_load_lds_dwordx4 v[186:187], off
	s_barrier
	s_waitcnt lgkmcnt(0)
	s_setprio 1
	s_waitcnt lgkmcnt(0)
	v_mfma_f32_16x16x32_bf16 v[116:119], v[206:209], v[170:173], v[116:119]
	v_mfma_f32_16x16x32_bf16 v[112:115], v[214:217], v[170:173], v[112:115]
	v_mfma_f32_16x16x32_bf16 v[100:103], v[206:209], v[178:181], v[100:103]
	v_mfma_f32_16x16x32_bf16 v[96:99], v[214:217], v[178:181], v[96:99]
	v_mfma_f32_16x16x32_bf16 v[84:87], v[206:209], v[190:193], v[84:87]
	v_mfma_f32_16x16x32_bf16 v[80:83], v[214:217], v[190:193], v[80:83]
	v_mfma_f32_16x16x32_bf16 v[68:71], v[206:209], v[198:201], v[68:71]
	v_mfma_f32_16x16x32_bf16 v[64:67], v[214:217], v[198:201], v[64:67]
	v_mfma_f32_16x16x32_bf16 v[116:119], v[210:213], v[174:177], v[116:119]
	v_mfma_f32_16x16x32_bf16 v[112:115], v[218:221], v[174:177], v[112:115]
	v_mfma_f32_16x16x32_bf16 v[100:103], v[210:213], v[182:185], v[100:103]
	v_mfma_f32_16x16x32_bf16 v[96:99], v[218:221], v[182:185], v[96:99]
	v_mfma_f32_16x16x32_bf16 v[84:87], v[210:213], v[194:197], v[84:87]
	v_mfma_f32_16x16x32_bf16 v[80:83], v[218:221], v[194:197], v[80:83]
	v_mfma_f32_16x16x32_bf16 v[68:71], v[210:213], v[202:205], v[68:71]
	v_mfma_f32_16x16x32_bf16 v[64:67], v[218:221], v[202:205], v[64:67]
	s_setprio 0
	s_mov_b32 m0, s31
	v_lshl_add_u64 v[222:223], s[38:39], 0, v[132:133]
	s_barrier
	ds_read_b128 v[170:173], v163 offset:16384
	ds_read_b128 v[174:177], v163 offset:17408
	ds_read_b128 v[178:181], v163 offset:18432
	ds_read_b128 v[182:185], v163 offset:19456
	ds_read_b128 v[190:193], v163 offset:20480
	ds_read_b128 v[194:197], v163 offset:21504
	ds_read_b128 v[198:201], v163 offset:22528
	ds_read_b128 v[202:205], v163 offset:23552
	global_load_lds_dwordx4 v[222:223], off
	v_lshl_add_u64 v[224:225], s[38:39], 0, v[136:137]
	s_mov_b32 m0, s45
	s_nop 0
	global_load_lds_dwordx4 v[224:225], off
	s_barrier
	s_waitcnt lgkmcnt(0)
	s_setprio 1
	s_waitcnt lgkmcnt(0)
	v_mfma_f32_16x16x32_bf16 v[60:63], v[128:131], v[170:173], v[60:63]
	v_mfma_f32_16x16x32_bf16 v[56:59], v[152:155], v[170:173], v[56:59]
	v_mfma_f32_16x16x32_bf16 v[44:47], v[128:131], v[178:181], v[44:47]
	v_mfma_f32_16x16x32_bf16 v[40:43], v[152:155], v[178:181], v[40:43]
	v_mfma_f32_16x16x32_bf16 v[28:31], v[128:131], v[190:193], v[28:31]
	v_mfma_f32_16x16x32_bf16 v[24:27], v[152:155], v[190:193], v[24:27]
	v_mfma_f32_16x16x32_bf16 v[12:15], v[128:131], v[198:201], v[12:15]
	v_mfma_f32_16x16x32_bf16 v[8:11], v[152:155], v[198:201], v[8:11]
	v_mfma_f32_16x16x32_bf16 v[60:63], v[148:151], v[174:177], v[60:63]
	v_mfma_f32_16x16x32_bf16 v[56:59], v[166:169], v[174:177], v[56:59]
	v_mfma_f32_16x16x32_bf16 v[44:47], v[148:151], v[182:185], v[44:47]
	v_mfma_f32_16x16x32_bf16 v[40:43], v[166:169], v[182:185], v[40:43]
	v_mfma_f32_16x16x32_bf16 v[28:31], v[148:151], v[194:197], v[28:31]
	v_mfma_f32_16x16x32_bf16 v[24:27], v[166:169], v[194:197], v[24:27]
	v_mfma_f32_16x16x32_bf16 v[12:15], v[148:151], v[202:205], v[12:15]
	v_mfma_f32_16x16x32_bf16 v[8:11], v[166:169], v[202:205], v[8:11]
	s_setprio 0
	s_barrier
	s_add_u32 s60, s36, 0x40000
	s_addc_u32 s61, s37, 0
	s_add_i32 s62, s53, s44
	v_lshl_add_u64 v[128:129], s[60:61], 0, v[134:135]
	s_mov_b32 m0, s62
	s_nop 0
	global_load_lds_dwordx4 v[128:129], off
	v_lshl_add_u64 v[128:129], s[60:61], 0, v[138:139]
	s_add_i32 m0, s62, 0x2000
	s_nop 0
	global_load_lds_dwordx4 v[128:129], off
	s_waitcnt vmcnt(6)
	s_barrier
	s_setprio 1
	v_mfma_f32_16x16x32_bf16 v[52:55], v[206:209], v[170:173], v[52:55]
	v_mfma_f32_16x16x32_bf16 v[48:51], v[214:217], v[170:173], v[48:51]
	v_mfma_f32_16x16x32_bf16 v[36:39], v[206:209], v[178:181], v[36:39]
	v_mfma_f32_16x16x32_bf16 v[32:35], v[214:217], v[178:181], v[32:35]
	v_mfma_f32_16x16x32_bf16 v[20:23], v[206:209], v[190:193], v[20:23]
	v_mfma_f32_16x16x32_bf16 v[16:19], v[214:217], v[190:193], v[16:19]
	v_mfma_f32_16x16x32_bf16 v[4:7], v[206:209], v[198:201], v[4:7]
	v_mfma_f32_16x16x32_bf16 v[0:3], v[214:217], v[198:201], v[0:3]
	v_mfma_f32_16x16x32_bf16 v[52:55], v[210:213], v[174:177], v[52:55]
	v_mfma_f32_16x16x32_bf16 v[48:51], v[218:221], v[174:177], v[48:51]
	v_mfma_f32_16x16x32_bf16 v[36:39], v[210:213], v[182:185], v[36:39]
	v_mfma_f32_16x16x32_bf16 v[32:35], v[218:221], v[182:185], v[32:35]
	v_mfma_f32_16x16x32_bf16 v[20:23], v[210:213], v[194:197], v[20:23]
	v_mfma_f32_16x16x32_bf16 v[16:19], v[218:221], v[194:197], v[16:19]
	v_mfma_f32_16x16x32_bf16 v[4:7], v[210:213], v[202:205], v[4:7]
	v_mfma_f32_16x16x32_bf16 v[0:3], v[218:221], v[202:205], v[0:3]
	s_setprio 0
	s_add_i32 s60, 0, 0x18000
	v_add_u32_e32 v158, s60, v160
	s_barrier
	ds_read_b128 v[128:131], v158
	ds_read_b128 v[148:151], v158 offset:1024
	ds_read_b128 v[152:155], v158 offset:2048
	ds_read_b128 v[166:169], v158 offset:3072
	s_add_u32 s38, s38, 0x40000
	s_addc_u32 s39, s39, 0
	s_mov_b32 m0, s46
	v_lshl_add_u64 v[206:207], s[38:39], 0, v[132:133]
	ds_read_b128 v[170:173], v163 offset:32768
	ds_read_b128 v[174:177], v163 offset:33792
	ds_read_b128 v[178:181], v163 offset:34816
	ds_read_b128 v[182:185], v163 offset:35840
	ds_read_b128 v[190:193], v163 offset:36864
	ds_read_b128 v[194:197], v163 offset:37888
	ds_read_b128 v[198:201], v163 offset:38912
	ds_read_b128 v[202:205], v163 offset:39936
	global_load_lds_dwordx4 v[206:207], off
	v_lshl_add_u64 v[206:207], s[38:39], 0, v[136:137]
	s_mov_b32 m0, s47
	s_nop 0
	global_load_lds_dwordx4 v[206:207], off
	s_waitcnt lgkmcnt(8)
	s_barrier
	s_waitcnt lgkmcnt(0)
	s_setprio 1
	s_waitcnt lgkmcnt(0)
	v_mfma_f32_16x16x32_bf16 v[124:127], v[128:131], v[170:173], v[124:127]
	v_mfma_f32_16x16x32_bf16 v[120:123], v[152:155], v[170:173], v[120:123]
	v_mfma_f32_16x16x32_bf16 v[108:111], v[128:131], v[178:181], v[108:111]
	v_mfma_f32_16x16x32_bf16 v[104:107], v[152:155], v[178:181], v[104:107]
	v_mfma_f32_16x16x32_bf16 v[92:95], v[128:131], v[190:193], v[92:95]
	v_mfma_f32_16x16x32_bf16 v[88:91], v[152:155], v[190:193], v[88:91]
	v_mfma_f32_16x16x32_bf16 v[76:79], v[128:131], v[198:201], v[76:79]
	v_mfma_f32_16x16x32_bf16 v[72:75], v[152:155], v[198:201], v[72:75]
	v_mfma_f32_16x16x32_bf16 v[124:127], v[148:151], v[174:177], v[124:127]
	v_mfma_f32_16x16x32_bf16 v[120:123], v[166:169], v[174:177], v[120:123]
	v_mfma_f32_16x16x32_bf16 v[108:111], v[148:151], v[182:185], v[108:111]
	v_mfma_f32_16x16x32_bf16 v[104:107], v[166:169], v[182:185], v[104:107]
	v_mfma_f32_16x16x32_bf16 v[92:95], v[148:151], v[194:197], v[92:95]
	v_mfma_f32_16x16x32_bf16 v[88:91], v[166:169], v[194:197], v[88:91]
	v_mfma_f32_16x16x32_bf16 v[76:79], v[148:151], v[202:205], v[76:79]
	v_mfma_f32_16x16x32_bf16 v[72:75], v[166:169], v[202:205], v[72:75]
	s_setprio 0
	s_barrier
	s_add_i32 s38, 0, 0x1c000
	s_add_i32 s39, s60, s44
	v_add_u32_e32 v158, s38, v160
	v_lshl_add_u64 v[156:157], v[156:157], 0, s[8:9]
	s_mov_b32 m0, s39
	ds_read_b128 v[206:209], v158
	ds_read_b128 v[210:213], v158 offset:1024
	ds_read_b128 v[214:217], v158 offset:2048
	ds_read_b128 v[218:221], v158 offset:3072
	global_load_lds_dwordx4 v[156:157], off
	v_lshl_add_u64 v[156:157], v[186:187], 0, s[8:9]
	s_add_i32 m0, s39, 0x2000
	s_nop 0
	global_load_lds_dwordx4 v[156:157], off
	s_barrier
	s_waitcnt lgkmcnt(0)
	s_setprio 1
	s_waitcnt lgkmcnt(0)
	v_mfma_f32_16x16x32_bf16 v[116:119], v[206:209], v[170:173], v[116:119]
	v_mfma_f32_16x16x32_bf16 v[112:115], v[214:217], v[170:173], v[112:115]
	v_mfma_f32_16x16x32_bf16 v[100:103], v[206:209], v[178:181], v[100:103]
	v_mfma_f32_16x16x32_bf16 v[96:99], v[214:217], v[178:181], v[96:99]
	v_mfma_f32_16x16x32_bf16 v[84:87], v[206:209], v[190:193], v[84:87]
	v_mfma_f32_16x16x32_bf16 v[80:83], v[214:217], v[190:193], v[80:83]
	v_mfma_f32_16x16x32_bf16 v[68:71], v[206:209], v[198:201], v[68:71]
	v_mfma_f32_16x16x32_bf16 v[64:67], v[214:217], v[198:201], v[64:67]
	v_mfma_f32_16x16x32_bf16 v[116:119], v[210:213], v[174:177], v[116:119]
	v_mfma_f32_16x16x32_bf16 v[112:115], v[218:221], v[174:177], v[112:115]
	v_mfma_f32_16x16x32_bf16 v[100:103], v[210:213], v[182:185], v[100:103]
	v_mfma_f32_16x16x32_bf16 v[96:99], v[218:221], v[182:185], v[96:99]
	v_mfma_f32_16x16x32_bf16 v[84:87], v[210:213], v[194:197], v[84:87]
	v_mfma_f32_16x16x32_bf16 v[80:83], v[218:221], v[194:197], v[80:83]
	v_mfma_f32_16x16x32_bf16 v[68:71], v[210:213], v[202:205], v[68:71]
	v_mfma_f32_16x16x32_bf16 v[64:67], v[218:221], v[202:205], v[64:67]
	s_setprio 0
	s_mov_b32 m0, s49
	v_lshl_add_u64 v[156:157], v[222:223], 0, s[8:9]
	s_barrier
	ds_read_b128 v[170:173], v163 offset:49152
	ds_read_b128 v[174:177], v163 offset:50176
	ds_read_b128 v[178:181], v163 offset:51200
	ds_read_b128 v[182:185], v163 offset:52224
	ds_read_b128 v[190:193], v163 offset:53248
	ds_read_b128 v[194:197], v163 offset:54272
	ds_read_b128 v[198:201], v163 offset:55296
	ds_read_b128 v[202:205], v163 offset:56320
	global_load_lds_dwordx4 v[156:157], off
	v_lshl_add_u64 v[156:157], v[224:225], 0, s[8:9]
	s_mov_b32 m0, s50
	s_nop 0
	global_load_lds_dwordx4 v[156:157], off
	s_barrier
	s_waitcnt lgkmcnt(0)
	s_setprio 1
	s_waitcnt lgkmcnt(0)
	v_mfma_f32_16x16x32_bf16 v[60:63], v[128:131], v[170:173], v[60:63]
	v_mfma_f32_16x16x32_bf16 v[56:59], v[152:155], v[170:173], v[56:59]
	v_mfma_f32_16x16x32_bf16 v[44:47], v[128:131], v[178:181], v[44:47]
	v_mfma_f32_16x16x32_bf16 v[40:43], v[152:155], v[178:181], v[40:43]
	v_mfma_f32_16x16x32_bf16 v[28:31], v[128:131], v[190:193], v[28:31]
	v_mfma_f32_16x16x32_bf16 v[24:27], v[152:155], v[190:193], v[24:27]
	v_mfma_f32_16x16x32_bf16 v[12:15], v[128:131], v[198:201], v[12:15]
	v_mfma_f32_16x16x32_bf16 v[8:11], v[152:155], v[198:201], v[8:11]
	v_mfma_f32_16x16x32_bf16 v[60:63], v[148:151], v[174:177], v[60:63]
	v_mfma_f32_16x16x32_bf16 v[56:59], v[166:169], v[174:177], v[56:59]
	v_mfma_f32_16x16x32_bf16 v[44:47], v[148:151], v[182:185], v[44:47]
	v_mfma_f32_16x16x32_bf16 v[40:43], v[166:169], v[182:185], v[40:43]
	v_mfma_f32_16x16x32_bf16 v[28:31], v[148:151], v[194:197], v[28:31]
	v_mfma_f32_16x16x32_bf16 v[24:27], v[166:169], v[194:197], v[24:27]
	v_mfma_f32_16x16x32_bf16 v[12:15], v[148:151], v[202:205], v[12:15]
	v_mfma_f32_16x16x32_bf16 v[8:11], v[166:169], v[202:205], v[8:11]
	s_setprio 0
	s_barrier
	s_add_u32 s36, s36, 0x40080
	s_addc_u32 s37, s37, 0
	s_add_i32 s38, s38, s44
	v_lshl_add_u64 v[128:129], s[36:37], 0, v[134:135]
	s_mov_b32 m0, s38
	s_nop 0
	global_load_lds_dwordx4 v[128:129], off
	v_lshl_add_u64 v[128:129], s[36:37], 0, v[138:139]
	s_add_i32 m0, s38, 0x2000
	s_nop 0
	global_load_lds_dwordx4 v[128:129], off
	s_waitcnt vmcnt(6)
	s_barrier
	s_setprio 1
	v_mfma_f32_16x16x32_bf16 v[52:55], v[206:209], v[170:173], v[52:55]
	v_mfma_f32_16x16x32_bf16 v[48:51], v[214:217], v[170:173], v[48:51]
	v_mfma_f32_16x16x32_bf16 v[36:39], v[206:209], v[178:181], v[36:39]
	v_mfma_f32_16x16x32_bf16 v[32:35], v[214:217], v[178:181], v[32:35]
	v_mfma_f32_16x16x32_bf16 v[20:23], v[206:209], v[190:193], v[20:23]
	v_mfma_f32_16x16x32_bf16 v[16:19], v[214:217], v[190:193], v[16:19]
	v_mfma_f32_16x16x32_bf16 v[4:7], v[206:209], v[198:201], v[4:7]
	v_mfma_f32_16x16x32_bf16 v[0:3], v[214:217], v[198:201], v[0:3]
	v_mfma_f32_16x16x32_bf16 v[52:55], v[210:213], v[174:177], v[52:55]
	v_mfma_f32_16x16x32_bf16 v[48:51], v[218:221], v[174:177], v[48:51]
	v_mfma_f32_16x16x32_bf16 v[36:39], v[210:213], v[182:185], v[36:39]
	v_mfma_f32_16x16x32_bf16 v[32:35], v[218:221], v[182:185], v[32:35]
	v_mfma_f32_16x16x32_bf16 v[20:23], v[210:213], v[194:197], v[20:23]
	v_mfma_f32_16x16x32_bf16 v[16:19], v[218:221], v[194:197], v[16:19]
	v_mfma_f32_16x16x32_bf16 v[4:7], v[210:213], v[202:205], v[4:7]
	v_mfma_f32_16x16x32_bf16 v[0:3], v[218:221], v[202:205], v[0:3]
	s_setprio 0
	s_add_i32 s59, s59, 2
	s_add_u32 s34, s34, 0x100
	s_addc_u32 s35, s35, 0
	s_add_u32 s57, s57, 0x100
	s_addc_u32 s58, s58, 0
	s_cmp_gt_u32 s59, 13
	s_barrier
	s_cbranch_scc0 .LBB0_286
	v_lshl_add_u32 v128, s30, 8, v159
	v_or_b32_e32 v156, 16, v128
	v_lshl_or_b32 v130, s54, 8, v161
	v_ashrrev_i32_e32 v129, 31, v128
	v_ashrrev_i32_e32 v157, 31, v156
	v_ashrrev_i32_e32 v131, 31, v130
	v_lshl_add_u64 v[152:153], v[128:129], 2, s[10:11]
	v_lshlrev_b64 v[154:155], 11, v[128:129]
	v_lshl_add_u64 v[170:171], v[156:157], 2, s[10:11]
	v_lshlrev_b64 v[186:187], 11, v[156:157]
	v_or_b32_e32 v156, 32, v128
	v_or_b32_e32 v128, 48, v128
	v_lshlrev_b64 v[148:149], 1, v[130:131]
	v_ashrrev_i32_e32 v157, 31, v156
	v_ashrrev_i32_e32 v129, 31, v128
	v_lshl_add_u64 v[150:151], s[0:1], 0, v[148:149]
	v_lshl_add_u64 v[182:183], v[156:157], 2, s[10:11]
	v_lshlrev_b64 v[198:199], 11, v[156:157]
	v_lshlrev_b64 v[156:157], 11, v[128:129]
	v_lshl_add_u64 v[130:131], v[150:151], 0, v[154:155]
	v_lshl_add_u64 v[178:179], v[150:151], 0, v[186:187]
	v_lshl_add_u64 v[190:191], v[150:151], 0, v[198:199]
	v_lshl_add_u64 v[192:193], v[128:129], 2, s[10:11]
	v_lshl_add_u64 v[128:129], v[150:151], 0, v[156:157]
	global_load_dword v200, v[152:153], off
	global_load_dwordx4 v[166:169], v[130:131], off
	global_load_dword v202, v[170:171], off
	s_nop 0
	global_load_dwordx4 v[170:173], v[130:131], off offset:256
	global_load_dwordx4 v[174:177], v[178:179], off
	s_nop 0
	global_load_dwordx4 v[178:181], v[178:179], off offset:256
	s_nop 0
	global_load_dword v204, v[182:183], off
	s_nop 0
	global_load_dwordx4 v[182:185], v[190:191], off
	global_load_dword v158, v[192:193], off
	s_nop 0
	global_load_dwordx4 v[190:193], v[190:191], off offset:256
	s_nop 0
	global_load_dwordx4 v[194:197], v[128:129], off
	s_nop 0
	global_load_dwordx4 v[128:131], v[128:129], off offset:256
	global_load_dword v216, v[152:153], off offset:512
	global_load_dword v218, v[152:153], off offset:576
	global_load_dword v220, v[152:153], off offset:640
	v_lshl_add_u64 v[252:253], v[154:155], 0, s[6:7]
	v_lshl_add_u64 v[252:253], v[150:151], 0, v[252:253]
	global_load_dwordx4 v[236:239], v[252:253], off
	global_load_dwordx4 v[240:243], v[252:253], off offset:256
	v_lshl_add_u64 v[252:253], v[154:155], 0, s[12:13]
	v_lshl_add_u64 v[252:253], v[150:151], 0, v[252:253]
	global_load_dwordx4 v[244:247], v[252:253], off
	global_load_dwordx4 v[248:251], v[252:253], off offset:256
	v_lshl_add_u64 v[252:253], v[154:155], 0, s[14:15]
	v_lshl_add_u64 v[252:253], v[150:151], 0, v[252:253]
	global_load_dwordx4 v[208:211], v[252:253], off
	global_load_dwordx4 v[212:215], v[252:253], off offset:256
	global_load_dword v252, v[152:153], off offset:704
	s_waitcnt vmcnt(10)
	v_mul_f32_e32 v124, v124, v200
	v_mul_f32_e32 v125, v125, v200
	v_mul_f32_e32 v206, v122, v200
	v_mul_f32_e32 v207, v123, v200
	v_mul_f32_e32 v122, v120, v200
	v_mul_f32_e32 v123, v121, v200
	v_lshlrev_b32_e32 v120, 16, v166
	v_and_b32_e32 v121, 0xffff0000, v166
	v_mul_f32_e32 v120, v124, v120
	v_mul_f32_e32 v121, v125, v121
	v_mul_f32_e32 v126, v126, v200
	v_mul_f32_e32 v127, v127, v200
	v_cvt_pk_bf16_f32 v120, v120, v121
	v_lshlrev_b32_e32 v121, 16, v167
	v_and_b32_e32 v124, 0xffff0000, v167
	v_mul_f32_e32 v121, v126, v121
	v_mul_f32_e32 v124, v127, v124
	v_cvt_pk_bf16_f32 v121, v121, v124
	v_lshlrev_b32_e32 v124, 16, v168
	v_mul_f32_e32 v122, v122, v124
	v_and_b32_e32 v124, 0xffff0000, v168
	v_mul_f32_e32 v123, v123, v124
	v_cvt_pk_bf16_f32 v122, v122, v123
	v_lshlrev_b32_e32 v123, 16, v169
	v_and_b32_e32 v124, 0xffff0000, v169
	v_mul_f32_e32 v123, v206, v123
	v_mul_f32_e32 v124, v207, v124
	v_cvt_pk_bf16_f32 v123, v123, v124
	v_lshl_add_u64 v[124:125], s[26:27], 0, v[154:155]
	v_lshl_add_u64 v[124:125], v[124:125], 0, v[148:149]
	global_store_dwordx4 v[124:125], v[120:123], off
	v_mul_f32_e32 v116, v116, v200
	v_mul_f32_e32 v117, v117, v200
	v_mul_f32_e32 v118, v118, v200
	v_mul_f32_e32 v119, v119, v200
	v_mul_f32_e32 v120, v114, v200
	v_mul_f32_e32 v121, v115, v200
	v_mul_f32_e32 v114, v112, v200
	v_mul_f32_e32 v115, v113, v200
	v_lshlrev_b32_e32 v112, 16, v170
	v_and_b32_e32 v113, 0xffff0000, v170
	v_mul_f32_e32 v112, v116, v112
	v_mul_f32_e32 v113, v117, v113
	v_cvt_pk_bf16_f32 v112, v112, v113
	v_lshlrev_b32_e32 v113, 16, v171
	v_and_b32_e32 v116, 0xffff0000, v171
	v_mul_f32_e32 v113, v118, v113
	v_mul_f32_e32 v116, v119, v116
	v_cvt_pk_bf16_f32 v113, v113, v116
	v_lshlrev_b32_e32 v116, 16, v172
	v_mul_f32_e32 v114, v114, v116
	v_and_b32_e32 v116, 0xffff0000, v172
	v_mul_f32_e32 v115, v115, v116
	v_cvt_pk_bf16_f32 v114, v114, v115
	v_lshlrev_b32_e32 v115, 16, v173
	v_mul_f32_e32 v115, v120, v115
	v_and_b32_e32 v116, 0xffff0000, v173
	v_mul_f32_e32 v116, v121, v116
	v_cvt_pk_bf16_f32 v115, v115, v116
	global_store_dwordx4 v[124:125], v[112:115], off offset:256
	v_mul_f32_e32 v108, v108, v202
	v_mul_f32_e32 v109, v109, v202
	v_mul_f32_e32 v110, v110, v202
	v_mul_f32_e32 v111, v111, v202
	v_mul_f32_e32 v112, v106, v202
	v_mul_f32_e32 v113, v107, v202
	v_mul_f32_e32 v106, v104, v202
	v_mul_f32_e32 v107, v105, v202
	v_lshlrev_b32_e32 v104, 16, v174
	v_and_b32_e32 v105, 0xffff0000, v174
	v_mul_f32_e32 v104, v108, v104
	v_mul_f32_e32 v105, v109, v105
	v_cvt_pk_bf16_f32 v104, v104, v105
	v_lshlrev_b32_e32 v105, 16, v175
	v_and_b32_e32 v108, 0xffff0000, v175
	v_mul_f32_e32 v105, v110, v105
	v_mul_f32_e32 v108, v111, v108
	v_cvt_pk_bf16_f32 v105, v105, v108
	v_lshlrev_b32_e32 v108, 16, v176
	v_mul_f32_e32 v106, v106, v108
	v_and_b32_e32 v108, 0xffff0000, v176
	v_mul_f32_e32 v107, v107, v108
	v_cvt_pk_bf16_f32 v106, v106, v107
	v_lshlrev_b32_e32 v107, 16, v177
	v_and_b32_e32 v108, 0xffff0000, v177
	v_mul_f32_e32 v107, v112, v107
	v_mul_f32_e32 v108, v113, v108
	v_cvt_pk_bf16_f32 v107, v107, v108
	v_lshl_add_u64 v[108:109], s[26:27], 0, v[186:187]
	v_lshl_add_u64 v[108:109], v[108:109], 0, v[148:149]
	global_store_dwordx4 v[108:109], v[104:107], off
	v_mul_f32_e32 v100, v100, v202
	v_mul_f32_e32 v101, v101, v202
	v_mul_f32_e32 v102, v102, v202
	v_mul_f32_e32 v103, v103, v202
	v_mul_f32_e32 v104, v98, v202
	v_mul_f32_e32 v105, v99, v202
	v_mul_f32_e32 v98, v96, v202
	v_mul_f32_e32 v99, v97, v202
	v_lshlrev_b32_e32 v96, 16, v178
	v_and_b32_e32 v97, 0xffff0000, v178
	v_mul_f32_e32 v96, v100, v96
	v_mul_f32_e32 v97, v101, v97
	v_cvt_pk_bf16_f32 v96, v96, v97
	v_lshlrev_b32_e32 v97, 16, v179
	v_and_b32_e32 v100, 0xffff0000, v179
	v_mul_f32_e32 v97, v102, v97
	v_mul_f32_e32 v100, v103, v100
	v_cvt_pk_bf16_f32 v97, v97, v100
	v_lshlrev_b32_e32 v100, 16, v180
	v_mul_f32_e32 v98, v98, v100
	v_and_b32_e32 v100, 0xffff0000, v180
	v_mul_f32_e32 v99, v99, v100
	v_cvt_pk_bf16_f32 v98, v98, v99
	v_lshlrev_b32_e32 v99, 16, v181
	v_mul_f32_e32 v99, v104, v99
	v_and_b32_e32 v100, 0xffff0000, v181
	v_mul_f32_e32 v100, v105, v100
	v_cvt_pk_bf16_f32 v99, v99, v100
	global_store_dwordx4 v[108:109], v[96:99], off offset:256
	v_mul_f32_e32 v92, v92, v204
	v_mul_f32_e32 v93, v93, v204
	v_mul_f32_e32 v94, v94, v204
	v_mul_f32_e32 v95, v95, v204
	v_mul_f32_e32 v96, v90, v204
	v_mul_f32_e32 v97, v91, v204
	v_mul_f32_e32 v90, v88, v204
	v_mul_f32_e32 v91, v89, v204
	v_lshlrev_b32_e32 v88, 16, v182
	v_and_b32_e32 v89, 0xffff0000, v182
	v_mul_f32_e32 v88, v92, v88
	v_mul_f32_e32 v89, v93, v89
	v_cvt_pk_bf16_f32 v88, v88, v89
	v_lshlrev_b32_e32 v89, 16, v183
	v_and_b32_e32 v92, 0xffff0000, v183
	v_mul_f32_e32 v89, v94, v89
	v_mul_f32_e32 v92, v95, v92
	v_cvt_pk_bf16_f32 v89, v89, v92
	v_lshlrev_b32_e32 v92, 16, v184
	v_mul_f32_e32 v90, v90, v92
	v_and_b32_e32 v92, 0xffff0000, v184
	v_mul_f32_e32 v91, v91, v92
	v_cvt_pk_bf16_f32 v90, v90, v91
	v_lshlrev_b32_e32 v91, 16, v185
	v_and_b32_e32 v92, 0xffff0000, v185
	v_mul_f32_e32 v91, v96, v91
	v_mul_f32_e32 v92, v97, v92
	v_cvt_pk_bf16_f32 v91, v91, v92
	v_lshl_add_u64 v[92:93], s[26:27], 0, v[198:199]
	v_lshl_add_u64 v[92:93], v[92:93], 0, v[148:149]
	global_store_dwordx4 v[92:93], v[88:91], off
	v_mul_f32_e32 v84, v84, v204
	v_mul_f32_e32 v85, v85, v204
	v_mul_f32_e32 v86, v86, v204
	v_mul_f32_e32 v87, v87, v204
	v_mul_f32_e32 v88, v82, v204
	v_mul_f32_e32 v89, v83, v204
	v_mul_f32_e32 v82, v80, v204
	v_mul_f32_e32 v83, v81, v204
	v_lshlrev_b32_e32 v80, 16, v190
	v_and_b32_e32 v81, 0xffff0000, v190
	v_mul_f32_e32 v80, v84, v80
	v_mul_f32_e32 v81, v85, v81
	v_cvt_pk_bf16_f32 v80, v80, v81
	v_lshlrev_b32_e32 v81, 16, v191
	v_and_b32_e32 v84, 0xffff0000, v191
	v_mul_f32_e32 v81, v86, v81
	v_mul_f32_e32 v84, v87, v84
	v_cvt_pk_bf16_f32 v81, v81, v84
	v_lshlrev_b32_e32 v84, 16, v192
	v_mul_f32_e32 v82, v82, v84
	v_and_b32_e32 v84, 0xffff0000, v192
	v_mul_f32_e32 v83, v83, v84
	v_cvt_pk_bf16_f32 v82, v82, v83
	v_lshlrev_b32_e32 v83, 16, v193
	v_mul_f32_e32 v83, v88, v83
	v_and_b32_e32 v84, 0xffff0000, v193
	v_mul_f32_e32 v84, v89, v84
	v_cvt_pk_bf16_f32 v83, v83, v84
	global_store_dwordx4 v[92:93], v[80:83], off offset:256
	v_mul_f32_e32 v76, v76, v158
	v_mul_f32_e32 v77, v77, v158
	v_mul_f32_e32 v78, v78, v158
	v_mul_f32_e32 v79, v79, v158
	v_mul_f32_e32 v80, v74, v158
	v_mul_f32_e32 v81, v75, v158
	v_mul_f32_e32 v74, v72, v158
	v_mul_f32_e32 v75, v73, v158
	v_lshlrev_b32_e32 v72, 16, v194
	v_and_b32_e32 v73, 0xffff0000, v194
	v_mul_f32_e32 v72, v76, v72
	v_mul_f32_e32 v73, v77, v73
	v_cvt_pk_bf16_f32 v72, v72, v73
	v_lshlrev_b32_e32 v73, 16, v195
	v_and_b32_e32 v76, 0xffff0000, v195
	v_mul_f32_e32 v73, v78, v73
	v_mul_f32_e32 v76, v79, v76
	v_cvt_pk_bf16_f32 v73, v73, v76
	v_lshlrev_b32_e32 v76, 16, v196
	v_mul_f32_e32 v74, v74, v76
	v_and_b32_e32 v76, 0xffff0000, v196
	v_mul_f32_e32 v75, v75, v76
	v_cvt_pk_bf16_f32 v74, v74, v75
	v_lshlrev_b32_e32 v75, 16, v197
	v_and_b32_e32 v76, 0xffff0000, v197
	v_mul_f32_e32 v75, v80, v75
	v_mul_f32_e32 v76, v81, v76
	v_cvt_pk_bf16_f32 v75, v75, v76
	v_lshl_add_u64 v[76:77], s[26:27], 0, v[156:157]
	v_lshl_add_u64 v[76:77], v[76:77], 0, v[148:149]
	global_store_dwordx4 v[76:77], v[72:75], off
	v_mul_f32_e32 v68, v68, v158
	v_mul_f32_e32 v69, v69, v158
	v_mul_f32_e32 v70, v70, v158
	v_mul_f32_e32 v71, v71, v158
	v_mul_f32_e32 v72, v66, v158
	v_mul_f32_e32 v73, v67, v158
	v_mul_f32_e32 v66, v64, v158
	v_mul_f32_e32 v67, v65, v158
	v_lshlrev_b32_e32 v64, 16, v128
	v_and_b32_e32 v65, 0xffff0000, v128
	v_mul_f32_e32 v64, v68, v64
	v_mul_f32_e32 v65, v69, v65
	v_cvt_pk_bf16_f32 v64, v64, v65
	v_lshlrev_b32_e32 v65, 16, v129
	v_and_b32_e32 v68, 0xffff0000, v129
	v_mul_f32_e32 v65, v70, v65
	v_mul_f32_e32 v68, v71, v68
	v_cvt_pk_bf16_f32 v65, v65, v68
	v_lshlrev_b32_e32 v68, 16, v130
	v_mul_f32_e32 v66, v66, v68
	v_and_b32_e32 v68, 0xffff0000, v130
	v_mul_f32_e32 v67, v67, v68
	v_cvt_pk_bf16_f32 v66, v66, v67
	v_lshlrev_b32_e32 v67, 16, v131
	v_mul_f32_e32 v67, v72, v67
	v_and_b32_e32 v68, 0xffff0000, v131
	v_mul_f32_e32 v68, v73, v68
	v_cvt_pk_bf16_f32 v67, v67, v68
	v_lshl_add_u64 v[100:101], v[154:155], 0, s[6:7]
	v_lshl_add_u64 v[102:103], v[154:155], 0, s[12:13]
	v_lshl_add_u64 v[104:105], v[154:155], 0, s[14:15]
	global_store_dwordx4 v[76:77], v[64:67], off offset:256
	v_lshl_add_u64 v[92:93], v[150:151], 0, v[104:105]
	v_lshl_add_u64 v[70:71], v[154:155], 0, s[18:19]
	v_lshl_add_u64 v[64:65], v[150:151], 0, v[100:101]
	v_lshl_add_u64 v[66:67], v[150:151], 0, v[102:103]
	v_lshl_add_u64 v[112:113], v[150:151], 0, v[70:71]
	s_nop 0
	s_nop 0
	global_load_dwordx4 v[96:99], v[112:113], off
	global_load_dwordx4 v[64:67], v[112:113], off offset:256
	s_waitcnt vmcnt(10)
	v_mul_f32_e32 v60, v60, v216
	v_mul_f32_e32 v61, v61, v216
	v_mul_f32_e32 v112, v58, v216
	v_mul_f32_e32 v113, v59, v216
	v_mul_f32_e32 v58, v56, v216
	v_mul_f32_e32 v59, v57, v216
	v_lshlrev_b32_e32 v56, 16, v236
	v_and_b32_e32 v57, 0xffff0000, v236
	v_mul_f32_e32 v56, v60, v56
	v_mul_f32_e32 v57, v61, v57
	v_mul_f32_e32 v62, v62, v216
	v_mul_f32_e32 v63, v63, v216
	v_cvt_pk_bf16_f32 v56, v56, v57
	v_lshlrev_b32_e32 v57, 16, v237
	v_and_b32_e32 v60, 0xffff0000, v237
	v_mul_f32_e32 v57, v62, v57
	v_mul_f32_e32 v60, v63, v60
	v_cvt_pk_bf16_f32 v57, v57, v60
	v_lshlrev_b32_e32 v60, 16, v238
	v_mul_f32_e32 v58, v58, v60
	v_and_b32_e32 v60, 0xffff0000, v238
	v_mul_f32_e32 v59, v59, v60
	v_cvt_pk_bf16_f32 v58, v58, v59
	v_lshlrev_b32_e32 v59, 16, v239
	v_and_b32_e32 v60, 0xffff0000, v239
	v_mul_f32_e32 v59, v112, v59
	v_mul_f32_e32 v60, v113, v60
	v_cvt_pk_bf16_f32 v59, v59, v60
	v_lshl_add_u64 v[60:61], s[26:27], 0, v[100:101]
	v_lshl_add_u64 v[60:61], v[60:61], 0, v[148:149]
	global_store_dwordx4 v[60:61], v[56:59], off
	v_mul_f32_e32 v52, v52, v216
	v_mul_f32_e32 v53, v53, v216
	v_mul_f32_e32 v54, v54, v216
	v_mul_f32_e32 v55, v55, v216
	v_mul_f32_e32 v56, v50, v216
	v_mul_f32_e32 v57, v51, v216
	v_mul_f32_e32 v50, v48, v216
	v_mul_f32_e32 v51, v49, v216
	v_lshlrev_b32_e32 v48, 16, v240
	v_and_b32_e32 v49, 0xffff0000, v240
	v_mul_f32_e32 v48, v52, v48
	v_mul_f32_e32 v49, v53, v49
	v_cvt_pk_bf16_f32 v48, v48, v49
	v_lshlrev_b32_e32 v49, 16, v241
	v_and_b32_e32 v52, 0xffff0000, v241
	v_mul_f32_e32 v49, v54, v49
	v_mul_f32_e32 v52, v55, v52
	v_cvt_pk_bf16_f32 v49, v49, v52
	v_lshlrev_b32_e32 v52, 16, v242
	v_mul_f32_e32 v50, v50, v52
	v_and_b32_e32 v52, 0xffff0000, v242
	v_mul_f32_e32 v51, v51, v52
	v_cvt_pk_bf16_f32 v50, v50, v51
	v_lshlrev_b32_e32 v51, 16, v243
	v_mul_f32_e32 v51, v56, v51
	v_and_b32_e32 v52, 0xffff0000, v243
	v_mul_f32_e32 v52, v57, v52
	v_cvt_pk_bf16_f32 v51, v51, v52
	global_store_dwordx4 v[60:61], v[48:51], off offset:256
	v_mul_f32_e32 v44, v44, v218
	v_mul_f32_e32 v45, v45, v218
	v_mul_f32_e32 v46, v46, v218
	v_mul_f32_e32 v47, v47, v218
	v_mul_f32_e32 v48, v42, v218
	v_mul_f32_e32 v49, v43, v218
	v_mul_f32_e32 v42, v40, v218
	v_mul_f32_e32 v43, v41, v218
	v_lshlrev_b32_e32 v40, 16, v244
	v_and_b32_e32 v41, 0xffff0000, v244
	v_mul_f32_e32 v40, v44, v40
	v_mul_f32_e32 v41, v45, v41
	v_cvt_pk_bf16_f32 v40, v40, v41
	v_lshlrev_b32_e32 v41, 16, v245
	v_and_b32_e32 v44, 0xffff0000, v245
	v_mul_f32_e32 v41, v46, v41
	v_mul_f32_e32 v44, v47, v44
	v_cvt_pk_bf16_f32 v41, v41, v44
	v_lshlrev_b32_e32 v44, 16, v246
	v_mul_f32_e32 v42, v42, v44
	v_and_b32_e32 v44, 0xffff0000, v246
	v_mul_f32_e32 v43, v43, v44
	v_cvt_pk_bf16_f32 v42, v42, v43
	v_lshlrev_b32_e32 v43, 16, v247
	v_and_b32_e32 v44, 0xffff0000, v247
	v_mul_f32_e32 v43, v48, v43
	v_mul_f32_e32 v44, v49, v44
	v_cvt_pk_bf16_f32 v43, v43, v44
	v_lshl_add_u64 v[44:45], s[26:27], 0, v[102:103]
	v_lshl_add_u64 v[44:45], v[44:45], 0, v[148:149]
	global_store_dwordx4 v[44:45], v[40:43], off
	v_mul_f32_e32 v36, v36, v218
	v_mul_f32_e32 v37, v37, v218
	v_mul_f32_e32 v38, v38, v218
	v_mul_f32_e32 v39, v39, v218
	v_mul_f32_e32 v40, v34, v218
	v_mul_f32_e32 v41, v35, v218
	v_mul_f32_e32 v34, v32, v218
	v_mul_f32_e32 v35, v33, v218
	v_lshlrev_b32_e32 v32, 16, v248
	v_and_b32_e32 v33, 0xffff0000, v248
	v_mul_f32_e32 v32, v36, v32
	v_mul_f32_e32 v33, v37, v33
	v_cvt_pk_bf16_f32 v32, v32, v33
	v_lshlrev_b32_e32 v33, 16, v249
	v_and_b32_e32 v36, 0xffff0000, v249
	v_mul_f32_e32 v33, v38, v33
	v_mul_f32_e32 v36, v39, v36
	v_cvt_pk_bf16_f32 v33, v33, v36
	v_lshlrev_b32_e32 v36, 16, v250
	v_mul_f32_e32 v34, v34, v36
	v_and_b32_e32 v36, 0xffff0000, v250
	v_mul_f32_e32 v35, v35, v36
	v_cvt_pk_bf16_f32 v34, v34, v35
	v_lshlrev_b32_e32 v35, 16, v251
	v_mul_f32_e32 v35, v40, v35
	v_and_b32_e32 v36, 0xffff0000, v251
	v_mul_f32_e32 v36, v41, v36
	v_cvt_pk_bf16_f32 v35, v35, v36
	global_store_dwordx4 v[44:45], v[32:35], off offset:256
	v_mul_f32_e32 v28, v28, v220
	v_mul_f32_e32 v29, v29, v220
	v_mul_f32_e32 v30, v30, v220
	v_mul_f32_e32 v31, v31, v220
	v_mul_f32_e32 v32, v26, v220
	v_mul_f32_e32 v33, v27, v220
	v_mul_f32_e32 v26, v24, v220
	v_mul_f32_e32 v27, v25, v220
	v_lshlrev_b32_e32 v24, 16, v208
	v_and_b32_e32 v25, 0xffff0000, v208
	v_mul_f32_e32 v24, v28, v24
	v_mul_f32_e32 v25, v29, v25
	v_cvt_pk_bf16_f32 v24, v24, v25
	v_lshlrev_b32_e32 v25, 16, v209
	v_and_b32_e32 v28, 0xffff0000, v209
	v_mul_f32_e32 v25, v30, v25
	v_mul_f32_e32 v28, v31, v28
	v_cvt_pk_bf16_f32 v25, v25, v28
	v_lshlrev_b32_e32 v28, 16, v210
	v_mul_f32_e32 v26, v26, v28
	v_and_b32_e32 v28, 0xffff0000, v210
	v_mul_f32_e32 v27, v27, v28
	v_cvt_pk_bf16_f32 v26, v26, v27
	v_lshlrev_b32_e32 v27, 16, v211
	v_and_b32_e32 v28, 0xffff0000, v211
	v_mul_f32_e32 v27, v32, v27
	v_mul_f32_e32 v28, v33, v28
	v_cvt_pk_bf16_f32 v27, v27, v28
	v_lshl_add_u64 v[28:29], s[26:27], 0, v[104:105]
	v_lshl_add_u64 v[28:29], v[28:29], 0, v[148:149]
	global_store_dwordx4 v[28:29], v[24:27], off
	v_mul_f32_e32 v20, v20, v220
	v_mul_f32_e32 v21, v21, v220
	v_mul_f32_e32 v22, v22, v220
	v_mul_f32_e32 v23, v23, v220
	v_mul_f32_e32 v24, v18, v220
	v_mul_f32_e32 v25, v19, v220
	v_mul_f32_e32 v18, v16, v220
	v_mul_f32_e32 v19, v17, v220
	v_lshlrev_b32_e32 v16, 16, v212
	v_and_b32_e32 v17, 0xffff0000, v212
	v_mul_f32_e32 v16, v20, v16
	v_mul_f32_e32 v17, v21, v17
	v_cvt_pk_bf16_f32 v16, v16, v17
	v_lshlrev_b32_e32 v17, 16, v213
	v_and_b32_e32 v20, 0xffff0000, v213
	v_mul_f32_e32 v17, v22, v17
	v_mul_f32_e32 v20, v23, v20
	v_cvt_pk_bf16_f32 v17, v17, v20
	v_lshlrev_b32_e32 v20, 16, v214
	v_mul_f32_e32 v18, v18, v20
	v_and_b32_e32 v20, 0xffff0000, v214
	v_mul_f32_e32 v19, v19, v20
	v_cvt_pk_bf16_f32 v18, v18, v19
	v_lshlrev_b32_e32 v19, 16, v215
	v_mul_f32_e32 v19, v24, v19
	v_and_b32_e32 v20, 0xffff0000, v215
	v_mul_f32_e32 v20, v25, v20
	v_cvt_pk_bf16_f32 v19, v19, v20
	global_store_dwordx4 v[28:29], v[16:19], off offset:256
	s_waitcnt vmcnt(6)
	v_mul_f32_e32 v12, v12, v252
	v_mul_f32_e32 v13, v13, v252
	v_mul_f32_e32 v14, v14, v252
	v_mul_f32_e32 v15, v15, v252
	v_mul_f32_e32 v16, v10, v252
	v_mul_f32_e32 v17, v11, v252
	v_mul_f32_e32 v10, v8, v252
	v_mul_f32_e32 v11, v9, v252
	v_lshlrev_b32_e32 v8, 16, v96
	v_and_b32_e32 v9, 0xffff0000, v96
	v_mul_f32_e32 v8, v12, v8
	v_mul_f32_e32 v9, v13, v9
	v_cvt_pk_bf16_f32 v8, v8, v9
	v_lshlrev_b32_e32 v9, 16, v97
	v_and_b32_e32 v12, 0xffff0000, v97
	v_mul_f32_e32 v9, v14, v9
	v_mul_f32_e32 v12, v15, v12
	v_cvt_pk_bf16_f32 v9, v9, v12
	v_lshlrev_b32_e32 v12, 16, v98
	v_mul_f32_e32 v10, v10, v12
	v_and_b32_e32 v12, 0xffff0000, v98
	v_mul_f32_e32 v11, v11, v12
	v_cvt_pk_bf16_f32 v10, v10, v11
	v_lshlrev_b32_e32 v11, 16, v99
	v_and_b32_e32 v12, 0xffff0000, v99
	v_mul_f32_e32 v11, v16, v11
	v_mul_f32_e32 v12, v17, v12
	v_cvt_pk_bf16_f32 v11, v11, v12
	v_lshl_add_u64 v[12:13], s[26:27], 0, v[70:71]
	v_lshl_add_u64 v[12:13], v[12:13], 0, v[148:149]
	global_store_dwordx4 v[12:13], v[8:11], off
	v_mul_f32_e32 v4, v4, v252
	v_mul_f32_e32 v5, v5, v252
	v_mul_f32_e32 v6, v6, v252
	v_mul_f32_e32 v7, v7, v252
	v_mul_f32_e32 v8, v2, v252
	v_mul_f32_e32 v9, v3, v252
	v_mul_f32_e32 v2, v0, v252
	v_mul_f32_e32 v3, v1, v252
	v_lshlrev_b32_e32 v0, 16, v64
	v_and_b32_e32 v1, 0xffff0000, v64
	v_mul_f32_e32 v0, v4, v0
	v_mul_f32_e32 v1, v5, v1
	v_cvt_pk_bf16_f32 v0, v0, v1
	v_lshlrev_b32_e32 v1, 16, v65
	v_and_b32_e32 v4, 0xffff0000, v65
	v_mul_f32_e32 v1, v6, v1
	v_mul_f32_e32 v4, v7, v4
	v_cvt_pk_bf16_f32 v1, v1, v4
	v_lshlrev_b32_e32 v4, 16, v66
	v_mul_f32_e32 v2, v2, v4
	v_and_b32_e32 v4, 0xffff0000, v66
	v_mul_f32_e32 v3, v3, v4
	v_cvt_pk_bf16_f32 v2, v2, v3
	v_lshlrev_b32_e32 v3, 16, v67
	v_mul_f32_e32 v3, v8, v3
	v_and_b32_e32 v4, 0xffff0000, v67
	s_and_b64 vcc, exec, s[2:3]
	s_mov_b32 s54, s20
	s_mov_b32 s30, s22
	s_mov_b64 s[36:37], s[28:29]
	s_mov_b64 s[34:35], s[24:25]
	v_mul_f32_e32 v4, v9, v4
	v_cvt_pk_bf16_f32 v3, v3, v4
	global_store_dwordx4 v[12:13], v[0:3], off offset:256
	s_cbranch_vccz .LBB0_279
	s_waitcnt vmcnt(0)
	s_cmpk_gt_u32 s40, 0xff
	s_cbranch_scc1 .LBB0_290
	s_barrier

.LBB0_364:
	ds_read_b128 v[128:131], v208
	ds_read_b128 v[132:135], v208 offset:1024
	ds_read_b128 v[136:139], v208 offset:2048
	ds_read_b128 v[140:143], v208 offset:3072
	s_add_u32 s24, s22, 0xfffc0080
	s_addc_u32 s25, s23, -1
	s_cmp_eq_u32 s51, 12
	s_cselect_b32 s29, s13, s25
	s_cselect_b32 s28, s21, s24
	s_cselect_b32 s25, s11, s50
	s_cselect_b32 s24, s48, s49
	v_lshl_add_u64 v[194:195], s[22:23], 0, v[184:185]
	s_add_i32 m0, s36, 0xc000
	ds_read_b128 v[144:147], v209
	ds_read_b128 v[148:151], v209 offset:1024
	ds_read_b128 v[152:155], v209 offset:2048
	ds_read_b128 v[156:159], v209 offset:3072
	ds_read_b128 v[160:163], v209 offset:4096
	ds_read_b128 v[164:167], v209 offset:5120
	ds_read_b128 v[168:171], v209 offset:6144
	ds_read_b128 v[172:175], v209 offset:7168
	global_load_lds_dwordx4 v[194:195], off
	v_lshl_add_u64 v[194:195], s[22:23], 0, v[186:187]
	s_add_i32 m0, s36, 0xe000
	s_nop 0
	global_load_lds_dwordx4 v[194:195], off
	s_waitcnt lgkmcnt(8)
	s_barrier
	s_waitcnt lgkmcnt(0)
	s_setprio 1
	s_waitcnt lgkmcnt(0)
	v_mfma_f32_16x16x32_bf16 v[124:127], v[128:131], v[144:147], v[124:127]
	v_mfma_f32_16x16x32_bf16 v[120:123], v[136:139], v[144:147], v[120:123]
	v_mfma_f32_16x16x32_bf16 v[108:111], v[128:131], v[152:155], v[108:111]
	v_mfma_f32_16x16x32_bf16 v[104:107], v[136:139], v[152:155], v[104:107]
	v_mfma_f32_16x16x32_bf16 v[92:95], v[128:131], v[160:163], v[92:95]
	v_mfma_f32_16x16x32_bf16 v[88:91], v[136:139], v[160:163], v[88:91]
	v_mfma_f32_16x16x32_bf16 v[76:79], v[128:131], v[168:171], v[76:79]
	v_mfma_f32_16x16x32_bf16 v[72:75], v[136:139], v[168:171], v[72:75]
	v_mfma_f32_16x16x32_bf16 v[124:127], v[132:135], v[148:151], v[124:127]
	v_mfma_f32_16x16x32_bf16 v[120:123], v[140:143], v[148:151], v[120:123]
	v_mfma_f32_16x16x32_bf16 v[108:111], v[132:135], v[156:159], v[108:111]
	v_mfma_f32_16x16x32_bf16 v[104:107], v[140:143], v[156:159], v[104:107]
	v_mfma_f32_16x16x32_bf16 v[92:95], v[132:135], v[164:167], v[92:95]
	v_mfma_f32_16x16x32_bf16 v[88:91], v[140:143], v[164:167], v[88:91]
	v_mfma_f32_16x16x32_bf16 v[76:79], v[132:135], v[172:175], v[76:79]
	v_mfma_f32_16x16x32_bf16 v[72:75], v[140:143], v[172:175], v[72:75]
	s_setprio 0
	s_barrier
	s_add_i32 s52, s45, s35
	v_lshl_add_u64 v[216:217], s[24:25], 0, v[178:179]
	s_mov_b32 m0, s52
	ds_read_b128 v[194:197], v210
	ds_read_b128 v[198:201], v210 offset:1024
	ds_read_b128 v[202:205], v210 offset:2048
	ds_read_b128 v[212:215], v210 offset:3072
	global_load_lds_dwordx4 v[216:217], off
	v_lshl_add_u64 v[218:219], s[24:25], 0, v[182:183]
	s_add_i32 m0, s52, 0x2000
	s_nop 0
	global_load_lds_dwordx4 v[218:219], off
	s_barrier
	s_waitcnt lgkmcnt(0)
	s_setprio 1
	s_waitcnt lgkmcnt(0)
	v_mfma_f32_16x16x32_bf16 v[116:119], v[194:197], v[144:147], v[116:119]
	v_mfma_f32_16x16x32_bf16 v[112:115], v[202:205], v[144:147], v[112:115]
	v_mfma_f32_16x16x32_bf16 v[100:103], v[194:197], v[152:155], v[100:103]
	v_mfma_f32_16x16x32_bf16 v[96:99], v[202:205], v[152:155], v[96:99]
	v_mfma_f32_16x16x32_bf16 v[84:87], v[194:197], v[160:163], v[84:87]
	v_mfma_f32_16x16x32_bf16 v[80:83], v[202:205], v[160:163], v[80:83]
	v_mfma_f32_16x16x32_bf16 v[68:71], v[194:197], v[168:171], v[68:71]
	v_mfma_f32_16x16x32_bf16 v[64:67], v[202:205], v[168:171], v[64:67]
	v_mfma_f32_16x16x32_bf16 v[116:119], v[198:201], v[148:151], v[116:119]
	v_mfma_f32_16x16x32_bf16 v[112:115], v[212:215], v[148:151], v[112:115]
	v_mfma_f32_16x16x32_bf16 v[100:103], v[198:201], v[156:159], v[100:103]
	v_mfma_f32_16x16x32_bf16 v[96:99], v[212:215], v[156:159], v[96:99]
	v_mfma_f32_16x16x32_bf16 v[84:87], v[198:201], v[164:167], v[84:87]
	v_mfma_f32_16x16x32_bf16 v[80:83], v[212:215], v[164:167], v[80:83]
	v_mfma_f32_16x16x32_bf16 v[68:71], v[198:201], v[172:175], v[68:71]
	v_mfma_f32_16x16x32_bf16 v[64:67], v[212:215], v[172:175], v[64:67]
	s_setprio 0
	s_mov_b32 m0, s36
	v_lshl_add_u64 v[220:221], s[28:29], 0, v[176:177]
	s_barrier
	ds_read_b128 v[144:147], v209 offset:16384
	ds_read_b128 v[148:151], v209 offset:17408
	ds_read_b128 v[152:155], v209 offset:18432
	ds_read_b128 v[156:159], v209 offset:19456
	ds_read_b128 v[160:163], v209 offset:20480
	ds_read_b128 v[164:167], v209 offset:21504
	ds_read_b128 v[168:171], v209 offset:22528
	ds_read_b128 v[172:175], v209 offset:23552
	global_load_lds_dwordx4 v[220:221], off
	v_lshl_add_u64 v[222:223], s[28:29], 0, v[180:181]
	s_mov_b32 m0, s37
	s_nop 0
	global_load_lds_dwordx4 v[222:223], off
	s_barrier
	s_waitcnt lgkmcnt(0)
	s_setprio 1
	s_waitcnt lgkmcnt(0)
	v_mfma_f32_16x16x32_bf16 v[60:63], v[128:131], v[144:147], v[60:63]
	v_mfma_f32_16x16x32_bf16 v[56:59], v[136:139], v[144:147], v[56:59]
	v_mfma_f32_16x16x32_bf16 v[44:47], v[128:131], v[152:155], v[44:47]
	v_mfma_f32_16x16x32_bf16 v[40:43], v[136:139], v[152:155], v[40:43]
	v_mfma_f32_16x16x32_bf16 v[28:31], v[128:131], v[160:163], v[28:31]
	v_mfma_f32_16x16x32_bf16 v[24:27], v[136:139], v[160:163], v[24:27]
	v_mfma_f32_16x16x32_bf16 v[12:15], v[128:131], v[168:171], v[12:15]
	v_mfma_f32_16x16x32_bf16 v[8:11], v[136:139], v[168:171], v[8:11]
	v_mfma_f32_16x16x32_bf16 v[60:63], v[132:135], v[148:151], v[60:63]
	v_mfma_f32_16x16x32_bf16 v[56:59], v[140:143], v[148:151], v[56:59]
	v_mfma_f32_16x16x32_bf16 v[44:47], v[132:135], v[156:159], v[44:47]
	v_mfma_f32_16x16x32_bf16 v[40:43], v[140:143], v[156:159], v[40:43]
	v_mfma_f32_16x16x32_bf16 v[28:31], v[132:135], v[164:167], v[28:31]
	v_mfma_f32_16x16x32_bf16 v[24:27], v[140:143], v[164:167], v[24:27]
	v_mfma_f32_16x16x32_bf16 v[12:15], v[132:135], v[172:175], v[12:15]
	v_mfma_f32_16x16x32_bf16 v[8:11], v[140:143], v[172:175], v[8:11]
	s_setprio 0
	s_barrier
	s_add_u32 s52, s24, 0x40000
	s_addc_u32 s53, s25, 0
	s_add_i32 s54, s46, s35
	v_lshl_add_u64 v[128:129], s[52:53], 0, v[178:179]
	s_mov_b32 m0, s54
	s_nop 0
	global_load_lds_dwordx4 v[128:129], off
	v_lshl_add_u64 v[128:129], s[52:53], 0, v[182:183]
	s_add_i32 m0, s54, 0x2000
	s_nop 0
	global_load_lds_dwordx4 v[128:129], off
	s_waitcnt vmcnt(6)
	s_barrier
	s_setprio 1
	v_mfma_f32_16x16x32_bf16 v[52:55], v[194:197], v[144:147], v[52:55]
	v_mfma_f32_16x16x32_bf16 v[48:51], v[202:205], v[144:147], v[48:51]
	v_mfma_f32_16x16x32_bf16 v[36:39], v[194:197], v[152:155], v[36:39]
	v_mfma_f32_16x16x32_bf16 v[32:35], v[202:205], v[152:155], v[32:35]
	v_mfma_f32_16x16x32_bf16 v[20:23], v[194:197], v[160:163], v[20:23]
	v_mfma_f32_16x16x32_bf16 v[16:19], v[202:205], v[160:163], v[16:19]
	v_mfma_f32_16x16x32_bf16 v[4:7], v[194:197], v[168:171], v[4:7]
	v_mfma_f32_16x16x32_bf16 v[0:3], v[202:205], v[168:171], v[0:3]
	v_mfma_f32_16x16x32_bf16 v[52:55], v[198:201], v[148:151], v[52:55]
	v_mfma_f32_16x16x32_bf16 v[48:51], v[212:215], v[148:151], v[48:51]
	v_mfma_f32_16x16x32_bf16 v[36:39], v[198:201], v[156:159], v[36:39]
	v_mfma_f32_16x16x32_bf16 v[32:35], v[212:215], v[156:159], v[32:35]
	v_mfma_f32_16x16x32_bf16 v[20:23], v[198:201], v[164:167], v[20:23]
	v_mfma_f32_16x16x32_bf16 v[16:19], v[212:215], v[164:167], v[16:19]
	v_mfma_f32_16x16x32_bf16 v[4:7], v[198:201], v[172:175], v[4:7]
	v_mfma_f32_16x16x32_bf16 v[0:3], v[212:215], v[172:175], v[0:3]
	s_setprio 0
	s_add_i32 s52, 0, 0x18000
	v_add_u32_e32 v140, s52, v206
	s_barrier
	ds_read_b128 v[128:131], v140
	ds_read_b128 v[132:135], v140 offset:1024
	ds_read_b128 v[136:139], v140 offset:2048
	ds_read_b128 v[140:143], v140 offset:3072
	s_add_u32 s28, s28, 0x40000
	s_addc_u32 s29, s29, 0
	s_mov_b32 m0, s38
	v_lshl_add_u64 v[194:195], s[28:29], 0, v[176:177]
	ds_read_b128 v[144:147], v209 offset:32768
	ds_read_b128 v[148:151], v209 offset:33792
	ds_read_b128 v[152:155], v209 offset:34816
	ds_read_b128 v[156:159], v209 offset:35840
	ds_read_b128 v[160:163], v209 offset:36864
	ds_read_b128 v[164:167], v209 offset:37888
	ds_read_b128 v[168:171], v209 offset:38912
	ds_read_b128 v[172:175], v209 offset:39936
	global_load_lds_dwordx4 v[194:195], off
	v_lshl_add_u64 v[194:195], s[28:29], 0, v[180:181]
	s_mov_b32 m0, s39
	s_nop 0
	global_load_lds_dwordx4 v[194:195], off
	s_waitcnt lgkmcnt(8)
	s_barrier
	s_waitcnt lgkmcnt(0)
	s_setprio 1
	s_waitcnt lgkmcnt(0)
	v_mfma_f32_16x16x32_bf16 v[124:127], v[128:131], v[144:147], v[124:127]
	v_mfma_f32_16x16x32_bf16 v[120:123], v[136:139], v[144:147], v[120:123]
	v_mfma_f32_16x16x32_bf16 v[108:111], v[128:131], v[152:155], v[108:111]
	v_mfma_f32_16x16x32_bf16 v[104:107], v[136:139], v[152:155], v[104:107]
	v_mfma_f32_16x16x32_bf16 v[92:95], v[128:131], v[160:163], v[92:95]
	v_mfma_f32_16x16x32_bf16 v[88:91], v[136:139], v[160:163], v[88:91]
	v_mfma_f32_16x16x32_bf16 v[76:79], v[128:131], v[168:171], v[76:79]
	v_mfma_f32_16x16x32_bf16 v[72:75], v[136:139], v[168:171], v[72:75]
	v_mfma_f32_16x16x32_bf16 v[124:127], v[132:135], v[148:151], v[124:127]
	v_mfma_f32_16x16x32_bf16 v[120:123], v[140:143], v[148:151], v[120:123]
	v_mfma_f32_16x16x32_bf16 v[108:111], v[132:135], v[156:159], v[108:111]
	v_mfma_f32_16x16x32_bf16 v[104:107], v[140:143], v[156:159], v[104:107]
	v_mfma_f32_16x16x32_bf16 v[92:95], v[132:135], v[164:167], v[92:95]
	v_mfma_f32_16x16x32_bf16 v[88:91], v[140:143], v[164:167], v[88:91]
	v_mfma_f32_16x16x32_bf16 v[76:79], v[132:135], v[172:175], v[76:79]
	v_mfma_f32_16x16x32_bf16 v[72:75], v[140:143], v[172:175], v[72:75]
	s_setprio 0
	s_barrier
	s_add_i32 s28, 0, 0x1c000
	s_add_i32 s29, s52, s35
	v_add_u32_e32 v212, s28, v206
	v_lshl_add_u64 v[216:217], v[216:217], 0, s[8:9]
	s_mov_b32 m0, s29
	ds_read_b128 v[194:197], v212
	ds_read_b128 v[198:201], v212 offset:1024
	ds_read_b128 v[202:205], v212 offset:2048
	ds_read_b128 v[212:215], v212 offset:3072
	global_load_lds_dwordx4 v[216:217], off
	v_lshl_add_u64 v[216:217], v[218:219], 0, s[8:9]
	s_add_i32 m0, s29, 0x2000
	s_nop 0
	global_load_lds_dwordx4 v[216:217], off
	s_barrier
	s_waitcnt lgkmcnt(0)
	s_setprio 1
	s_waitcnt lgkmcnt(0)
	v_mfma_f32_16x16x32_bf16 v[116:119], v[194:197], v[144:147], v[116:119]
	v_mfma_f32_16x16x32_bf16 v[112:115], v[202:205], v[144:147], v[112:115]
	v_mfma_f32_16x16x32_bf16 v[100:103], v[194:197], v[152:155], v[100:103]
	v_mfma_f32_16x16x32_bf16 v[96:99], v[202:205], v[152:155], v[96:99]
	v_mfma_f32_16x16x32_bf16 v[84:87], v[194:197], v[160:163], v[84:87]
	v_mfma_f32_16x16x32_bf16 v[80:83], v[202:205], v[160:163], v[80:83]
	v_mfma_f32_16x16x32_bf16 v[68:71], v[194:197], v[168:171], v[68:71]
	v_mfma_f32_16x16x32_bf16 v[64:67], v[202:205], v[168:171], v[64:67]
	v_mfma_f32_16x16x32_bf16 v[116:119], v[198:201], v[148:151], v[116:119]
	v_mfma_f32_16x16x32_bf16 v[112:115], v[212:215], v[148:151], v[112:115]
	v_mfma_f32_16x16x32_bf16 v[100:103], v[198:201], v[156:159], v[100:103]
	v_mfma_f32_16x16x32_bf16 v[96:99], v[212:215], v[156:159], v[96:99]
	v_mfma_f32_16x16x32_bf16 v[84:87], v[198:201], v[164:167], v[84:87]
	v_mfma_f32_16x16x32_bf16 v[80:83], v[212:215], v[164:167], v[80:83]
	v_mfma_f32_16x16x32_bf16 v[68:71], v[198:201], v[172:175], v[68:71]
	v_mfma_f32_16x16x32_bf16 v[64:67], v[212:215], v[172:175], v[64:67]
	s_setprio 0
	s_mov_b32 m0, s41
	v_lshl_add_u64 v[216:217], v[220:221], 0, s[8:9]
	s_barrier
	ds_read_b128 v[144:147], v209 offset:49152
	ds_read_b128 v[148:151], v209 offset:50176
	ds_read_b128 v[152:155], v209 offset:51200
	ds_read_b128 v[156:159], v209 offset:52224
	ds_read_b128 v[160:163], v209 offset:53248
	ds_read_b128 v[164:167], v209 offset:54272
	ds_read_b128 v[168:171], v209 offset:55296
	ds_read_b128 v[172:175], v209 offset:56320
	global_load_lds_dwordx4 v[216:217], off
	v_lshl_add_u64 v[216:217], v[222:223], 0, s[8:9]
	s_mov_b32 m0, s42
	s_nop 0
	global_load_lds_dwordx4 v[216:217], off
	s_barrier
	s_waitcnt lgkmcnt(0)
	s_setprio 1
	s_waitcnt lgkmcnt(0)
	v_mfma_f32_16x16x32_bf16 v[60:63], v[128:131], v[144:147], v[60:63]
	v_mfma_f32_16x16x32_bf16 v[56:59], v[136:139], v[144:147], v[56:59]
	v_mfma_f32_16x16x32_bf16 v[44:47], v[128:131], v[152:155], v[44:47]
	v_mfma_f32_16x16x32_bf16 v[40:43], v[136:139], v[152:155], v[40:43]
	v_mfma_f32_16x16x32_bf16 v[28:31], v[128:131], v[160:163], v[28:31]
	v_mfma_f32_16x16x32_bf16 v[24:27], v[136:139], v[160:163], v[24:27]
	v_mfma_f32_16x16x32_bf16 v[12:15], v[128:131], v[168:171], v[12:15]
	v_mfma_f32_16x16x32_bf16 v[8:11], v[136:139], v[168:171], v[8:11]
	v_mfma_f32_16x16x32_bf16 v[60:63], v[132:135], v[148:151], v[60:63]
	v_mfma_f32_16x16x32_bf16 v[56:59], v[140:143], v[148:151], v[56:59]
	v_mfma_f32_16x16x32_bf16 v[44:47], v[132:135], v[156:159], v[44:47]
	v_mfma_f32_16x16x32_bf16 v[40:43], v[140:143], v[156:159], v[40:43]
	v_mfma_f32_16x16x32_bf16 v[28:31], v[132:135], v[164:167], v[28:31]
	v_mfma_f32_16x16x32_bf16 v[24:27], v[140:143], v[164:167], v[24:27]
	v_mfma_f32_16x16x32_bf16 v[12:15], v[132:135], v[172:175], v[12:15]
	v_mfma_f32_16x16x32_bf16 v[8:11], v[140:143], v[172:175], v[8:11]
	s_setprio 0
	s_barrier
	s_add_u32 s24, s24, 0x40080
	s_addc_u32 s25, s25, 0
	s_add_i32 s28, s28, s35
	v_lshl_add_u64 v[128:129], s[24:25], 0, v[178:179]
	s_mov_b32 m0, s28
	s_nop 0
	global_load_lds_dwordx4 v[128:129], off
	v_lshl_add_u64 v[128:129], s[24:25], 0, v[182:183]
	s_add_i32 m0, s28, 0x2000
	s_nop 0
	global_load_lds_dwordx4 v[128:129], off
	s_waitcnt vmcnt(6)
	s_barrier
	s_setprio 1
	v_mfma_f32_16x16x32_bf16 v[52:55], v[194:197], v[144:147], v[52:55]
	v_mfma_f32_16x16x32_bf16 v[48:51], v[202:205], v[144:147], v[48:51]
	v_mfma_f32_16x16x32_bf16 v[36:39], v[194:197], v[152:155], v[36:39]
	v_mfma_f32_16x16x32_bf16 v[32:35], v[202:205], v[152:155], v[32:35]
	v_mfma_f32_16x16x32_bf16 v[20:23], v[194:197], v[160:163], v[20:23]
	v_mfma_f32_16x16x32_bf16 v[16:19], v[202:205], v[160:163], v[16:19]
	v_mfma_f32_16x16x32_bf16 v[4:7], v[194:197], v[168:171], v[4:7]
	v_mfma_f32_16x16x32_bf16 v[0:3], v[202:205], v[168:171], v[0:3]
	v_mfma_f32_16x16x32_bf16 v[52:55], v[198:201], v[148:151], v[52:55]
	v_mfma_f32_16x16x32_bf16 v[48:51], v[212:215], v[148:151], v[48:51]
	v_mfma_f32_16x16x32_bf16 v[36:39], v[198:201], v[156:159], v[36:39]
	v_mfma_f32_16x16x32_bf16 v[32:35], v[212:215], v[156:159], v[32:35]
	v_mfma_f32_16x16x32_bf16 v[20:23], v[198:201], v[164:167], v[20:23]
	v_mfma_f32_16x16x32_bf16 v[16:19], v[212:215], v[164:167], v[16:19]
	v_mfma_f32_16x16x32_bf16 v[4:7], v[198:201], v[172:175], v[4:7]
	v_mfma_f32_16x16x32_bf16 v[0:3], v[212:215], v[172:175], v[0:3]
	s_setprio 0
	s_add_i32 s51, s51, 2
	s_add_u32 s22, s22, 0x100
	s_addc_u32 s23, s23, 0
	s_add_u32 s49, s49, 0x100
	s_addc_u32 s50, s50, 0
	s_cmp_gt_u32 s51, 13
	s_barrier
	s_cbranch_scc0 .LBB0_364
	v_lshl_add_u32 v196, s20, 8, v189
	v_lshl_or_b32 v194, s6, 8, v207
	v_readlane_b32 s48, v235, 5
	v_ashrrev_i32_e32 v195, 31, v194
	v_readlane_b32 s49, v235, 6
	v_ashrrev_i32_e32 v197, 31, v196
	v_lshlrev_b64 v[128:129], 12, v[196:197]
	v_lshl_add_u64 v[198:199], v[194:195], 2, s[48:49]
	v_or_b32_e32 v204, 16, v196
	v_lshl_add_u64 v[128:129], v[198:199], 0, v[128:129]
	v_ashrrev_i32_e32 v205, 31, v204
	global_load_dwordx4 v[212:215], v[128:129], off offset:16 nt
	global_load_dwordx4 v[216:219], v[128:129], off nt
	global_load_dwordx4 v[220:223], v[128:129], off offset:528 nt
	global_load_dwordx4 v[224:227], v[128:129], off offset:512 nt
	v_lshlrev_b64 v[128:129], 12, v[204:205]
	v_or_b32_e32 v202, 32, v196
	v_lshl_add_u64 v[128:129], v[198:199], 0, v[128:129]
	v_ashrrev_i32_e32 v203, 31, v202
	global_load_dwordx4 v[168:171], v[128:129], off offset:16 nt
	global_load_dwordx4 v[172:175], v[128:129], off nt
	global_load_dwordx4 v[160:163], v[128:129], off offset:528 nt
	global_load_dwordx4 v[164:167], v[128:129], off offset:512 nt
	v_lshlrev_b64 v[128:129], 12, v[202:203]
	v_or_b32_e32 v200, 48, v196
	v_lshl_add_u64 v[128:129], v[198:199], 0, v[128:129]
	v_ashrrev_i32_e32 v201, 31, v200
	global_load_dwordx4 v[152:155], v[128:129], off offset:16 nt
	global_load_dwordx4 v[156:159], v[128:129], off nt
	global_load_dwordx4 v[144:147], v[128:129], off offset:528 nt
	global_load_dwordx4 v[148:151], v[128:129], off offset:512 nt
	v_lshlrev_b64 v[128:129], 12, v[200:201]
	v_lshl_add_u64 v[132:133], v[198:199], 0, v[128:129]
	global_load_dwordx4 v[136:139], v[132:133], off offset:16 nt
	global_load_dwordx4 v[140:143], v[132:133], off nt
	global_load_dwordx4 v[128:131], v[132:133], off offset:528 nt
	s_nop 0
	global_load_dwordx4 v[132:135], v[132:133], off offset:512 nt
	s_lshl_b32 s20, s6, 2
	s_ashr_i32 s21, s20, 31
	v_readlane_b32 s50, v235, 7
	v_readlane_b32 s51, v235, 8
	v_readlane_b32 s52, v235, 9
	v_readlane_b32 s53, v235, 10
	v_readlane_b32 s54, v235, 11
	v_readlane_b32 s55, v235, 12
	v_readlane_b32 s56, v235, 13
	v_readlane_b32 s57, v235, 14
	v_readlane_b32 s58, v235, 15
	v_readlane_b32 s59, v235, 16
	v_readlane_b32 s60, v235, 17
	v_readlane_b32 s61, v235, 18
	v_readlane_b32 s62, v235, 19
	v_readlane_b32 s63, v235, 20
	s_waitcnt vmcnt(0)
	v_add_f32_e32 v126, v126, v218
	v_add_f32_e32 v127, v127, v219
	v_add_f32_e32 v124, v124, v216
	v_add_f32_e32 v125, v125, v217
	v_add_f32_e32 v214, v122, v214
	v_add_f32_e32 v215, v123, v215
	v_mul_f32_e32 v122, v125, v125
	v_mul_f32_e32 v123, v127, v127
	v_add_f32_e32 v120, v120, v212
	v_add_f32_e32 v121, v121, v213
	v_fmac_f32_e32 v122, v124, v124
	v_fmac_f32_e32 v123, v126, v126
	v_add_f32_e32 v122, v122, v123
	v_mul_f32_e32 v123, v121, v121
	v_mul_f32_e32 v212, v215, v215
	v_fmac_f32_e32 v123, v120, v120
	v_fmac_f32_e32 v212, v214, v214
	v_add_f32_e32 v118, v118, v226
	v_add_f32_e32 v119, v119, v227
	v_add_f32_e32 v116, v116, v224
	v_add_f32_e32 v117, v117, v225
	v_add_f32_e32 v123, v123, v212
	v_add_f32_e32 v212, v112, v220
	v_add_f32_e32 v213, v113, v221
	v_mul_f32_e32 v112, v117, v117
	v_mul_f32_e32 v113, v119, v119
	v_add_f32_e32 v216, v122, v123
	v_cvt_pk_bf16_f32 v122, v124, v125
	v_cvt_pk_bf16_f32 v123, v126, v127
	v_add_f32_e32 v126, v114, v222
	v_add_f32_e32 v127, v115, v223
	v_fmac_f32_e32 v112, v116, v116
	v_fmac_f32_e32 v113, v118, v118
	v_add_f32_e32 v112, v112, v113
	v_mul_f32_e32 v113, v213, v213
	v_mul_f32_e32 v114, v127, v127
	v_fmac_f32_e32 v113, v212, v212
	v_fmac_f32_e32 v114, v126, v126
	v_add_f32_e32 v113, v113, v114
	v_add_f32_e32 v112, v112, v113
	v_and_b32_e32 v113, 64, v211
	v_cvt_pk_bf16_f32 v124, v120, v121
	v_add_f32_e32 v115, v216, v112
	v_xor_b32_e32 v112, 16, v211
	v_add_u32_e32 v121, 64, v113
	v_cmp_lt_i32_e32 vcc, v112, v121
	v_lshlrev_b64 v[228:229], 11, v[196:197]
	v_cvt_pk_bf16_f32 v125, v214, v215
	s_nop 0
	v_cndmask_b32_e32 v112, v211, v112, vcc
	v_lshlrev_b32_e32 v120, 2, v112
	ds_bpermute_b32 v216, v120, v115
	v_lshl_add_u64 v[112:113], s[64:65], 0, v[228:229]
	v_lshl_add_u64 v[214:215], v[194:195], 1, v[112:113]
	v_xor_b32_e32 v113, 32, v211
	v_cmp_lt_i32_e32 vcc, v113, v121
	s_waitcnt lgkmcnt(0)
	v_add_f32_e32 v112, v115, v216
	global_store_dwordx4 v[214:215], v[122:125], off
	v_cndmask_b32_e32 v113, v211, v113, vcc
	v_lshlrev_b32_e32 v121, 2, v113
	ds_bpermute_b32 v113, v121, v112
	v_cvt_pk_bf16_f32 v114, v116, v117
	v_cvt_pk_bf16_f32 v115, v118, v119
	v_cvt_pk_bf16_f32 v116, v212, v213
	v_cvt_pk_bf16_f32 v117, v126, v127
	global_store_dwordx4 v[214:215], v[114:117], off offset:256
	s_and_saveexec_b64 s[22:23], s[2:3]
	s_cbranch_execz .LBB0_367
	v_lshlrev_b64 v[114:115], 6, v[196:197]
	v_lshl_add_u64 v[114:115], s[74:75], 0, v[114:115]
	v_lshl_add_u64 v[114:115], s[20:21], 2, v[114:115]
	s_lshl_b32 s6, s40, 2
	v_lshl_add_u64 v[114:115], v[114:115], 0, s[6:7]
	s_waitcnt lgkmcnt(0)
	v_add_f32_e32 v112, v112, v113
	global_store_dword v[114:115], v112, off
.LBB0_367:
	s_or_b64 exec, exec, s[22:23]
	v_add_f32_e32 v110, v110, v174
	v_add_f32_e32 v111, v111, v175
	v_add_f32_e32 v108, v108, v172
	v_add_f32_e32 v109, v109, v173
	v_add_f32_e32 v114, v106, v170
	v_add_f32_e32 v115, v107, v171
	v_add_f32_e32 v106, v104, v168
	v_add_f32_e32 v107, v105, v169
	v_mul_f32_e32 v104, v109, v109
	v_mul_f32_e32 v105, v111, v111
	v_fmac_f32_e32 v104, v108, v108
	v_fmac_f32_e32 v105, v110, v110
	v_add_f32_e32 v104, v104, v105
	v_mul_f32_e32 v105, v107, v107
	v_mul_f32_e32 v116, v115, v115
	v_fmac_f32_e32 v105, v106, v106
	v_fmac_f32_e32 v116, v114, v114
	v_add_f32_e32 v105, v105, v116
	v_add_f32_e32 v102, v102, v166
	v_add_f32_e32 v103, v103, v167
	v_add_f32_e32 v100, v100, v164
	v_add_f32_e32 v101, v101, v165
	v_add_f32_e32 v116, v104, v105
	v_cvt_pk_bf16_f32 v104, v108, v109
	v_cvt_pk_bf16_f32 v105, v110, v111
	v_add_f32_e32 v110, v96, v160
	v_add_f32_e32 v111, v97, v161
	v_mul_f32_e32 v96, v101, v101
	v_mul_f32_e32 v97, v103, v103
	v_add_f32_e32 v108, v98, v162
	v_add_f32_e32 v109, v99, v163
	v_fmac_f32_e32 v96, v100, v100
	v_fmac_f32_e32 v97, v102, v102
	v_add_f32_e32 v96, v96, v97
	v_mul_f32_e32 v97, v111, v111
	v_mul_f32_e32 v98, v109, v109
	v_fmac_f32_e32 v97, v110, v110
	v_fmac_f32_e32 v98, v108, v108
	v_add_f32_e32 v97, v97, v98
	v_add_f32_e32 v96, v96, v97
	v_add_f32_e32 v99, v116, v96
	v_cvt_pk_bf16_f32 v106, v106, v107
	v_cvt_pk_bf16_f32 v107, v114, v115
	ds_bpermute_b32 v114, v120, v99
	s_waitcnt lgkmcnt(1)
	v_lshlrev_b64 v[112:113], 11, v[204:205]
	v_lshl_add_u64 v[96:97], s[64:65], 0, v[112:113]
	v_lshl_add_u64 v[112:113], v[194:195], 1, v[96:97]
	global_store_dwordx4 v[112:113], v[104:107], off
	s_waitcnt lgkmcnt(0)
	v_add_f32_e32 v96, v99, v114
	ds_bpermute_b32 v97, v121, v96
	v_cvt_pk_bf16_f32 v98, v100, v101
	v_cvt_pk_bf16_f32 v99, v102, v103
	v_cvt_pk_bf16_f32 v100, v110, v111
	v_cvt_pk_bf16_f32 v101, v108, v109
	global_store_dwordx4 v[112:113], v[98:101], off offset:256
	s_and_saveexec_b64 s[22:23], s[2:3]
	s_cbranch_execz .LBB0_369
	v_lshlrev_b64 v[98:99], 6, v[204:205]
	v_lshl_add_u64 v[98:99], s[74:75], 0, v[98:99]
	v_lshl_add_u64 v[98:99], s[20:21], 2, v[98:99]
	s_lshl_b32 s6, s40, 2
	v_lshl_add_u64 v[98:99], v[98:99], 0, s[6:7]
	s_waitcnt lgkmcnt(0)
	v_add_f32_e32 v96, v96, v97
	global_store_dword v[98:99], v96, off
.LBB0_369:
	s_or_b64 exec, exec, s[22:23]
	v_add_f32_e32 v94, v94, v158
	v_add_f32_e32 v95, v95, v159
	v_add_f32_e32 v92, v92, v156
	v_add_f32_e32 v93, v93, v157
	v_add_f32_e32 v98, v90, v154
	v_add_f32_e32 v99, v91, v155
	v_add_f32_e32 v90, v88, v152
	v_add_f32_e32 v91, v89, v153
	v_mul_f32_e32 v88, v93, v93
	v_mul_f32_e32 v89, v95, v95
	v_fmac_f32_e32 v88, v92, v92
	v_fmac_f32_e32 v89, v94, v94
	v_add_f32_e32 v88, v88, v89
	v_mul_f32_e32 v89, v91, v91
	v_mul_f32_e32 v100, v99, v99
	v_fmac_f32_e32 v89, v90, v90
	v_fmac_f32_e32 v100, v98, v98
	v_add_f32_e32 v89, v89, v100
	v_add_f32_e32 v86, v86, v150
	v_add_f32_e32 v87, v87, v151
	v_add_f32_e32 v84, v84, v148
	v_add_f32_e32 v85, v85, v149
	v_add_f32_e32 v100, v88, v89
	v_cvt_pk_bf16_f32 v88, v92, v93
	v_cvt_pk_bf16_f32 v89, v94, v95
	v_add_f32_e32 v94, v80, v144
	v_add_f32_e32 v95, v81, v145
	v_mul_f32_e32 v80, v85, v85
	v_mul_f32_e32 v81, v87, v87
	v_add_f32_e32 v92, v82, v146
	v_add_f32_e32 v93, v83, v147
	v_fmac_f32_e32 v80, v84, v84
	v_fmac_f32_e32 v81, v86, v86
	v_add_f32_e32 v80, v80, v81
	v_mul_f32_e32 v81, v95, v95
	v_mul_f32_e32 v82, v93, v93
	v_fmac_f32_e32 v81, v94, v94
	v_fmac_f32_e32 v82, v92, v92
	v_add_f32_e32 v81, v81, v82
	v_add_f32_e32 v80, v80, v81
	v_add_f32_e32 v83, v100, v80
	v_cvt_pk_bf16_f32 v90, v90, v91
	v_cvt_pk_bf16_f32 v91, v98, v99
	ds_bpermute_b32 v98, v120, v83
	s_waitcnt lgkmcnt(1)
	v_lshlrev_b64 v[96:97], 11, v[202:203]
	v_lshl_add_u64 v[80:81], s[64:65], 0, v[96:97]
	v_lshl_add_u64 v[96:97], v[194:195], 1, v[80:81]
	global_store_dwordx4 v[96:97], v[88:91], off
	s_waitcnt lgkmcnt(0)
	v_add_f32_e32 v80, v83, v98
	ds_bpermute_b32 v81, v121, v80
	v_cvt_pk_bf16_f32 v82, v84, v85
	v_cvt_pk_bf16_f32 v83, v86, v87
	v_cvt_pk_bf16_f32 v84, v94, v95
	v_cvt_pk_bf16_f32 v85, v92, v93
	global_store_dwordx4 v[96:97], v[82:85], off offset:256
	s_and_saveexec_b64 s[22:23], s[2:3]
	s_cbranch_execz .LBB0_371
	v_lshlrev_b64 v[82:83], 6, v[202:203]
	v_lshl_add_u64 v[82:83], s[74:75], 0, v[82:83]
	v_lshl_add_u64 v[82:83], s[20:21], 2, v[82:83]
	s_lshl_b32 s6, s40, 2
	v_lshl_add_u64 v[82:83], v[82:83], 0, s[6:7]
	s_waitcnt lgkmcnt(0)
	v_add_f32_e32 v80, v80, v81
	global_store_dword v[82:83], v80, off
.LBB0_371:
	s_or_b64 exec, exec, s[22:23]
	v_add_f32_e32 v78, v78, v142
	v_add_f32_e32 v79, v79, v143
	v_add_f32_e32 v76, v76, v140
	v_add_f32_e32 v77, v77, v141
	v_add_f32_e32 v82, v74, v138
	v_add_f32_e32 v83, v75, v139
	v_add_f32_e32 v74, v72, v136
	v_add_f32_e32 v75, v73, v137
	v_mul_f32_e32 v72, v77, v77
	v_mul_f32_e32 v73, v79, v79
	v_fmac_f32_e32 v72, v76, v76
	v_fmac_f32_e32 v73, v78, v78
	v_add_f32_e32 v72, v72, v73
	v_mul_f32_e32 v73, v75, v75
	v_mul_f32_e32 v84, v83, v83
	v_fmac_f32_e32 v73, v74, v74
	v_fmac_f32_e32 v84, v82, v82
	v_add_f32_e32 v73, v73, v84
	v_add_f32_e32 v70, v70, v134
	v_add_f32_e32 v71, v71, v135
	v_add_f32_e32 v68, v68, v132
	v_add_f32_e32 v69, v69, v133
	v_add_f32_e32 v84, v72, v73
	v_cvt_pk_bf16_f32 v72, v76, v77
	v_cvt_pk_bf16_f32 v73, v78, v79
	v_add_f32_e32 v78, v64, v128
	v_add_f32_e32 v79, v65, v129
	v_mul_f32_e32 v64, v69, v69
	v_mul_f32_e32 v65, v71, v71
	v_add_f32_e32 v76, v66, v130
	v_add_f32_e32 v77, v67, v131
	v_fmac_f32_e32 v64, v68, v68
	v_fmac_f32_e32 v65, v70, v70
	v_add_f32_e32 v64, v64, v65
	v_mul_f32_e32 v65, v79, v79
	v_mul_f32_e32 v66, v77, v77
	v_fmac_f32_e32 v65, v78, v78
	v_fmac_f32_e32 v66, v76, v76
	v_add_f32_e32 v65, v65, v66
	v_add_f32_e32 v64, v64, v65
	v_add_f32_e32 v67, v84, v64
	v_cvt_pk_bf16_f32 v74, v74, v75
	v_cvt_pk_bf16_f32 v75, v82, v83
	ds_bpermute_b32 v82, v120, v67
	s_waitcnt lgkmcnt(1)
	v_lshlrev_b64 v[80:81], 11, v[200:201]
	v_lshl_add_u64 v[64:65], s[64:65], 0, v[80:81]
	v_lshl_add_u64 v[80:81], v[194:195], 1, v[64:65]
	global_store_dwordx4 v[80:81], v[72:75], off
	s_waitcnt lgkmcnt(0)
	v_add_f32_e32 v64, v67, v82
	ds_bpermute_b32 v65, v121, v64
	v_cvt_pk_bf16_f32 v66, v68, v69
	v_cvt_pk_bf16_f32 v67, v70, v71
	v_cvt_pk_bf16_f32 v68, v78, v79
	v_cvt_pk_bf16_f32 v69, v76, v77
	global_store_dwordx4 v[80:81], v[66:69], off offset:256
	s_and_saveexec_b64 s[22:23], s[2:3]
	s_cbranch_execz .LBB0_373
	v_lshlrev_b64 v[66:67], 6, v[200:201]
	v_lshl_add_u64 v[66:67], s[74:75], 0, v[66:67]
	v_lshl_add_u64 v[66:67], s[20:21], 2, v[66:67]
	s_lshl_b32 s6, s40, 2
	v_lshl_add_u64 v[66:67], v[66:67], 0, s[6:7]
	s_waitcnt lgkmcnt(0)
	v_add_f32_e32 v64, v64, v65
	global_store_dword v[66:67], v64, off
.LBB0_373:
	s_or_b64 exec, exec, s[22:23]
	v_add_u32_e32 v118, 0x80, v196
	v_ashrrev_i32_e32 v119, 31, v118
	s_waitcnt lgkmcnt(0)
	v_lshlrev_b64 v[64:65], 12, v[118:119]
	v_add_u32_e32 v116, 0x90, v196
	v_lshl_add_u64 v[64:65], v[198:199], 0, v[64:65]
	v_ashrrev_i32_e32 v117, 31, v116
	global_load_dwordx4 v[122:125], v[64:65], off offset:16 nt
	global_load_dwordx4 v[126:129], v[64:65], off nt
	global_load_dwordx4 v[130:133], v[64:65], off offset:528 nt
	global_load_dwordx4 v[134:137], v[64:65], off offset:512 nt
	v_lshlrev_b64 v[64:65], 12, v[116:117]
	v_add_u32_e32 v114, 0xa0, v196
	v_lshl_add_u64 v[64:65], v[198:199], 0, v[64:65]
	v_ashrrev_i32_e32 v115, 31, v114
	global_load_dwordx4 v[104:107], v[64:65], off offset:16 nt
	global_load_dwordx4 v[108:111], v[64:65], off nt
	global_load_dwordx4 v[96:99], v[64:65], off offset:528 nt
	global_load_dwordx4 v[100:103], v[64:65], off offset:512 nt
	v_lshlrev_b64 v[64:65], 12, v[114:115]
	v_add_u32_e32 v112, 0xb0, v196
	v_lshl_add_u64 v[64:65], v[198:199], 0, v[64:65]
	v_ashrrev_i32_e32 v113, 31, v112
	global_load_dwordx4 v[88:91], v[64:65], off offset:16 nt
	global_load_dwordx4 v[92:95], v[64:65], off nt
	global_load_dwordx4 v[80:83], v[64:65], off offset:528 nt
	global_load_dwordx4 v[84:87], v[64:65], off offset:512 nt
	v_lshlrev_b64 v[64:65], 12, v[112:113]
	v_lshl_add_u64 v[68:69], v[198:199], 0, v[64:65]
	global_load_dwordx4 v[72:75], v[68:69], off offset:16 nt
	global_load_dwordx4 v[76:79], v[68:69], off nt
	global_load_dwordx4 v[64:67], v[68:69], off offset:528 nt
	s_nop 0
	global_load_dwordx4 v[68:71], v[68:69], off offset:512 nt
	s_waitcnt vmcnt(14)
	v_add_f32_e32 v62, v62, v128
	v_add_f32_e32 v63, v63, v129
	v_add_f32_e32 v60, v60, v126
	v_add_f32_e32 v61, v61, v127
	v_add_f32_e32 v124, v58, v124
	v_add_f32_e32 v125, v59, v125
	v_add_f32_e32 v58, v56, v122
	v_add_f32_e32 v59, v57, v123
	v_mul_f32_e32 v56, v61, v61
	v_mul_f32_e32 v57, v63, v63
	v_fmac_f32_e32 v56, v60, v60
	v_fmac_f32_e32 v57, v62, v62
	v_add_f32_e32 v56, v56, v57
	v_mul_f32_e32 v57, v59, v59
	v_mul_f32_e32 v122, v125, v125
	v_fmac_f32_e32 v57, v58, v58
	v_fmac_f32_e32 v122, v124, v124
	v_add_f32_e32 v57, v57, v122
	s_waitcnt vmcnt(12)
	v_add_f32_e32 v54, v54, v136
	v_add_f32_e32 v55, v55, v137
	v_add_f32_e32 v52, v52, v134
	v_add_f32_e32 v53, v53, v135
	v_add_f32_e32 v122, v56, v57
	v_cvt_pk_bf16_f32 v56, v60, v61
	v_cvt_pk_bf16_f32 v57, v62, v63
	v_add_f32_e32 v62, v48, v130
	v_add_f32_e32 v63, v49, v131
	v_mul_f32_e32 v48, v53, v53
	v_mul_f32_e32 v49, v55, v55
	v_add_f32_e32 v60, v50, v132
	v_add_f32_e32 v61, v51, v133
	v_fmac_f32_e32 v48, v52, v52
	v_fmac_f32_e32 v49, v54, v54
	v_add_f32_e32 v48, v48, v49
	v_mul_f32_e32 v49, v63, v63
	v_mul_f32_e32 v50, v61, v61
	v_fmac_f32_e32 v49, v62, v62
	v_fmac_f32_e32 v50, v60, v60
	v_add_f32_e32 v49, v49, v50
	v_add_f32_e32 v48, v48, v49
	v_add_f32_e32 v51, v122, v48
	v_cvt_pk_bf16_f32 v58, v58, v59
	v_cvt_pk_bf16_f32 v59, v124, v125
	ds_bpermute_b32 v124, v120, v51
	v_lshlrev_b64 v[138:139], 11, v[118:119]
	v_lshl_add_u64 v[48:49], s[64:65], 0, v[138:139]
	v_lshl_add_u64 v[122:123], v[194:195], 1, v[48:49]
	global_store_dwordx4 v[122:123], v[56:59], off
	s_waitcnt lgkmcnt(0)
	v_add_f32_e32 v48, v51, v124
	ds_bpermute_b32 v49, v121, v48
	v_cvt_pk_bf16_f32 v50, v52, v53
	v_cvt_pk_bf16_f32 v51, v54, v55
	v_cvt_pk_bf16_f32 v52, v62, v63
	v_cvt_pk_bf16_f32 v53, v60, v61
	global_store_dwordx4 v[122:123], v[50:53], off offset:256
	s_and_saveexec_b64 s[22:23], s[2:3]
	s_cbranch_execz .LBB0_375
	v_lshlrev_b64 v[50:51], 6, v[118:119]
	v_lshl_add_u64 v[50:51], s[74:75], 0, v[50:51]
	v_lshl_add_u64 v[50:51], s[20:21], 2, v[50:51]
	s_lshl_b32 s6, s40, 2
	v_lshl_add_u64 v[50:51], v[50:51], 0, s[6:7]
	s_waitcnt lgkmcnt(0)
	v_add_f32_e32 v48, v48, v49
	global_store_dword v[50:51], v48, off
.LBB0_375:
	s_or_b64 exec, exec, s[22:23]
	s_waitcnt vmcnt(12)
	v_add_f32_e32 v46, v46, v110
	v_add_f32_e32 v47, v47, v111
	v_add_f32_e32 v44, v44, v108
	v_add_f32_e32 v45, v45, v109
	v_add_f32_e32 v50, v42, v106
	v_add_f32_e32 v51, v43, v107
	v_add_f32_e32 v42, v40, v104
	v_add_f32_e32 v43, v41, v105
	v_mul_f32_e32 v40, v45, v45
	v_mul_f32_e32 v41, v47, v47
	v_fmac_f32_e32 v40, v44, v44
	v_fmac_f32_e32 v41, v46, v46
	v_add_f32_e32 v40, v40, v41
	v_mul_f32_e32 v41, v43, v43
	v_mul_f32_e32 v52, v51, v51
	v_fmac_f32_e32 v41, v42, v42
	v_fmac_f32_e32 v52, v50, v50
	v_add_f32_e32 v41, v41, v52
	s_waitcnt vmcnt(10)
	v_add_f32_e32 v38, v38, v102
	v_add_f32_e32 v39, v39, v103
	v_add_f32_e32 v36, v36, v100
	v_add_f32_e32 v37, v37, v101
	v_add_f32_e32 v52, v40, v41
	v_cvt_pk_bf16_f32 v40, v44, v45
	v_cvt_pk_bf16_f32 v41, v46, v47
	v_add_f32_e32 v46, v32, v96
	v_add_f32_e32 v47, v33, v97
	v_mul_f32_e32 v32, v37, v37
	v_mul_f32_e32 v33, v39, v39
	v_add_f32_e32 v44, v34, v98
	v_add_f32_e32 v45, v35, v99
	v_fmac_f32_e32 v32, v36, v36
	v_fmac_f32_e32 v33, v38, v38
	v_add_f32_e32 v32, v32, v33
	v_mul_f32_e32 v33, v47, v47
	v_mul_f32_e32 v34, v45, v45
	v_fmac_f32_e32 v33, v46, v46
	v_fmac_f32_e32 v34, v44, v44
	v_add_f32_e32 v33, v33, v34
	v_add_f32_e32 v32, v32, v33
	v_add_f32_e32 v35, v52, v32
	v_cvt_pk_bf16_f32 v42, v42, v43
	v_cvt_pk_bf16_f32 v43, v50, v51
	ds_bpermute_b32 v50, v120, v35
	s_waitcnt lgkmcnt(1)
	v_lshlrev_b64 v[48:49], 11, v[116:117]
	v_lshl_add_u64 v[32:33], s[64:65], 0, v[48:49]
	v_lshl_add_u64 v[48:49], v[194:195], 1, v[32:33]
	global_store_dwordx4 v[48:49], v[40:43], off
	s_waitcnt lgkmcnt(0)
	v_add_f32_e32 v32, v35, v50
	ds_bpermute_b32 v33, v121, v32
	v_cvt_pk_bf16_f32 v34, v36, v37
	v_cvt_pk_bf16_f32 v35, v38, v39
	v_cvt_pk_bf16_f32 v36, v46, v47
	v_cvt_pk_bf16_f32 v37, v44, v45
	global_store_dwordx4 v[48:49], v[34:37], off offset:256
	s_and_saveexec_b64 s[22:23], s[2:3]
	s_cbranch_execz .LBB0_377
	v_lshlrev_b64 v[34:35], 6, v[116:117]
	v_lshl_add_u64 v[34:35], s[74:75], 0, v[34:35]
	v_lshl_add_u64 v[34:35], s[20:21], 2, v[34:35]
	s_lshl_b32 s6, s40, 2
	v_lshl_add_u64 v[34:35], v[34:35], 0, s[6:7]
	s_waitcnt lgkmcnt(0)
	v_add_f32_e32 v32, v32, v33
	global_store_dword v[34:35], v32, off
.LBB0_377:
	s_or_b64 exec, exec, s[22:23]
	s_waitcnt vmcnt(10)
	v_add_f32_e32 v30, v30, v94
	v_add_f32_e32 v31, v31, v95
	v_add_f32_e32 v28, v28, v92
	v_add_f32_e32 v29, v29, v93
	v_add_f32_e32 v34, v26, v90
	v_add_f32_e32 v35, v27, v91
	v_add_f32_e32 v26, v24, v88
	v_add_f32_e32 v27, v25, v89
	v_mul_f32_e32 v24, v29, v29
	v_mul_f32_e32 v25, v31, v31
	v_fmac_f32_e32 v24, v28, v28
	v_fmac_f32_e32 v25, v30, v30
	v_add_f32_e32 v24, v24, v25
	v_mul_f32_e32 v25, v27, v27
	v_mul_f32_e32 v36, v35, v35
	v_fmac_f32_e32 v25, v26, v26
	v_fmac_f32_e32 v36, v34, v34
	v_add_f32_e32 v25, v25, v36
	s_waitcnt vmcnt(8)
	v_add_f32_e32 v22, v22, v86
	v_add_f32_e32 v23, v23, v87
	v_add_f32_e32 v20, v20, v84
	v_add_f32_e32 v21, v21, v85
	v_add_f32_e32 v36, v24, v25
	v_cvt_pk_bf16_f32 v24, v28, v29
	v_cvt_pk_bf16_f32 v25, v30, v31
	v_add_f32_e32 v30, v16, v80
	v_add_f32_e32 v31, v17, v81
	v_mul_f32_e32 v16, v21, v21
	v_mul_f32_e32 v17, v23, v23
	v_add_f32_e32 v28, v18, v82
	v_add_f32_e32 v29, v19, v83
	v_fmac_f32_e32 v16, v20, v20
	v_fmac_f32_e32 v17, v22, v22
	v_add_f32_e32 v16, v16, v17
	v_mul_f32_e32 v17, v31, v31
	v_mul_f32_e32 v18, v29, v29
	v_fmac_f32_e32 v17, v30, v30
	v_fmac_f32_e32 v18, v28, v28
	v_add_f32_e32 v17, v17, v18
	v_add_f32_e32 v16, v16, v17
	v_add_f32_e32 v19, v36, v16
	v_cvt_pk_bf16_f32 v26, v26, v27
	v_cvt_pk_bf16_f32 v27, v34, v35
	ds_bpermute_b32 v34, v120, v19
	s_waitcnt lgkmcnt(1)
	v_lshlrev_b64 v[32:33], 11, v[114:115]
	v_lshl_add_u64 v[16:17], s[64:65], 0, v[32:33]
	v_lshl_add_u64 v[32:33], v[194:195], 1, v[16:17]
	global_store_dwordx4 v[32:33], v[24:27], off
	s_waitcnt lgkmcnt(0)
	v_add_f32_e32 v16, v19, v34
	ds_bpermute_b32 v17, v121, v16
	v_cvt_pk_bf16_f32 v18, v20, v21
	v_cvt_pk_bf16_f32 v19, v22, v23
	v_cvt_pk_bf16_f32 v20, v30, v31
	v_cvt_pk_bf16_f32 v21, v28, v29
	global_store_dwordx4 v[32:33], v[18:21], off offset:256
	s_and_saveexec_b64 s[22:23], s[2:3]
	s_cbranch_execz .LBB0_379
	v_lshlrev_b64 v[18:19], 6, v[114:115]
	v_lshl_add_u64 v[18:19], s[74:75], 0, v[18:19]
	v_lshl_add_u64 v[18:19], s[20:21], 2, v[18:19]
	s_lshl_b32 s6, s40, 2
	v_lshl_add_u64 v[18:19], v[18:19], 0, s[6:7]
	s_waitcnt lgkmcnt(0)
	v_add_f32_e32 v16, v16, v17
	global_store_dword v[18:19], v16, off
.LBB0_379:
	s_or_b64 exec, exec, s[22:23]
	s_waitcnt vmcnt(8)
	v_add_f32_e32 v14, v14, v78
	v_add_f32_e32 v15, v15, v79
	v_add_f32_e32 v12, v12, v76
	v_add_f32_e32 v13, v13, v77
	v_add_f32_e32 v18, v10, v74
	v_add_f32_e32 v19, v11, v75
	v_add_f32_e32 v10, v8, v72
	v_add_f32_e32 v11, v9, v73
	v_mul_f32_e32 v8, v13, v13
	v_mul_f32_e32 v9, v15, v15
	v_fmac_f32_e32 v8, v12, v12
	v_fmac_f32_e32 v9, v14, v14
	v_add_f32_e32 v8, v8, v9
	v_mul_f32_e32 v9, v11, v11
	v_mul_f32_e32 v20, v19, v19
	v_fmac_f32_e32 v9, v10, v10
	v_fmac_f32_e32 v20, v18, v18
	v_add_f32_e32 v9, v9, v20
	s_waitcnt vmcnt(6)
	v_add_f32_e32 v6, v6, v70
	v_add_f32_e32 v7, v7, v71
	v_add_f32_e32 v4, v4, v68
	v_add_f32_e32 v5, v5, v69
	v_add_f32_e32 v20, v8, v9
	v_cvt_pk_bf16_f32 v8, v12, v13
	v_cvt_pk_bf16_f32 v9, v14, v15
	v_add_f32_e32 v14, v0, v64
	v_add_f32_e32 v15, v1, v65
	v_mul_f32_e32 v0, v5, v5
	v_mul_f32_e32 v1, v7, v7
	v_add_f32_e32 v12, v2, v66
	v_add_f32_e32 v13, v3, v67
	v_fmac_f32_e32 v0, v4, v4
	v_fmac_f32_e32 v1, v6, v6
	v_add_f32_e32 v0, v0, v1
	v_mul_f32_e32 v1, v15, v15
	v_mul_f32_e32 v2, v13, v13
	v_fmac_f32_e32 v1, v14, v14
	v_fmac_f32_e32 v2, v12, v12
	v_add_f32_e32 v1, v1, v2
	v_add_f32_e32 v0, v0, v1
	v_add_f32_e32 v3, v20, v0
	v_cvt_pk_bf16_f32 v10, v10, v11
	v_cvt_pk_bf16_f32 v11, v18, v19
	ds_bpermute_b32 v18, v120, v3
	s_waitcnt lgkmcnt(1)
	v_lshlrev_b64 v[16:17], 11, v[112:113]
	v_lshl_add_u64 v[0:1], s[64:65], 0, v[16:17]
	v_lshl_add_u64 v[16:17], v[194:195], 1, v[0:1]
	global_store_dwordx4 v[16:17], v[8:11], off
	s_waitcnt lgkmcnt(0)
	v_add_f32_e32 v0, v3, v18
	ds_bpermute_b32 v1, v121, v0
	v_cvt_pk_bf16_f32 v2, v4, v5
	v_cvt_pk_bf16_f32 v3, v6, v7
	v_cvt_pk_bf16_f32 v4, v14, v15
	v_cvt_pk_bf16_f32 v5, v12, v13
	global_store_dwordx4 v[16:17], v[2:5], off offset:256
	s_and_saveexec_b64 s[22:23], s[2:3]
	s_cbranch_execz .LBB0_356
	v_lshlrev_b64 v[2:3], 6, v[112:113]
	v_lshl_add_u64 v[2:3], s[74:75], 0, v[2:3]
	v_lshl_add_u64 v[2:3], s[20:21], 2, v[2:3]
	s_lshl_b32 s6, s40, 2
	v_lshl_add_u64 v[2:3], v[2:3], 0, s[6:7]
	s_waitcnt lgkmcnt(0)
	v_add_f32_e32 v0, v0, v1
	global_store_dword v[2:3], v0, off
	s_branch .LBB0_356

.LBB0_457:
	s_and_b32 s30, s62, 1
	s_lshl_b32 s11, s30, 12
	s_add_i32 s13, s11, 0
	s_add_i32 s13, s13, 0x24010
	s_lshl_b32 s31, s52, 2
	s_add_i32 s31, s13, s31
	v_lshl_add_u32 v68, v189, 2, s31
	ds_read_b128 v[96:99], v68 offset:3072
	ds_read_b128 v[68:71], v68 offset:3584
	s_lshl_b32 s34, s30, 13
	s_add_i32 s35, s34, 0
	s_add_i32 s35, s35, 0x20000
	s_waitcnt lgkmcnt(0)
	v_mul_f32_e32 v166, v146, v98
	v_mul_f32_e32 v167, v147, v98
	v_mul_f32_e32 v164, v144, v98
	v_mul_f32_e32 v165, v145, v98
	v_mul_f32_e32 v158, v82, v98
	v_mul_f32_e32 v159, v83, v98
	v_mul_f32_e32 v156, v80, v98
	v_mul_f32_e32 v157, v81, v98
	v_mul_f32_e32 v82, v142, v98
	v_mul_f32_e32 v83, v143, v98
	v_mul_f32_e32 v80, v140, v98
	v_mul_f32_e32 v81, v141, v98
	v_mul_f32_e32 v94, v94, v98
	v_mul_f32_e32 v95, v95, v98
	v_mul_f32_e32 v92, v92, v98
	v_mul_f32_e32 v93, v93, v98
	v_mov_b32_e32 v98, v99
	v_mul_f32_e32 v162, v86, v98
	v_mul_f32_e32 v163, v87, v98
	v_mul_f32_e32 v160, v84, v98
	v_mul_f32_e32 v161, v85, v98
	v_mul_f32_e32 v86, v134, v98
	v_mul_f32_e32 v87, v135, v98
	v_mul_f32_e32 v84, v132, v98
	v_mul_f32_e32 v85, v133, v98
	v_mul_f32_e32 v134, v130, v70
	v_mul_f32_e32 v135, v131, v70
	v_mul_f32_e32 v132, v128, v70
	v_mul_f32_e32 v133, v129, v70
	v_mul_f32_e32 v130, v46, v70
	v_mul_f32_e32 v131, v47, v70
	v_mul_f32_e32 v128, v44, v70
	v_mul_f32_e32 v129, v45, v70
	v_mul_f32_e32 v46, v126, v70
	v_mul_f32_e32 v47, v127, v70
	v_mul_f32_e32 v44, v124, v70
	v_mul_f32_e32 v45, v125, v70
	v_mul_f32_e32 v50, v50, v70
	v_mul_f32_e32 v51, v51, v70
	v_mul_f32_e32 v48, v48, v70
	v_mul_f32_e32 v49, v49, v70
	v_mov_b32_e32 v70, v71
	v_mul_f32_e32 v170, v138, v98
	v_mul_f32_e32 v171, v139, v98
	v_mul_f32_e32 v168, v136, v98
	v_mul_f32_e32 v169, v137, v98
	v_mul_f32_e32 v90, v90, v98
	v_mul_f32_e32 v91, v91, v98
	v_mul_f32_e32 v88, v88, v98
	v_mul_f32_e32 v89, v89, v98
	v_mul_f32_e32 v126, v122, v70
	v_mul_f32_e32 v127, v123, v70
	v_mul_f32_e32 v124, v120, v70
	v_mul_f32_e32 v125, v121, v70
	v_mul_f32_e32 v122, v54, v70
	v_mul_f32_e32 v123, v55, v70
	v_mul_f32_e32 v120, v52, v70
	v_mul_f32_e32 v121, v53, v70
	v_mul_f32_e32 v54, v118, v70
	v_mul_f32_e32 v55, v119, v70
	v_mul_f32_e32 v52, v116, v70
	v_mul_f32_e32 v53, v117, v70
	v_mul_f32_e32 v58, v58, v70
	v_mul_f32_e32 v59, v59, v70
	v_mul_f32_e32 v56, v56, v70
	v_mul_f32_e32 v57, v57, v70
	s_and_saveexec_b64 s[30:31], s[6:7]
	s_cbranch_execz .LBB0_459
	s_add_i32 s36, s55, s35
	v_lshl_add_u32 v70, v210, 2, s36
	ds_write_b128 v70, v[164:167]
	ds_write_b128 v70, v[80:83] offset:16
	ds_write_b128 v70, v[156:159] offset:512
	ds_write_b128 v70, v[92:95] offset:528
	ds_write_b128 v70, v[168:171] offset:1024
	ds_write_b128 v70, v[84:87] offset:1040
	ds_write_b128 v70, v[160:163] offset:1536
	ds_write_b128 v70, v[88:91] offset:1552
	ds_write_b128 v70, v[132:135] offset:4096
	ds_write_b128 v70, v[44:47] offset:4112
	ds_write_b128 v70, v[128:131] offset:4608
	ds_write_b128 v70, v[48:51] offset:4624
	ds_write_b128 v70, v[124:127] offset:5120
	ds_write_b128 v70, v[52:55] offset:5136
	ds_write_b128 v70, v[120:123] offset:5632
	ds_write_b128 v70, v[56:59] offset:5648

.LBB0_462:
	s_waitcnt lgkmcnt(0)
	v_mov_b32_dpp v180, v168 row_shr:1 row_mask:0xf bank_mask:0xf
	v_mul_f32_e32 v112, v112, v96
	v_mul_f32_e32 v113, v113, v96
	v_mul_f32_e32 v70, v102, v97
	v_mul_f32_e32 v71, v103, v97
	v_mul_f32_e32 v102, v148, v180
	v_mov_b32_dpp v184, v164 row_shr:1 row_mask:0xf bank_mask:0xf
	v_fmac_f32_e32 v102, v112, v152
	v_fmac_f32_e32 v102, v144, v184
	v_mul_f32_e32 v98, v106, v96
	v_mul_f32_e32 v99, v107, v96
	v_mul_f32_e32 v106, v104, v96
	v_mul_f32_e32 v107, v105, v96
	v_mul_f32_e32 v104, v110, v97
	v_mul_f32_e32 v105, v111, v97
	v_mul_f32_e32 v111, v168, v152
	v_mul_f32_e32 v168, 0xbfb8aa3b, v102
	v_mul_f32_e32 v108, v108, v97
	v_mul_f32_e32 v109, v109, v97
	v_mul_f32_e32 v110, v164, v152
	v_exp_f32_e32 v168, v168
	v_mul_f32_e32 v100, v100, v97
	v_mul_f32_e32 v101, v101, v97
	v_mul_f32_e32 v103, v108, v152
	v_fmac_f32_e32 v110, v108, v148
	v_fmac_f32_e32 v111, v164, v148
	v_mov_b32_dpp v172, v160 row_shr:1 row_mask:0xf bank_mask:0xf
	v_mul_f32_e32 v164, v156, v140
	v_fmac_f32_e32 v103, v112, v148
	v_fmac_f32_e32 v110, v112, v144
	v_fmac_f32_e32 v111, v108, v144
	v_mul_f32_e32 v108, v136, v172
	v_mul_f32_e32 v112, v100, v140
	v_fmac_f32_e32 v164, v100, v136
	v_fmac_f32_e32 v108, v106, v140
	v_fmac_f32_e32 v112, v106, v136
	v_fmac_f32_e32 v164, v106, v116
	v_mul_f32_e32 v106, v160, v140
	v_fmac_f32_e32 v103, v144, v180
	v_mov_b32_dpp v176, v156 row_shr:1 row_mask:0xf bank_mask:0xf
	v_fmac_f32_e32 v106, v156, v136
	v_add_f32_e32 v156, 1.0, v168
	v_rcp_f32_e32 v156, v156
	v_mul_f32_e32 v160, 0xbfb8aa3b, v103
	v_exp_f32_e32 v160, v160
	v_fmac_f32_e32 v108, v116, v176
	v_fmac_f32_e32 v106, v100, v116
	v_mul_f32_e32 v100, v102, v156
	v_mul_f32_e32 v100, v108, v100
	v_add_f32_e32 v102, 1.0, v160
	v_mul_f32_e32 v108, 0xbfb8aa3b, v110
	v_rcp_f32_e32 v102, v102
	v_exp_f32_e32 v108, v108
	v_mul_f32_e32 v156, 0xbfb8aa3b, v111
	v_exp_f32_e32 v156, v156
	v_mul_f32_e32 v102, v103, v102
	v_add_f32_e32 v103, 1.0, v108
	v_rcp_f32_e32 v103, v103
	v_add_f32_e32 v108, 1.0, v156
	v_rcp_f32_e32 v108, v108
	v_fmac_f32_e32 v112, v116, v172
	v_mul_f32_e32 v112, v112, v102
	v_mul_f32_e32 v102, v110, v103
	v_mul_f32_e32 v110, v164, v102
	v_mul_f32_e32 v102, v111, v108
	v_mov_b32_dpp v181, v169 row_shr:1 row_mask:0xf bank_mask:0xf
	v_mul_f32_e32 v106, v106, v102
	v_mul_f32_e32 v102, v149, v181
	v_mov_b32_dpp v185, v165 row_shr:1 row_mask:0xf bank_mask:0xf
	v_fmac_f32_e32 v102, v113, v153
	v_fmac_f32_e32 v102, v145, v185
	v_mul_f32_e32 v160, 0xbfb8aa3b, v102
	v_mul_f32_e32 v108, v165, v153
	v_mul_f32_e32 v111, v169, v153
	v_exp_f32_e32 v160, v160
	v_mul_f32_e32 v103, v109, v153
	v_fmac_f32_e32 v108, v109, v149
	v_fmac_f32_e32 v111, v165, v149
	v_mov_b32_dpp v173, v161 row_shr:1 row_mask:0xf bank_mask:0xf
	v_mul_f32_e32 v156, v157, v141
	v_fmac_f32_e32 v103, v113, v149
	v_fmac_f32_e32 v108, v113, v145
	v_fmac_f32_e32 v111, v109, v145
	v_mul_f32_e32 v109, v137, v173
	v_mul_f32_e32 v113, v101, v141
	v_fmac_f32_e32 v156, v101, v137
	v_fmac_f32_e32 v109, v107, v141
	v_fmac_f32_e32 v113, v107, v137
	v_fmac_f32_e32 v156, v107, v117
	v_mul_f32_e32 v107, v161, v141
	v_fmac_f32_e32 v103, v145, v181
	v_mov_b32_dpp v177, v157 row_shr:1 row_mask:0xf bank_mask:0xf
	v_fmac_f32_e32 v107, v157, v137
	v_add_f32_e32 v157, 1.0, v160
	v_rcp_f32_e32 v157, v157
	v_mul_f32_e32 v160, 0xbfb8aa3b, v103
	v_exp_f32_e32 v160, v160
	v_fmac_f32_e32 v109, v117, v177
	v_fmac_f32_e32 v107, v101, v117
	v_mul_f32_e32 v101, v102, v157
	v_mul_f32_e32 v101, v109, v101
	v_add_f32_e32 v102, 1.0, v160
	v_mul_f32_e32 v109, 0xbfb8aa3b, v108
	v_rcp_f32_e32 v102, v102
	v_exp_f32_e32 v109, v109
	v_mul_f32_e32 v157, 0xbfb8aa3b, v111
	v_exp_f32_e32 v157, v157
	v_mul_f32_e32 v102, v103, v102
	v_add_f32_e32 v103, 1.0, v109
	v_rcp_f32_e32 v103, v103
	v_add_f32_e32 v109, 1.0, v157
	v_rcp_f32_e32 v109, v109
	v_fmac_f32_e32 v113, v117, v173
	v_mul_f32_e32 v113, v113, v102
	v_mul_f32_e32 v102, v108, v103
	v_mul_f32_e32 v108, v156, v102
	v_mul_f32_e32 v102, v111, v109
	v_mov_b32_dpp v182, v170 row_shr:1 row_mask:0xf bank_mask:0xf
	v_mul_f32_e32 v114, v114, v96
	v_mul_f32_e32 v115, v115, v96
	v_mul_f32_e32 v107, v107, v102
	v_mul_f32_e32 v102, v150, v182
	v_mov_b32_dpp v186, v166 row_shr:1 row_mask:0xf bank_mask:0xf
	v_fmac_f32_e32 v102, v114, v154
	v_fmac_f32_e32 v102, v146, v186
	v_mul_f32_e32 v157, 0xbfb8aa3b, v102
	v_exp_f32_e32 v157, v157
	v_mul_f32_e32 v109, v166, v154
	v_mul_f32_e32 v111, v170, v154
	v_mul_f32_e32 v103, v104, v154
	v_fmac_f32_e32 v109, v104, v150
	v_fmac_f32_e32 v111, v166, v150
	v_mov_b32_dpp v174, v162 row_shr:1 row_mask:0xf bank_mask:0xf
	v_mul_f32_e32 v156, v158, v142
	v_fmac_f32_e32 v103, v114, v150
	v_fmac_f32_e32 v109, v114, v146
	v_fmac_f32_e32 v111, v104, v146
	v_mul_f32_e32 v104, v138, v174
	v_mul_f32_e32 v114, v70, v142
	v_fmac_f32_e32 v156, v70, v138
	v_fmac_f32_e32 v103, v146, v182
	v_fmac_f32_e32 v104, v98, v142
	v_fmac_f32_e32 v114, v98, v138
	v_fmac_f32_e32 v156, v98, v118
	v_mul_f32_e32 v98, v162, v142
	v_add_f32_e32 v157, 1.0, v157
	v_mov_b32_dpp v178, v158 row_shr:1 row_mask:0xf bank_mask:0xf
	v_fmac_f32_e32 v98, v158, v138
	v_rcp_f32_e32 v157, v157
	v_mul_f32_e32 v158, 0xbfb8aa3b, v103
	v_exp_f32_e32 v158, v158
	v_fmac_f32_e32 v104, v118, v178
	v_fmac_f32_e32 v98, v70, v118
	v_mul_f32_e32 v70, v102, v157
	v_mul_f32_e32 v70, v104, v70
	v_add_f32_e32 v102, 1.0, v158
	v_mul_f32_e32 v104, 0xbfb8aa3b, v109
	v_rcp_f32_e32 v102, v102
	v_exp_f32_e32 v104, v104
	v_mul_f32_e32 v157, 0xbfb8aa3b, v111
	v_exp_f32_e32 v157, v157
	v_mul_f32_e32 v102, v103, v102
	v_add_f32_e32 v103, 1.0, v104
	v_rcp_f32_e32 v103, v103
	v_add_f32_e32 v104, 1.0, v157
	v_rcp_f32_e32 v104, v104
	v_fmac_f32_e32 v114, v118, v174
	v_mul_f32_e32 v114, v114, v102
	v_mul_f32_e32 v102, v109, v103
	v_mul_f32_e32 v109, v156, v102
	v_mul_f32_e32 v102, v111, v104
	v_mov_b32_dpp v183, v171 row_shr:1 row_mask:0xf bank_mask:0xf
	v_mul_f32_e32 v104, v98, v102
	v_mul_f32_e32 v98, v151, v183
	v_mov_b32_dpp v187, v167 row_shr:1 row_mask:0xf bank_mask:0xf
	v_fmac_f32_e32 v98, v115, v155
	v_fmac_f32_e32 v98, v147, v187
	v_mul_f32_e32 v157, 0xbfb8aa3b, v98
	v_exp_f32_e32 v157, v157
	v_mul_f32_e32 v102, v105, v155
	v_fmac_f32_e32 v102, v115, v151
	v_fmac_f32_e32 v102, v147, v183
	v_mul_f32_e32 v103, v167, v155
	v_mul_f32_e32 v111, v171, v155
	v_add_f32_e32 v157, 1.0, v157
	v_fmac_f32_e32 v103, v105, v151
	v_fmac_f32_e32 v111, v167, v151
	v_mov_b32_dpp v175, v163 row_shr:1 row_mask:0xf bank_mask:0xf
	v_mul_f32_e32 v156, v159, v143
	v_rcp_f32_e32 v157, v157
	v_mul_f32_e32 v158, 0xbfb8aa3b, v102
	v_fmac_f32_e32 v103, v115, v147
	v_fmac_f32_e32 v111, v105, v147
	v_mul_f32_e32 v105, v139, v175
	v_mul_f32_e32 v115, v71, v143
	v_fmac_f32_e32 v156, v71, v139
	v_exp_f32_e32 v158, v158
	v_fmac_f32_e32 v105, v99, v143
	v_fmac_f32_e32 v115, v99, v139
	v_fmac_f32_e32 v156, v99, v119
	v_mul_f32_e32 v99, v163, v143
	v_mov_b32_dpp v179, v159 row_shr:1 row_mask:0xf bank_mask:0xf
	v_fmac_f32_e32 v99, v159, v139
	v_fmac_f32_e32 v105, v119, v179
	v_fmac_f32_e32 v99, v71, v119
	v_mul_f32_e32 v71, v98, v157
	v_mul_f32_e32 v71, v105, v71
	v_add_f32_e32 v98, 1.0, v158
	v_mul_f32_e32 v105, 0xbfb8aa3b, v103
	v_rcp_f32_e32 v98, v98
	v_exp_f32_e32 v105, v105
	v_mul_f32_e32 v157, 0xbfb8aa3b, v111
	v_exp_f32_e32 v157, v157
	v_mul_f32_e32 v98, v102, v98
	v_add_f32_e32 v102, 1.0, v105
	v_rcp_f32_e32 v102, v102
	v_add_f32_e32 v105, 1.0, v157
	v_rcp_f32_e32 v105, v105
	s_addk_i32 s13, 0x800
	s_and_b64 s[36:37], s[28:29], exec
	s_cselect_b32 s13, s13, s30
	v_fmac_f32_e32 v115, v119, v175
	v_mul_f32_e32 v102, v103, v102
	s_cmp_lg_u32 s13, 0
	v_mul_f32_e32 v98, v115, v98
	v_mul_f32_e32 v115, v156, v102
	v_mul_f32_e32 v102, v111, v105
	s_cselect_b64 s[30:31], -1, 0
	s_cmp_eq_u32 s13, 0
	v_lshl_add_u32 v160, v210, 2, s13
	v_mul_f32_e32 v105, v99, v102
	v_cvt_pk_bf16_f32 v102, v100, v101
	v_cvt_pk_bf16_f32 v103, v70, v71
	v_cvt_pk_bf16_f32 v100, v112, v113
	v_cvt_pk_bf16_f32 v101, v114, v98
	v_cvt_pk_bf16_f32 v98, v110, v108
	v_cvt_pk_bf16_f32 v99, v109, v115
	v_cvt_pk_bf16_f32 v70, v106, v107
	v_cvt_pk_bf16_f32 v71, v104, v105
	s_cbranch_scc1 .LBB0_464
	ds_read_b128 v[156:159], v160
	ds_read_b128 v[108:111], v160 offset:512
	ds_read_b128 v[112:115], v160 offset:1024
	ds_read_b128 v[104:107], v160 offset:1536
	s_branch .LBB0_465

.LBB0_465:
	v_mul_f32_e32 v72, v72, v69
	v_mul_f32_e32 v73, v73, v69
	v_mul_f32_e32 v76, v76, v68
	v_mul_f32_e32 v77, v77, v68
	v_mul_f32_e32 v162, v64, v68
	v_mul_f32_e32 v163, v65, v68
	v_mul_f32_e32 v64, v74, v69
	v_mul_f32_e32 v65, v75, v69
	s_waitcnt lgkmcnt(0)
	v_mov_b32_dpp v112, v124 row_shr:1 row_mask:0xf bank_mask:0xf
	v_mul_f32_e32 v75, v72, v152
	v_mul_f32_e32 v74, v148, v112
	v_fmac_f32_e32 v75, v76, v148
	v_mov_b32_dpp v156, v132 row_shr:1 row_mask:0xf bank_mask:0xf
	v_fmac_f32_e32 v74, v76, v152
	v_fmac_f32_e32 v75, v144, v112
	v_mul_f32_e32 v112, v132, v152
	v_fmac_f32_e32 v74, v144, v156
	v_fmac_f32_e32 v112, v72, v148
	v_fmac_f32_e32 v112, v76, v144
	v_mul_f32_e32 v76, v124, v152
	v_mul_f32_e32 v124, 0xbfb8aa3b, v74
	v_fmac_f32_e32 v76, v132, v148
	v_mov_b32_dpp v104, v120 row_shr:1 row_mask:0xf bank_mask:0xf
	v_exp_f32_e32 v124, v124
	v_fmac_f32_e32 v76, v72, v144
	v_mul_f32_e32 v72, v136, v104
	v_mul_f32_e32 v60, v60, v69
	v_mul_f32_e32 v61, v61, v69
	v_mov_b32_dpp v108, v128 row_shr:1 row_mask:0xf bank_mask:0xf
	v_fmac_f32_e32 v72, v162, v140
	v_fmac_f32_e32 v72, v116, v108
	v_mul_f32_e32 v108, v60, v140
	v_fmac_f32_e32 v108, v162, v136
	v_mul_f32_e32 v120, v120, v140
	v_add_f32_e32 v124, 1.0, v124
	v_fmac_f32_e32 v108, v116, v104
	v_mul_f32_e32 v104, v128, v140
	v_fmac_f32_e32 v120, v128, v136
	v_rcp_f32_e32 v124, v124
	v_mul_f32_e32 v128, 0xbfb8aa3b, v75
	v_exp_f32_e32 v128, v128
	v_fmac_f32_e32 v104, v60, v136
	v_fmac_f32_e32 v120, v60, v116
	v_mul_f32_e32 v60, v74, v124
	v_fmac_f32_e32 v104, v162, v116
	v_mul_f32_e32 v60, v72, v60
	v_add_f32_e32 v72, 1.0, v128
	v_mul_f32_e32 v116, 0xbfb8aa3b, v76
	v_rcp_f32_e32 v72, v72
	v_exp_f32_e32 v116, v116
	v_mul_f32_e32 v74, 0xbfb8aa3b, v112
	v_exp_f32_e32 v74, v74
	v_mul_f32_e32 v72, v75, v72
	v_add_f32_e32 v75, 1.0, v116
	v_rcp_f32_e32 v75, v75
	v_add_f32_e32 v74, 1.0, v74
	v_rcp_f32_e32 v74, v74
	v_mov_b32_dpp v113, v125 row_shr:1 row_mask:0xf bank_mask:0xf
	v_mul_f32_e32 v75, v76, v75
	v_mul_f32_e32 v76, v149, v113
	v_mov_b32_dpp v157, v133 row_shr:1 row_mask:0xf bank_mask:0xf
	v_fmac_f32_e32 v76, v77, v153
	v_fmac_f32_e32 v76, v145, v157
	v_mul_f32_e32 v74, v112, v74
	v_mul_f32_e32 v112, 0xbfb8aa3b, v76
	v_mul_f32_e32 v72, v108, v72
	v_mul_f32_e32 v108, v133, v153
	v_exp_f32_e32 v112, v112
	v_mul_f32_e32 v74, v104, v74
	v_mul_f32_e32 v104, v73, v153
	v_fmac_f32_e32 v108, v73, v149
	v_fmac_f32_e32 v104, v77, v149
	v_fmac_f32_e32 v108, v77, v145
	v_mul_f32_e32 v77, v125, v153
	v_fmac_f32_e32 v77, v133, v149
	v_mov_b32_dpp v105, v121 row_shr:1 row_mask:0xf bank_mask:0xf
	v_fmac_f32_e32 v104, v145, v113
	v_fmac_f32_e32 v77, v73, v145
	v_mul_f32_e32 v73, v137, v105
	v_add_f32_e32 v112, 1.0, v112
	v_mov_b32_dpp v109, v129 row_shr:1 row_mask:0xf bank_mask:0xf
	v_fmac_f32_e32 v73, v163, v141
	v_rcp_f32_e32 v112, v112
	v_mul_f32_e32 v116, 0xbfb8aa3b, v104
	v_fmac_f32_e32 v73, v117, v109
	v_mul_f32_e32 v109, v61, v141
	v_exp_f32_e32 v116, v116
	v_fmac_f32_e32 v109, v163, v137
	v_mul_f32_e32 v113, v121, v141
	v_fmac_f32_e32 v109, v117, v105
	v_mul_f32_e32 v105, v129, v141
	v_fmac_f32_e32 v113, v129, v137
	v_fmac_f32_e32 v105, v61, v137
	v_fmac_f32_e32 v113, v61, v117
	v_mul_f32_e32 v61, v76, v112
	v_mul_f32_e32 v76, 0xbfb8aa3b, v108
	v_mul_f32_e32 v61, v73, v61
	v_add_f32_e32 v73, 1.0, v116
	v_exp_f32_e32 v76, v76
	v_mul_f32_e32 v112, 0xbfb8aa3b, v77
	v_rcp_f32_e32 v73, v73
	v_exp_f32_e32 v112, v112
	v_add_f32_e32 v76, 1.0, v76
	v_rcp_f32_e32 v76, v76
	v_mul_f32_e32 v73, v104, v73
	v_add_f32_e32 v104, 1.0, v112
	v_rcp_f32_e32 v104, v104
	v_fmac_f32_e32 v105, v163, v117
	v_mul_f32_e32 v76, v108, v76
	v_mov_b32_dpp v114, v126 row_shr:1 row_mask:0xf bank_mask:0xf
	v_mul_f32_e32 v108, v134, v154
	v_mul_f32_e32 v78, v78, v68
	v_mul_f32_e32 v79, v79, v68
	v_mul_f32_e32 v76, v105, v76
	v_mul_f32_e32 v77, v77, v104
	v_mul_f32_e32 v104, v150, v114
	v_mul_f32_e32 v105, v64, v154
	v_fmac_f32_e32 v108, v64, v150
	v_fmac_f32_e32 v104, v78, v154
	v_fmac_f32_e32 v105, v78, v150
	v_fmac_f32_e32 v108, v78, v146
	v_mul_f32_e32 v78, v126, v154
	v_fmac_f32_e32 v78, v134, v150
	v_mov_b32_dpp v106, v122 row_shr:1 row_mask:0xf bank_mask:0xf
	v_mul_f32_e32 v66, v66, v68
	v_mul_f32_e32 v67, v67, v68
	v_mov_b32_dpp v158, v134 row_shr:1 row_mask:0xf bank_mask:0xf
	v_fmac_f32_e32 v78, v64, v146
	v_mul_f32_e32 v64, v138, v106
	v_fmac_f32_e32 v104, v146, v158
	v_mov_b32_dpp v110, v130 row_shr:1 row_mask:0xf bank_mask:0xf
	v_fmac_f32_e32 v64, v66, v142
	v_fmac_f32_e32 v64, v118, v110
	v_mul_f32_e32 v110, 0xbfb8aa3b, v104
	v_exp_f32_e32 v110, v110
	v_mul_f32_e32 v62, v62, v69
	v_mul_f32_e32 v63, v63, v69
	v_mul_f32_e32 v73, v109, v73
	v_mul_f32_e32 v109, v62, v142
	v_fmac_f32_e32 v105, v146, v114
	v_fmac_f32_e32 v109, v66, v138
	v_add_f32_e32 v110, 1.0, v110
	v_fmac_f32_e32 v109, v118, v106
	v_mul_f32_e32 v106, v130, v142
	v_rcp_f32_e32 v110, v110
	v_mul_f32_e32 v112, 0xbfb8aa3b, v105
	v_fmac_f32_e32 v106, v62, v138
	v_exp_f32_e32 v112, v112
	v_fmac_f32_e32 v106, v66, v118
	v_mul_f32_e32 v66, v122, v142
	v_fmac_f32_e32 v66, v130, v138
	v_fmac_f32_e32 v66, v62, v118
	v_mul_f32_e32 v62, v104, v110
	v_mul_f32_e32 v104, 0xbfb8aa3b, v108
	v_mul_f32_e32 v62, v64, v62
	v_add_f32_e32 v64, 1.0, v112
	v_exp_f32_e32 v104, v104
	v_mul_f32_e32 v110, 0xbfb8aa3b, v78
	v_rcp_f32_e32 v64, v64
	v_exp_f32_e32 v110, v110
	v_add_f32_e32 v104, 1.0, v104
	v_rcp_f32_e32 v104, v104
	v_mul_f32_e32 v64, v105, v64
	v_add_f32_e32 v105, 1.0, v110
	v_rcp_f32_e32 v105, v105
	v_mul_f32_e32 v109, v109, v64
	v_mul_f32_e32 v64, v108, v104
	v_mul_f32_e32 v104, v106, v64
	v_mul_f32_e32 v64, v78, v105
	v_mov_b32_dpp v115, v127 row_shr:1 row_mask:0xf bank_mask:0xf
	v_mul_f32_e32 v78, v66, v64
	v_mul_f32_e32 v64, v151, v115
	v_mov_b32_dpp v159, v135 row_shr:1 row_mask:0xf bank_mask:0xf
	v_fmac_f32_e32 v64, v79, v155
	v_fmac_f32_e32 v64, v147, v159
	v_mul_f32_e32 v108, 0xbfb8aa3b, v64
	v_exp_f32_e32 v108, v108
	v_mul_f32_e32 v105, v135, v155
	v_mul_f32_e32 v66, v65, v155
	v_fmac_f32_e32 v105, v65, v151
	v_fmac_f32_e32 v66, v79, v151
	v_fmac_f32_e32 v105, v79, v147
	v_mul_f32_e32 v79, v127, v155
	v_mul_f32_e32 v106, v63, v143
	v_fmac_f32_e32 v79, v135, v151
	v_mov_b32_dpp v107, v123 row_shr:1 row_mask:0xf bank_mask:0xf
	v_fmac_f32_e32 v106, v67, v139
	v_add_f32_e32 v108, 1.0, v108
	v_fmac_f32_e32 v66, v147, v115
	v_fmac_f32_e32 v79, v65, v147
	v_mul_f32_e32 v65, v139, v107
	v_fmac_f32_e32 v106, v119, v107
	v_mul_f32_e32 v107, v131, v143
	v_rcp_f32_e32 v108, v108
	v_fmac_f32_e32 v107, v63, v139
	v_mul_f32_e32 v110, 0xbfb8aa3b, v66
	v_fmac_f32_e32 v65, v67, v143
	v_fmac_f32_e32 v107, v67, v119
	v_mul_f32_e32 v67, v123, v143
	v_exp_f32_e32 v110, v110
	v_mov_b32_dpp v111, v131 row_shr:1 row_mask:0xf bank_mask:0xf
	v_fmac_f32_e32 v67, v131, v139
	v_fmac_f32_e32 v65, v119, v111
	v_fmac_f32_e32 v67, v63, v119
	v_mul_f32_e32 v63, v64, v108
	v_mul_f32_e32 v63, v65, v63
	v_mul_f32_e32 v65, 0xbfb8aa3b, v105
	v_add_f32_e32 v64, 1.0, v110
	v_exp_f32_e32 v65, v65
	v_mul_f32_e32 v108, 0xbfb8aa3b, v79
	v_rcp_f32_e32 v64, v64
	v_exp_f32_e32 v108, v108
	v_add_f32_e32 v65, 1.0, v65
	v_rcp_f32_e32 v65, v65
	v_mul_f32_e32 v64, v66, v64
	v_add_f32_e32 v66, 1.0, v108
	v_rcp_f32_e32 v66, v66
	v_mul_f32_e32 v106, v106, v64
	v_mul_f32_e32 v64, v105, v65
	v_mul_f32_e32 v75, v120, v75
	v_mul_f32_e32 v77, v113, v77
	v_mul_f32_e32 v105, v107, v64
	v_mul_f32_e32 v64, v79, v66
	v_mul_f32_e32 v79, v67, v64
	v_cvt_pk_bf16_f32 v66, v60, v61
	v_cvt_pk_bf16_f32 v67, v62, v63
	v_cvt_pk_bf16_f32 v64, v72, v73
	v_cvt_pk_bf16_f32 v65, v109, v106
	v_cvt_pk_bf16_f32 v62, v74, v76
	v_cvt_pk_bf16_f32 v63, v104, v105
	v_cvt_pk_bf16_f32 v60, v75, v77
	v_cvt_pk_bf16_f32 v61, v78, v79
	ds_read_b128 v[74:77], v218 offset:16
	ds_read_b128 v[106:109], v218 offset:528
	ds_read_b128 v[114:117], v218 offset:1552
	ds_read_b128 v[110:113], v218 offset:1040
	ds_read_b128 v[118:121], v218 offset:2064
	ds_read_b128 v[122:125], v218 offset:2576
	v_mov_b32_e32 v78, 0
	s_andn2_b64 vcc, exec, s[34:35]
	v_mov_b32_e32 v126, 0
	v_mov_b32_e32 v142, 0
	v_mov_b32_e32 v128, 0
	v_mov_b32_e32 v104, 0
	v_mov_b32_e32 v130, 0
	v_mov_b32_e32 v144, 0
	v_mov_b32_e32 v132, 0
	v_mov_b32_e32 v134, 0
	v_mov_b32_e32 v127, 0
	v_mov_b32_e32 v143, 0
	v_mov_b32_e32 v129, 0
	v_mov_b32_e32 v105, 0
	v_mov_b32_e32 v131, 0
	v_mov_b32_e32 v145, 0
	v_mov_b32_e32 v133, 0
	v_mov_b32_e32 v135, 0
	s_cbranch_vccnz .LBB0_467
	ds_read_b128 v[126:129], v217 offset:1552
	ds_read_b128 v[130:133], v217 offset:528
	ds_read_b128 v[136:139], v217 offset:16
	ds_read_b128 v[146:149], v217 offset:1040
	s_waitcnt lgkmcnt(0)
	v_mov_b32_e32 v142, v127
	v_mov_b32_e32 v104, v129
	v_mov_b32_e32 v144, v131
	v_mov_b32_e32 v134, v133
	v_mov_b32_e32 v127, v146
	v_mov_b32_e32 v143, v147
	v_mov_b32_e32 v129, v148
	v_mov_b32_e32 v105, v149
	v_mov_b32_e32 v131, v136
	v_mov_b32_e32 v145, v137
	v_mov_b32_e32 v133, v138
	v_mov_b32_e32 v135, v139
.LBB0_467:
	v_mov_b32_e32 v136, v96
	v_mov_b32_e32 v137, v96
	v_mov_b32_e32 v148, v97
	v_mov_b32_e32 v149, v97
	v_mov_b32_e32 v140, v96
	v_mov_b32_e32 v141, v96
	v_mov_b32_e32 v96, v97
	v_mul_f32_e32 v138, v42, v140
	v_mul_f32_e32 v139, v43, v141
	v_mul_f32_e32 v40, v40, v136
	v_mul_f32_e32 v41, v41, v137
	v_mul_f32_e32 v42, v32, v136
	v_mul_f32_e32 v43, v33, v137
	v_mul_f32_e32 v136, v38, v96
	v_mul_f32_e32 v137, v39, v97
	v_mul_f32_e32 v38, v36, v148
	v_mul_f32_e32 v39, v37, v149
	v_mov_b32_dpp v127, v84 row_shr:1 row_mask:0xf bank_mask:0xf
	v_mov_b32_dpp v126, v88 row_shr:1 row_mask:0xf bank_mask:0xf
	s_waitcnt lgkmcnt(0)
	v_mov_b32_e32 v36, v118
	v_mov_b32_e32 v37, v106
	v_mul_f32_e32 v140, v34, v140
	v_mul_f32_e32 v141, v35, v141
	v_mul_f32_e32 v30, v30, v96
	v_mul_f32_e32 v31, v31, v97
	v_mov_b32_e32 v96, v42
	v_mov_b32_e32 v97, v40
	v_mov_b32_e32 v34, v122
	v_mov_b32_e32 v35, v110
	v_mul_f32_e32 v32, v36, v126
	v_mul_f32_e32 v33, v37, v127
	v_mul_f32_e32 v28, v28, v148
	v_mul_f32_e32 v29, v29, v149
	v_mov_b32_dpp v131, v80 row_shr:1 row_mask:0xf bank_mask:0xf
	v_mov_b32_dpp v130, v92 row_shr:1 row_mask:0xf bank_mask:0xf
	v_fma_f32 v148, v96, v34, v32
	v_fma_f32 v149, v97, v35, v33
	v_mov_b32_e32 v32, v114
	v_mov_b32_e32 v33, v74
	v_fma_f32 v130, v32, v130, v148
	v_fma_f32 v131, v33, v131, v149
	v_mov_b32_e32 v148, v28
	v_mul_f32_e32 v28, 0xbfb8aa3b, v131
	v_exp_f32_e32 v28, v28
	v_mov_b32_e32 v149, v38
	v_mul_f32_e32 v150, v148, v34
	v_mul_f32_e32 v151, v149, v35
	v_mov_b32_dpp v143, v85 row_shr:1 row_mask:0xf bank_mask:0xf
	v_fmac_f32_e32 v150, v96, v36
	v_fmac_f32_e32 v151, v97, v37
	v_add_f32_e32 v28, 1.0, v28
	v_fma_f32 v126, v32, v126, v150
	v_fma_f32 v127, v33, v127, v151
	v_mov_b32_e32 v150, v92
	v_mov_b32_e32 v151, v80
	v_mul_f32_e32 v152, v150, v34
	v_mul_f32_e32 v153, v151, v35
	v_rcp_f32_e32 v28, v28
	v_mul_f32_e32 v38, 0xbfb8aa3b, v127
	v_fmac_f32_e32 v152, v148, v36
	v_fmac_f32_e32 v153, v149, v37
	v_exp_f32_e32 v38, v38
	v_fma_f32 v96, v96, v32, v152
	v_fma_f32 v97, v97, v33, v153
	v_mov_b32_e32 v152, v88
	v_mov_b32_e32 v153, v84
	v_mul_f32_e32 v152, v152, v34
	v_mul_f32_e32 v153, v153, v35
	v_mul_f32_e32 v28, v131, v28
	v_fma_f32 v150, v150, v36, v152
	v_fma_f32 v151, v151, v37, v153
	v_mul_f32_e32 v79, v130, v28
	v_fma_f32 v148, v148, v32, v150
	v_fma_f32 v149, v149, v33, v151
	v_add_f32_e32 v28, 1.0, v38
	v_mul_f32_e32 v38, 0xbfb8aa3b, v97
	v_exp_f32_e32 v38, v38
	v_mul_f32_e32 v40, 0xbfb8aa3b, v149
	v_exp_f32_e32 v40, v40
	v_rcp_f32_e32 v28, v28
	v_add_f32_e32 v38, 1.0, v38
	v_rcp_f32_e32 v38, v38
	v_add_f32_e32 v40, 1.0, v40
	v_rcp_f32_e32 v40, v40
	v_mul_f32_e32 v28, v127, v28
	v_mul_f32_e32 v114, v126, v28
	v_mul_f32_e32 v28, v97, v38
	v_mov_b32_dpp v142, v89 row_shr:1 row_mask:0xf bank_mask:0xf
	v_mov_b32_e32 v106, v119
	v_mul_f32_e32 v118, v96, v28
	v_mul_f32_e32 v28, v149, v40
	v_mov_b32_e32 v40, v43
	v_mov_b32_e32 v110, v123
	v_mul_f32_e32 v42, v106, v142
	v_mul_f32_e32 v43, v107, v143
	v_mov_b32_dpp v145, v81 row_shr:1 row_mask:0xf bank_mask:0xf
	v_mov_b32_dpp v144, v93 row_shr:1 row_mask:0xf bank_mask:0xf
	v_fmac_f32_e32 v42, v40, v110
	v_fmac_f32_e32 v43, v41, v111
	v_mov_b32_e32 v74, v115
	v_fmac_f32_e32 v42, v74, v144
	v_fmac_f32_e32 v43, v75, v145
	v_mov_b32_e32 v38, v29
	v_mul_f32_e32 v84, 0xbfb8aa3b, v43
	v_exp_f32_e32 v88, v84
	v_mul_f32_e32 v122, v148, v28
	v_mul_f32_e32 v28, v38, v110
	v_mul_f32_e32 v29, v39, v111
	v_mov_b32_e32 v84, v89
	v_fmac_f32_e32 v28, v40, v106
	v_fmac_f32_e32 v29, v41, v107
	v_mov_b32_e32 v80, v93
	v_mul_f32_e32 v84, v84, v110
	v_mul_f32_e32 v85, v85, v111
	v_fmac_f32_e32 v28, v74, v142
	v_fmac_f32_e32 v29, v75, v143
	v_mul_f32_e32 v92, v80, v110
	v_mul_f32_e32 v93, v81, v111
	v_fma_f32 v80, v80, v106, v84
	v_fma_f32 v81, v81, v107, v85
	v_add_f32_e32 v84, 1.0, v88
	v_rcp_f32_e32 v84, v84
	v_mul_f32_e32 v85, 0xbfb8aa3b, v29
	v_exp_f32_e32 v85, v85
	v_fmac_f32_e32 v92, v38, v106
	v_fmac_f32_e32 v93, v39, v107
	v_mul_f32_e32 v43, v43, v84
	v_fma_f32 v40, v40, v74, v92
	v_fma_f32 v41, v41, v75, v93
	v_fma_f32 v38, v38, v74, v80
	v_fma_f32 v39, v39, v75, v81
	v_mul_f32_e32 v115, v42, v43
	v_add_f32_e32 v42, 1.0, v85
	v_mul_f32_e32 v43, 0xbfb8aa3b, v41
	v_rcp_f32_e32 v42, v42
	v_exp_f32_e32 v43, v43
	v_mul_f32_e32 v80, 0xbfb8aa3b, v39
	v_exp_f32_e32 v80, v80
	v_mul_f32_e32 v29, v29, v42
	v_add_f32_e32 v42, 1.0, v43
	v_rcp_f32_e32 v42, v42
	v_add_f32_e32 v43, 1.0, v80
	v_rcp_f32_e32 v43, v43
	v_mul_f32_e32 v119, v28, v29
	v_mul_f32_e32 v28, v41, v42
	v_mul_f32_e32 v123, v40, v28
	v_mul_f32_e32 v28, v39, v43
	v_mov_b32_dpp v129, v86 row_shr:1 row_mask:0xf bank_mask:0xf
	v_mov_b32_dpp v128, v90 row_shr:1 row_mask:0xf bank_mask:0xf
	v_mov_b32_e32 v42, v120
	v_mov_b32_e32 v43, v108
	v_mul_f32_e32 v126, v38, v28
	v_mov_b32_e32 v28, v140
	v_mov_b32_e32 v29, v138
	v_mov_b32_e32 v40, v124
	v_mov_b32_e32 v41, v112
	v_mul_f32_e32 v38, v42, v128
	v_mul_f32_e32 v39, v43, v129
	v_mov_b32_dpp v133, v82 row_shr:1 row_mask:0xf bank_mask:0xf
	v_mov_b32_dpp v132, v94 row_shr:1 row_mask:0xf bank_mask:0xf
	v_fma_f32 v80, v28, v40, v38
	v_fma_f32 v81, v29, v41, v39
	v_mov_b32_e32 v38, v116
	v_mov_b32_e32 v39, v76
	v_fmac_f32_e32 v80, v38, v132
	v_fmac_f32_e32 v81, v39, v133
	v_mov_b32_e32 v84, v30
	v_mul_f32_e32 v30, 0xbfb8aa3b, v81
	v_exp_f32_e32 v30, v30
	v_mov_b32_e32 v85, v136
	v_mul_f32_e32 v88, v84, v40
	v_mul_f32_e32 v89, v85, v41
	v_mov_b32_e32 v92, v94
	v_fmac_f32_e32 v88, v28, v42
	v_fmac_f32_e32 v89, v29, v43
	v_mov_b32_e32 v93, v82
	v_fmac_f32_e32 v88, v38, v128
	v_fmac_f32_e32 v89, v39, v129
	v_add_f32_e32 v30, 1.0, v30
	v_mul_f32_e32 v96, v92, v40
	v_mul_f32_e32 v97, v93, v41
	v_rcp_f32_e32 v30, v30
	v_mul_f32_e32 v76, 0xbfb8aa3b, v89
	v_fmac_f32_e32 v96, v84, v42
	v_fmac_f32_e32 v97, v85, v43
	v_exp_f32_e32 v76, v76
	v_fma_f32 v28, v28, v38, v96
	v_fma_f32 v29, v29, v39, v97
	v_mov_b32_e32 v96, v90
	v_mov_b32_e32 v97, v86
	v_mul_f32_e32 v96, v96, v40
	v_mul_f32_e32 v97, v97, v41
	v_mul_f32_e32 v30, v81, v30
	v_fma_f32 v92, v92, v42, v96
	v_fma_f32 v93, v93, v43, v97
	v_mul_f32_e32 v90, v80, v30
	v_fma_f32 v84, v84, v38, v92
	v_fma_f32 v85, v85, v39, v93
	v_add_f32_e32 v30, 1.0, v76
	v_mul_f32_e32 v76, 0xbfb8aa3b, v29
	v_exp_f32_e32 v76, v76
	v_mul_f32_e32 v80, 0xbfb8aa3b, v85
	v_exp_f32_e32 v80, v80
	v_rcp_f32_e32 v30, v30
	v_add_f32_e32 v76, 1.0, v76
	v_rcp_f32_e32 v76, v76
	v_add_f32_e32 v80, 1.0, v80
	v_rcp_f32_e32 v80, v80
	v_mul_f32_e32 v30, v89, v30
	v_mul_f32_e32 v29, v29, v76
	v_mul_f32_e32 v89, v28, v29
	v_mul_f32_e32 v28, v85, v80
	v_mov_b32_dpp v105, v87 row_shr:1 row_mask:0xf bank_mask:0xf
	v_mov_b32_dpp v104, v91 row_shr:1 row_mask:0xf bank_mask:0xf
	v_mov_b32_e32 v108, v121
	v_mul_f32_e32 v92, v84, v28
	v_mov_b32_e32 v138, v141
	v_mov_b32_e32 v112, v125
	v_mul_f32_e32 v28, v108, v104
	v_mul_f32_e32 v29, v109, v105
	v_mov_b32_dpp v135, v83 row_shr:1 row_mask:0xf bank_mask:0xf
	v_mov_b32_dpp v134, v95 row_shr:1 row_mask:0xf bank_mask:0xf
	v_fmac_f32_e32 v28, v138, v112
	v_fmac_f32_e32 v29, v139, v113
	v_mov_b32_e32 v76, v117
	v_fmac_f32_e32 v28, v76, v134
	v_fmac_f32_e32 v29, v77, v135
	v_mov_b32_e32 v136, v31
	v_mul_f32_e32 v84, 0xbfb8aa3b, v29
	v_exp_f32_e32 v93, v84
	v_mul_f32_e32 v88, v88, v30
	v_mul_f32_e32 v30, v136, v112
	v_mul_f32_e32 v31, v137, v113
	v_mov_b32_e32 v86, v91
	v_fmac_f32_e32 v30, v138, v108
	v_fmac_f32_e32 v31, v139, v109
	v_mov_b32_e32 v82, v95
	v_mul_f32_e32 v84, v86, v112
	v_mul_f32_e32 v85, v87, v113
	v_fmac_f32_e32 v30, v76, v104
	v_fmac_f32_e32 v31, v77, v105
	v_mul_f32_e32 v80, v82, v112
	v_mul_f32_e32 v81, v83, v113
	v_fma_f32 v82, v82, v108, v84
	v_fma_f32 v83, v83, v109, v85
	v_add_f32_e32 v84, 1.0, v93
	v_rcp_f32_e32 v84, v84
	v_mul_f32_e32 v85, 0xbfb8aa3b, v31
	v_exp_f32_e32 v85, v85
	v_fmac_f32_e32 v80, v136, v108
	v_fmac_f32_e32 v81, v137, v109
	v_mul_f32_e32 v29, v29, v84
	v_fmac_f32_e32 v80, v138, v76
	v_fmac_f32_e32 v81, v139, v77
	v_fmac_f32_e32 v82, v136, v76
	v_fmac_f32_e32 v83, v137, v77
	v_mul_f32_e32 v28, v28, v29
	v_add_f32_e32 v29, 1.0, v85
	v_mul_f32_e32 v84, 0xbfb8aa3b, v81
	v_rcp_f32_e32 v29, v29
	v_exp_f32_e32 v84, v84
	v_mul_f32_e32 v85, 0xbfb8aa3b, v83
	v_exp_f32_e32 v85, v85
	v_mul_f32_e32 v29, v31, v29
	v_add_f32_e32 v31, 1.0, v84
	v_rcp_f32_e32 v31, v31
	v_add_f32_e32 v84, 1.0, v85
	v_rcp_f32_e32 v84, v84
	v_mul_f32_e32 v85, v30, v29
	v_mul_f32_e32 v29, v81, v31
	v_lshl_or_b32 v72, s60, 7, v210
	v_mul_f32_e32 v80, v80, v29
	v_mul_f32_e32 v29, v83, v84
	v_lshl_add_u32 v146, s61, 8, v209
	v_ashrrev_i32_e32 v73, 31, v72
	v_mul_f32_e32 v81, v82, v29
	v_cvt_pk_bf16_f32 v104, v79, v115
	v_cvt_pk_bf16_f32 v105, v90, v28
	v_mov_b64_e32 v[28:29], s[24:25]
	v_mad_i64_i32 v[30:31], s[34:35], v146, s58, v[28:29]
	v_lshlrev_b64 v[82:83], 1, v[72:73]
	v_lshl_add_u64 v[30:31], v[30:31], 0, v[82:83]
	global_store_dwordx4 v[30:31], v[102:105], off nt
	v_or_b32_e32 v30, 1, v146
	v_mad_i64_i32 v[30:31], s[34:35], v30, s58, v[28:29]
	v_lshl_add_u64 v[30:31], v[30:31], 0, v[82:83]
	v_cvt_pk_bf16_f32 v102, v114, v119
	v_cvt_pk_bf16_f32 v103, v88, v85
	global_store_dwordx4 v[30:31], v[100:103], off nt
	v_or_b32_e32 v30, 2, v146
	v_mad_i64_i32 v[30:31], s[34:35], v30, s58, v[28:29]
	v_lshl_add_u64 v[30:31], v[30:31], 0, v[82:83]
	v_cvt_pk_bf16_f32 v100, v118, v123
	v_cvt_pk_bf16_f32 v101, v89, v80
	global_store_dwordx4 v[30:31], v[98:101], off nt
	v_or_b32_e32 v30, 3, v146
	v_mad_i64_i32 v[28:29], s[34:35], v30, s58, v[28:29]
	v_cvt_pk_bf16_f32 v72, v122, v126
	v_cvt_pk_bf16_f32 v73, v92, v81
	v_lshl_add_u64 v[28:29], v[28:29], 0, v[82:83]
	global_store_dwordx4 v[28:29], v[70:73], off nt
	s_andn2_b64 vcc, exec, s[30:31]
	v_mov_b32_e32 v84, 0
	v_mov_b32_e32 v80, 0
	v_mov_b32_e32 v70, 0
	v_mov_b32_e32 v28, 0
	v_mov_b32_e32 v86, 0
	v_mov_b32_e32 v30, 0
	v_mov_b32_e32 v72, 0
	v_mov_b32_e32 v79, 0
	v_mov_b32_e32 v85, 0
	v_mov_b32_e32 v81, 0
	v_mov_b32_e32 v71, 0
	v_mov_b32_e32 v29, 0
	v_mov_b32_e32 v87, 0
	v_mov_b32_e32 v31, 0
	v_mov_b32_e32 v73, 0
	s_cbranch_vccnz .LBB0_469
	ds_read_b128 v[78:81], v160 offset:1552
	ds_read_b128 v[28:31], v160 offset:528
	ds_read_b128 v[88:91], v160 offset:16
	ds_read_b128 v[92:95], v160 offset:1040
	s_waitcnt lgkmcnt(0)
	v_mov_b32_e32 v84, v79
	v_mov_b32_e32 v70, v81
	v_mov_b32_e32 v86, v29
	v_mov_b32_e32 v72, v31
	v_mov_b32_e32 v79, v92
	v_mov_b32_e32 v85, v93
	v_mov_b32_e32 v81, v94
	v_mov_b32_e32 v71, v95
	v_mov_b32_e32 v29, v88
	v_mov_b32_e32 v87, v89
	v_mov_b32_e32 v31, v90
	v_mov_b32_e32 v73, v91
.LBB0_469:
	v_mov_b32_e32 v88, v68
	v_mov_b32_e32 v89, v68
	v_mov_b32_e32 v92, v68
	v_mov_b32_e32 v93, v68
	v_mul_f32_e32 v12, v12, v88
	v_mul_f32_e32 v13, v13, v89
	v_mul_f32_e32 v88, v4, v88
	v_mul_f32_e32 v89, v5, v89
	v_mov_b32_e32 v68, v69
	v_mov_b32_dpp v79, v52 row_shr:1 row_mask:0xf bank_mask:0xf
	v_mov_b32_dpp v78, v56 row_shr:1 row_mask:0xf bank_mask:0xf
	v_mov_b32_e32 v90, v69
	v_mov_b32_e32 v91, v69
	v_mul_f32_e32 v4, v10, v68
	v_mul_f32_e32 v5, v11, v69
	v_mul_f32_e32 v2, v2, v68
	v_mul_f32_e32 v3, v3, v69
	v_mov_b32_e32 v10, v88
	v_mov_b32_e32 v11, v12
	v_mul_f32_e32 v68, v36, v78
	v_mul_f32_e32 v69, v37, v79
	v_mov_b32_dpp v29, v44 row_shr:1 row_mask:0xf bank_mask:0xf
	v_mov_b32_dpp v28, v48 row_shr:1 row_mask:0xf bank_mask:0xf
	v_fmac_f32_e32 v68, v10, v34
	v_fmac_f32_e32 v69, v11, v35
	v_mul_f32_e32 v0, v0, v90
	v_mul_f32_e32 v1, v1, v91
	v_fma_f32 v28, v32, v28, v68
	v_fma_f32 v29, v33, v29, v69
	v_mov_b32_e32 v68, v0
	v_mul_f32_e32 v0, 0xbfb8aa3b, v29
	v_mul_f32_e32 v8, v8, v90
	v_mul_f32_e32 v9, v9, v91
	v_exp_f32_e32 v0, v0
	v_mov_b32_e32 v69, v8
	v_mul_f32_e32 v90, v68, v34
	v_mul_f32_e32 v91, v69, v35
	v_mul_f32_e32 v14, v14, v92
	v_mul_f32_e32 v15, v15, v93
	v_fmac_f32_e32 v90, v10, v36
	v_fmac_f32_e32 v91, v11, v37
	v_add_f32_e32 v0, 1.0, v0
	v_fma_f32 v78, v32, v78, v90
	v_fma_f32 v79, v33, v79, v91
	v_mov_b32_e32 v90, v48
	v_mov_b32_e32 v91, v44
	v_mul_f32_e32 v6, v6, v92
	v_mul_f32_e32 v7, v7, v93
	v_mul_f32_e32 v92, v90, v34
	v_mul_f32_e32 v93, v91, v35
	v_rcp_f32_e32 v0, v0
	v_mul_f32_e32 v8, 0xbfb8aa3b, v79
	v_fmac_f32_e32 v92, v68, v36
	v_fmac_f32_e32 v93, v69, v37
	v_exp_f32_e32 v8, v8
	v_fma_f32 v10, v10, v32, v92
	v_fma_f32 v11, v11, v33, v93
	v_mov_b32_e32 v92, v56
	v_mov_b32_e32 v93, v52
	v_mul_f32_e32 v34, v92, v34
	v_mul_f32_e32 v35, v93, v35
	v_mul_f32_e32 v0, v29, v0
	v_fmac_f32_e32 v34, v90, v36
	v_fmac_f32_e32 v35, v91, v37
	v_mov_b32_dpp v85, v53 row_shr:1 row_mask:0xf bank_mask:0xf
	v_fma_f32 v32, v68, v32, v34
	v_fma_f32 v33, v69, v33, v35
	v_mul_f32_e32 v34, v28, v0
	v_add_f32_e32 v0, 1.0, v8
	v_mul_f32_e32 v8, 0xbfb8aa3b, v11
	v_exp_f32_e32 v8, v8
	v_mul_f32_e32 v12, 0xbfb8aa3b, v33
	v_exp_f32_e32 v12, v12
	v_rcp_f32_e32 v0, v0
	v_add_f32_e32 v8, 1.0, v8
	v_rcp_f32_e32 v8, v8
	v_add_f32_e32 v12, 1.0, v12
	v_rcp_f32_e32 v12, v12
	v_mul_f32_e32 v0, v79, v0
	v_mul_f32_e32 v35, v78, v0
	v_mul_f32_e32 v0, v11, v8
	v_mov_b32_dpp v84, v57 row_shr:1 row_mask:0xf bank_mask:0xf
	v_mul_f32_e32 v36, v10, v0
	v_mul_f32_e32 v0, v33, v12
	v_mov_b32_e32 v12, v89
	v_mul_f32_e32 v10, v106, v84
	v_mul_f32_e32 v11, v107, v85
	v_mov_b32_e32 v44, v49
	v_mov_b32_dpp v87, v45 row_shr:1 row_mask:0xf bank_mask:0xf
	v_mov_b32_dpp v86, v49 row_shr:1 row_mask:0xf bank_mask:0xf
	v_fmac_f32_e32 v10, v12, v110
	v_fmac_f32_e32 v11, v13, v111
	v_mov_b32_e32 v8, v1
	v_mul_f32_e32 v28, v44, v110
	v_mul_f32_e32 v29, v45, v111
	v_mul_f32_e32 v32, v32, v0
	v_fmac_f32_e32 v10, v74, v86
	v_fmac_f32_e32 v11, v75, v87
	v_mul_f32_e32 v0, v8, v110
	v_mul_f32_e32 v1, v9, v111
	v_fmac_f32_e32 v28, v8, v106
	v_fmac_f32_e32 v29, v9, v107
	v_fmac_f32_e32 v0, v12, v106
	v_fmac_f32_e32 v1, v13, v107
	v_fma_f32 v12, v12, v74, v28
	v_fma_f32 v13, v13, v75, v29
	v_mul_f32_e32 v28, 0xbfb8aa3b, v11
	v_exp_f32_e32 v33, v28
	v_fmac_f32_e32 v0, v74, v84
	v_fmac_f32_e32 v1, v75, v85
	v_mov_b32_e32 v52, v57
	v_mul_f32_e32 v37, 0xbfb8aa3b, v1
	v_add_f32_e32 v33, 1.0, v33
	v_rcp_f32_e32 v33, v33
	v_exp_f32_e32 v37, v37
	v_mul_f32_e32 v28, v52, v110
	v_mul_f32_e32 v29, v53, v111
	v_mov_b32_dpp v81, v54 row_shr:1 row_mask:0xf bank_mask:0xf
	v_fmac_f32_e32 v28, v44, v106
	v_fmac_f32_e32 v29, v45, v107
	v_mul_f32_e32 v11, v11, v33
	v_fma_f32 v8, v8, v74, v28
	v_fma_f32 v9, v9, v75, v29
	v_mul_f32_e32 v33, v10, v11
	v_add_f32_e32 v10, 1.0, v37
	v_mul_f32_e32 v11, 0xbfb8aa3b, v13
	v_rcp_f32_e32 v10, v10
	v_exp_f32_e32 v11, v11
	v_mul_f32_e32 v28, 0xbfb8aa3b, v9
	v_exp_f32_e32 v28, v28
	v_mul_f32_e32 v1, v1, v10
	v_add_f32_e32 v10, 1.0, v11
	v_rcp_f32_e32 v10, v10
	v_add_f32_e32 v11, 1.0, v28
	v_rcp_f32_e32 v11, v11
	v_mul_f32_e32 v37, v0, v1
	v_mul_f32_e32 v0, v13, v10
	v_mul_f32_e32 v44, v12, v0
	v_mul_f32_e32 v0, v9, v11
	v_mov_b32_dpp v80, v58 row_shr:1 row_mask:0xf bank_mask:0xf
	v_mul_f32_e32 v45, v8, v0
	v_mov_b32_e32 v0, v6
	v_mov_b32_e32 v1, v14
	v_mul_f32_e32 v8, v42, v80
	v_mul_f32_e32 v9, v43, v81
	v_mov_b32_dpp v31, v46 row_shr:1 row_mask:0xf bank_mask:0xf
	v_mov_b32_dpp v30, v50 row_shr:1 row_mask:0xf bank_mask:0xf
	v_fmac_f32_e32 v8, v0, v40
	v_fmac_f32_e32 v9, v1, v41
	v_mov_b32_e32 v10, v2
	v_fmac_f32_e32 v8, v38, v30
	v_fmac_f32_e32 v9, v39, v31
	v_mov_b32_e32 v11, v4
	v_mul_f32_e32 v2, 0xbfb8aa3b, v9
	v_exp_f32_e32 v2, v2
	v_mul_f32_e32 v12, v10, v40
	v_mul_f32_e32 v13, v11, v41
	v_mov_b32_e32 v28, v50
	v_fmac_f32_e32 v12, v0, v42
	v_fmac_f32_e32 v13, v1, v43
	v_mov_b32_e32 v29, v46
	v_fmac_f32_e32 v12, v38, v80
	v_fmac_f32_e32 v13, v39, v81
	v_add_f32_e32 v2, 1.0, v2
	v_mul_f32_e32 v30, v28, v40
	v_mul_f32_e32 v31, v29, v41
	v_rcp_f32_e32 v2, v2
	v_mul_f32_e32 v4, 0xbfb8aa3b, v13
	v_fmac_f32_e32 v30, v10, v42
	v_fmac_f32_e32 v31, v11, v43
	v_exp_f32_e32 v4, v4
	v_fma_f32 v0, v0, v38, v30
	v_fma_f32 v1, v1, v39, v31
	v_mov_b32_e32 v30, v58
	v_mov_b32_e32 v31, v54
	v_mul_f32_e32 v30, v30, v40
	v_mul_f32_e32 v31, v31, v41
	v_mul_f32_e32 v2, v9, v2
	v_fma_f32 v28, v28, v42, v30
	v_fma_f32 v29, v29, v43, v31
	v_mov_b32_dpp v71, v55 row_shr:1 row_mask:0xf bank_mask:0xf
	v_fma_f32 v10, v10, v38, v28
	v_fma_f32 v11, v11, v39, v29
	v_mul_f32_e32 v28, v8, v2
	v_add_f32_e32 v2, 1.0, v4
	v_mul_f32_e32 v4, 0xbfb8aa3b, v1
	v_exp_f32_e32 v4, v4
	v_mul_f32_e32 v6, 0xbfb8aa3b, v11
	v_exp_f32_e32 v6, v6
	v_rcp_f32_e32 v2, v2
	v_add_f32_e32 v4, 1.0, v4
	v_rcp_f32_e32 v4, v4
	v_add_f32_e32 v6, 1.0, v6
	v_rcp_f32_e32 v6, v6
	v_mul_f32_e32 v2, v13, v2
	v_mul_f32_e32 v1, v1, v4
	v_mul_f32_e32 v13, v0, v1
	v_mul_f32_e32 v0, v11, v6
	v_mov_b32_dpp v70, v59 row_shr:1 row_mask:0xf bank_mask:0xf
	v_mul_f32_e32 v10, v10, v0
	v_mov_b32_e32 v14, v7
	v_mul_f32_e32 v0, v108, v70
	v_mul_f32_e32 v1, v109, v71
	v_mov_b32_dpp v73, v47 row_shr:1 row_mask:0xf bank_mask:0xf
	v_mov_b32_dpp v72, v51 row_shr:1 row_mask:0xf bank_mask:0xf
	v_fmac_f32_e32 v0, v14, v112
	v_fmac_f32_e32 v1, v15, v113
	v_mov_b32_e32 v4, v3
	v_fmac_f32_e32 v0, v76, v72
	v_fmac_f32_e32 v1, v77, v73
	v_mul_f32_e32 v12, v12, v2
	v_mul_f32_e32 v8, 0xbfb8aa3b, v1
	v_exp_f32_e32 v11, v8
	v_mul_f32_e32 v2, v4, v112
	v_mul_f32_e32 v3, v5, v113
	v_mov_b32_e32 v46, v51
	v_fmac_f32_e32 v2, v14, v108
	v_fmac_f32_e32 v3, v15, v109
	v_mul_f32_e32 v6, v46, v112
	v_mul_f32_e32 v7, v47, v113
	v_fmac_f32_e32 v2, v76, v70
	v_fmac_f32_e32 v3, v77, v71
	v_fmac_f32_e32 v6, v4, v108
	v_fmac_f32_e32 v7, v5, v109
	v_add_f32_e32 v11, 1.0, v11
	v_fmac_f32_e32 v6, v14, v76
	v_fmac_f32_e32 v7, v15, v77
	v_rcp_f32_e32 v11, v11
	v_mul_f32_e32 v14, 0xbfb8aa3b, v3
	v_exp_f32_e32 v14, v14
	v_mov_b32_e32 v54, v59
	v_mul_f32_e32 v8, v54, v112
	v_mul_f32_e32 v9, v55, v113
	v_mul_f32_e32 v1, v1, v11
	v_fmac_f32_e32 v8, v46, v108
	v_fmac_f32_e32 v9, v47, v109
	v_mul_f32_e32 v0, v0, v1
	v_fma_f32 v4, v4, v76, v8
	v_fma_f32 v5, v5, v77, v9
	v_add_f32_e32 v1, 1.0, v14
	v_mul_f32_e32 v8, 0xbfb8aa3b, v7
	v_rcp_f32_e32 v1, v1
	v_exp_f32_e32 v8, v8
	v_mul_f32_e32 v9, 0xbfb8aa3b, v5
	v_exp_f32_e32 v9, v9
	v_mul_f32_e32 v1, v3, v1
	v_add_f32_e32 v3, 1.0, v8
	v_rcp_f32_e32 v3, v3
	v_add_f32_e32 v8, 1.0, v9
	v_rcp_f32_e32 v8, v8
	v_mul_f32_e32 v9, v2, v1
	v_mul_f32_e32 v1, v7, v3
	v_mul_f32_e32 v6, v6, v1
	v_mul_f32_e32 v1, v5, v8
	v_add_u32_e32 v94, 0x80, v146
	v_mul_f32_e32 v4, v4, v1
	v_cvt_pk_bf16_f32 v68, v34, v33
	v_cvt_pk_bf16_f32 v69, v28, v0
	v_mov_b64_e32 v[0:1], s[24:25]
	v_mad_i64_i32 v[2:3], s[30:31], v94, s58, v[0:1]
	v_lshl_add_u64 v[2:3], v[2:3], 0, v[82:83]
	global_store_dwordx4 v[2:3], v[66:69], off nt
	v_add_u32_e32 v2, 0x81, v146
	v_mad_i64_i32 v[2:3], s[30:31], v2, s58, v[0:1]
	v_lshl_add_u64 v[2:3], v[2:3], 0, v[82:83]
	v_cvt_pk_bf16_f32 v66, v35, v37
	v_cvt_pk_bf16_f32 v67, v12, v9
	global_store_dwordx4 v[2:3], v[64:67], off nt
	v_add_u32_e32 v2, 0x82, v146
	v_mad_i64_i32 v[2:3], s[30:31], v2, s58, v[0:1]
	v_lshl_add_u64 v[2:3], v[2:3], 0, v[82:83]
	v_cvt_pk_bf16_f32 v64, v36, v44
	v_cvt_pk_bf16_f32 v65, v13, v6
	global_store_dwordx4 v[2:3], v[62:65], off nt
	v_add_u32_e32 v2, 0x83, v146
	v_mad_i64_i32 v[0:1], s[30:31], v2, s58, v[0:1]
	v_lshl_add_u64 v[0:1], v[0:1], 0, v[82:83]
	v_cvt_pk_bf16_f32 v62, v32, v45
	v_cvt_pk_bf16_f32 v63, v10, v4
	global_store_dwordx4 v[0:1], v[60:63], off nt
	s_and_b64 vcc, exec, s[8:9]
	s_mov_b64 s[8:9], -1
	s_cbranch_vccnz .LBB0_450
	s_xor_b32 s8, s11, 0x1000
	s_add_i32 s11, s8, 0
	s_add_i32 s11, s11, 0x24010
	s_and_saveexec_b64 s[8:9], s[2:3]
	s_cbranch_execz .LBB0_472
	v_add3_u32 v0, s11, v215, v190
	s_waitcnt vmcnt(8)
	ds_write_b128 v0, v[16:19]

.LBB0_554:
	ds_read_b128 v[128:131], v190
	ds_read_b128 v[132:135], v190 offset:1024
	ds_read_b128 v[136:139], v190 offset:2048
	ds_read_b128 v[140:143], v190 offset:3072
	s_add_u32 s18, s14, 0x100
	s_addc_u32 s19, s15, 0
	s_cmp_eq_u32 s51, 40
	s_cselect_b32 s23, s1, s19
	s_cselect_b32 s22, s0, s18
	s_cselect_b32 s21, s7, s50
	s_cselect_b32 s20, s6, s49
	v_lshl_add_u64 v[184:185], s[14:15], 0, v[160:161]
	s_add_i32 m0, s34, 0xc000
	ds_read_b128 v[144:147], v191
	ds_read_b128 v[148:151], v191 offset:1024
	ds_read_b128 v[168:171], v191 offset:2048
	ds_read_b128 v[172:175], v191 offset:3072
	ds_read_b128 v[176:179], v191 offset:4096
	ds_read_b128 v[180:183], v191 offset:5120
	ds_read_b128 v[194:197], v191 offset:6144
	ds_read_b128 v[198:201], v191 offset:7168
	global_load_lds_dwordx4 v[184:185], off
	v_lshl_add_u64 v[184:185], s[14:15], 0, v[162:163]
	s_add_i32 m0, s34, 0xe000
	s_nop 0
	global_load_lds_dwordx4 v[184:185], off
	s_waitcnt lgkmcnt(8)
	s_barrier
	s_waitcnt lgkmcnt(0)
	s_setprio 1
	s_waitcnt lgkmcnt(0)
	v_mfma_f32_16x16x32_bf16 v[124:127], v[128:131], v[144:147], v[124:127]
	v_mfma_f32_16x16x32_bf16 v[120:123], v[136:139], v[144:147], v[120:123]
	v_mfma_f32_16x16x32_bf16 v[108:111], v[128:131], v[168:171], v[108:111]
	v_mfma_f32_16x16x32_bf16 v[104:107], v[136:139], v[168:171], v[104:107]
	v_mfma_f32_16x16x32_bf16 v[92:95], v[128:131], v[176:179], v[92:95]
	v_mfma_f32_16x16x32_bf16 v[88:91], v[136:139], v[176:179], v[88:91]
	v_mfma_f32_16x16x32_bf16 v[76:79], v[128:131], v[194:197], v[76:79]
	v_mfma_f32_16x16x32_bf16 v[72:75], v[136:139], v[194:197], v[72:75]
	v_mfma_f32_16x16x32_bf16 v[124:127], v[132:135], v[148:151], v[124:127]
	v_mfma_f32_16x16x32_bf16 v[120:123], v[140:143], v[148:151], v[120:123]
	v_mfma_f32_16x16x32_bf16 v[108:111], v[132:135], v[172:175], v[108:111]
	v_mfma_f32_16x16x32_bf16 v[104:107], v[140:143], v[172:175], v[104:107]
	v_mfma_f32_16x16x32_bf16 v[92:95], v[132:135], v[180:183], v[92:95]
	v_mfma_f32_16x16x32_bf16 v[88:91], v[140:143], v[180:183], v[88:91]
	v_mfma_f32_16x16x32_bf16 v[76:79], v[132:135], v[198:201], v[76:79]
	v_mfma_f32_16x16x32_bf16 v[72:75], v[140:143], v[198:201], v[72:75]
	s_setprio 0
	s_barrier
	s_add_i32 s14, s43, s31
	v_lshl_add_u64 v[184:185], s[20:21], 0, v[154:155]
	s_mov_b32 m0, s14
	ds_read_b128 v[202:205], v192
	ds_read_b128 v[206:209], v192 offset:1024
	ds_read_b128 v[210:213], v192 offset:2048
	ds_read_b128 v[214:217], v192 offset:3072
	global_load_lds_dwordx4 v[184:185], off
	v_lshl_add_u64 v[218:219], s[20:21], 0, v[158:159]
	s_add_i32 m0, s14, 0x2000
	s_nop 0
	global_load_lds_dwordx4 v[218:219], off
	s_barrier
	s_waitcnt lgkmcnt(0)
	s_setprio 1
	s_waitcnt lgkmcnt(0)
	v_mfma_f32_16x16x32_bf16 v[116:119], v[202:205], v[144:147], v[116:119]
	v_mfma_f32_16x16x32_bf16 v[112:115], v[210:213], v[144:147], v[112:115]
	v_mfma_f32_16x16x32_bf16 v[100:103], v[202:205], v[168:171], v[100:103]
	v_mfma_f32_16x16x32_bf16 v[96:99], v[210:213], v[168:171], v[96:99]
	v_mfma_f32_16x16x32_bf16 v[84:87], v[202:205], v[176:179], v[84:87]
	v_mfma_f32_16x16x32_bf16 v[80:83], v[210:213], v[176:179], v[80:83]
	v_mfma_f32_16x16x32_bf16 v[68:71], v[202:205], v[194:197], v[68:71]
	v_mfma_f32_16x16x32_bf16 v[64:67], v[210:213], v[194:197], v[64:67]
	v_mfma_f32_16x16x32_bf16 v[116:119], v[206:209], v[148:151], v[116:119]
	v_mfma_f32_16x16x32_bf16 v[112:115], v[214:217], v[148:151], v[112:115]
	v_mfma_f32_16x16x32_bf16 v[100:103], v[206:209], v[172:175], v[100:103]
	v_mfma_f32_16x16x32_bf16 v[96:99], v[214:217], v[172:175], v[96:99]
	v_mfma_f32_16x16x32_bf16 v[84:87], v[206:209], v[180:183], v[84:87]
	v_mfma_f32_16x16x32_bf16 v[80:83], v[214:217], v[180:183], v[80:83]
	v_mfma_f32_16x16x32_bf16 v[68:71], v[206:209], v[198:201], v[68:71]
	v_mfma_f32_16x16x32_bf16 v[64:67], v[214:217], v[198:201], v[64:67]
	s_setprio 0
	s_mov_b32 m0, s34
	v_lshl_add_u64 v[220:221], s[22:23], 0, v[152:153]
	s_barrier
	ds_read_b128 v[144:147], v191 offset:16384
	ds_read_b128 v[148:151], v191 offset:17408
	ds_read_b128 v[168:171], v191 offset:18432
	ds_read_b128 v[172:175], v191 offset:19456
	ds_read_b128 v[176:179], v191 offset:20480
	ds_read_b128 v[180:183], v191 offset:21504
	ds_read_b128 v[194:197], v191 offset:22528
	ds_read_b128 v[198:201], v191 offset:23552
	global_load_lds_dwordx4 v[220:221], off
	v_lshl_add_u64 v[222:223], s[22:23], 0, v[156:157]
	s_mov_b32 m0, s35
	s_nop 0
	global_load_lds_dwordx4 v[222:223], off
	s_barrier
	s_waitcnt lgkmcnt(0)
	s_setprio 1
	s_waitcnt lgkmcnt(0)
	v_mfma_f32_16x16x32_bf16 v[60:63], v[128:131], v[144:147], v[60:63]
	v_mfma_f32_16x16x32_bf16 v[56:59], v[136:139], v[144:147], v[56:59]
	v_mfma_f32_16x16x32_bf16 v[44:47], v[128:131], v[168:171], v[44:47]
	v_mfma_f32_16x16x32_bf16 v[40:43], v[136:139], v[168:171], v[40:43]
	v_mfma_f32_16x16x32_bf16 v[28:31], v[128:131], v[176:179], v[28:31]
	v_mfma_f32_16x16x32_bf16 v[24:27], v[136:139], v[176:179], v[24:27]
	v_mfma_f32_16x16x32_bf16 v[12:15], v[128:131], v[194:197], v[12:15]
	v_mfma_f32_16x16x32_bf16 v[8:11], v[136:139], v[194:197], v[8:11]
	v_mfma_f32_16x16x32_bf16 v[60:63], v[132:135], v[148:151], v[60:63]
	v_mfma_f32_16x16x32_bf16 v[56:59], v[140:143], v[148:151], v[56:59]
	v_mfma_f32_16x16x32_bf16 v[44:47], v[132:135], v[172:175], v[44:47]
	v_mfma_f32_16x16x32_bf16 v[40:43], v[140:143], v[172:175], v[40:43]
	v_mfma_f32_16x16x32_bf16 v[28:31], v[132:135], v[180:183], v[28:31]
	v_mfma_f32_16x16x32_bf16 v[24:27], v[140:143], v[180:183], v[24:27]
	v_mfma_f32_16x16x32_bf16 v[12:15], v[132:135], v[198:201], v[12:15]
	v_mfma_f32_16x16x32_bf16 v[8:11], v[140:143], v[198:201], v[8:11]
	s_setprio 0
	s_barrier
	s_add_u32 s14, s20, 0xb0000
	s_addc_u32 s15, s21, 0
	s_add_i32 s52, s44, s31
	v_lshl_add_u64 v[128:129], s[14:15], 0, v[154:155]
	s_mov_b32 m0, s52
	s_nop 0
	global_load_lds_dwordx4 v[128:129], off
	v_lshl_add_u64 v[128:129], s[14:15], 0, v[158:159]
	s_add_i32 m0, s52, 0x2000
	s_nop 0
	global_load_lds_dwordx4 v[128:129], off
	s_waitcnt vmcnt(6)
	s_barrier
	s_setprio 1
	v_mfma_f32_16x16x32_bf16 v[52:55], v[202:205], v[144:147], v[52:55]
	v_mfma_f32_16x16x32_bf16 v[48:51], v[210:213], v[144:147], v[48:51]
	v_mfma_f32_16x16x32_bf16 v[36:39], v[202:205], v[168:171], v[36:39]
	v_mfma_f32_16x16x32_bf16 v[32:35], v[210:213], v[168:171], v[32:35]
	v_mfma_f32_16x16x32_bf16 v[20:23], v[202:205], v[176:179], v[20:23]
	v_mfma_f32_16x16x32_bf16 v[16:19], v[210:213], v[176:179], v[16:19]
	v_mfma_f32_16x16x32_bf16 v[4:7], v[202:205], v[194:197], v[4:7]
	v_mfma_f32_16x16x32_bf16 v[0:3], v[210:213], v[194:197], v[0:3]
	v_mfma_f32_16x16x32_bf16 v[52:55], v[206:209], v[148:151], v[52:55]
	v_mfma_f32_16x16x32_bf16 v[48:51], v[214:217], v[148:151], v[48:51]
	v_mfma_f32_16x16x32_bf16 v[36:39], v[206:209], v[172:175], v[36:39]
	v_mfma_f32_16x16x32_bf16 v[32:35], v[214:217], v[172:175], v[32:35]
	v_mfma_f32_16x16x32_bf16 v[20:23], v[206:209], v[180:183], v[20:23]
	v_mfma_f32_16x16x32_bf16 v[16:19], v[214:217], v[180:183], v[16:19]
	v_mfma_f32_16x16x32_bf16 v[4:7], v[206:209], v[198:201], v[4:7]
	v_mfma_f32_16x16x32_bf16 v[0:3], v[214:217], v[198:201], v[0:3]
	s_setprio 0
	s_add_i32 s52, 0, 0x18000
	v_add_u32_e32 v140, s52, v187
	s_barrier
	ds_read_b128 v[128:131], v140
	ds_read_b128 v[132:135], v140 offset:1024
	ds_read_b128 v[136:139], v140 offset:2048
	ds_read_b128 v[140:143], v140 offset:3072
	s_add_u32 s14, s22, 0xb0000
	s_addc_u32 s15, s23, 0
	s_mov_b32 m0, s36
	v_lshl_add_u64 v[202:203], s[14:15], 0, v[152:153]
	ds_read_b128 v[144:147], v191 offset:32768
	ds_read_b128 v[148:151], v191 offset:33792
	ds_read_b128 v[168:171], v191 offset:34816
	ds_read_b128 v[172:175], v191 offset:35840
	ds_read_b128 v[176:179], v191 offset:36864
	ds_read_b128 v[180:183], v191 offset:37888
	ds_read_b128 v[194:197], v191 offset:38912
	ds_read_b128 v[198:201], v191 offset:39936
	global_load_lds_dwordx4 v[202:203], off
	v_lshl_add_u64 v[202:203], s[14:15], 0, v[156:157]
	s_mov_b32 m0, s37
	s_nop 0
	global_load_lds_dwordx4 v[202:203], off
	s_waitcnt lgkmcnt(8)
	s_barrier
	s_waitcnt lgkmcnt(0)
	s_setprio 1
	s_waitcnt lgkmcnt(0)
	v_mfma_f32_16x16x32_bf16 v[124:127], v[128:131], v[144:147], v[124:127]
	v_mfma_f32_16x16x32_bf16 v[120:123], v[136:139], v[144:147], v[120:123]
	v_mfma_f32_16x16x32_bf16 v[108:111], v[128:131], v[168:171], v[108:111]
	v_mfma_f32_16x16x32_bf16 v[104:107], v[136:139], v[168:171], v[104:107]
	v_mfma_f32_16x16x32_bf16 v[92:95], v[128:131], v[176:179], v[92:95]
	v_mfma_f32_16x16x32_bf16 v[88:91], v[136:139], v[176:179], v[88:91]
	v_mfma_f32_16x16x32_bf16 v[76:79], v[128:131], v[194:197], v[76:79]
	v_mfma_f32_16x16x32_bf16 v[72:75], v[136:139], v[194:197], v[72:75]
	v_mfma_f32_16x16x32_bf16 v[124:127], v[132:135], v[148:151], v[124:127]
	v_mfma_f32_16x16x32_bf16 v[120:123], v[140:143], v[148:151], v[120:123]
	v_mfma_f32_16x16x32_bf16 v[108:111], v[132:135], v[172:175], v[108:111]
	v_mfma_f32_16x16x32_bf16 v[104:107], v[140:143], v[172:175], v[104:107]
	v_mfma_f32_16x16x32_bf16 v[92:95], v[132:135], v[180:183], v[92:95]
	v_mfma_f32_16x16x32_bf16 v[88:91], v[140:143], v[180:183], v[88:91]
	v_mfma_f32_16x16x32_bf16 v[76:79], v[132:135], v[198:201], v[76:79]
	v_mfma_f32_16x16x32_bf16 v[72:75], v[140:143], v[198:201], v[72:75]
	s_setprio 0
	s_barrier
	s_add_i32 s22, 0, 0x1c000
	s_add_i32 s14, s52, s31
	v_add_u32_e32 v214, s22, v187
	v_lshl_add_u64 v[184:185], v[184:185], 0, s[12:13]
	s_mov_b32 m0, s14
	ds_read_b128 v[202:205], v214
	ds_read_b128 v[206:209], v214 offset:1024
	ds_read_b128 v[210:213], v214 offset:2048
	ds_read_b128 v[214:217], v214 offset:3072
	global_load_lds_dwordx4 v[184:185], off
	v_lshl_add_u64 v[184:185], v[218:219], 0, s[12:13]
	s_add_i32 m0, s14, 0x2000
	s_nop 0
	global_load_lds_dwordx4 v[184:185], off
	s_barrier
	s_waitcnt lgkmcnt(0)
	s_setprio 1
	s_waitcnt lgkmcnt(0)
	v_mfma_f32_16x16x32_bf16 v[116:119], v[202:205], v[144:147], v[116:119]
	v_mfma_f32_16x16x32_bf16 v[112:115], v[210:213], v[144:147], v[112:115]
	v_mfma_f32_16x16x32_bf16 v[100:103], v[202:205], v[168:171], v[100:103]
	v_mfma_f32_16x16x32_bf16 v[96:99], v[210:213], v[168:171], v[96:99]
	v_mfma_f32_16x16x32_bf16 v[84:87], v[202:205], v[176:179], v[84:87]
	v_mfma_f32_16x16x32_bf16 v[80:83], v[210:213], v[176:179], v[80:83]
	v_mfma_f32_16x16x32_bf16 v[68:71], v[202:205], v[194:197], v[68:71]
	v_mfma_f32_16x16x32_bf16 v[64:67], v[210:213], v[194:197], v[64:67]
	v_mfma_f32_16x16x32_bf16 v[116:119], v[206:209], v[148:151], v[116:119]
	v_mfma_f32_16x16x32_bf16 v[112:115], v[214:217], v[148:151], v[112:115]
	v_mfma_f32_16x16x32_bf16 v[100:103], v[206:209], v[172:175], v[100:103]
	v_mfma_f32_16x16x32_bf16 v[96:99], v[214:217], v[172:175], v[96:99]
	v_mfma_f32_16x16x32_bf16 v[84:87], v[206:209], v[180:183], v[84:87]
	v_mfma_f32_16x16x32_bf16 v[80:83], v[214:217], v[180:183], v[80:83]
	v_mfma_f32_16x16x32_bf16 v[68:71], v[206:209], v[198:201], v[68:71]
	v_mfma_f32_16x16x32_bf16 v[64:67], v[214:217], v[198:201], v[64:67]
	s_setprio 0
	s_mov_b32 m0, s39
	v_lshl_add_u64 v[184:185], v[220:221], 0, s[12:13]
	s_barrier
	ds_read_b128 v[144:147], v191 offset:49152
	ds_read_b128 v[148:151], v191 offset:50176
	ds_read_b128 v[168:171], v191 offset:51200
	ds_read_b128 v[172:175], v191 offset:52224
	ds_read_b128 v[176:179], v191 offset:53248
	ds_read_b128 v[180:183], v191 offset:54272
	ds_read_b128 v[194:197], v191 offset:55296
	ds_read_b128 v[198:201], v191 offset:56320
	global_load_lds_dwordx4 v[184:185], off
	v_lshl_add_u64 v[184:185], v[222:223], 0, s[12:13]
	s_mov_b32 m0, s40
	s_nop 0
	global_load_lds_dwordx4 v[184:185], off
	s_barrier
	s_waitcnt lgkmcnt(0)
	s_setprio 1
	s_waitcnt lgkmcnt(0)
	v_mfma_f32_16x16x32_bf16 v[60:63], v[128:131], v[144:147], v[60:63]
	v_mfma_f32_16x16x32_bf16 v[56:59], v[136:139], v[144:147], v[56:59]
	v_mfma_f32_16x16x32_bf16 v[44:47], v[128:131], v[168:171], v[44:47]
	v_mfma_f32_16x16x32_bf16 v[40:43], v[136:139], v[168:171], v[40:43]
	v_mfma_f32_16x16x32_bf16 v[28:31], v[128:131], v[176:179], v[28:31]
	v_mfma_f32_16x16x32_bf16 v[24:27], v[136:139], v[176:179], v[24:27]
	v_mfma_f32_16x16x32_bf16 v[12:15], v[128:131], v[194:197], v[12:15]
	v_mfma_f32_16x16x32_bf16 v[8:11], v[136:139], v[194:197], v[8:11]
	v_mfma_f32_16x16x32_bf16 v[60:63], v[132:135], v[148:151], v[60:63]
	v_mfma_f32_16x16x32_bf16 v[56:59], v[140:143], v[148:151], v[56:59]
	v_mfma_f32_16x16x32_bf16 v[44:47], v[132:135], v[172:175], v[44:47]
	v_mfma_f32_16x16x32_bf16 v[40:43], v[140:143], v[172:175], v[40:43]
	v_mfma_f32_16x16x32_bf16 v[28:31], v[132:135], v[180:183], v[28:31]
	v_mfma_f32_16x16x32_bf16 v[24:27], v[140:143], v[180:183], v[24:27]
	v_mfma_f32_16x16x32_bf16 v[12:15], v[132:135], v[198:201], v[12:15]
	v_mfma_f32_16x16x32_bf16 v[8:11], v[140:143], v[198:201], v[8:11]
	s_setprio 0
	s_barrier
	s_add_u32 s14, s20, 0xb0080
	s_addc_u32 s15, s21, 0
	s_add_i32 s20, s22, s31
	v_lshl_add_u64 v[128:129], s[14:15], 0, v[154:155]
	s_mov_b32 m0, s20
	s_nop 0
	global_load_lds_dwordx4 v[128:129], off
	v_lshl_add_u64 v[128:129], s[14:15], 0, v[158:159]
	s_add_i32 m0, s20, 0x2000
	s_nop 0
	global_load_lds_dwordx4 v[128:129], off
	s_waitcnt vmcnt(6)
	s_barrier
	s_setprio 1
	v_mfma_f32_16x16x32_bf16 v[52:55], v[202:205], v[144:147], v[52:55]
	v_mfma_f32_16x16x32_bf16 v[48:51], v[210:213], v[144:147], v[48:51]
	v_mfma_f32_16x16x32_bf16 v[36:39], v[202:205], v[168:171], v[36:39]
	v_mfma_f32_16x16x32_bf16 v[32:35], v[210:213], v[168:171], v[32:35]
	v_mfma_f32_16x16x32_bf16 v[20:23], v[202:205], v[176:179], v[20:23]
	v_mfma_f32_16x16x32_bf16 v[16:19], v[210:213], v[176:179], v[16:19]
	v_mfma_f32_16x16x32_bf16 v[4:7], v[202:205], v[194:197], v[4:7]
	v_mfma_f32_16x16x32_bf16 v[0:3], v[210:213], v[194:197], v[0:3]
	v_mfma_f32_16x16x32_bf16 v[52:55], v[206:209], v[148:151], v[52:55]
	v_mfma_f32_16x16x32_bf16 v[48:51], v[214:217], v[148:151], v[48:51]
	v_mfma_f32_16x16x32_bf16 v[36:39], v[206:209], v[172:175], v[36:39]
	v_mfma_f32_16x16x32_bf16 v[32:35], v[214:217], v[172:175], v[32:35]
	v_mfma_f32_16x16x32_bf16 v[20:23], v[206:209], v[180:183], v[20:23]
	v_mfma_f32_16x16x32_bf16 v[16:19], v[214:217], v[180:183], v[16:19]
	v_mfma_f32_16x16x32_bf16 v[4:7], v[206:209], v[198:201], v[4:7]
	v_mfma_f32_16x16x32_bf16 v[0:3], v[214:217], v[198:201], v[0:3]
	s_setprio 0
	s_add_i32 s51, s51, 2
	s_add_u32 s49, s49, 0x100
	s_addc_u32 s50, s50, 0
	s_cmp_gt_u32 s51, 41
	s_mov_b64 s[14:15], s[18:19]
	s_barrier
	s_cbranch_scc0 .LBB0_554
	v_lshl_or_b32 v168, s10, 8, v189
	v_lshl_add_u32 v170, s48, 8, v186
	v_ashrrev_i32_e32 v169, 31, v168
	v_lshlrev_b64 v[202:203], 1, v[168:169]
	v_ashrrev_i32_e32 v171, 31, v170
	v_or_b32_e32 v182, 16, v170
	v_lshl_add_u64 v[172:173], s[64:65], 0, v[202:203]
	v_lshlrev_b64 v[204:205], 11, v[170:171]
	v_ashrrev_i32_e32 v183, 31, v182
	v_or_b32_e32 v178, 32, v170
	v_lshl_add_u64 v[128:129], v[172:173], 0, v[204:205]
	v_lshlrev_b64 v[184:185], 11, v[182:183]
	v_ashrrev_i32_e32 v179, 31, v178
	v_or_b32_e32 v174, 48, v170
	global_load_dwordx4 v[194:197], v[128:129], off
	global_load_dwordx4 v[198:201], v[128:129], off offset:256
	v_lshl_add_u64 v[128:129], v[172:173], 0, v[184:185]
	v_lshlrev_b64 v[180:181], 11, v[178:179]
	v_ashrrev_i32_e32 v175, 31, v174
	global_load_dwordx4 v[148:151], v[128:129], off
	global_load_dwordx4 v[144:147], v[128:129], off offset:256
	v_lshl_add_u64 v[128:129], v[172:173], 0, v[180:181]
	v_lshlrev_b64 v[176:177], 11, v[174:175]
	global_load_dwordx4 v[140:143], v[128:129], off
	global_load_dwordx4 v[136:139], v[128:129], off offset:256
	v_lshl_add_u64 v[128:129], v[172:173], 0, v[176:177]
	global_load_dwordx4 v[132:135], v[128:129], off
	s_nop 0
	global_load_dwordx4 v[128:131], v[128:129], off offset:256
	s_lshl_b32 s14, s10, 2
	s_ashr_i32 s15, s14, 31
	v_add_u32_e32 v252, 0x80, v170
	v_ashrrev_i32_e32 v253, 31, v252
	v_lshlrev_b64 v[252:253], 11, v[252:253]
	v_lshl_add_u64 v[252:253], v[172:173], 0, v[252:253]
	global_load_dwordx4 v[236:239], v[252:253], off
	global_load_dwordx4 v[240:243], v[252:253], off offset:256
	v_add_u32_e32 v252, 0x90, v170
	v_ashrrev_i32_e32 v253, 31, v252
	v_lshlrev_b64 v[252:253], 11, v[252:253]
	v_lshl_add_u64 v[252:253], v[172:173], 0, v[252:253]
	global_load_dwordx4 v[244:247], v[252:253], off
	global_load_dwordx4 v[248:251], v[252:253], off offset:256
	v_add_u32_e32 v252, 0xa0, v170
	v_ashrrev_i32_e32 v253, 31, v252
	v_lshlrev_b64 v[252:253], 11, v[252:253]
	v_lshl_add_u64 v[252:253], v[172:173], 0, v[252:253]
	global_load_dwordx4 v[210:213], v[252:253], off
	global_load_dwordx4 v[214:217], v[252:253], off offset:256
	s_waitcnt vmcnt(6)
	v_lshlrev_b32_e32 v206, 16, v194
	v_and_b32_e32 v207, 0xffff0000, v194
	v_lshlrev_b32_e32 v194, 16, v195
	v_and_b32_e32 v195, 0xffff0000, v195
	v_lshlrev_b32_e32 v208, 16, v196
	v_and_b32_e32 v209, 0xffff0000, v196
	v_lshlrev_b32_e32 v196, 16, v197
	v_and_b32_e32 v197, 0xffff0000, v197
	v_add_f32_e32 v126, v126, v194
	v_add_f32_e32 v127, v127, v195
	v_add_f32_e32 v124, v124, v206
	v_add_f32_e32 v125, v125, v207
	v_add_f32_e32 v194, v122, v196
	v_add_f32_e32 v195, v123, v197
	v_add_f32_e32 v122, v120, v208
	v_add_f32_e32 v123, v121, v209
	v_mul_f32_e32 v120, v125, v125
	v_mul_f32_e32 v121, v127, v127
	v_fmac_f32_e32 v120, v124, v124
	v_fmac_f32_e32 v121, v126, v126
	v_add_f32_e32 v120, v120, v121
	v_mul_f32_e32 v121, v123, v123
	v_mul_f32_e32 v196, v195, v195
	v_fmac_f32_e32 v121, v122, v122
	v_fmac_f32_e32 v196, v194, v194
	v_add_f32_e32 v121, v121, v196
	v_add_f32_e32 v206, v120, v121
	v_cvt_pk_bf16_f32 v120, v124, v125
	v_cvt_pk_bf16_f32 v121, v126, v127
	v_lshlrev_b32_e32 v124, 16, v198
	v_and_b32_e32 v125, 0xffff0000, v198
	v_lshlrev_b32_e32 v126, 16, v199
	v_and_b32_e32 v127, 0xffff0000, v199
	v_cvt_pk_bf16_f32 v122, v122, v123
	v_cvt_pk_bf16_f32 v123, v194, v195
	v_lshlrev_b32_e32 v194, 16, v200
	v_and_b32_e32 v195, 0xffff0000, v200
	v_add_f32_e32 v118, v118, v126
	v_add_f32_e32 v119, v119, v127
	v_add_f32_e32 v116, v116, v124
	v_add_f32_e32 v117, v117, v125
	v_lshlrev_b32_e32 v196, 16, v201
	v_and_b32_e32 v197, 0xffff0000, v201
	v_add_f32_e32 v126, v112, v194
	v_add_f32_e32 v127, v113, v195
	v_mul_f32_e32 v112, v117, v117
	v_mul_f32_e32 v113, v119, v119
	v_add_f32_e32 v124, v114, v196
	v_add_f32_e32 v125, v115, v197
	v_fmac_f32_e32 v112, v116, v116
	v_fmac_f32_e32 v113, v118, v118
	v_add_f32_e32 v112, v112, v113
	v_mul_f32_e32 v113, v127, v127
	v_mul_f32_e32 v114, v125, v125
	v_fmac_f32_e32 v113, v126, v126
	v_fmac_f32_e32 v114, v124, v124
	v_add_f32_e32 v113, v113, v114
	v_add_f32_e32 v112, v112, v113
	v_and_b32_e32 v114, 64, v193
	v_add_f32_e32 v113, v206, v112
	v_xor_b32_e32 v112, 16, v193
	v_add_u32_e32 v196, 64, v114
	v_cmp_lt_i32_e32 vcc, v112, v196
	v_lshl_add_u64 v[114:115], s[64:65], 0, v[204:205]
	v_lshl_add_u64 v[194:195], v[114:115], 0, v[202:203]
	v_cndmask_b32_e32 v112, v193, v112, vcc
	v_lshlrev_b32_e32 v112, 2, v112
	ds_bpermute_b32 v197, v112, v113
	global_store_dwordx4 v[194:195], v[120:123], off
	v_cvt_pk_bf16_f32 v116, v116, v117
	v_cvt_pk_bf16_f32 v117, v118, v119
	v_cvt_pk_bf16_f32 v118, v126, v127
	s_waitcnt lgkmcnt(0)
	v_add_f32_e32 v114, v113, v197
	v_xor_b32_e32 v113, 32, v193
	v_cmp_lt_i32_e32 vcc, v113, v196
	v_cvt_pk_bf16_f32 v119, v124, v125
	global_store_dwordx4 v[194:195], v[116:119], off offset:256
	s_nop 0
	v_cndmask_b32_e32 v113, v193, v113, vcc
	v_lshlrev_b32_e32 v113, 2, v113
	ds_bpermute_b32 v115, v113, v114
	s_and_saveexec_b64 s[18:19], s[2:3]
	s_cbranch_execz .LBB0_557
	s_waitcnt lgkmcnt(0)
	v_add_f32_e32 v116, v114, v115
	v_lshlrev_b64 v[114:115], 6, v[170:171]
	v_lshl_add_u64 v[114:115], s[74:75], 0, v[114:115]
	v_lshl_add_u64 v[114:115], s[14:15], 2, v[114:115]
	s_lshl_b32 s10, s38, 2
	v_lshl_add_u64 v[114:115], v[114:115], 0, s[10:11]
	global_store_dword v[114:115], v116, off
.LBB0_557:
	s_or_b64 exec, exec, s[18:19]
	v_lshlrev_b32_e32 v114, 16, v148
	s_waitcnt lgkmcnt(0)
	v_and_b32_e32 v115, 0xffff0000, v148
	v_lshlrev_b32_e32 v116, 16, v149
	v_and_b32_e32 v117, 0xffff0000, v149
	v_lshlrev_b32_e32 v118, 16, v150
	v_and_b32_e32 v119, 0xffff0000, v150
	v_lshlrev_b32_e32 v120, 16, v151
	v_and_b32_e32 v121, 0xffff0000, v151
	v_add_f32_e32 v110, v110, v116
	v_add_f32_e32 v111, v111, v117
	v_add_f32_e32 v108, v108, v114
	v_add_f32_e32 v109, v109, v115
	v_add_f32_e32 v114, v106, v120
	v_add_f32_e32 v115, v107, v121
	v_add_f32_e32 v106, v104, v118
	v_add_f32_e32 v107, v105, v119
	v_mul_f32_e32 v104, v109, v109
	v_mul_f32_e32 v105, v111, v111
	v_fmac_f32_e32 v104, v108, v108
	v_fmac_f32_e32 v105, v110, v110
	v_add_f32_e32 v104, v104, v105
	v_mul_f32_e32 v105, v107, v107
	v_mul_f32_e32 v116, v115, v115
	v_fmac_f32_e32 v105, v106, v106
	v_fmac_f32_e32 v116, v114, v114
	v_add_f32_e32 v105, v105, v116
	v_add_f32_e32 v118, v104, v105
	v_cvt_pk_bf16_f32 v104, v108, v109
	v_cvt_pk_bf16_f32 v105, v110, v111
	v_lshlrev_b32_e32 v108, 16, v144
	v_and_b32_e32 v109, 0xffff0000, v144
	v_lshlrev_b32_e32 v110, 16, v145
	v_and_b32_e32 v111, 0xffff0000, v145
	v_cvt_pk_bf16_f32 v106, v106, v107
	v_cvt_pk_bf16_f32 v107, v114, v115
	v_lshlrev_b32_e32 v114, 16, v146
	v_and_b32_e32 v115, 0xffff0000, v146
	v_add_f32_e32 v102, v102, v110
	v_add_f32_e32 v103, v103, v111
	v_add_f32_e32 v100, v100, v108
	v_add_f32_e32 v101, v101, v109
	v_lshlrev_b32_e32 v116, 16, v147
	v_and_b32_e32 v117, 0xffff0000, v147
	v_add_f32_e32 v110, v96, v114
	v_add_f32_e32 v111, v97, v115
	v_mul_f32_e32 v96, v101, v101
	v_mul_f32_e32 v97, v103, v103
	v_add_f32_e32 v108, v98, v116
	v_add_f32_e32 v109, v99, v117
	v_fmac_f32_e32 v96, v100, v100
	v_fmac_f32_e32 v97, v102, v102
	v_add_f32_e32 v96, v96, v97
	v_mul_f32_e32 v97, v111, v111
	v_mul_f32_e32 v98, v109, v109
	v_fmac_f32_e32 v97, v110, v110
	v_fmac_f32_e32 v98, v108, v108
	v_add_f32_e32 v97, v97, v98
	v_add_f32_e32 v96, v96, v97
	v_add_f32_e32 v99, v118, v96
	ds_bpermute_b32 v116, v112, v99
	v_lshl_add_u64 v[96:97], s[64:65], 0, v[184:185]
	v_lshl_add_u64 v[114:115], v[168:169], 1, v[96:97]
	global_store_dwordx4 v[114:115], v[104:107], off
	v_cvt_pk_bf16_f32 v98, v100, v101
	s_waitcnt lgkmcnt(0)
	v_add_f32_e32 v96, v99, v116
	ds_bpermute_b32 v97, v113, v96
	v_cvt_pk_bf16_f32 v99, v102, v103
	v_cvt_pk_bf16_f32 v100, v110, v111
	v_cvt_pk_bf16_f32 v101, v108, v109
	global_store_dwordx4 v[114:115], v[98:101], off offset:256
	s_and_saveexec_b64 s[18:19], s[2:3]
	s_cbranch_execz .LBB0_559
	s_waitcnt lgkmcnt(0)
	v_add_f32_e32 v98, v96, v97
	v_lshlrev_b64 v[96:97], 6, v[182:183]
	v_lshl_add_u64 v[96:97], s[74:75], 0, v[96:97]
	v_lshl_add_u64 v[96:97], s[14:15], 2, v[96:97]
	s_lshl_b32 s10, s38, 2
	v_lshl_add_u64 v[96:97], v[96:97], 0, s[10:11]
	global_store_dword v[96:97], v98, off
.LBB0_559:
	s_or_b64 exec, exec, s[18:19]
	v_lshlrev_b32_e32 v96, 16, v140
	s_waitcnt lgkmcnt(0)
	v_and_b32_e32 v97, 0xffff0000, v140
	v_lshlrev_b32_e32 v98, 16, v141
	v_and_b32_e32 v99, 0xffff0000, v141
	v_lshlrev_b32_e32 v100, 16, v142
	v_and_b32_e32 v101, 0xffff0000, v142
	v_lshlrev_b32_e32 v102, 16, v143
	v_and_b32_e32 v103, 0xffff0000, v143
	v_add_f32_e32 v94, v94, v98
	v_add_f32_e32 v95, v95, v99
	v_add_f32_e32 v92, v92, v96
	v_add_f32_e32 v93, v93, v97
	v_add_f32_e32 v96, v90, v102
	v_add_f32_e32 v97, v91, v103
	v_add_f32_e32 v90, v88, v100
	v_add_f32_e32 v91, v89, v101
	v_mul_f32_e32 v88, v93, v93
	v_mul_f32_e32 v89, v95, v95
	v_fmac_f32_e32 v88, v92, v92
	v_fmac_f32_e32 v89, v94, v94
	v_add_f32_e32 v88, v88, v89
	v_mul_f32_e32 v89, v91, v91
	v_mul_f32_e32 v98, v97, v97
	v_fmac_f32_e32 v89, v90, v90
	v_fmac_f32_e32 v98, v96, v96
	v_add_f32_e32 v89, v89, v98
	v_add_f32_e32 v100, v88, v89
	v_cvt_pk_bf16_f32 v88, v92, v93
	v_cvt_pk_bf16_f32 v89, v94, v95
	v_lshlrev_b32_e32 v92, 16, v136
	v_and_b32_e32 v93, 0xffff0000, v136
	v_lshlrev_b32_e32 v94, 16, v137
	v_and_b32_e32 v95, 0xffff0000, v137
	v_cvt_pk_bf16_f32 v90, v90, v91
	v_cvt_pk_bf16_f32 v91, v96, v97
	v_lshlrev_b32_e32 v96, 16, v138
	v_and_b32_e32 v97, 0xffff0000, v138
	v_add_f32_e32 v86, v86, v94
	v_add_f32_e32 v87, v87, v95
	v_add_f32_e32 v84, v84, v92
	v_add_f32_e32 v85, v85, v93
	v_lshlrev_b32_e32 v98, 16, v139
	v_and_b32_e32 v99, 0xffff0000, v139
	v_add_f32_e32 v94, v80, v96
	v_add_f32_e32 v95, v81, v97
	v_mul_f32_e32 v80, v85, v85
	v_mul_f32_e32 v81, v87, v87
	v_add_f32_e32 v92, v82, v98
	v_add_f32_e32 v93, v83, v99
	v_fmac_f32_e32 v80, v84, v84
	v_fmac_f32_e32 v81, v86, v86
	v_add_f32_e32 v80, v80, v81
	v_mul_f32_e32 v81, v95, v95
	v_mul_f32_e32 v82, v93, v93
	v_fmac_f32_e32 v81, v94, v94
	v_fmac_f32_e32 v82, v92, v92
	v_add_f32_e32 v81, v81, v82
	v_add_f32_e32 v80, v80, v81
	v_add_f32_e32 v83, v100, v80
	ds_bpermute_b32 v98, v112, v83
	v_lshl_add_u64 v[80:81], s[64:65], 0, v[180:181]
	v_lshl_add_u64 v[96:97], v[168:169], 1, v[80:81]
	global_store_dwordx4 v[96:97], v[88:91], off
	v_cvt_pk_bf16_f32 v82, v84, v85
	s_waitcnt lgkmcnt(0)
	v_add_f32_e32 v80, v83, v98
	ds_bpermute_b32 v81, v113, v80
	v_cvt_pk_bf16_f32 v83, v86, v87
	v_cvt_pk_bf16_f32 v84, v94, v95
	v_cvt_pk_bf16_f32 v85, v92, v93
	global_store_dwordx4 v[96:97], v[82:85], off offset:256
	s_and_saveexec_b64 s[18:19], s[2:3]
	s_cbranch_execz .LBB0_561
	s_waitcnt lgkmcnt(0)
	v_add_f32_e32 v82, v80, v81
	v_lshlrev_b64 v[80:81], 6, v[178:179]
	v_lshl_add_u64 v[80:81], s[74:75], 0, v[80:81]
	v_lshl_add_u64 v[80:81], s[14:15], 2, v[80:81]
	s_lshl_b32 s10, s38, 2
	v_lshl_add_u64 v[80:81], v[80:81], 0, s[10:11]
	global_store_dword v[80:81], v82, off
.LBB0_561:
	s_or_b64 exec, exec, s[18:19]
	v_lshlrev_b32_e32 v80, 16, v132
	s_waitcnt lgkmcnt(0)
	v_and_b32_e32 v81, 0xffff0000, v132
	v_lshlrev_b32_e32 v82, 16, v133
	v_and_b32_e32 v83, 0xffff0000, v133
	v_lshlrev_b32_e32 v84, 16, v134
	v_and_b32_e32 v85, 0xffff0000, v134
	v_lshlrev_b32_e32 v86, 16, v135
	v_and_b32_e32 v87, 0xffff0000, v135
	v_add_f32_e32 v78, v78, v82
	v_add_f32_e32 v79, v79, v83
	v_add_f32_e32 v76, v76, v80
	v_add_f32_e32 v77, v77, v81
	v_add_f32_e32 v80, v74, v86
	v_add_f32_e32 v81, v75, v87
	v_add_f32_e32 v74, v72, v84
	v_add_f32_e32 v75, v73, v85
	v_mul_f32_e32 v72, v77, v77
	v_mul_f32_e32 v73, v79, v79
	v_fmac_f32_e32 v72, v76, v76
	v_fmac_f32_e32 v73, v78, v78
	v_add_f32_e32 v72, v72, v73
	v_mul_f32_e32 v73, v75, v75
	v_mul_f32_e32 v82, v81, v81
	v_fmac_f32_e32 v73, v74, v74
	v_fmac_f32_e32 v82, v80, v80
	v_add_f32_e32 v73, v73, v82
	v_add_f32_e32 v84, v72, v73
	v_cvt_pk_bf16_f32 v72, v76, v77
	v_cvt_pk_bf16_f32 v73, v78, v79
	v_lshlrev_b32_e32 v76, 16, v128
	v_and_b32_e32 v77, 0xffff0000, v128
	v_lshlrev_b32_e32 v78, 16, v129
	v_and_b32_e32 v79, 0xffff0000, v129
	v_cvt_pk_bf16_f32 v74, v74, v75
	v_cvt_pk_bf16_f32 v75, v80, v81
	v_lshlrev_b32_e32 v80, 16, v130
	v_and_b32_e32 v81, 0xffff0000, v130
	v_add_f32_e32 v70, v70, v78
	v_add_f32_e32 v71, v71, v79
	v_add_f32_e32 v68, v68, v76
	v_add_f32_e32 v69, v69, v77
	v_lshlrev_b32_e32 v82, 16, v131
	v_and_b32_e32 v83, 0xffff0000, v131
	v_add_f32_e32 v78, v64, v80
	v_add_f32_e32 v79, v65, v81
	v_mul_f32_e32 v64, v69, v69
	v_mul_f32_e32 v65, v71, v71
	v_add_f32_e32 v76, v66, v82
	v_add_f32_e32 v77, v67, v83
	v_fmac_f32_e32 v64, v68, v68
	v_fmac_f32_e32 v65, v70, v70
	v_add_f32_e32 v64, v64, v65
	v_mul_f32_e32 v65, v79, v79
	v_mul_f32_e32 v66, v77, v77
	v_fmac_f32_e32 v65, v78, v78
	v_fmac_f32_e32 v66, v76, v76
	v_add_f32_e32 v65, v65, v66
	v_add_f32_e32 v64, v64, v65
	v_add_f32_e32 v67, v84, v64
	ds_bpermute_b32 v82, v112, v67
	v_lshl_add_u64 v[64:65], s[64:65], 0, v[176:177]
	v_lshl_add_u64 v[80:81], v[168:169], 1, v[64:65]
	global_store_dwordx4 v[80:81], v[72:75], off
	v_cvt_pk_bf16_f32 v66, v68, v69
	s_waitcnt lgkmcnt(0)
	v_add_f32_e32 v64, v67, v82
	ds_bpermute_b32 v65, v113, v64
	v_cvt_pk_bf16_f32 v67, v70, v71
	v_cvt_pk_bf16_f32 v68, v78, v79
	v_cvt_pk_bf16_f32 v69, v76, v77
	global_store_dwordx4 v[80:81], v[66:69], off offset:256
	s_and_saveexec_b64 s[18:19], s[2:3]
	s_cbranch_execz .LBB0_563
	s_waitcnt lgkmcnt(0)
	v_add_f32_e32 v66, v64, v65
	v_lshlrev_b64 v[64:65], 6, v[174:175]
	v_lshl_add_u64 v[64:65], s[74:75], 0, v[64:65]
	v_lshl_add_u64 v[64:65], s[14:15], 2, v[64:65]
	s_lshl_b32 s10, s38, 2
	v_lshl_add_u64 v[64:65], v[64:65], 0, s[10:11]
	global_store_dword v[64:65], v66, off
.LBB0_563:
	s_or_b64 exec, exec, s[18:19]
	v_add_u32_e32 v100, 0x80, v170
	v_ashrrev_i32_e32 v101, 31, v100
	v_add_u32_e32 v96, 0x90, v170
	v_lshlrev_b64 v[110:111], 11, v[100:101]
	v_ashrrev_i32_e32 v97, 31, v96
	v_add_u32_e32 v92, 0xa0, v170
	s_waitcnt lgkmcnt(0)
	v_lshl_add_u64 v[64:65], v[172:173], 0, v[110:111]
	v_lshlrev_b64 v[98:99], 11, v[96:97]
	v_ashrrev_i32_e32 v93, 31, v92
	v_add_u32_e32 v88, 0xb0, v170
	v_lshl_add_u64 v[64:65], v[172:173], 0, v[98:99]
	v_lshlrev_b64 v[94:95], 11, v[92:93]
	v_ashrrev_i32_e32 v89, 31, v88
	v_lshl_add_u64 v[64:65], v[172:173], 0, v[94:95]
	v_lshlrev_b64 v[90:91], 11, v[88:89]
	v_lshl_add_u64 v[64:65], v[172:173], 0, v[90:91]
	global_load_dwordx4 v[68:71], v[64:65], off
	s_nop 0
	global_load_dwordx4 v[64:67], v[64:65], off offset:256
	s_waitcnt vmcnt(15)
	v_lshlrev_b32_e32 v114, 16, v236
	v_and_b32_e32 v115, 0xffff0000, v236
	v_lshlrev_b32_e32 v236, 16, v237
	v_and_b32_e32 v237, 0xffff0000, v237
	v_lshlrev_b32_e32 v116, 16, v238
	v_and_b32_e32 v117, 0xffff0000, v238
	v_lshlrev_b32_e32 v238, 16, v239
	v_and_b32_e32 v239, 0xffff0000, v239
	v_add_f32_e32 v62, v62, v236
	v_add_f32_e32 v63, v63, v237
	v_add_f32_e32 v60, v60, v114
	v_add_f32_e32 v61, v61, v115
	v_add_f32_e32 v236, v58, v238
	v_add_f32_e32 v237, v59, v239
	v_add_f32_e32 v58, v56, v116
	v_add_f32_e32 v59, v57, v117
	v_mul_f32_e32 v56, v61, v61
	v_mul_f32_e32 v57, v63, v63
	v_fmac_f32_e32 v56, v60, v60
	v_fmac_f32_e32 v57, v62, v62
	v_add_f32_e32 v56, v56, v57
	v_mul_f32_e32 v57, v59, v59
	v_mul_f32_e32 v238, v237, v237
	v_fmac_f32_e32 v57, v58, v58
	v_fmac_f32_e32 v238, v236, v236
	v_add_f32_e32 v57, v57, v238
	v_add_f32_e32 v114, v56, v57
	v_cvt_pk_bf16_f32 v56, v60, v61
	v_cvt_pk_bf16_f32 v57, v62, v63
	s_waitcnt vmcnt(14)
	v_lshlrev_b32_e32 v60, 16, v240
	v_and_b32_e32 v61, 0xffff0000, v240
	v_lshlrev_b32_e32 v62, 16, v241
	v_and_b32_e32 v63, 0xffff0000, v241
	v_cvt_pk_bf16_f32 v58, v58, v59
	v_cvt_pk_bf16_f32 v59, v236, v237
	v_lshlrev_b32_e32 v236, 16, v242
	v_and_b32_e32 v237, 0xffff0000, v242
	v_add_f32_e32 v54, v54, v62
	v_add_f32_e32 v55, v55, v63
	v_add_f32_e32 v52, v52, v60
	v_add_f32_e32 v53, v53, v61
	v_lshlrev_b32_e32 v238, 16, v243
	v_and_b32_e32 v239, 0xffff0000, v243
	v_add_f32_e32 v62, v48, v236
	v_add_f32_e32 v63, v49, v237
	v_mul_f32_e32 v48, v53, v53
	v_mul_f32_e32 v49, v55, v55
	v_add_f32_e32 v60, v50, v238
	v_add_f32_e32 v61, v51, v239
	v_fmac_f32_e32 v48, v52, v52
	v_fmac_f32_e32 v49, v54, v54
	v_add_f32_e32 v48, v48, v49
	v_mul_f32_e32 v49, v63, v63
	v_mul_f32_e32 v50, v61, v61
	v_fmac_f32_e32 v49, v62, v62
	v_fmac_f32_e32 v50, v60, v60
	v_add_f32_e32 v49, v49, v50
	v_add_f32_e32 v48, v48, v49
	v_add_f32_e32 v51, v114, v48
	ds_bpermute_b32 v238, v112, v51
	v_lshl_add_u64 v[48:49], s[64:65], 0, v[110:111]
	v_lshl_add_u64 v[236:237], v[168:169], 1, v[48:49]
	global_store_dwordx4 v[236:237], v[56:59], off
	v_cvt_pk_bf16_f32 v50, v52, v53
	s_waitcnt lgkmcnt(0)
	v_add_f32_e32 v48, v51, v238
	ds_bpermute_b32 v49, v113, v48
	v_cvt_pk_bf16_f32 v51, v54, v55
	v_cvt_pk_bf16_f32 v52, v62, v63
	v_cvt_pk_bf16_f32 v53, v60, v61
	global_store_dwordx4 v[236:237], v[50:53], off offset:256
	s_and_saveexec_b64 s[18:19], s[2:3]
	s_cbranch_execz .LBB0_565
	s_waitcnt lgkmcnt(0)
	v_add_f32_e32 v50, v48, v49
	v_lshlrev_b64 v[48:49], 6, v[100:101]
	v_lshl_add_u64 v[48:49], s[74:75], 0, v[48:49]
	v_lshl_add_u64 v[48:49], s[14:15], 2, v[48:49]
	s_lshl_b32 s10, s38, 2
	v_lshl_add_u64 v[48:49], v[48:49], 0, s[10:11]
	global_store_dword v[48:49], v50, off
.LBB0_565:
	s_or_b64 exec, exec, s[18:19]
	s_waitcnt vmcnt(15)
	v_lshlrev_b32_e32 v48, 16, v244
	s_waitcnt lgkmcnt(0)
	v_and_b32_e32 v49, 0xffff0000, v244
	v_lshlrev_b32_e32 v50, 16, v245
	v_and_b32_e32 v51, 0xffff0000, v245
	v_lshlrev_b32_e32 v52, 16, v246
	v_and_b32_e32 v53, 0xffff0000, v246
	v_lshlrev_b32_e32 v54, 16, v247
	v_and_b32_e32 v55, 0xffff0000, v247
	v_add_f32_e32 v46, v46, v50
	v_add_f32_e32 v47, v47, v51
	v_add_f32_e32 v44, v44, v48
	v_add_f32_e32 v45, v45, v49
	v_add_f32_e32 v48, v42, v54
	v_add_f32_e32 v49, v43, v55
	v_add_f32_e32 v42, v40, v52
	v_add_f32_e32 v43, v41, v53
	v_mul_f32_e32 v40, v45, v45
	v_mul_f32_e32 v41, v47, v47
	v_fmac_f32_e32 v40, v44, v44
	v_fmac_f32_e32 v41, v46, v46
	v_add_f32_e32 v40, v40, v41
	v_mul_f32_e32 v41, v43, v43
	v_mul_f32_e32 v50, v49, v49
	v_fmac_f32_e32 v41, v42, v42
	v_fmac_f32_e32 v50, v48, v48
	v_add_f32_e32 v41, v41, v50
	v_add_f32_e32 v52, v40, v41
	v_cvt_pk_bf16_f32 v40, v44, v45
	v_cvt_pk_bf16_f32 v41, v46, v47
	s_waitcnt vmcnt(14)
	v_lshlrev_b32_e32 v44, 16, v248
	v_and_b32_e32 v45, 0xffff0000, v248
	v_lshlrev_b32_e32 v46, 16, v249
	v_and_b32_e32 v47, 0xffff0000, v249
	v_cvt_pk_bf16_f32 v42, v42, v43
	v_cvt_pk_bf16_f32 v43, v48, v49
	v_lshlrev_b32_e32 v48, 16, v250
	v_and_b32_e32 v49, 0xffff0000, v250
	v_add_f32_e32 v38, v38, v46
	v_add_f32_e32 v39, v39, v47
	v_add_f32_e32 v36, v36, v44
	v_add_f32_e32 v37, v37, v45
	v_lshlrev_b32_e32 v50, 16, v251
	v_and_b32_e32 v51, 0xffff0000, v251
	v_add_f32_e32 v46, v32, v48
	v_add_f32_e32 v47, v33, v49
	v_mul_f32_e32 v32, v37, v37
	v_mul_f32_e32 v33, v39, v39
	v_add_f32_e32 v44, v34, v50
	v_add_f32_e32 v45, v35, v51
	v_fmac_f32_e32 v32, v36, v36
	v_fmac_f32_e32 v33, v38, v38
	v_add_f32_e32 v32, v32, v33
	v_mul_f32_e32 v33, v47, v47
	v_mul_f32_e32 v34, v45, v45
	v_fmac_f32_e32 v33, v46, v46
	v_fmac_f32_e32 v34, v44, v44
	v_add_f32_e32 v33, v33, v34
	v_add_f32_e32 v32, v32, v33
	v_add_f32_e32 v35, v52, v32
	ds_bpermute_b32 v50, v112, v35
	v_lshl_add_u64 v[32:33], s[64:65], 0, v[98:99]
	v_lshl_add_u64 v[48:49], v[168:169], 1, v[32:33]
	global_store_dwordx4 v[48:49], v[40:43], off
	v_cvt_pk_bf16_f32 v34, v36, v37
	s_waitcnt lgkmcnt(0)
	v_add_f32_e32 v32, v35, v50
	ds_bpermute_b32 v33, v113, v32
	v_cvt_pk_bf16_f32 v35, v38, v39
	v_cvt_pk_bf16_f32 v36, v46, v47
	v_cvt_pk_bf16_f32 v37, v44, v45
	global_store_dwordx4 v[48:49], v[34:37], off offset:256
	s_and_saveexec_b64 s[18:19], s[2:3]
	s_cbranch_execz .LBB0_567
	s_waitcnt lgkmcnt(0)
	v_add_f32_e32 v34, v32, v33
	v_lshlrev_b64 v[32:33], 6, v[96:97]
	v_lshl_add_u64 v[32:33], s[74:75], 0, v[32:33]
	v_lshl_add_u64 v[32:33], s[14:15], 2, v[32:33]
	s_lshl_b32 s10, s38, 2
	v_lshl_add_u64 v[32:33], v[32:33], 0, s[10:11]
	global_store_dword v[32:33], v34, off
.LBB0_567:
	s_or_b64 exec, exec, s[18:19]
	s_waitcnt vmcnt(15)
	v_lshlrev_b32_e32 v32, 16, v210
	s_waitcnt lgkmcnt(0)
	v_and_b32_e32 v33, 0xffff0000, v210
	v_lshlrev_b32_e32 v34, 16, v211
	v_and_b32_e32 v35, 0xffff0000, v211
	v_lshlrev_b32_e32 v36, 16, v212
	v_and_b32_e32 v37, 0xffff0000, v212
	v_lshlrev_b32_e32 v38, 16, v213
	v_and_b32_e32 v39, 0xffff0000, v213
	v_add_f32_e32 v30, v30, v34
	v_add_f32_e32 v31, v31, v35
	v_add_f32_e32 v28, v28, v32
	v_add_f32_e32 v29, v29, v33
	v_add_f32_e32 v32, v26, v38
	v_add_f32_e32 v33, v27, v39
	v_add_f32_e32 v26, v24, v36
	v_add_f32_e32 v27, v25, v37
	v_mul_f32_e32 v24, v29, v29
	v_mul_f32_e32 v25, v31, v31
	v_fmac_f32_e32 v24, v28, v28
	v_fmac_f32_e32 v25, v30, v30
	v_add_f32_e32 v24, v24, v25
	v_mul_f32_e32 v25, v27, v27
	v_mul_f32_e32 v34, v33, v33
	v_fmac_f32_e32 v25, v26, v26
	v_fmac_f32_e32 v34, v32, v32
	v_add_f32_e32 v25, v25, v34
	v_add_f32_e32 v36, v24, v25
	v_cvt_pk_bf16_f32 v24, v28, v29
	v_cvt_pk_bf16_f32 v25, v30, v31
	s_waitcnt vmcnt(14)
	v_lshlrev_b32_e32 v28, 16, v214
	v_and_b32_e32 v29, 0xffff0000, v214
	v_lshlrev_b32_e32 v30, 16, v215
	v_and_b32_e32 v31, 0xffff0000, v215
	v_cvt_pk_bf16_f32 v26, v26, v27
	v_cvt_pk_bf16_f32 v27, v32, v33
	v_lshlrev_b32_e32 v32, 16, v216
	v_and_b32_e32 v33, 0xffff0000, v216
	v_add_f32_e32 v22, v22, v30
	v_add_f32_e32 v23, v23, v31
	v_add_f32_e32 v20, v20, v28
	v_add_f32_e32 v21, v21, v29
	v_lshlrev_b32_e32 v34, 16, v217
	v_and_b32_e32 v35, 0xffff0000, v217
	v_add_f32_e32 v30, v16, v32
	v_add_f32_e32 v31, v17, v33
	v_mul_f32_e32 v16, v21, v21
	v_mul_f32_e32 v17, v23, v23
	v_add_f32_e32 v28, v18, v34
	v_add_f32_e32 v29, v19, v35
	v_fmac_f32_e32 v16, v20, v20
	v_fmac_f32_e32 v17, v22, v22
	v_add_f32_e32 v16, v16, v17
	v_mul_f32_e32 v17, v31, v31
	v_mul_f32_e32 v18, v29, v29
	v_fmac_f32_e32 v17, v30, v30
	v_fmac_f32_e32 v18, v28, v28
	v_add_f32_e32 v17, v17, v18
	v_add_f32_e32 v16, v16, v17
	v_add_f32_e32 v19, v36, v16
	ds_bpermute_b32 v34, v112, v19
	v_lshl_add_u64 v[16:17], s[64:65], 0, v[94:95]
	v_lshl_add_u64 v[32:33], v[168:169], 1, v[16:17]
	global_store_dwordx4 v[32:33], v[24:27], off
	v_cvt_pk_bf16_f32 v18, v20, v21
	s_waitcnt lgkmcnt(0)
	v_add_f32_e32 v16, v19, v34
	ds_bpermute_b32 v17, v113, v16
	v_cvt_pk_bf16_f32 v19, v22, v23
	v_cvt_pk_bf16_f32 v20, v30, v31
	v_cvt_pk_bf16_f32 v21, v28, v29
	global_store_dwordx4 v[32:33], v[18:21], off offset:256
	s_and_saveexec_b64 s[18:19], s[2:3]
	s_cbranch_execz .LBB0_569
	s_waitcnt lgkmcnt(0)
	v_add_f32_e32 v18, v16, v17
	v_lshlrev_b64 v[16:17], 6, v[92:93]
	v_lshl_add_u64 v[16:17], s[74:75], 0, v[16:17]
	v_lshl_add_u64 v[16:17], s[14:15], 2, v[16:17]
	s_lshl_b32 s10, s38, 2
	v_lshl_add_u64 v[16:17], v[16:17], 0, s[10:11]
	global_store_dword v[16:17], v18, off
.LBB0_569:
	s_or_b64 exec, exec, s[18:19]
	s_waitcnt vmcnt(7)
	v_lshlrev_b32_e32 v16, 16, v68
	s_waitcnt lgkmcnt(0)
	v_and_b32_e32 v17, 0xffff0000, v68
	v_lshlrev_b32_e32 v18, 16, v69
	v_and_b32_e32 v19, 0xffff0000, v69
	v_lshlrev_b32_e32 v20, 16, v70
	v_and_b32_e32 v21, 0xffff0000, v70
	v_lshlrev_b32_e32 v22, 16, v71
	v_and_b32_e32 v23, 0xffff0000, v71
	v_add_f32_e32 v14, v14, v18
	v_add_f32_e32 v15, v15, v19
	v_add_f32_e32 v12, v12, v16
	v_add_f32_e32 v13, v13, v17
	v_add_f32_e32 v16, v10, v22
	v_add_f32_e32 v17, v11, v23
	v_add_f32_e32 v10, v8, v20
	v_add_f32_e32 v11, v9, v21
	v_mul_f32_e32 v8, v13, v13
	v_mul_f32_e32 v9, v15, v15
	v_fmac_f32_e32 v8, v12, v12
	v_fmac_f32_e32 v9, v14, v14
	v_add_f32_e32 v8, v8, v9
	v_mul_f32_e32 v9, v11, v11
	v_mul_f32_e32 v18, v17, v17
	v_fmac_f32_e32 v9, v10, v10
	v_fmac_f32_e32 v18, v16, v16
	v_add_f32_e32 v9, v9, v18
	v_add_f32_e32 v20, v8, v9
	v_cvt_pk_bf16_f32 v8, v12, v13
	v_cvt_pk_bf16_f32 v9, v14, v15
	s_waitcnt vmcnt(6)
	v_lshlrev_b32_e32 v12, 16, v64
	v_and_b32_e32 v13, 0xffff0000, v64
	v_lshlrev_b32_e32 v14, 16, v65
	v_and_b32_e32 v15, 0xffff0000, v65
	v_cvt_pk_bf16_f32 v10, v10, v11
	v_cvt_pk_bf16_f32 v11, v16, v17
	v_lshlrev_b32_e32 v16, 16, v66
	v_and_b32_e32 v17, 0xffff0000, v66
	v_add_f32_e32 v6, v6, v14
	v_add_f32_e32 v7, v7, v15
	v_add_f32_e32 v4, v4, v12
	v_add_f32_e32 v5, v5, v13
	v_lshlrev_b32_e32 v18, 16, v67
	v_and_b32_e32 v19, 0xffff0000, v67
	v_add_f32_e32 v14, v0, v16
	v_add_f32_e32 v15, v1, v17
	v_mul_f32_e32 v0, v5, v5
	v_mul_f32_e32 v1, v7, v7
	v_add_f32_e32 v12, v2, v18
	v_add_f32_e32 v13, v3, v19
	v_fmac_f32_e32 v0, v4, v4
	v_fmac_f32_e32 v1, v6, v6
	v_add_f32_e32 v0, v0, v1
	v_mul_f32_e32 v1, v15, v15
	v_mul_f32_e32 v2, v13, v13
	v_fmac_f32_e32 v1, v14, v14
	v_fmac_f32_e32 v2, v12, v12
	v_add_f32_e32 v1, v1, v2
	v_add_f32_e32 v0, v0, v1
	v_add_f32_e32 v3, v20, v0
	ds_bpermute_b32 v18, v112, v3
	v_lshl_add_u64 v[0:1], s[64:65], 0, v[90:91]
	v_lshl_add_u64 v[16:17], v[168:169], 1, v[0:1]
	global_store_dwordx4 v[16:17], v[8:11], off
	v_cvt_pk_bf16_f32 v2, v4, v5
	s_waitcnt lgkmcnt(0)
	v_add_f32_e32 v0, v3, v18
	ds_bpermute_b32 v1, v113, v0
	v_cvt_pk_bf16_f32 v3, v6, v7
	v_cvt_pk_bf16_f32 v4, v14, v15
	v_cvt_pk_bf16_f32 v5, v12, v13
	global_store_dwordx4 v[16:17], v[2:5], off offset:256
	s_and_saveexec_b64 s[18:19], s[2:3]
	s_cbranch_execz .LBB0_542
	s_waitcnt lgkmcnt(0)
	v_add_f32_e32 v2, v0, v1
	v_lshlrev_b64 v[0:1], 6, v[88:89]
	v_lshl_add_u64 v[0:1], s[74:75], 0, v[0:1]
	v_lshl_add_u64 v[0:1], s[14:15], 2, v[0:1]
	s_lshl_b32 s10, s38, 2
	v_lshl_add_u64 v[0:1], v[0:1], 0, s[10:11]
	global_store_dword v[0:1], v2, off
	s_branch .LBB0_542

.LBB0_645:
	s_lshl_b32 s8, s37, 12
	s_and_b32 s23, s8, 0x1000
	v_add_u32_e32 v138, s23, v176
	v_add_u32_e32 v138, 0xc00, v138
	s_cmp_gt_i32 s14, 5
	v_lshl_add_u32 v162, s36, 8, v174
	ds_read2_b32 v[168:169], v138 offset1:16
	ds_read2_b32 v[166:167], v138 offset0:32 offset1:48
	ds_read2_b32 v[164:165], v138 offset0:128 offset1:144
	ds_read2_b32 v[160:161], v138 offset0:160 offset1:176
	s_cselect_b64 s[42:43], -1, 0
	s_cmp_lt_u32 s14, 10
	s_cselect_b64 s[36:37], -1, 0
	s_cmp_gt_u32 s14, 9
	v_ashrrev_i32_e32 v163, 31, v162
	s_cselect_b64 s[40:41], -1, 0
	s_lshl_b32 s14, s14, 8
	v_lshlrev_b64 v[170:171], 11, v[162:163]
	s_waitcnt lgkmcnt(0)
	v_mul_f32_e32 v134, v134, v168
	v_mul_f32_e32 v135, v135, v168
	v_mul_f32_e32 v132, v132, v168
	v_mul_f32_e32 v133, v133, v168
	v_mul_f32_e32 v130, v130, v168
	v_mul_f32_e32 v131, v131, v168
	v_mul_f32_e32 v128, v128, v168
	v_mul_f32_e32 v129, v129, v168
	s_mov_b64 s[8:9], -1
	s_and_b64 vcc, exec, s[42:43]
	s_cbranch_vccz .LBB0_653
	s_and_b64 vcc, exec, s[40:41]
	s_cbranch_vccz .LBB0_650
	s_and_saveexec_b64 s[8:9], s[4:5]
	s_cbranch_execz .LBB0_649
	v_mul_f32_e32 v163, 0xbfb8aa3b, v134
	v_exp_f32_e32 v182, v163
	v_mul_f32_e32 v163, 0xbfb8aa3b, v135
	v_exp_f32_e32 v183, v163
	v_mul_f32_e32 v138, 0xbfb8aa3b, v132
	v_exp_f32_e32 v172, v138
	v_mul_f32_e32 v138, 0xbfb8aa3b, v128
	v_exp_f32_e32 v186, v138
	v_mul_f32_e32 v138, 0xbfb8aa3b, v133
	v_exp_f32_e32 v173, v138
	v_mul_f32_e32 v138, 0xbfb8aa3b, v129
	v_add_f32_e32 v182, 1.0, v182
	v_add_f32_e32 v183, 1.0, v183
	v_exp_f32_e32 v187, v138
	v_div_scale_f32 v138, s[38:39], v183, v183, 1.0
	v_rcp_f32_e32 v163, v138
	v_mul_f32_e32 v184, 0xbfb8aa3b, v130
	v_exp_f32_e32 v190, v184
	v_add_f32_e32 v172, 1.0, v172
	v_add_f32_e32 v173, 1.0, v173
	v_fma_f32 v184, -v138, v163, 1.0
	v_fmac_f32_e32 v163, v184, v163
	v_div_scale_f32 v184, vcc, 1.0, v183, 1.0
	v_mul_f32_e32 v185, v184, v163
	v_fma_f32 v189, -v138, v185, v184
	v_fmac_f32_e32 v185, v189, v163
	v_fma_f32 v138, -v138, v185, v184
	v_div_scale_f32 v184, s[38:39], v182, v182, 1.0
	v_rcp_f32_e32 v189, v184
	v_div_fmas_f32 v138, v138, v163, v185
	v_div_fixup_f32 v185, v138, v183, 1.0
	v_fma_f32 v138, -v184, v189, 1.0
	v_fmac_f32_e32 v189, v138, v189
	v_div_scale_f32 v138, vcc, 1.0, v182, 1.0
	v_mul_f32_e32 v163, v138, v189
	v_fma_f32 v183, -v184, v163, v138
	v_fmac_f32_e32 v163, v183, v189
	v_div_scale_f32 v183, s[38:39], v173, v173, 1.0
	v_rcp_f32_e32 v191, v183
	v_fma_f32 v138, -v184, v163, v138
	v_div_fmas_f32 v138, v138, v189, v163
	v_div_fixup_f32 v184, v138, v182, 1.0
	v_fma_f32 v138, -v183, v191, 1.0
	v_fmac_f32_e32 v191, v138, v191
	v_div_scale_f32 v138, vcc, 1.0, v173, 1.0
	v_mul_f32_e32 v163, v138, v191
	v_fma_f32 v182, -v183, v163, v138
	v_fmac_f32_e32 v163, v182, v191
	v_fma_f32 v138, -v183, v163, v138
	v_div_scale_f32 v182, s[38:39], v172, v172, 1.0
	v_div_fmas_f32 v138, v138, v191, v163
	v_rcp_f32_e32 v189, v182
	v_div_fixup_f32 v183, v138, v173, 1.0
	v_mul_f32_e32 v173, 0xbfb8aa3b, v131
	v_exp_f32_e32 v191, v173
	v_fma_f32 v138, -v182, v189, 1.0
	v_fmac_f32_e32 v189, v138, v189
	v_div_scale_f32 v138, vcc, 1.0, v172, 1.0
	v_add_f32_e32 v190, 1.0, v190
	v_add_f32_e32 v191, 1.0, v191
	v_mul_f32_e32 v163, v138, v189
	v_div_scale_f32 v192, s[38:39], v191, v191, 1.0
	v_fma_f32 v173, -v182, v163, v138
	v_rcp_f32_e32 v193, v192
	v_fmac_f32_e32 v163, v173, v189
	v_fma_f32 v138, -v182, v163, v138
	v_div_fmas_f32 v138, v138, v189, v163
	v_div_fixup_f32 v182, v138, v172, 1.0
	v_fma_f32 v138, -v192, v193, 1.0
	v_fmac_f32_e32 v193, v138, v193
	v_div_scale_f32 v138, vcc, 1.0, v191, 1.0
	v_mul_f32_e32 v163, v138, v193
	v_add_f32_e32 v172, 1.0, v186
	v_add_f32_e32 v173, 1.0, v187
	v_fma_f32 v186, -v192, v163, v138
	v_fmac_f32_e32 v163, v186, v193
	v_div_scale_f32 v186, s[38:39], v190, v190, 1.0
	v_rcp_f32_e32 v187, v186
	v_fma_f32 v138, -v192, v163, v138
	v_div_fmas_f32 v138, v138, v193, v163
	v_div_fixup_f32 v193, v138, v191, 1.0
	v_fma_f32 v138, -v186, v187, 1.0
	v_fmac_f32_e32 v187, v138, v187
	v_div_scale_f32 v138, vcc, 1.0, v190, 1.0
	v_mul_f32_e32 v163, v138, v187
	v_fma_f32 v189, -v186, v163, v138
	v_fmac_f32_e32 v163, v189, v187
	v_fma_f32 v138, -v186, v163, v138
	v_div_scale_f32 v186, s[38:39], v173, v173, 1.0
	v_rcp_f32_e32 v189, v186
	v_div_fmas_f32 v138, v138, v187, v163
	v_div_fixup_f32 v192, v138, v190, 1.0
	v_fma_f32 v138, -v186, v189, 1.0
	v_fmac_f32_e32 v189, v138, v189
	v_div_scale_f32 v138, vcc, 1.0, v173, 1.0
	v_mul_f32_e32 v163, v138, v189
	v_fma_f32 v187, -v186, v163, v138
	v_fmac_f32_e32 v163, v187, v189
	v_fma_f32 v138, -v186, v163, v138
	v_div_scale_f32 v186, s[38:39], v172, v172, 1.0
	v_rcp_f32_e32 v187, v186
	v_div_fmas_f32 v138, v138, v189, v163
	v_div_fixup_f32 v191, v138, v173, 1.0
	v_fma_f32 v138, -v186, v187, 1.0
	v_fmac_f32_e32 v187, v138, v187
	v_div_scale_f32 v138, vcc, 1.0, v172, 1.0
	v_mul_f32_e32 v163, v138, v187
	v_fma_f32 v173, -v186, v163, v138
	v_fmac_f32_e32 v163, v173, v187
	v_fma_f32 v138, -v186, v163, v138
	v_div_fmas_f32 v138, v138, v187, v163
	v_div_fixup_f32 v190, v138, v172, 1.0
	v_mad_i64_i32 v[172:173], s[38:39], v162, s53, v[150:151]
	global_store_dwordx4 v[172:173], v[182:185], off
	global_store_dwordx4 v[172:173], v[190:193], off offset:16

.LBB0_650:
	s_andn2_b64 vcc, exec, s[8:9]
	s_cbranch_vccnz .LBB0_652
	v_mul_f32_e32 v172, s18, v134
	v_mul_f32_e32 v173, s18, v135
	v_mul_f32_e32 v182, s18, v132
	v_mul_f32_e32 v183, s18, v133
	v_lshlrev_b32_e32 v138, 1, v146
	v_cvt_pk_bf16_f32 v182, v182, v183
	v_cvt_pk_bf16_f32 v183, v172, v173
	v_lshl_add_u64 v[172:173], s[10:11], 0, v[170:171]
	v_lshl_add_u64 v[172:173], s[14:15], 1, v[172:173]
	v_mul_f32_e32 v184, s18, v128
	v_mul_f32_e32 v185, s18, v129
	v_lshl_add_u64 v[172:173], v[172:173], 0, v[138:139]
	v_mul_f32_e32 v186, s18, v130
	v_mul_f32_e32 v187, s18, v131
	v_cvt_pk_bf16_f32 v184, v184, v185
	s_nop 0
	v_cvt_pk_bf16_f32 v185, v186, v187
	global_store_dwordx4 v[172:173], v[182:185], off offset:-3072

.LBB0_655:
	v_mov_b32_e32 v130, v168
	v_mov_b32_e32 v131, v168
	v_mov_b32_e32 v132, v168
	v_mov_b32_e32 v133, v168
	v_mul_f32_e32 v128, v124, v130
	v_mul_f32_e32 v129, v125, v131
	v_mul_f32_e32 v124, v122, v132
	v_mul_f32_e32 v125, v123, v133
	v_cndmask_b32_e64 v122, 0, 1, s[42:43]
	v_mul_f32_e32 v126, v126, v132
	v_mul_f32_e32 v127, v127, v133
	v_cmp_ne_u32_e64 s[8:9], 1, v122
	s_andn2_b64 vcc, exec, s[42:43]
	v_mul_f32_e32 v130, v120, v130
	v_mul_f32_e32 v131, v121, v131
	s_cbranch_vccnz .LBB0_660
	s_mov_b64 s[42:43], 0
	s_and_b64 vcc, exec, s[36:37]
	s_mov_b64 s[44:45], 0
	s_cbranch_vccz .LBB0_658
	v_mul_f32_e32 v122, s18, v126
	v_mul_f32_e32 v123, s18, v127
	v_mul_f32_e32 v120, s18, v128
	v_mul_f32_e32 v121, s18, v129
	v_mul_f32_e32 v132, s18, v124
	v_mul_f32_e32 v133, s18, v125
	v_mul_f32_e32 v134, s18, v130
	v_mul_f32_e32 v135, s18, v131
	v_cvt_pk_bf16_f32 v120, v120, v121
	v_cvt_pk_bf16_f32 v121, v122, v123
	s_mov_b64 s[44:45], -1
	v_cvt_pk_bf16_f32 v122, v134, v135
	v_cvt_pk_bf16_f32 v123, v132, v133
	v_lshl_add_u64 v[132:133], s[10:11], 0, v[170:171]
	v_lshl_add_u64 v[132:133], s[14:15], 1, v[132:133]
	v_lshl_add_u64 v[132:133], v[132:133], 0, s[20:21]
	s_and_b64 vcc, exec, s[42:43]
	s_cbranch_vccz .LBB0_661
	s_branch .LBB0_659

.LBB0_663:
	s_nop 1
	v_or_b32_e32 v122, 16, v162
	v_ashrrev_i32_e32 v123, 31, v122
	v_mov_b32_e32 v124, v169
	v_lshlrev_b64 v[120:121], 11, v[122:123]
	v_mul_f32_e32 v118, v118, v124
	v_mul_f32_e32 v119, v119, v124
	v_mul_f32_e32 v116, v116, v124
	v_mul_f32_e32 v117, v117, v124
	v_mul_f32_e32 v114, v114, v124
	v_mul_f32_e32 v115, v115, v124
	v_mul_f32_e32 v112, v112, v124
	v_mul_f32_e32 v113, v113, v124
	s_and_b64 vcc, exec, s[8:9]
	s_mov_b64 s[42:43], -1
	s_cbranch_vccnz .LBB0_671
	s_andn2_b64 vcc, exec, s[40:41]
	s_cbranch_vccnz .LBB0_668
	s_and_saveexec_b64 s[42:43], s[4:5]
	s_cbranch_execz .LBB0_667
	v_mul_f32_e32 v125, 0xbfb8aa3b, v118
	v_exp_f32_e32 v126, v125
	v_mul_f32_e32 v125, 0xbfb8aa3b, v119
	v_exp_f32_e32 v127, v125
	v_mul_f32_e32 v123, 0xbfb8aa3b, v116
	v_exp_f32_e32 v124, v123
	v_mul_f32_e32 v123, 0xbfb8aa3b, v112
	v_exp_f32_e32 v128, v123
	v_mul_f32_e32 v123, 0xbfb8aa3b, v117
	v_exp_f32_e32 v125, v123
	v_mul_f32_e32 v123, 0xbfb8aa3b, v113
	v_add_f32_e32 v126, 1.0, v126
	v_add_f32_e32 v127, 1.0, v127
	v_exp_f32_e32 v129, v123
	v_div_scale_f32 v123, s[44:45], v127, v127, 1.0
	v_rcp_f32_e32 v131, v123
	v_add_f32_e32 v124, 1.0, v124
	v_add_f32_e32 v125, 1.0, v125
	v_mul_f32_e32 v130, 0xbfb8aa3b, v114
	v_exp_f32_e32 v130, v130
	v_fma_f32 v132, -v123, v131, 1.0
	v_fmac_f32_e32 v131, v132, v131
	v_div_scale_f32 v132, vcc, 1.0, v127, 1.0
	v_mul_f32_e32 v133, v132, v131
	v_fma_f32 v134, -v123, v133, v132
	v_fmac_f32_e32 v133, v134, v131
	v_fma_f32 v123, -v123, v133, v132
	v_div_scale_f32 v132, s[44:45], v126, v126, 1.0
	v_rcp_f32_e32 v134, v132
	v_div_fmas_f32 v123, v123, v131, v133
	v_div_fixup_f32 v127, v123, v127, 1.0
	v_add_f32_e32 v128, 1.0, v128
	v_add_f32_e32 v129, 1.0, v129
	v_fma_f32 v123, -v132, v134, 1.0
	v_fmac_f32_e32 v134, v123, v134
	v_div_scale_f32 v123, vcc, 1.0, v126, 1.0
	v_mul_f32_e32 v131, v123, v134
	v_fma_f32 v133, -v132, v131, v123
	v_fmac_f32_e32 v131, v133, v134
	v_fma_f32 v123, -v132, v131, v123
	v_div_scale_f32 v132, s[44:45], v125, v125, 1.0
	v_rcp_f32_e32 v133, v132
	v_div_fmas_f32 v123, v123, v134, v131
	v_div_fixup_f32 v126, v123, v126, 1.0
	v_fma_f32 v123, -v132, v133, 1.0
	v_fmac_f32_e32 v133, v123, v133
	v_div_scale_f32 v123, vcc, 1.0, v125, 1.0
	v_mul_f32_e32 v131, v123, v133
	v_fma_f32 v134, -v132, v131, v123
	v_fmac_f32_e32 v131, v134, v133
	v_fma_f32 v123, -v132, v131, v123
	v_div_scale_f32 v132, s[44:45], v124, v124, 1.0
	v_rcp_f32_e32 v134, v132
	v_div_fmas_f32 v123, v123, v133, v131
	v_mul_f32_e32 v131, 0xbfb8aa3b, v115
	v_div_fixup_f32 v125, v123, v125, 1.0
	v_fma_f32 v123, -v132, v134, 1.0
	v_exp_f32_e32 v131, v131
	v_fmac_f32_e32 v134, v123, v134
	v_div_scale_f32 v123, vcc, 1.0, v124, 1.0
	v_mul_f32_e32 v133, v123, v134
	v_fma_f32 v135, -v132, v133, v123
	v_fmac_f32_e32 v133, v135, v134
	v_add_f32_e32 v130, 1.0, v130
	v_add_f32_e32 v131, 1.0, v131
	v_fma_f32 v123, -v132, v133, v123
	v_div_scale_f32 v132, s[44:45], v131, v131, 1.0
	v_rcp_f32_e32 v135, v132
	v_div_fmas_f32 v123, v123, v134, v133
	v_div_fixup_f32 v124, v123, v124, 1.0
	v_fma_f32 v123, -v132, v135, 1.0
	v_fmac_f32_e32 v135, v123, v135
	v_div_scale_f32 v123, vcc, 1.0, v131, 1.0
	v_mul_f32_e32 v133, v123, v135
	v_fma_f32 v134, -v132, v133, v123
	v_fmac_f32_e32 v133, v134, v135
	v_fma_f32 v123, -v132, v133, v123
	v_div_scale_f32 v132, s[44:45], v130, v130, 1.0
	v_rcp_f32_e32 v134, v132
	v_div_fmas_f32 v123, v123, v135, v133
	v_div_fixup_f32 v131, v123, v131, 1.0
	v_fma_f32 v123, -v132, v134, 1.0
	v_fmac_f32_e32 v134, v123, v134
	v_div_scale_f32 v123, vcc, 1.0, v130, 1.0
	v_mul_f32_e32 v133, v123, v134
	v_fma_f32 v135, -v132, v133, v123
	v_fmac_f32_e32 v133, v135, v134
	v_fma_f32 v123, -v132, v133, v123
	v_div_scale_f32 v132, s[44:45], v129, v129, 1.0
	v_rcp_f32_e32 v135, v132
	v_div_fmas_f32 v123, v123, v134, v133
	v_div_fixup_f32 v130, v123, v130, 1.0
	v_fma_f32 v123, -v132, v135, 1.0
	v_fmac_f32_e32 v135, v123, v135
	v_div_scale_f32 v123, vcc, 1.0, v129, 1.0
	v_mul_f32_e32 v133, v123, v135
	v_fma_f32 v134, -v132, v133, v123
	v_fmac_f32_e32 v133, v134, v135
	v_fma_f32 v123, -v132, v133, v123
	v_div_scale_f32 v132, s[44:45], v128, v128, 1.0
	v_rcp_f32_e32 v134, v132
	v_div_fmas_f32 v123, v123, v135, v133
	v_div_fixup_f32 v129, v123, v129, 1.0
	v_fma_f32 v123, -v132, v134, 1.0
	v_fmac_f32_e32 v134, v123, v134
	v_div_scale_f32 v123, vcc, 1.0, v128, 1.0
	v_mul_f32_e32 v133, v123, v134
	v_fma_f32 v135, -v132, v133, v123
	v_fmac_f32_e32 v133, v135, v134
	v_fma_f32 v123, -v132, v133, v123
	v_div_fmas_f32 v123, v123, v134, v133
	v_mad_i64_i32 v[132:133], s[44:45], v122, s53, v[150:151]
	v_div_fixup_f32 v128, v123, v128, 1.0
	global_store_dwordx4 v[132:133], v[124:127], off
	global_store_dwordx4 v[132:133], v[128:131], off offset:16

.LBB0_668:
	s_andn2_b64 vcc, exec, s[42:43]
	s_cbranch_vccnz .LBB0_670
	v_mul_f32_e32 v126, s18, v118
	v_mul_f32_e32 v127, s18, v119
	v_mul_f32_e32 v124, s18, v116
	v_mul_f32_e32 v125, s18, v117
	v_mul_f32_e32 v128, s18, v114
	v_mul_f32_e32 v129, s18, v115
	v_mul_f32_e32 v130, s18, v112
	v_mul_f32_e32 v131, s18, v113
	v_cvt_pk_bf16_f32 v124, v124, v125
	v_cvt_pk_bf16_f32 v125, v126, v127
	v_lshlrev_b32_e32 v138, 1, v146
	v_cvt_pk_bf16_f32 v126, v130, v131
	v_cvt_pk_bf16_f32 v127, v128, v129
	v_lshl_add_u64 v[128:129], s[10:11], 0, v[120:121]
	v_lshl_add_u64 v[128:129], s[14:15], 1, v[128:129]
	v_lshl_add_u64 v[128:129], v[128:129], 0, v[138:139]
	global_store_dwordx4 v[128:129], v[124:127], off offset:-3072

.LBB0_673:
	v_mov_b32_e32 v168, v169
	v_mov_b32_e32 v114, v169
	v_mov_b32_e32 v115, v169
	v_mul_f32_e32 v110, v110, v114
	v_mul_f32_e32 v111, v111, v115
	v_mul_f32_e32 v112, v108, v168
	v_mul_f32_e32 v113, v109, v169
	v_mul_f32_e32 v108, v106, v114
	v_mul_f32_e32 v109, v107, v115
	s_and_b64 vcc, exec, s[8:9]
	v_mul_f32_e32 v114, v104, v168
	v_mul_f32_e32 v115, v105, v169
	s_cbranch_vccnz .LBB0_676
	s_mov_b64 s[42:43], 0
	s_and_b64 vcc, exec, s[36:37]
	s_mov_b64 s[44:45], 0
	s_cbranch_vccz .LBB0_677
	v_mul_f32_e32 v106, s18, v110
	v_mul_f32_e32 v107, s18, v111
	v_mul_f32_e32 v104, s18, v112
	v_mul_f32_e32 v105, s18, v113
	v_mul_f32_e32 v116, s18, v108
	v_mul_f32_e32 v117, s18, v109
	v_mul_f32_e32 v118, s18, v114
	v_mul_f32_e32 v119, s18, v115
	v_cvt_pk_bf16_f32 v104, v104, v105
	v_cvt_pk_bf16_f32 v105, v106, v107
	s_mov_b64 s[44:45], -1
	v_cvt_pk_bf16_f32 v106, v118, v119
	v_cvt_pk_bf16_f32 v107, v116, v117
	v_lshl_add_u64 v[116:117], s[10:11], 0, v[120:121]
	v_lshl_add_u64 v[116:117], s[14:15], 1, v[116:117]
	v_lshl_add_u64 v[116:117], v[116:117], 0, s[20:21]
	s_branch .LBB0_677

.LBB0_681:
	s_nop 1
	v_or_b32_e32 v106, 32, v162
	v_ashrrev_i32_e32 v107, 31, v106
	v_lshlrev_b64 v[104:105], 11, v[106:107]
	v_mul_f32_e32 v102, v102, v166
	v_mul_f32_e32 v103, v103, v166
	v_mul_f32_e32 v100, v100, v166
	v_mul_f32_e32 v101, v101, v166
	v_mul_f32_e32 v98, v98, v166
	v_mul_f32_e32 v99, v99, v166
	v_mul_f32_e32 v96, v96, v166
	v_mul_f32_e32 v97, v97, v166
	s_and_b64 vcc, exec, s[8:9]
	s_mov_b64 s[42:43], -1
	s_cbranch_vccnz .LBB0_689
	s_andn2_b64 vcc, exec, s[40:41]
	s_cbranch_vccnz .LBB0_686
	s_and_saveexec_b64 s[42:43], s[4:5]
	s_cbranch_execz .LBB0_685
	v_mul_f32_e32 v109, 0xbfb8aa3b, v102
	v_exp_f32_e32 v110, v109
	v_mul_f32_e32 v109, 0xbfb8aa3b, v103
	v_exp_f32_e32 v111, v109
	v_mul_f32_e32 v107, 0xbfb8aa3b, v100
	v_exp_f32_e32 v108, v107
	v_mul_f32_e32 v107, 0xbfb8aa3b, v96
	v_exp_f32_e32 v112, v107
	v_mul_f32_e32 v107, 0xbfb8aa3b, v101
	v_exp_f32_e32 v109, v107
	v_mul_f32_e32 v107, 0xbfb8aa3b, v97
	v_add_f32_e32 v110, 1.0, v110
	v_add_f32_e32 v111, 1.0, v111
	v_exp_f32_e32 v113, v107
	v_div_scale_f32 v107, s[44:45], v111, v111, 1.0
	v_rcp_f32_e32 v115, v107
	v_add_f32_e32 v108, 1.0, v108
	v_add_f32_e32 v109, 1.0, v109
	v_mul_f32_e32 v114, 0xbfb8aa3b, v98
	v_exp_f32_e32 v114, v114
	v_fma_f32 v116, -v107, v115, 1.0
	v_fmac_f32_e32 v115, v116, v115
	v_div_scale_f32 v116, vcc, 1.0, v111, 1.0
	v_mul_f32_e32 v117, v116, v115
	v_fma_f32 v118, -v107, v117, v116
	v_fmac_f32_e32 v117, v118, v115
	v_fma_f32 v107, -v107, v117, v116
	v_div_scale_f32 v116, s[44:45], v110, v110, 1.0
	v_rcp_f32_e32 v118, v116
	v_div_fmas_f32 v107, v107, v115, v117
	v_div_fixup_f32 v111, v107, v111, 1.0
	v_add_f32_e32 v112, 1.0, v112
	v_add_f32_e32 v113, 1.0, v113
	v_fma_f32 v107, -v116, v118, 1.0
	v_fmac_f32_e32 v118, v107, v118
	v_div_scale_f32 v107, vcc, 1.0, v110, 1.0
	v_mul_f32_e32 v115, v107, v118
	v_fma_f32 v117, -v116, v115, v107
	v_fmac_f32_e32 v115, v117, v118
	v_fma_f32 v107, -v116, v115, v107
	v_div_scale_f32 v116, s[44:45], v109, v109, 1.0
	v_rcp_f32_e32 v117, v116
	v_div_fmas_f32 v107, v107, v118, v115
	v_div_fixup_f32 v110, v107, v110, 1.0
	v_fma_f32 v107, -v116, v117, 1.0
	v_fmac_f32_e32 v117, v107, v117
	v_div_scale_f32 v107, vcc, 1.0, v109, 1.0
	v_mul_f32_e32 v115, v107, v117
	v_fma_f32 v118, -v116, v115, v107
	v_fmac_f32_e32 v115, v118, v117
	v_fma_f32 v107, -v116, v115, v107
	v_div_scale_f32 v116, s[44:45], v108, v108, 1.0
	v_rcp_f32_e32 v118, v116
	v_div_fmas_f32 v107, v107, v117, v115
	v_mul_f32_e32 v115, 0xbfb8aa3b, v99
	v_div_fixup_f32 v109, v107, v109, 1.0
	v_fma_f32 v107, -v116, v118, 1.0
	v_exp_f32_e32 v115, v115
	v_fmac_f32_e32 v118, v107, v118
	v_div_scale_f32 v107, vcc, 1.0, v108, 1.0
	v_mul_f32_e32 v117, v107, v118
	v_fma_f32 v119, -v116, v117, v107
	v_fmac_f32_e32 v117, v119, v118
	v_add_f32_e32 v114, 1.0, v114
	v_add_f32_e32 v115, 1.0, v115
	v_fma_f32 v107, -v116, v117, v107
	v_div_scale_f32 v116, s[44:45], v115, v115, 1.0
	v_rcp_f32_e32 v119, v116
	v_div_fmas_f32 v107, v107, v118, v117
	v_div_fixup_f32 v108, v107, v108, 1.0
	v_fma_f32 v107, -v116, v119, 1.0
	v_fmac_f32_e32 v119, v107, v119
	v_div_scale_f32 v107, vcc, 1.0, v115, 1.0
	v_mul_f32_e32 v117, v107, v119
	v_fma_f32 v118, -v116, v117, v107
	v_fmac_f32_e32 v117, v118, v119
	v_fma_f32 v107, -v116, v117, v107
	v_div_scale_f32 v116, s[44:45], v114, v114, 1.0
	v_rcp_f32_e32 v118, v116
	v_div_fmas_f32 v107, v107, v119, v117
	v_div_fixup_f32 v115, v107, v115, 1.0
	v_fma_f32 v107, -v116, v118, 1.0
	v_fmac_f32_e32 v118, v107, v118
	v_div_scale_f32 v107, vcc, 1.0, v114, 1.0
	v_mul_f32_e32 v117, v107, v118
	v_fma_f32 v119, -v116, v117, v107
	v_fmac_f32_e32 v117, v119, v118
	v_fma_f32 v107, -v116, v117, v107
	v_div_scale_f32 v116, s[44:45], v113, v113, 1.0
	v_rcp_f32_e32 v119, v116
	v_div_fmas_f32 v107, v107, v118, v117
	v_div_fixup_f32 v114, v107, v114, 1.0
	v_fma_f32 v107, -v116, v119, 1.0
	v_fmac_f32_e32 v119, v107, v119
	v_div_scale_f32 v107, vcc, 1.0, v113, 1.0
	v_mul_f32_e32 v117, v107, v119
	v_fma_f32 v118, -v116, v117, v107
	v_fmac_f32_e32 v117, v118, v119
	v_fma_f32 v107, -v116, v117, v107
	v_div_scale_f32 v116, s[44:45], v112, v112, 1.0
	v_rcp_f32_e32 v118, v116
	v_div_fmas_f32 v107, v107, v119, v117
	v_div_fixup_f32 v113, v107, v113, 1.0
	v_fma_f32 v107, -v116, v118, 1.0
	v_fmac_f32_e32 v118, v107, v118
	v_div_scale_f32 v107, vcc, 1.0, v112, 1.0
	v_mul_f32_e32 v117, v107, v118
	v_fma_f32 v119, -v116, v117, v107
	v_fmac_f32_e32 v117, v119, v118
	v_fma_f32 v107, -v116, v117, v107
	v_div_fmas_f32 v107, v107, v118, v117
	v_mad_i64_i32 v[116:117], s[44:45], v106, s53, v[150:151]
	v_div_fixup_f32 v112, v107, v112, 1.0
	global_store_dwordx4 v[116:117], v[108:111], off
	global_store_dwordx4 v[116:117], v[112:115], off offset:16

.LBB0_686:
	s_andn2_b64 vcc, exec, s[42:43]
	s_cbranch_vccnz .LBB0_688
	v_mul_f32_e32 v110, s18, v102
	v_mul_f32_e32 v111, s18, v103
	v_mul_f32_e32 v108, s18, v100
	v_mul_f32_e32 v109, s18, v101
	v_mul_f32_e32 v112, s18, v98
	v_mul_f32_e32 v113, s18, v99
	v_mul_f32_e32 v114, s18, v96
	v_mul_f32_e32 v115, s18, v97
	v_cvt_pk_bf16_f32 v108, v108, v109
	v_cvt_pk_bf16_f32 v109, v110, v111
	v_lshlrev_b32_e32 v138, 1, v146
	v_cvt_pk_bf16_f32 v110, v114, v115
	v_cvt_pk_bf16_f32 v111, v112, v113
	v_lshl_add_u64 v[112:113], s[10:11], 0, v[104:105]
	v_lshl_add_u64 v[112:113], s[14:15], 1, v[112:113]
	v_lshl_add_u64 v[112:113], v[112:113], 0, v[138:139]
	global_store_dwordx4 v[112:113], v[108:111], off offset:-3072

.LBB0_691:
	v_mov_b32_e32 v98, v166
	v_mov_b32_e32 v99, v166
	v_mov_b32_e32 v100, v166
	v_mov_b32_e32 v101, v166
	v_mul_f32_e32 v94, v94, v100
	v_mul_f32_e32 v95, v95, v101
	v_mul_f32_e32 v96, v92, v98
	v_mul_f32_e32 v97, v93, v99
	v_mul_f32_e32 v92, v90, v100
	v_mul_f32_e32 v93, v91, v101
	s_and_b64 vcc, exec, s[8:9]
	v_mul_f32_e32 v98, v88, v98
	v_mul_f32_e32 v99, v89, v99
	s_cbranch_vccnz .LBB0_694
	s_mov_b64 s[42:43], 0
	s_and_b64 vcc, exec, s[36:37]
	s_mov_b64 s[44:45], 0
	s_cbranch_vccz .LBB0_695
	v_mul_f32_e32 v90, s18, v94
	v_mul_f32_e32 v91, s18, v95
	v_mul_f32_e32 v88, s18, v96
	v_mul_f32_e32 v89, s18, v97
	v_mul_f32_e32 v100, s18, v92
	v_mul_f32_e32 v101, s18, v93
	v_mul_f32_e32 v102, s18, v98
	v_mul_f32_e32 v103, s18, v99
	v_cvt_pk_bf16_f32 v88, v88, v89
	v_cvt_pk_bf16_f32 v89, v90, v91
	s_mov_b64 s[44:45], -1
	v_cvt_pk_bf16_f32 v90, v102, v103
	v_cvt_pk_bf16_f32 v91, v100, v101
	v_lshl_add_u64 v[100:101], s[10:11], 0, v[104:105]
	v_lshl_add_u64 v[100:101], s[14:15], 1, v[100:101]
	v_lshl_add_u64 v[100:101], v[100:101], 0, s[20:21]
	s_branch .LBB0_695

.LBB0_699:
	s_nop 1
	v_or_b32_e32 v90, 48, v162
	v_ashrrev_i32_e32 v91, 31, v90
	v_mov_b32_e32 v92, v167
	v_lshlrev_b64 v[88:89], 11, v[90:91]
	v_mul_f32_e32 v86, v86, v92
	v_mul_f32_e32 v87, v87, v92
	v_mul_f32_e32 v84, v84, v92
	v_mul_f32_e32 v85, v85, v92
	v_mul_f32_e32 v82, v82, v92
	v_mul_f32_e32 v83, v83, v92
	v_mul_f32_e32 v80, v80, v92
	v_mul_f32_e32 v81, v81, v92
	s_and_b64 vcc, exec, s[8:9]
	s_mov_b64 s[42:43], -1
	s_cbranch_vccnz .LBB0_707
	s_andn2_b64 vcc, exec, s[40:41]
	s_cbranch_vccnz .LBB0_704
	s_and_saveexec_b64 s[42:43], s[4:5]
	s_cbranch_execz .LBB0_703
	v_mul_f32_e32 v93, 0xbfb8aa3b, v86
	v_exp_f32_e32 v94, v93
	v_mul_f32_e32 v93, 0xbfb8aa3b, v87
	v_exp_f32_e32 v95, v93
	v_mul_f32_e32 v91, 0xbfb8aa3b, v84
	v_exp_f32_e32 v92, v91
	v_mul_f32_e32 v91, 0xbfb8aa3b, v80
	v_exp_f32_e32 v96, v91
	v_mul_f32_e32 v91, 0xbfb8aa3b, v85
	v_exp_f32_e32 v93, v91
	v_mul_f32_e32 v91, 0xbfb8aa3b, v81
	v_add_f32_e32 v94, 1.0, v94
	v_add_f32_e32 v95, 1.0, v95
	v_exp_f32_e32 v97, v91
	v_div_scale_f32 v91, s[44:45], v95, v95, 1.0
	v_rcp_f32_e32 v99, v91
	v_add_f32_e32 v92, 1.0, v92
	v_add_f32_e32 v93, 1.0, v93
	v_mul_f32_e32 v98, 0xbfb8aa3b, v82
	v_exp_f32_e32 v98, v98
	v_fma_f32 v100, -v91, v99, 1.0
	v_fmac_f32_e32 v99, v100, v99
	v_div_scale_f32 v100, vcc, 1.0, v95, 1.0
	v_mul_f32_e32 v101, v100, v99
	v_fma_f32 v102, -v91, v101, v100
	v_fmac_f32_e32 v101, v102, v99
	v_fma_f32 v91, -v91, v101, v100
	v_div_scale_f32 v100, s[44:45], v94, v94, 1.0
	v_rcp_f32_e32 v102, v100
	v_div_fmas_f32 v91, v91, v99, v101
	v_div_fixup_f32 v95, v91, v95, 1.0
	v_add_f32_e32 v96, 1.0, v96
	v_add_f32_e32 v97, 1.0, v97
	v_fma_f32 v91, -v100, v102, 1.0
	v_fmac_f32_e32 v102, v91, v102
	v_div_scale_f32 v91, vcc, 1.0, v94, 1.0
	v_mul_f32_e32 v99, v91, v102
	v_fma_f32 v101, -v100, v99, v91
	v_fmac_f32_e32 v99, v101, v102
	v_fma_f32 v91, -v100, v99, v91
	v_div_scale_f32 v100, s[44:45], v93, v93, 1.0
	v_rcp_f32_e32 v101, v100
	v_div_fmas_f32 v91, v91, v102, v99
	v_div_fixup_f32 v94, v91, v94, 1.0
	v_fma_f32 v91, -v100, v101, 1.0
	v_fmac_f32_e32 v101, v91, v101
	v_div_scale_f32 v91, vcc, 1.0, v93, 1.0
	v_mul_f32_e32 v99, v91, v101
	v_fma_f32 v102, -v100, v99, v91
	v_fmac_f32_e32 v99, v102, v101
	v_fma_f32 v91, -v100, v99, v91
	v_div_scale_f32 v100, s[44:45], v92, v92, 1.0
	v_rcp_f32_e32 v102, v100
	v_div_fmas_f32 v91, v91, v101, v99
	v_mul_f32_e32 v99, 0xbfb8aa3b, v83
	v_div_fixup_f32 v93, v91, v93, 1.0
	v_fma_f32 v91, -v100, v102, 1.0
	v_exp_f32_e32 v99, v99
	v_fmac_f32_e32 v102, v91, v102
	v_div_scale_f32 v91, vcc, 1.0, v92, 1.0
	v_mul_f32_e32 v101, v91, v102
	v_fma_f32 v103, -v100, v101, v91
	v_fmac_f32_e32 v101, v103, v102
	v_add_f32_e32 v98, 1.0, v98
	v_add_f32_e32 v99, 1.0, v99
	v_fma_f32 v91, -v100, v101, v91
	v_div_scale_f32 v100, s[44:45], v99, v99, 1.0
	v_rcp_f32_e32 v103, v100
	v_div_fmas_f32 v91, v91, v102, v101
	v_div_fixup_f32 v92, v91, v92, 1.0
	v_fma_f32 v91, -v100, v103, 1.0
	v_fmac_f32_e32 v103, v91, v103
	v_div_scale_f32 v91, vcc, 1.0, v99, 1.0
	v_mul_f32_e32 v101, v91, v103
	v_fma_f32 v102, -v100, v101, v91
	v_fmac_f32_e32 v101, v102, v103
	v_fma_f32 v91, -v100, v101, v91
	v_div_scale_f32 v100, s[44:45], v98, v98, 1.0
	v_rcp_f32_e32 v102, v100
	v_div_fmas_f32 v91, v91, v103, v101
	v_div_fixup_f32 v99, v91, v99, 1.0
	v_fma_f32 v91, -v100, v102, 1.0
	v_fmac_f32_e32 v102, v91, v102
	v_div_scale_f32 v91, vcc, 1.0, v98, 1.0
	v_mul_f32_e32 v101, v91, v102
	v_fma_f32 v103, -v100, v101, v91
	v_fmac_f32_e32 v101, v103, v102
	v_fma_f32 v91, -v100, v101, v91
	v_div_scale_f32 v100, s[44:45], v97, v97, 1.0
	v_rcp_f32_e32 v103, v100
	v_div_fmas_f32 v91, v91, v102, v101
	v_div_fixup_f32 v98, v91, v98, 1.0
	v_fma_f32 v91, -v100, v103, 1.0
	v_fmac_f32_e32 v103, v91, v103
	v_div_scale_f32 v91, vcc, 1.0, v97, 1.0
	v_mul_f32_e32 v101, v91, v103
	v_fma_f32 v102, -v100, v101, v91
	v_fmac_f32_e32 v101, v102, v103
	v_fma_f32 v91, -v100, v101, v91
	v_div_scale_f32 v100, s[44:45], v96, v96, 1.0
	v_rcp_f32_e32 v102, v100
	v_div_fmas_f32 v91, v91, v103, v101
	v_div_fixup_f32 v97, v91, v97, 1.0
	v_fma_f32 v91, -v100, v102, 1.0
	v_fmac_f32_e32 v102, v91, v102
	v_div_scale_f32 v91, vcc, 1.0, v96, 1.0
	v_mul_f32_e32 v101, v91, v102
	v_fma_f32 v103, -v100, v101, v91
	v_fmac_f32_e32 v101, v103, v102
	v_fma_f32 v91, -v100, v101, v91
	v_div_fmas_f32 v91, v91, v102, v101
	v_mad_i64_i32 v[100:101], s[44:45], v90, s53, v[150:151]
	v_div_fixup_f32 v96, v91, v96, 1.0
	global_store_dwordx4 v[100:101], v[92:95], off
	global_store_dwordx4 v[100:101], v[96:99], off offset:16

.LBB0_704:
	s_andn2_b64 vcc, exec, s[42:43]
	s_cbranch_vccnz .LBB0_706
	v_mul_f32_e32 v94, s18, v86
	v_mul_f32_e32 v95, s18, v87
	v_mul_f32_e32 v92, s18, v84
	v_mul_f32_e32 v93, s18, v85
	v_mul_f32_e32 v96, s18, v82
	v_mul_f32_e32 v97, s18, v83
	v_mul_f32_e32 v98, s18, v80
	v_mul_f32_e32 v99, s18, v81
	v_cvt_pk_bf16_f32 v92, v92, v93
	v_cvt_pk_bf16_f32 v93, v94, v95
	v_lshlrev_b32_e32 v138, 1, v146
	v_cvt_pk_bf16_f32 v94, v98, v99
	v_cvt_pk_bf16_f32 v95, v96, v97
	v_lshl_add_u64 v[96:97], s[10:11], 0, v[88:89]
	v_lshl_add_u64 v[96:97], s[14:15], 1, v[96:97]
	v_lshl_add_u64 v[96:97], v[96:97], 0, v[138:139]
	global_store_dwordx4 v[96:97], v[92:95], off offset:-3072

.LBB0_709:
	v_mov_b32_e32 v166, v167
	v_mov_b32_e32 v82, v167
	v_mov_b32_e32 v83, v167
	v_mul_f32_e32 v78, v78, v82
	v_mul_f32_e32 v79, v79, v83
	v_mul_f32_e32 v80, v76, v166
	v_mul_f32_e32 v81, v77, v167
	v_mul_f32_e32 v76, v74, v82
	v_mul_f32_e32 v77, v75, v83
	s_and_b64 vcc, exec, s[8:9]
	v_mul_f32_e32 v82, v72, v166
	v_mul_f32_e32 v83, v73, v167
	s_cbranch_vccnz .LBB0_712
	s_mov_b64 s[42:43], 0
	s_and_b64 vcc, exec, s[36:37]
	s_mov_b64 s[44:45], 0
	s_cbranch_vccz .LBB0_713
	v_mul_f32_e32 v74, s18, v78
	v_mul_f32_e32 v75, s18, v79
	v_mul_f32_e32 v72, s18, v80
	v_mul_f32_e32 v73, s18, v81
	v_mul_f32_e32 v84, s18, v76
	v_mul_f32_e32 v85, s18, v77
	v_mul_f32_e32 v86, s18, v82
	v_mul_f32_e32 v87, s18, v83
	v_cvt_pk_bf16_f32 v72, v72, v73
	v_cvt_pk_bf16_f32 v73, v74, v75
	s_mov_b64 s[44:45], -1
	v_cvt_pk_bf16_f32 v74, v86, v87
	v_cvt_pk_bf16_f32 v75, v84, v85
	v_lshl_add_u64 v[84:85], s[10:11], 0, v[88:89]
	v_lshl_add_u64 v[84:85], s[14:15], 1, v[84:85]
	v_lshl_add_u64 v[84:85], v[84:85], 0, s[20:21]
	s_branch .LBB0_713

.LBB0_717:
	s_nop 1
	v_add_u32_e32 v74, 0x80, v162
	v_ashrrev_i32_e32 v75, 31, v74
	v_lshlrev_b64 v[72:73], 11, v[74:75]
	v_mul_f32_e32 v70, v70, v164
	v_mul_f32_e32 v71, v71, v164
	v_mul_f32_e32 v68, v68, v164
	v_mul_f32_e32 v69, v69, v164
	v_mul_f32_e32 v66, v66, v164
	v_mul_f32_e32 v67, v67, v164
	v_mul_f32_e32 v64, v64, v164
	v_mul_f32_e32 v65, v65, v164
	s_and_b64 vcc, exec, s[8:9]
	s_mov_b64 s[42:43], -1
	s_cbranch_vccnz .LBB0_725
	s_andn2_b64 vcc, exec, s[40:41]
	s_cbranch_vccnz .LBB0_722
	s_and_saveexec_b64 s[42:43], s[4:5]
	s_cbranch_execz .LBB0_721
	v_mul_f32_e32 v77, 0xbfb8aa3b, v70
	v_exp_f32_e32 v78, v77
	v_mul_f32_e32 v77, 0xbfb8aa3b, v71
	v_exp_f32_e32 v79, v77
	v_mul_f32_e32 v75, 0xbfb8aa3b, v68
	v_exp_f32_e32 v76, v75
	v_mul_f32_e32 v75, 0xbfb8aa3b, v64
	v_exp_f32_e32 v80, v75
	v_mul_f32_e32 v75, 0xbfb8aa3b, v69
	v_exp_f32_e32 v77, v75
	v_mul_f32_e32 v75, 0xbfb8aa3b, v65
	v_add_f32_e32 v78, 1.0, v78
	v_add_f32_e32 v79, 1.0, v79
	v_exp_f32_e32 v81, v75
	v_div_scale_f32 v75, s[44:45], v79, v79, 1.0
	v_rcp_f32_e32 v83, v75
	v_add_f32_e32 v76, 1.0, v76
	v_add_f32_e32 v77, 1.0, v77
	v_mul_f32_e32 v82, 0xbfb8aa3b, v66
	v_exp_f32_e32 v82, v82
	v_fma_f32 v84, -v75, v83, 1.0
	v_fmac_f32_e32 v83, v84, v83
	v_div_scale_f32 v84, vcc, 1.0, v79, 1.0
	v_mul_f32_e32 v85, v84, v83
	v_fma_f32 v86, -v75, v85, v84
	v_fmac_f32_e32 v85, v86, v83
	v_fma_f32 v75, -v75, v85, v84
	v_div_scale_f32 v84, s[44:45], v78, v78, 1.0
	v_rcp_f32_e32 v86, v84
	v_div_fmas_f32 v75, v75, v83, v85
	v_div_fixup_f32 v79, v75, v79, 1.0
	v_add_f32_e32 v80, 1.0, v80
	v_add_f32_e32 v81, 1.0, v81
	v_fma_f32 v75, -v84, v86, 1.0
	v_fmac_f32_e32 v86, v75, v86
	v_div_scale_f32 v75, vcc, 1.0, v78, 1.0
	v_mul_f32_e32 v83, v75, v86
	v_fma_f32 v85, -v84, v83, v75
	v_fmac_f32_e32 v83, v85, v86
	v_fma_f32 v75, -v84, v83, v75
	v_div_scale_f32 v84, s[44:45], v77, v77, 1.0
	v_rcp_f32_e32 v85, v84
	v_div_fmas_f32 v75, v75, v86, v83
	v_div_fixup_f32 v78, v75, v78, 1.0
	v_fma_f32 v75, -v84, v85, 1.0
	v_fmac_f32_e32 v85, v75, v85
	v_div_scale_f32 v75, vcc, 1.0, v77, 1.0
	v_mul_f32_e32 v83, v75, v85
	v_fma_f32 v86, -v84, v83, v75
	v_fmac_f32_e32 v83, v86, v85
	v_fma_f32 v75, -v84, v83, v75
	v_div_scale_f32 v84, s[44:45], v76, v76, 1.0
	v_rcp_f32_e32 v86, v84
	v_div_fmas_f32 v75, v75, v85, v83
	v_mul_f32_e32 v83, 0xbfb8aa3b, v67
	v_div_fixup_f32 v77, v75, v77, 1.0
	v_fma_f32 v75, -v84, v86, 1.0
	v_exp_f32_e32 v83, v83
	v_fmac_f32_e32 v86, v75, v86
	v_div_scale_f32 v75, vcc, 1.0, v76, 1.0
	v_mul_f32_e32 v85, v75, v86
	v_fma_f32 v87, -v84, v85, v75
	v_fmac_f32_e32 v85, v87, v86
	v_add_f32_e32 v82, 1.0, v82
	v_add_f32_e32 v83, 1.0, v83
	v_fma_f32 v75, -v84, v85, v75
	v_div_scale_f32 v84, s[44:45], v83, v83, 1.0
	v_rcp_f32_e32 v87, v84
	v_div_fmas_f32 v75, v75, v86, v85
	v_div_fixup_f32 v76, v75, v76, 1.0
	v_fma_f32 v75, -v84, v87, 1.0
	v_fmac_f32_e32 v87, v75, v87
	v_div_scale_f32 v75, vcc, 1.0, v83, 1.0
	v_mul_f32_e32 v85, v75, v87
	v_fma_f32 v86, -v84, v85, v75
	v_fmac_f32_e32 v85, v86, v87
	v_fma_f32 v75, -v84, v85, v75
	v_div_scale_f32 v84, s[44:45], v82, v82, 1.0
	v_rcp_f32_e32 v86, v84
	v_div_fmas_f32 v75, v75, v87, v85
	v_div_fixup_f32 v83, v75, v83, 1.0
	v_fma_f32 v75, -v84, v86, 1.0
	v_fmac_f32_e32 v86, v75, v86
	v_div_scale_f32 v75, vcc, 1.0, v82, 1.0
	v_mul_f32_e32 v85, v75, v86
	v_fma_f32 v87, -v84, v85, v75
	v_fmac_f32_e32 v85, v87, v86
	v_fma_f32 v75, -v84, v85, v75
	v_div_scale_f32 v84, s[44:45], v81, v81, 1.0
	v_rcp_f32_e32 v87, v84
	v_div_fmas_f32 v75, v75, v86, v85
	v_div_fixup_f32 v82, v75, v82, 1.0
	v_fma_f32 v75, -v84, v87, 1.0
	v_fmac_f32_e32 v87, v75, v87
	v_div_scale_f32 v75, vcc, 1.0, v81, 1.0
	v_mul_f32_e32 v85, v75, v87
	v_fma_f32 v86, -v84, v85, v75
	v_fmac_f32_e32 v85, v86, v87
	v_fma_f32 v75, -v84, v85, v75
	v_div_scale_f32 v84, s[44:45], v80, v80, 1.0
	v_rcp_f32_e32 v86, v84
	v_div_fmas_f32 v75, v75, v87, v85
	v_div_fixup_f32 v81, v75, v81, 1.0
	v_fma_f32 v75, -v84, v86, 1.0
	v_fmac_f32_e32 v86, v75, v86
	v_div_scale_f32 v75, vcc, 1.0, v80, 1.0
	v_mul_f32_e32 v85, v75, v86
	v_fma_f32 v87, -v84, v85, v75
	v_fmac_f32_e32 v85, v87, v86
	v_fma_f32 v75, -v84, v85, v75
	v_div_fmas_f32 v75, v75, v86, v85
	v_mad_i64_i32 v[84:85], s[44:45], v74, s53, v[150:151]
	v_div_fixup_f32 v80, v75, v80, 1.0
	global_store_dwordx4 v[84:85], v[76:79], off
	global_store_dwordx4 v[84:85], v[80:83], off offset:16

.LBB0_722:
	s_andn2_b64 vcc, exec, s[42:43]
	s_cbranch_vccnz .LBB0_724
	v_mul_f32_e32 v78, s18, v70
	v_mul_f32_e32 v79, s18, v71
	v_mul_f32_e32 v76, s18, v68
	v_mul_f32_e32 v77, s18, v69
	v_mul_f32_e32 v80, s18, v66
	v_mul_f32_e32 v81, s18, v67
	v_mul_f32_e32 v82, s18, v64
	v_mul_f32_e32 v83, s18, v65
	v_cvt_pk_bf16_f32 v76, v76, v77
	v_cvt_pk_bf16_f32 v77, v78, v79
	v_lshlrev_b32_e32 v138, 1, v146
	v_cvt_pk_bf16_f32 v78, v82, v83
	v_cvt_pk_bf16_f32 v79, v80, v81
	v_lshl_add_u64 v[80:81], s[10:11], 0, v[72:73]
	v_lshl_add_u64 v[80:81], s[14:15], 1, v[80:81]
	v_lshl_add_u64 v[80:81], v[80:81], 0, v[138:139]
	global_store_dwordx4 v[80:81], v[76:79], off offset:-3072

.LBB0_727:
	v_mov_b32_e32 v66, v164
	v_mov_b32_e32 v67, v164
	v_mov_b32_e32 v68, v164
	v_mov_b32_e32 v69, v164
	v_mul_f32_e32 v62, v62, v68
	v_mul_f32_e32 v63, v63, v69
	v_mul_f32_e32 v64, v60, v66
	v_mul_f32_e32 v65, v61, v67
	v_mul_f32_e32 v60, v58, v68
	v_mul_f32_e32 v61, v59, v69
	s_and_b64 vcc, exec, s[8:9]
	v_mul_f32_e32 v66, v56, v66
	v_mul_f32_e32 v67, v57, v67
	s_cbranch_vccnz .LBB0_730
	s_mov_b64 s[42:43], 0
	s_and_b64 vcc, exec, s[36:37]
	s_mov_b64 s[44:45], 0
	s_cbranch_vccz .LBB0_731
	v_mul_f32_e32 v58, s18, v62
	v_mul_f32_e32 v59, s18, v63
	v_mul_f32_e32 v56, s18, v64
	v_mul_f32_e32 v57, s18, v65
	v_mul_f32_e32 v68, s18, v60
	v_mul_f32_e32 v69, s18, v61
	v_mul_f32_e32 v70, s18, v66
	v_mul_f32_e32 v71, s18, v67
	v_cvt_pk_bf16_f32 v56, v56, v57
	v_cvt_pk_bf16_f32 v57, v58, v59
	s_mov_b64 s[44:45], -1
	v_cvt_pk_bf16_f32 v58, v70, v71
	v_cvt_pk_bf16_f32 v59, v68, v69
	v_lshl_add_u64 v[68:69], s[10:11], 0, v[72:73]
	v_lshl_add_u64 v[68:69], s[14:15], 1, v[68:69]
	v_lshl_add_u64 v[68:69], v[68:69], 0, s[20:21]
	s_branch .LBB0_731

.LBB0_735:
	s_nop 1
	v_add_u32_e32 v58, 0x90, v162
	v_ashrrev_i32_e32 v59, 31, v58
	v_mov_b32_e32 v60, v165
	v_lshlrev_b64 v[56:57], 11, v[58:59]
	v_mul_f32_e32 v54, v54, v60
	v_mul_f32_e32 v55, v55, v60
	v_mul_f32_e32 v52, v52, v60
	v_mul_f32_e32 v53, v53, v60
	v_mul_f32_e32 v50, v50, v60
	v_mul_f32_e32 v51, v51, v60
	v_mul_f32_e32 v48, v48, v60
	v_mul_f32_e32 v49, v49, v60
	s_and_b64 vcc, exec, s[8:9]
	s_mov_b64 s[42:43], -1
	s_cbranch_vccnz .LBB0_743
	s_andn2_b64 vcc, exec, s[40:41]
	s_cbranch_vccnz .LBB0_740
	s_and_saveexec_b64 s[42:43], s[4:5]
	s_cbranch_execz .LBB0_739
	v_mul_f32_e32 v61, 0xbfb8aa3b, v54
	v_exp_f32_e32 v62, v61
	v_mul_f32_e32 v61, 0xbfb8aa3b, v55
	v_exp_f32_e32 v63, v61
	v_mul_f32_e32 v59, 0xbfb8aa3b, v52
	v_exp_f32_e32 v60, v59
	v_mul_f32_e32 v59, 0xbfb8aa3b, v48
	v_exp_f32_e32 v64, v59
	v_mul_f32_e32 v59, 0xbfb8aa3b, v53
	v_exp_f32_e32 v61, v59
	v_mul_f32_e32 v59, 0xbfb8aa3b, v49
	v_add_f32_e32 v62, 1.0, v62
	v_add_f32_e32 v63, 1.0, v63
	v_exp_f32_e32 v65, v59
	v_div_scale_f32 v59, s[44:45], v63, v63, 1.0
	v_rcp_f32_e32 v67, v59
	v_add_f32_e32 v60, 1.0, v60
	v_add_f32_e32 v61, 1.0, v61
	v_mul_f32_e32 v66, 0xbfb8aa3b, v50
	v_exp_f32_e32 v66, v66
	v_fma_f32 v68, -v59, v67, 1.0
	v_fmac_f32_e32 v67, v68, v67
	v_div_scale_f32 v68, vcc, 1.0, v63, 1.0
	v_mul_f32_e32 v69, v68, v67
	v_fma_f32 v70, -v59, v69, v68
	v_fmac_f32_e32 v69, v70, v67
	v_fma_f32 v59, -v59, v69, v68
	v_div_scale_f32 v68, s[44:45], v62, v62, 1.0
	v_rcp_f32_e32 v70, v68
	v_div_fmas_f32 v59, v59, v67, v69
	v_div_fixup_f32 v63, v59, v63, 1.0
	v_add_f32_e32 v64, 1.0, v64
	v_add_f32_e32 v65, 1.0, v65
	v_fma_f32 v59, -v68, v70, 1.0
	v_fmac_f32_e32 v70, v59, v70
	v_div_scale_f32 v59, vcc, 1.0, v62, 1.0
	v_mul_f32_e32 v67, v59, v70
	v_fma_f32 v69, -v68, v67, v59
	v_fmac_f32_e32 v67, v69, v70
	v_fma_f32 v59, -v68, v67, v59
	v_div_scale_f32 v68, s[44:45], v61, v61, 1.0
	v_rcp_f32_e32 v69, v68
	v_div_fmas_f32 v59, v59, v70, v67
	v_div_fixup_f32 v62, v59, v62, 1.0
	v_fma_f32 v59, -v68, v69, 1.0
	v_fmac_f32_e32 v69, v59, v69
	v_div_scale_f32 v59, vcc, 1.0, v61, 1.0
	v_mul_f32_e32 v67, v59, v69
	v_fma_f32 v70, -v68, v67, v59
	v_fmac_f32_e32 v67, v70, v69
	v_fma_f32 v59, -v68, v67, v59
	v_div_scale_f32 v68, s[44:45], v60, v60, 1.0
	v_rcp_f32_e32 v70, v68
	v_div_fmas_f32 v59, v59, v69, v67
	v_mul_f32_e32 v67, 0xbfb8aa3b, v51
	v_div_fixup_f32 v61, v59, v61, 1.0
	v_fma_f32 v59, -v68, v70, 1.0
	v_exp_f32_e32 v67, v67
	v_fmac_f32_e32 v70, v59, v70
	v_div_scale_f32 v59, vcc, 1.0, v60, 1.0
	v_mul_f32_e32 v69, v59, v70
	v_fma_f32 v71, -v68, v69, v59
	v_fmac_f32_e32 v69, v71, v70
	v_add_f32_e32 v66, 1.0, v66
	v_add_f32_e32 v67, 1.0, v67
	v_fma_f32 v59, -v68, v69, v59
	v_div_scale_f32 v68, s[44:45], v67, v67, 1.0
	v_rcp_f32_e32 v71, v68
	v_div_fmas_f32 v59, v59, v70, v69
	v_div_fixup_f32 v60, v59, v60, 1.0
	v_fma_f32 v59, -v68, v71, 1.0
	v_fmac_f32_e32 v71, v59, v71
	v_div_scale_f32 v59, vcc, 1.0, v67, 1.0
	v_mul_f32_e32 v69, v59, v71
	v_fma_f32 v70, -v68, v69, v59
	v_fmac_f32_e32 v69, v70, v71
	v_fma_f32 v59, -v68, v69, v59
	v_div_scale_f32 v68, s[44:45], v66, v66, 1.0
	v_rcp_f32_e32 v70, v68
	v_div_fmas_f32 v59, v59, v71, v69
	v_div_fixup_f32 v67, v59, v67, 1.0
	v_fma_f32 v59, -v68, v70, 1.0
	v_fmac_f32_e32 v70, v59, v70
	v_div_scale_f32 v59, vcc, 1.0, v66, 1.0
	v_mul_f32_e32 v69, v59, v70
	v_fma_f32 v71, -v68, v69, v59
	v_fmac_f32_e32 v69, v71, v70
	v_fma_f32 v59, -v68, v69, v59
	v_div_scale_f32 v68, s[44:45], v65, v65, 1.0
	v_rcp_f32_e32 v71, v68
	v_div_fmas_f32 v59, v59, v70, v69
	v_div_fixup_f32 v66, v59, v66, 1.0
	v_fma_f32 v59, -v68, v71, 1.0
	v_fmac_f32_e32 v71, v59, v71
	v_div_scale_f32 v59, vcc, 1.0, v65, 1.0
	v_mul_f32_e32 v69, v59, v71
	v_fma_f32 v70, -v68, v69, v59
	v_fmac_f32_e32 v69, v70, v71
	v_fma_f32 v59, -v68, v69, v59
	v_div_scale_f32 v68, s[44:45], v64, v64, 1.0
	v_rcp_f32_e32 v70, v68
	v_div_fmas_f32 v59, v59, v71, v69
	v_div_fixup_f32 v65, v59, v65, 1.0
	v_fma_f32 v59, -v68, v70, 1.0
	v_fmac_f32_e32 v70, v59, v70
	v_div_scale_f32 v59, vcc, 1.0, v64, 1.0
	v_mul_f32_e32 v69, v59, v70
	v_fma_f32 v71, -v68, v69, v59
	v_fmac_f32_e32 v69, v71, v70
	v_fma_f32 v59, -v68, v69, v59
	v_div_fmas_f32 v59, v59, v70, v69
	v_mad_i64_i32 v[68:69], s[44:45], v58, s53, v[150:151]
	v_div_fixup_f32 v64, v59, v64, 1.0
	global_store_dwordx4 v[68:69], v[60:63], off
	global_store_dwordx4 v[68:69], v[64:67], off offset:16

.LBB0_740:
	s_andn2_b64 vcc, exec, s[42:43]
	s_cbranch_vccnz .LBB0_742
	v_mul_f32_e32 v62, s18, v54
	v_mul_f32_e32 v63, s18, v55
	v_mul_f32_e32 v60, s18, v52
	v_mul_f32_e32 v61, s18, v53
	v_mul_f32_e32 v64, s18, v50
	v_mul_f32_e32 v65, s18, v51
	v_mul_f32_e32 v66, s18, v48
	v_mul_f32_e32 v67, s18, v49
	v_cvt_pk_bf16_f32 v60, v60, v61
	v_cvt_pk_bf16_f32 v61, v62, v63
	v_lshlrev_b32_e32 v138, 1, v146
	v_cvt_pk_bf16_f32 v62, v66, v67
	v_cvt_pk_bf16_f32 v63, v64, v65
	v_lshl_add_u64 v[64:65], s[10:11], 0, v[56:57]
	v_lshl_add_u64 v[64:65], s[14:15], 1, v[64:65]
	v_lshl_add_u64 v[64:65], v[64:65], 0, v[138:139]
	global_store_dwordx4 v[64:65], v[60:63], off offset:-3072

.LBB0_745:
	v_mov_b32_e32 v164, v165
	v_mov_b32_e32 v50, v165
	v_mov_b32_e32 v51, v165
	v_mul_f32_e32 v46, v46, v50
	v_mul_f32_e32 v47, v47, v51
	v_mul_f32_e32 v48, v44, v164
	v_mul_f32_e32 v49, v45, v165
	v_mul_f32_e32 v44, v42, v50
	v_mul_f32_e32 v45, v43, v51
	s_and_b64 vcc, exec, s[8:9]
	v_mul_f32_e32 v50, v40, v164
	v_mul_f32_e32 v51, v41, v165
	s_cbranch_vccnz .LBB0_748
	s_mov_b64 s[42:43], 0
	s_and_b64 vcc, exec, s[36:37]
	s_mov_b64 s[44:45], 0
	s_cbranch_vccz .LBB0_749
	v_mul_f32_e32 v42, s18, v46
	v_mul_f32_e32 v43, s18, v47
	v_mul_f32_e32 v40, s18, v48
	v_mul_f32_e32 v41, s18, v49
	v_mul_f32_e32 v52, s18, v44
	v_mul_f32_e32 v53, s18, v45
	v_mul_f32_e32 v54, s18, v50
	v_mul_f32_e32 v55, s18, v51
	v_cvt_pk_bf16_f32 v40, v40, v41
	v_cvt_pk_bf16_f32 v41, v42, v43
	s_mov_b64 s[44:45], -1
	v_cvt_pk_bf16_f32 v42, v54, v55
	v_cvt_pk_bf16_f32 v43, v52, v53
	v_lshl_add_u64 v[52:53], s[10:11], 0, v[56:57]
	v_lshl_add_u64 v[52:53], s[14:15], 1, v[52:53]
	v_lshl_add_u64 v[52:53], v[52:53], 0, s[20:21]
	s_branch .LBB0_749

.LBB0_753:
	s_nop 1
	v_add_u32_e32 v42, 0xa0, v162
	v_ashrrev_i32_e32 v43, 31, v42
	v_lshlrev_b64 v[40:41], 11, v[42:43]
	v_mul_f32_e32 v38, v38, v160
	v_mul_f32_e32 v39, v39, v160
	v_mul_f32_e32 v36, v36, v160
	v_mul_f32_e32 v37, v37, v160
	v_mul_f32_e32 v34, v34, v160
	v_mul_f32_e32 v35, v35, v160
	v_mul_f32_e32 v32, v32, v160
	v_mul_f32_e32 v33, v33, v160
	s_and_b64 vcc, exec, s[8:9]
	s_mov_b64 s[42:43], -1
	s_cbranch_vccnz .LBB0_761
	s_andn2_b64 vcc, exec, s[40:41]
	s_cbranch_vccnz .LBB0_758
	s_and_saveexec_b64 s[42:43], s[4:5]
	s_cbranch_execz .LBB0_757
	v_mul_f32_e32 v45, 0xbfb8aa3b, v38
	v_exp_f32_e32 v46, v45
	v_mul_f32_e32 v45, 0xbfb8aa3b, v39
	v_exp_f32_e32 v47, v45
	v_mul_f32_e32 v43, 0xbfb8aa3b, v36
	v_exp_f32_e32 v44, v43
	v_mul_f32_e32 v43, 0xbfb8aa3b, v32
	v_exp_f32_e32 v48, v43
	v_mul_f32_e32 v43, 0xbfb8aa3b, v37
	v_exp_f32_e32 v45, v43
	v_mul_f32_e32 v43, 0xbfb8aa3b, v33
	v_add_f32_e32 v46, 1.0, v46
	v_add_f32_e32 v47, 1.0, v47
	v_exp_f32_e32 v49, v43
	v_div_scale_f32 v43, s[44:45], v47, v47, 1.0
	v_rcp_f32_e32 v51, v43
	v_add_f32_e32 v44, 1.0, v44
	v_add_f32_e32 v45, 1.0, v45
	v_mul_f32_e32 v50, 0xbfb8aa3b, v34
	v_exp_f32_e32 v50, v50
	v_fma_f32 v52, -v43, v51, 1.0
	v_fmac_f32_e32 v51, v52, v51
	v_div_scale_f32 v52, vcc, 1.0, v47, 1.0
	v_mul_f32_e32 v53, v52, v51
	v_fma_f32 v54, -v43, v53, v52
	v_fmac_f32_e32 v53, v54, v51
	v_fma_f32 v43, -v43, v53, v52
	v_div_scale_f32 v52, s[44:45], v46, v46, 1.0
	v_rcp_f32_e32 v54, v52
	v_div_fmas_f32 v43, v43, v51, v53
	v_div_fixup_f32 v47, v43, v47, 1.0
	v_add_f32_e32 v48, 1.0, v48
	v_add_f32_e32 v49, 1.0, v49
	v_fma_f32 v43, -v52, v54, 1.0
	v_fmac_f32_e32 v54, v43, v54
	v_div_scale_f32 v43, vcc, 1.0, v46, 1.0
	v_mul_f32_e32 v51, v43, v54
	v_fma_f32 v53, -v52, v51, v43
	v_fmac_f32_e32 v51, v53, v54
	v_fma_f32 v43, -v52, v51, v43
	v_div_scale_f32 v52, s[44:45], v45, v45, 1.0
	v_rcp_f32_e32 v53, v52
	v_div_fmas_f32 v43, v43, v54, v51
	v_div_fixup_f32 v46, v43, v46, 1.0
	v_fma_f32 v43, -v52, v53, 1.0
	v_fmac_f32_e32 v53, v43, v53
	v_div_scale_f32 v43, vcc, 1.0, v45, 1.0
	v_mul_f32_e32 v51, v43, v53
	v_fma_f32 v54, -v52, v51, v43
	v_fmac_f32_e32 v51, v54, v53
	v_fma_f32 v43, -v52, v51, v43
	v_div_scale_f32 v52, s[44:45], v44, v44, 1.0
	v_rcp_f32_e32 v54, v52
	v_div_fmas_f32 v43, v43, v53, v51
	v_mul_f32_e32 v51, 0xbfb8aa3b, v35
	v_div_fixup_f32 v45, v43, v45, 1.0
	v_fma_f32 v43, -v52, v54, 1.0
	v_exp_f32_e32 v51, v51
	v_fmac_f32_e32 v54, v43, v54
	v_div_scale_f32 v43, vcc, 1.0, v44, 1.0
	v_mul_f32_e32 v53, v43, v54
	v_fma_f32 v55, -v52, v53, v43
	v_fmac_f32_e32 v53, v55, v54
	v_add_f32_e32 v50, 1.0, v50
	v_add_f32_e32 v51, 1.0, v51
	v_fma_f32 v43, -v52, v53, v43
	v_div_scale_f32 v52, s[44:45], v51, v51, 1.0
	v_rcp_f32_e32 v55, v52
	v_div_fmas_f32 v43, v43, v54, v53
	v_div_fixup_f32 v44, v43, v44, 1.0
	v_fma_f32 v43, -v52, v55, 1.0
	v_fmac_f32_e32 v55, v43, v55
	v_div_scale_f32 v43, vcc, 1.0, v51, 1.0
	v_mul_f32_e32 v53, v43, v55
	v_fma_f32 v54, -v52, v53, v43
	v_fmac_f32_e32 v53, v54, v55
	v_fma_f32 v43, -v52, v53, v43
	v_div_scale_f32 v52, s[44:45], v50, v50, 1.0
	v_rcp_f32_e32 v54, v52
	v_div_fmas_f32 v43, v43, v55, v53
	v_div_fixup_f32 v51, v43, v51, 1.0
	v_fma_f32 v43, -v52, v54, 1.0
	v_fmac_f32_e32 v54, v43, v54
	v_div_scale_f32 v43, vcc, 1.0, v50, 1.0
	v_mul_f32_e32 v53, v43, v54
	v_fma_f32 v55, -v52, v53, v43
	v_fmac_f32_e32 v53, v55, v54
	v_fma_f32 v43, -v52, v53, v43
	v_div_scale_f32 v52, s[44:45], v49, v49, 1.0
	v_rcp_f32_e32 v55, v52
	v_div_fmas_f32 v43, v43, v54, v53
	v_div_fixup_f32 v50, v43, v50, 1.0
	v_fma_f32 v43, -v52, v55, 1.0
	v_fmac_f32_e32 v55, v43, v55
	v_div_scale_f32 v43, vcc, 1.0, v49, 1.0
	v_mul_f32_e32 v53, v43, v55
	v_fma_f32 v54, -v52, v53, v43
	v_fmac_f32_e32 v53, v54, v55
	v_fma_f32 v43, -v52, v53, v43
	v_div_scale_f32 v52, s[44:45], v48, v48, 1.0
	v_rcp_f32_e32 v54, v52
	v_div_fmas_f32 v43, v43, v55, v53
	v_div_fixup_f32 v49, v43, v49, 1.0
	v_fma_f32 v43, -v52, v54, 1.0
	v_fmac_f32_e32 v54, v43, v54
	v_div_scale_f32 v43, vcc, 1.0, v48, 1.0
	v_mul_f32_e32 v53, v43, v54
	v_fma_f32 v55, -v52, v53, v43
	v_fmac_f32_e32 v53, v55, v54
	v_fma_f32 v43, -v52, v53, v43
	v_div_fmas_f32 v43, v43, v54, v53
	v_mad_i64_i32 v[52:53], s[44:45], v42, s53, v[150:151]
	v_div_fixup_f32 v48, v43, v48, 1.0
	global_store_dwordx4 v[52:53], v[44:47], off
	global_store_dwordx4 v[52:53], v[48:51], off offset:16

.LBB0_758:
	s_andn2_b64 vcc, exec, s[42:43]
	s_cbranch_vccnz .LBB0_760
	v_mul_f32_e32 v46, s18, v38
	v_mul_f32_e32 v47, s18, v39
	v_mul_f32_e32 v44, s18, v36
	v_mul_f32_e32 v45, s18, v37
	v_mul_f32_e32 v48, s18, v34
	v_mul_f32_e32 v49, s18, v35
	v_mul_f32_e32 v50, s18, v32
	v_mul_f32_e32 v51, s18, v33
	v_cvt_pk_bf16_f32 v44, v44, v45
	v_cvt_pk_bf16_f32 v45, v46, v47
	v_lshlrev_b32_e32 v138, 1, v146
	v_cvt_pk_bf16_f32 v46, v50, v51
	v_cvt_pk_bf16_f32 v47, v48, v49
	v_lshl_add_u64 v[48:49], s[10:11], 0, v[40:41]
	v_lshl_add_u64 v[48:49], s[14:15], 1, v[48:49]
	v_lshl_add_u64 v[48:49], v[48:49], 0, v[138:139]
	global_store_dwordx4 v[48:49], v[44:47], off offset:-3072

.LBB0_763:
	v_mov_b32_e32 v34, v160
	v_mov_b32_e32 v35, v160
	v_mov_b32_e32 v36, v160
	v_mov_b32_e32 v37, v160
	v_mul_f32_e32 v22, v22, v36
	v_mul_f32_e32 v23, v23, v37
	v_mul_f32_e32 v32, v20, v34
	v_mul_f32_e32 v33, v21, v35
	v_mul_f32_e32 v20, v18, v36
	v_mul_f32_e32 v21, v19, v37
	s_and_b64 vcc, exec, s[8:9]
	v_mul_f32_e32 v34, v16, v34
	v_mul_f32_e32 v35, v17, v35
	s_cbranch_vccnz .LBB0_766
	s_mov_b64 s[42:43], 0
	s_and_b64 vcc, exec, s[36:37]
	s_mov_b64 s[44:45], 0
	s_cbranch_vccz .LBB0_767
	v_mul_f32_e32 v18, s18, v22
	v_mul_f32_e32 v19, s18, v23
	v_mul_f32_e32 v16, s18, v32
	v_mul_f32_e32 v17, s18, v33
	v_mul_f32_e32 v36, s18, v20
	v_mul_f32_e32 v37, s18, v21
	v_mul_f32_e32 v38, s18, v34
	v_mul_f32_e32 v39, s18, v35
	v_cvt_pk_bf16_f32 v16, v16, v17
	v_cvt_pk_bf16_f32 v17, v18, v19
	s_mov_b64 s[44:45], -1
	v_cvt_pk_bf16_f32 v18, v38, v39
	v_cvt_pk_bf16_f32 v19, v36, v37
	v_lshl_add_u64 v[36:37], s[10:11], 0, v[40:41]
	v_lshl_add_u64 v[36:37], s[14:15], 1, v[36:37]
	v_lshl_add_u64 v[36:37], v[36:37], 0, s[20:21]
	s_branch .LBB0_767

.LBB0_771:
	s_nop 1
	v_add_u32_e32 v18, 0xb0, v162
	v_ashrrev_i32_e32 v19, 31, v18
	v_mov_b32_e32 v20, v161
	v_lshlrev_b64 v[16:17], 11, v[18:19]
	v_mul_f32_e32 v14, v14, v20
	v_mul_f32_e32 v15, v15, v20
	v_mul_f32_e32 v12, v12, v20
	v_mul_f32_e32 v13, v13, v20
	v_mul_f32_e32 v10, v10, v20
	v_mul_f32_e32 v11, v11, v20
	v_mul_f32_e32 v8, v8, v20
	v_mul_f32_e32 v9, v9, v20
	s_and_b64 vcc, exec, s[8:9]
	s_mov_b64 s[42:43], -1
	s_cbranch_vccnz .LBB0_779
	s_andn2_b64 vcc, exec, s[40:41]
	s_mov_b64 s[40:41], -1
	s_cbranch_vccnz .LBB0_776
	s_and_saveexec_b64 s[40:41], s[4:5]
	s_cbranch_execz .LBB0_775
	v_mul_f32_e32 v21, 0xbfb8aa3b, v14
	v_exp_f32_e32 v22, v21
	v_mul_f32_e32 v21, 0xbfb8aa3b, v15
	v_exp_f32_e32 v23, v21
	v_mul_f32_e32 v19, 0xbfb8aa3b, v12
	v_exp_f32_e32 v20, v19
	v_mul_f32_e32 v19, 0xbfb8aa3b, v8
	v_exp_f32_e32 v32, v19
	v_mul_f32_e32 v19, 0xbfb8aa3b, v13
	v_exp_f32_e32 v21, v19
	v_mul_f32_e32 v19, 0xbfb8aa3b, v9
	v_add_f32_e32 v22, 1.0, v22
	v_add_f32_e32 v23, 1.0, v23
	v_exp_f32_e32 v33, v19
	v_div_scale_f32 v19, s[42:43], v23, v23, 1.0
	v_rcp_f32_e32 v35, v19
	v_add_f32_e32 v20, 1.0, v20
	v_add_f32_e32 v21, 1.0, v21
	v_mul_f32_e32 v34, 0xbfb8aa3b, v10
	v_exp_f32_e32 v34, v34
	v_fma_f32 v36, -v19, v35, 1.0
	v_fmac_f32_e32 v35, v36, v35
	v_div_scale_f32 v36, vcc, 1.0, v23, 1.0
	v_mul_f32_e32 v37, v36, v35
	v_fma_f32 v38, -v19, v37, v36
	v_fmac_f32_e32 v37, v38, v35
	v_fma_f32 v19, -v19, v37, v36
	v_div_scale_f32 v36, s[42:43], v22, v22, 1.0
	v_rcp_f32_e32 v38, v36
	v_div_fmas_f32 v19, v19, v35, v37
	v_div_fixup_f32 v23, v19, v23, 1.0
	v_add_f32_e32 v32, 1.0, v32
	v_add_f32_e32 v33, 1.0, v33
	v_fma_f32 v19, -v36, v38, 1.0
	v_fmac_f32_e32 v38, v19, v38
	v_div_scale_f32 v19, vcc, 1.0, v22, 1.0
	v_mul_f32_e32 v35, v19, v38
	v_fma_f32 v37, -v36, v35, v19
	v_fmac_f32_e32 v35, v37, v38
	v_fma_f32 v19, -v36, v35, v19
	v_div_scale_f32 v36, s[42:43], v21, v21, 1.0
	v_rcp_f32_e32 v37, v36
	v_div_fmas_f32 v19, v19, v38, v35
	v_div_fixup_f32 v22, v19, v22, 1.0
	v_fma_f32 v19, -v36, v37, 1.0
	v_fmac_f32_e32 v37, v19, v37
	v_div_scale_f32 v19, vcc, 1.0, v21, 1.0
	v_mul_f32_e32 v35, v19, v37
	v_fma_f32 v38, -v36, v35, v19
	v_fmac_f32_e32 v35, v38, v37
	v_fma_f32 v19, -v36, v35, v19
	v_div_scale_f32 v36, s[42:43], v20, v20, 1.0
	v_rcp_f32_e32 v38, v36
	v_div_fmas_f32 v19, v19, v37, v35
	v_mul_f32_e32 v35, 0xbfb8aa3b, v11
	v_div_fixup_f32 v21, v19, v21, 1.0
	v_fma_f32 v19, -v36, v38, 1.0
	v_exp_f32_e32 v35, v35
	v_fmac_f32_e32 v38, v19, v38
	v_div_scale_f32 v19, vcc, 1.0, v20, 1.0
	v_mul_f32_e32 v37, v19, v38
	v_fma_f32 v39, -v36, v37, v19
	v_fmac_f32_e32 v37, v39, v38
	v_add_f32_e32 v34, 1.0, v34
	v_add_f32_e32 v35, 1.0, v35
	v_fma_f32 v19, -v36, v37, v19
	v_div_scale_f32 v36, s[42:43], v35, v35, 1.0
	v_rcp_f32_e32 v39, v36
	v_div_fmas_f32 v19, v19, v38, v37
	v_div_fixup_f32 v20, v19, v20, 1.0
	v_fma_f32 v19, -v36, v39, 1.0
	v_fmac_f32_e32 v39, v19, v39
	v_div_scale_f32 v19, vcc, 1.0, v35, 1.0
	v_mul_f32_e32 v37, v19, v39
	v_fma_f32 v38, -v36, v37, v19
	v_fmac_f32_e32 v37, v38, v39
	v_fma_f32 v19, -v36, v37, v19
	v_div_scale_f32 v36, s[42:43], v34, v34, 1.0
	v_rcp_f32_e32 v38, v36
	v_div_fmas_f32 v19, v19, v39, v37
	v_div_fixup_f32 v35, v19, v35, 1.0
	v_fma_f32 v19, -v36, v38, 1.0
	v_fmac_f32_e32 v38, v19, v38
	v_div_scale_f32 v19, vcc, 1.0, v34, 1.0
	v_mul_f32_e32 v37, v19, v38
	v_fma_f32 v39, -v36, v37, v19
	v_fmac_f32_e32 v37, v39, v38
	v_fma_f32 v19, -v36, v37, v19
	v_div_scale_f32 v36, s[42:43], v33, v33, 1.0
	v_rcp_f32_e32 v39, v36
	v_div_fmas_f32 v19, v19, v38, v37
	v_div_fixup_f32 v34, v19, v34, 1.0
	v_fma_f32 v19, -v36, v39, 1.0
	v_fmac_f32_e32 v39, v19, v39
	v_div_scale_f32 v19, vcc, 1.0, v33, 1.0
	v_mul_f32_e32 v37, v19, v39
	v_fma_f32 v38, -v36, v37, v19
	v_fmac_f32_e32 v37, v38, v39
	v_fma_f32 v19, -v36, v37, v19
	v_div_scale_f32 v36, s[42:43], v32, v32, 1.0
	v_rcp_f32_e32 v38, v36
	v_div_fmas_f32 v19, v19, v39, v37
	v_div_fixup_f32 v33, v19, v33, 1.0
	v_fma_f32 v19, -v36, v38, 1.0
	v_fmac_f32_e32 v38, v19, v38
	v_div_scale_f32 v19, vcc, 1.0, v32, 1.0
	v_mul_f32_e32 v37, v19, v38
	v_fma_f32 v39, -v36, v37, v19
	v_fmac_f32_e32 v37, v39, v38
	v_fma_f32 v19, -v36, v37, v19
	v_div_fmas_f32 v19, v19, v38, v37
	v_mad_i64_i32 v[36:37], s[42:43], v18, s53, v[150:151]
	v_div_fixup_f32 v32, v19, v32, 1.0
	global_store_dwordx4 v[36:37], v[20:23], off
	global_store_dwordx4 v[36:37], v[32:35], off offset:16

.LBB0_776:
	s_andn2_b64 vcc, exec, s[40:41]
	s_cbranch_vccnz .LBB0_778
	v_mul_f32_e32 v22, s18, v14
	v_mul_f32_e32 v23, s18, v15
	v_mul_f32_e32 v20, s18, v12
	v_mul_f32_e32 v21, s18, v13
	v_mul_f32_e32 v32, s18, v10
	v_mul_f32_e32 v33, s18, v11
	v_mul_f32_e32 v34, s18, v8
	v_mul_f32_e32 v35, s18, v9
	v_cvt_pk_bf16_f32 v20, v20, v21
	v_cvt_pk_bf16_f32 v21, v22, v23
	v_lshlrev_b32_e32 v138, 1, v146
	v_cvt_pk_bf16_f32 v22, v34, v35
	v_cvt_pk_bf16_f32 v23, v32, v33
	v_lshl_add_u64 v[32:33], s[10:11], 0, v[16:17]
	v_lshl_add_u64 v[32:33], s[14:15], 1, v[32:33]
	v_lshl_add_u64 v[32:33], v[32:33], 0, v[138:139]
	global_store_dwordx4 v[32:33], v[20:23], off offset:-3072

.LBB0_781:
	v_mov_b32_e32 v160, v161
	v_mov_b32_e32 v10, v161
	v_mov_b32_e32 v11, v161
	v_mul_f32_e32 v6, v6, v10
	v_mul_f32_e32 v7, v7, v11
	v_mul_f32_e32 v8, v4, v160
	v_mul_f32_e32 v9, v5, v161
	v_mul_f32_e32 v4, v2, v10
	v_mul_f32_e32 v5, v3, v11
	s_and_b64 vcc, exec, s[8:9]
	v_mul_f32_e32 v10, v0, v160
	v_mul_f32_e32 v11, v1, v161
	s_cbranch_vccnz .LBB0_787
	s_mov_b64 s[8:9], 0
	s_and_b64 vcc, exec, s[36:37]
	s_mov_b64 s[36:37], 0
	s_cbranch_vccz .LBB0_784
	v_mul_f32_e32 v2, s18, v6
	v_mul_f32_e32 v3, s18, v7
	v_mul_f32_e32 v0, s18, v8
	v_mul_f32_e32 v1, s18, v9
	v_mul_f32_e32 v12, s18, v4
	v_mul_f32_e32 v13, s18, v5
	v_mul_f32_e32 v14, s18, v10
	v_mul_f32_e32 v15, s18, v11
	v_cvt_pk_bf16_f32 v0, v0, v1
	v_cvt_pk_bf16_f32 v1, v2, v3
	s_mov_b64 s[36:37], -1
	v_cvt_pk_bf16_f32 v2, v14, v15
	v_cvt_pk_bf16_f32 v3, v12, v13
	v_lshl_add_u64 v[12:13], s[10:11], 0, v[16:17]
	v_lshl_add_u64 v[12:13], s[14:15], 1, v[12:13]
	v_lshl_add_u64 v[12:13], v[12:13], 0, s[20:21]

.LBB0_860:
	s_or_b64 exec, exec, s[30:31]
	v_bfi_b32 v11, s68, v11, v10
	v_bfi_b32 v10, s68, v9, v8
	v_bfi_b32 v15, s68, v15, v14
	v_bfi_b32 v14, s68, v13, v12
	v_mul_f32_e32 v0, 0.5, v0
	v_mul_f32_e32 v1, 0.5, v1
	v_add_f32_e32 v8, 1.0, v10
	v_add_f32_e32 v9, 1.0, v11
	v_mul_f32_e32 v4, 0.5, v4
	v_mul_f32_e32 v5, 0.5, v5
	v_add_f32_e32 v12, 1.0, v14
	v_add_f32_e32 v13, 1.0, v15
	v_mul_f32_e32 v0, v0, v8
	v_mul_f32_e32 v1, v1, v9
	v_lshlrev_b64 v[8:9], 9, v[64:65]
	v_mul_f32_e32 v4, v4, v12
	v_mul_f32_e32 v5, v5, v13
	v_bfi_b32 v13, s68, v23, v22
	v_bfi_b32 v12, s68, v19, v18
	v_lshl_add_u64 v[8:9], s[0:1], 0, v[8:9]
	v_mul_f32_e32 v2, 0.5, v2
	v_mul_f32_e32 v3, 0.5, v3
	v_add_f32_e32 v10, 1.0, v12
	v_add_f32_e32 v11, 1.0, v13
	v_lshl_add_u64 v[8:9], v[8:9], 0, v[80:81]
	v_bfi_b32 v21, s68, v21, v20
	v_bfi_b32 v20, s68, v17, v16
	v_mul_f32_e32 v2, v2, v10
	v_mul_f32_e32 v3, v3, v11
	v_lshl_add_u64 v[10:11], v[8:9], 0, s[18:19]
	v_add_co_u32_e32 v8, vcc, 0x16000, v8
	v_mul_f32_e32 v6, 0.5, v6
	v_mul_f32_e32 v7, 0.5, v7
	v_add_f32_e32 v14, 1.0, v20
	v_add_f32_e32 v15, 1.0, v21
	v_addc_co_u32_e32 v9, vcc, 0, v9, vcc
	v_mul_f32_e32 v6, v6, v14
	v_mul_f32_e32 v7, v7, v15
	s_and_b64 vcc, exec, s[2:3]
	s_mov_b32 s30, s20
	s_mov_b32 s70, s69
	s_mov_b64 s[36:37], s[28:29]
	s_mov_b64 s[34:35], s[22:23]
	global_store_dwordx4 v[8:9], v[4:7], off
	global_store_dwordx4 v[10:11], v[0:3], off offset:16
	s_cbranch_vccnz .LBB0_1131

.LBB0_875:
	s_lshl_b32 s0, s30, 7
	s_ashr_i32 s1, s0, 31
	v_lshl_add_u64 v[8:9], s[0:1], 2, v[84:85]
	global_load_dwordx4 v[16:19], v[8:9], off
	s_nop 0
	global_load_dwordx4 v[8:11], v[8:9], off offset:16
	s_waitcnt vmcnt(0)
	v_add_f32_e32 v68, v68, v16
	v_add_f32_e32 v69, v69, v17
	s_nop 0
	v_mul_f32_e32 v80, 0x3d372713, v68
	v_mul_f32_e32 v80, v68, v80
	v_fma_f32 v80, v68, v80, v68
	v_mul_f32_e32 v80, 0x3f4c422a, v80
	v_cmp_nlt_f32_e64 s[0:1], |v80|, s61
	s_and_saveexec_b64 s[34:35], s[0:1]
	s_xor_b64 s[0:1], exec, s[34:35]
	s_cbranch_execz .LBB0_877
	v_add_f32_e64 v98, |v80|, |v80|
	v_mul_f32_e32 v99, 0x3fb8aa3b, v98
	v_rndne_f32_e32 v100, v99
	v_sub_f32_e32 v101, v99, v100
	v_fma_f32 v99, v98, s62, -v99
	v_fmac_f32_e32 v99, 0x32a5705f, v98
	v_add_f32_e32 v99, v101, v99
	v_cvt_i32_f32_e32 v100, v100
	v_exp_f32_e32 v99, v99
	v_cmp_ngt_f32_e32 vcc, s63, v98
	v_ldexp_f32 v99, v99, v100
	s_nop 0
	v_cndmask_b32_e32 v99, 0, v99, vcc
	v_cmp_nlt_f32_e32 vcc, s67, v98
	s_nop 1
	v_cndmask_b32_e32 v98, v97, v99, vcc
	v_add_f32_e32 v98, 1.0, v98
	v_rcp_f32_e32 v98, v98
	s_nop 0
	v_fma_f32 v98, v98, -2.0, 1.0
.LBB0_877:
	s_andn2_saveexec_b64 s[0:1], s[0:1]
	v_mul_f32_e32 v98, v80, v80
	v_fmamk_f32 v99, v98, 0xbbbac73d, v96
	v_fmaak_f32 v99, v98, v99, 0xbd5c1c4e
	v_fmaak_f32 v99, v98, v99, 0x3e088382
	v_fmaak_f32 v99, v98, v99, 0xbeaaaa99
	v_mul_f32_e64 v99, |v80|, v99
	v_fma_f32 v98, v98, v99, |v80|
	s_or_b64 exec, exec, s[0:1]
	v_add_f32_e32 v64, v64, v8
	v_add_f32_e32 v65, v65, v9
	s_nop 0
	v_mul_f32_e32 v99, 0x3d372713, v64
	v_mul_f32_e32 v99, v64, v99
	v_fma_f32 v99, v64, v99, v64
	v_mul_f32_e32 v99, 0x3f4c422a, v99
	v_cmp_nlt_f32_e64 s[0:1], |v99|, s61
	s_and_saveexec_b64 s[34:35], s[0:1]
	s_xor_b64 s[0:1], exec, s[34:35]
	s_cbranch_execz .LBB0_881
	v_add_f32_e64 v100, |v99|, |v99|
	v_mul_f32_e32 v101, 0x3fb8aa3b, v100
	v_rndne_f32_e32 v102, v101
	v_sub_f32_e32 v103, v101, v102
	v_fma_f32 v101, v100, s62, -v101
	v_fmac_f32_e32 v101, 0x32a5705f, v100
	v_add_f32_e32 v101, v103, v101
	v_cvt_i32_f32_e32 v102, v102
	v_exp_f32_e32 v101, v101
	v_cmp_ngt_f32_e32 vcc, s63, v100
	v_ldexp_f32 v101, v101, v102
	s_nop 0
	v_cndmask_b32_e32 v101, 0, v101, vcc
	v_cmp_nlt_f32_e32 vcc, s67, v100
	s_nop 1
	v_cndmask_b32_e32 v100, v97, v101, vcc
	v_add_f32_e32 v100, 1.0, v100
	v_rcp_f32_e32 v100, v100
	s_nop 0
	v_fma_f32 v100, v100, -2.0, 1.0
.LBB0_881:
	s_andn2_saveexec_b64 s[0:1], s[0:1]
	v_mul_f32_e32 v100, v99, v99
	v_fmamk_f32 v101, v100, 0xbbbac73d, v96
	v_fmaak_f32 v101, v100, v101, 0xbd5c1c4e
	v_fmaak_f32 v101, v100, v101, 0x3e088382
	v_fmaak_f32 v101, v100, v101, 0xbeaaaa99
	v_mul_f32_e64 v101, |v99|, v101
	v_fma_f32 v100, v100, v101, |v99|
	s_or_b64 exec, exec, s[0:1]
	v_mul_f32_e32 v101, 0x3d372713, v69
	v_mul_f32_e32 v101, v69, v101
	v_fma_f32 v101, v69, v101, v69
	v_mul_f32_e32 v101, 0x3f4c422a, v101
	v_add_f32_e32 v70, v70, v18
	v_add_f32_e32 v71, v71, v19
	v_cmp_nlt_f32_e64 s[0:1], |v101|, s61
	s_and_saveexec_b64 s[34:35], s[0:1]
	s_xor_b64 s[0:1], exec, s[34:35]
	s_cbranch_execz .LBB0_885
	v_add_f32_e64 v102, |v101|, |v101|
	v_mul_f32_e32 v103, 0x3fb8aa3b, v102
	v_rndne_f32_e32 v104, v103
	v_sub_f32_e32 v105, v103, v104
	v_fma_f32 v103, v102, s62, -v103
	v_fmac_f32_e32 v103, 0x32a5705f, v102
	v_add_f32_e32 v103, v105, v103
	v_cvt_i32_f32_e32 v104, v104
	v_exp_f32_e32 v103, v103
	v_cmp_ngt_f32_e32 vcc, s63, v102
	v_ldexp_f32 v103, v103, v104
	s_nop 0
	v_cndmask_b32_e32 v103, 0, v103, vcc
	v_cmp_nlt_f32_e32 vcc, s67, v102
	s_nop 1
	v_cndmask_b32_e32 v102, v97, v103, vcc
	v_add_f32_e32 v102, 1.0, v102
	v_rcp_f32_e32 v102, v102
	s_nop 0
	v_fma_f32 v102, v102, -2.0, 1.0
.LBB0_885:
	s_andn2_saveexec_b64 s[0:1], s[0:1]
	v_mul_f32_e32 v102, v101, v101
	v_fmamk_f32 v103, v102, 0xbbbac73d, v96
	v_fmaak_f32 v103, v102, v103, 0xbd5c1c4e
	v_fmaak_f32 v103, v102, v103, 0x3e088382
	v_fmaak_f32 v103, v102, v103, 0xbeaaaa99
	v_mul_f32_e64 v103, |v101|, v103
	v_fma_f32 v102, v102, v103, |v101|
	s_or_b64 exec, exec, s[0:1]
	v_mul_f32_e32 v103, 0x3d372713, v65
	v_mul_f32_e32 v103, v65, v103
	v_fma_f32 v103, v65, v103, v65
	v_mul_f32_e32 v103, 0x3f4c422a, v103
	v_add_f32_e32 v66, v66, v10
	v_add_f32_e32 v67, v67, v11
	v_cmp_nlt_f32_e64 s[0:1], |v103|, s61
	s_and_saveexec_b64 s[34:35], s[0:1]
	s_xor_b64 s[0:1], exec, s[34:35]
	s_cbranch_execz .LBB0_889
	v_add_f32_e64 v104, |v103|, |v103|
	v_mul_f32_e32 v105, 0x3fb8aa3b, v104
	v_rndne_f32_e32 v106, v105
	v_sub_f32_e32 v107, v105, v106
	v_fma_f32 v105, v104, s62, -v105
	v_fmac_f32_e32 v105, 0x32a5705f, v104
	v_add_f32_e32 v105, v107, v105
	v_cvt_i32_f32_e32 v106, v106
	v_exp_f32_e32 v105, v105
	v_cmp_ngt_f32_e32 vcc, s63, v104
	v_ldexp_f32 v105, v105, v106
	s_nop 0
	v_cndmask_b32_e32 v105, 0, v105, vcc
	v_cmp_nlt_f32_e32 vcc, s67, v104
	s_nop 1
	v_cndmask_b32_e32 v104, v97, v105, vcc
	v_add_f32_e32 v104, 1.0, v104
	v_rcp_f32_e32 v104, v104
	s_nop 0
	v_fma_f32 v104, v104, -2.0, 1.0

.LBB0_905:
	s_andn2_saveexec_b64 s[0:1], s[0:1]
	v_mul_f32_e32 v112, v111, v111
	v_fmamk_f32 v113, v112, 0xbbbac73d, v96
	v_fmaak_f32 v113, v112, v113, 0xbd5c1c4e
	v_fmaak_f32 v113, v112, v113, 0x3e088382
	v_fmaak_f32 v113, v112, v113, 0xbeaaaa99
	v_mul_f32_e64 v113, |v111|, v113
	v_fma_f32 v112, v112, v113, |v111|
	s_or_b64 exec, exec, s[0:1]
	v_bfi_b32 v80, s68, v98, v80
	v_mul_f32_e32 v68, 0.5, v68
	v_add_f32_e32 v80, 1.0, v80
	v_mul_f32_e32 v68, v68, v80
	v_bfi_b32 v80, s68, v102, v101
	v_mul_f32_e32 v69, 0.5, v69
	v_add_f32_e32 v80, 1.0, v80
	v_mul_f32_e32 v69, v69, v80
	v_bfi_b32 v80, s68, v106, v105
	v_mul_f32_e32 v70, 0.5, v70
	v_add_f32_e32 v80, 1.0, v80
	v_mul_f32_e32 v70, v70, v80
	v_bfi_b32 v80, s68, v110, v109
	v_mul_f32_e32 v71, 0.5, v71
	v_add_f32_e32 v80, 1.0, v80
	v_mul_f32_e32 v71, v71, v80
	v_bfi_b32 v80, s68, v100, v99
	v_mul_f32_e32 v64, 0.5, v64
	v_add_f32_e32 v80, 1.0, v80
	v_mul_f32_e32 v98, v64, v80
	v_mul_f32_e32 v64, 0.5, v65
	v_bfi_b32 v65, s68, v104, v103
	v_add_f32_e32 v65, 1.0, v65
	v_mul_f32_e32 v99, v64, v65
	v_bfi_b32 v65, s68, v108, v107
	v_mul_f32_e32 v64, 0.5, v66
	v_add_f32_e32 v65, 1.0, v65
	s_ashr_i32 s31, s30, 31
	v_bfi_b32 v66, s68, v112, v111
	v_mul_f32_e32 v100, v64, v65
	v_lshl_add_u32 v64, s70, 8, v83
	s_lshl_b64 s[0:1], s[30:31], 23
	v_mul_f32_e32 v65, 0.5, v67
	v_add_f32_e32 v66, 1.0, v66
	v_mul_f32_e32 v101, v65, v66
	v_ashrrev_i32_e32 v65, 31, v64
	s_add_u32 s0, s52, s0
	s_addc_u32 s1, s53, s1
	v_lshlrev_b64 v[66:67], 9, v[64:65]
	v_lshl_add_u64 v[66:67], s[0:1], 0, v[66:67]
	v_lshlrev_b32_e32 v80, 2, v82
	v_lshl_add_u64 v[66:67], v[66:67], 0, v[80:81]
	v_add_f32_e32 v60, v60, v16
	v_add_f32_e32 v61, v61, v17
	global_store_dwordx4 v[66:67], v[68:71], off
	global_store_dwordx4 v[66:67], v[98:101], off offset:16
	v_mul_f32_e32 v66, 0x3d372713, v60
	v_mul_f32_e32 v66, v60, v66
	v_fma_f32 v66, v60, v66, v60
	v_mul_f32_e32 v66, 0x3f4c422a, v66
	v_cmp_nlt_f32_e64 s[30:31], |v66|, s61
	s_and_saveexec_b64 s[34:35], s[30:31]
	s_xor_b64 s[30:31], exec, s[34:35]
	s_cbranch_execz .LBB0_909
	v_add_f32_e64 v67, |v66|, |v66|
	v_mul_f32_e32 v68, 0x3fb8aa3b, v67
	v_rndne_f32_e32 v69, v68
	v_sub_f32_e32 v70, v68, v69
	v_fma_f32 v68, v67, s62, -v68
	v_fmac_f32_e32 v68, 0x32a5705f, v67
	v_add_f32_e32 v68, v70, v68
	v_cvt_i32_f32_e32 v69, v69
	v_exp_f32_e32 v68, v68
	v_cmp_ngt_f32_e32 vcc, s63, v67
	v_ldexp_f32 v68, v68, v69
	s_nop 0
	v_cndmask_b32_e32 v68, 0, v68, vcc
	v_cmp_nlt_f32_e32 vcc, s67, v67
	s_nop 1
	v_cndmask_b32_e32 v67, v97, v68, vcc
	v_add_f32_e32 v67, 1.0, v67
	v_rcp_f32_e32 v67, v67
	s_nop 0
	v_fma_f32 v67, v67, -2.0, 1.0
.LBB0_909:
	s_andn2_saveexec_b64 s[30:31], s[30:31]
	v_mul_f32_e32 v67, v66, v66
	v_fmamk_f32 v68, v67, 0xbbbac73d, v96
	v_fmaak_f32 v68, v67, v68, 0xbd5c1c4e
	v_fmaak_f32 v68, v67, v68, 0x3e088382
	v_fmaak_f32 v68, v67, v68, 0xbeaaaa99
	v_mul_f32_e64 v68, |v66|, v68
	v_fma_f32 v67, v67, v68, |v66|
	s_or_b64 exec, exec, s[30:31]
	v_add_f32_e32 v56, v56, v8
	v_add_f32_e32 v57, v57, v9
	s_nop 0
	v_mul_f32_e32 v68, 0x3d372713, v56
	v_mul_f32_e32 v68, v56, v68
	v_fma_f32 v68, v56, v68, v56
	v_mul_f32_e32 v68, 0x3f4c422a, v68
	v_cmp_nlt_f32_e64 s[30:31], |v68|, s61
	s_and_saveexec_b64 s[34:35], s[30:31]
	s_xor_b64 s[30:31], exec, s[34:35]
	s_cbranch_execz .LBB0_913
	v_add_f32_e64 v69, |v68|, |v68|
	v_mul_f32_e32 v70, 0x3fb8aa3b, v69
	v_rndne_f32_e32 v71, v70
	v_sub_f32_e32 v98, v70, v71
	v_fma_f32 v70, v69, s62, -v70
	v_fmac_f32_e32 v70, 0x32a5705f, v69
	v_add_f32_e32 v70, v98, v70
	v_cvt_i32_f32_e32 v71, v71
	v_exp_f32_e32 v70, v70
	v_cmp_ngt_f32_e32 vcc, s63, v69
	v_ldexp_f32 v70, v70, v71
	s_nop 0
	v_cndmask_b32_e32 v70, 0, v70, vcc
	v_cmp_nlt_f32_e32 vcc, s67, v69
	s_nop 1
	v_cndmask_b32_e32 v69, v97, v70, vcc
	v_add_f32_e32 v69, 1.0, v69
	v_rcp_f32_e32 v69, v69
	s_nop 0
	v_fma_f32 v69, v69, -2.0, 1.0
.LBB0_913:
	s_andn2_saveexec_b64 s[30:31], s[30:31]
	v_mul_f32_e32 v69, v68, v68
	v_fmamk_f32 v70, v69, 0xbbbac73d, v96
	v_fmaak_f32 v70, v69, v70, 0xbd5c1c4e
	v_fmaak_f32 v70, v69, v70, 0x3e088382
	v_fmaak_f32 v70, v69, v70, 0xbeaaaa99
	v_mul_f32_e64 v70, |v68|, v70
	v_fma_f32 v69, v69, v70, |v68|
	s_or_b64 exec, exec, s[30:31]
	v_mul_f32_e32 v70, 0x3d372713, v61
	v_mul_f32_e32 v70, v61, v70
	v_fma_f32 v70, v61, v70, v61
	v_mul_f32_e32 v70, 0x3f4c422a, v70
	v_add_f32_e32 v62, v62, v18
	v_add_f32_e32 v63, v63, v19
	v_cmp_nlt_f32_e64 s[30:31], |v70|, s61
	s_and_saveexec_b64 s[34:35], s[30:31]
	s_xor_b64 s[30:31], exec, s[34:35]
	s_cbranch_execz .LBB0_917
	v_add_f32_e64 v71, |v70|, |v70|
	v_mul_f32_e32 v98, 0x3fb8aa3b, v71
	v_rndne_f32_e32 v99, v98
	v_sub_f32_e32 v100, v98, v99
	v_fma_f32 v98, v71, s62, -v98
	v_fmac_f32_e32 v98, 0x32a5705f, v71
	v_add_f32_e32 v98, v100, v98
	v_cvt_i32_f32_e32 v99, v99
	v_exp_f32_e32 v98, v98
	v_cmp_ngt_f32_e32 vcc, s63, v71
	v_ldexp_f32 v98, v98, v99
	s_nop 0
	v_cndmask_b32_e32 v98, 0, v98, vcc
	v_cmp_nlt_f32_e32 vcc, s67, v71
	s_nop 1
	v_cndmask_b32_e32 v71, v97, v98, vcc
	v_add_f32_e32 v71, 1.0, v71
	v_rcp_f32_e32 v71, v71
	s_nop 0
	v_fma_f32 v71, v71, -2.0, 1.0
.LBB0_917:
	s_andn2_saveexec_b64 s[30:31], s[30:31]
	v_mul_f32_e32 v71, v70, v70
	v_fmamk_f32 v98, v71, 0xbbbac73d, v96
	v_fmaak_f32 v98, v71, v98, 0xbd5c1c4e
	v_fmaak_f32 v98, v71, v98, 0x3e088382
	v_fmaak_f32 v98, v71, v98, 0xbeaaaa99
	v_mul_f32_e64 v98, |v70|, v98
	v_fma_f32 v71, v71, v98, |v70|
	s_or_b64 exec, exec, s[30:31]
	v_mul_f32_e32 v98, 0x3d372713, v57
	v_mul_f32_e32 v98, v57, v98
	v_fma_f32 v98, v57, v98, v57
	v_mul_f32_e32 v98, 0x3f4c422a, v98
	v_add_f32_e32 v58, v58, v10
	v_add_f32_e32 v59, v59, v11
	v_cmp_nlt_f32_e64 s[30:31], |v98|, s61
	s_and_saveexec_b64 s[34:35], s[30:31]
	s_xor_b64 s[30:31], exec, s[34:35]
	s_cbranch_execz .LBB0_921
	v_add_f32_e64 v99, |v98|, |v98|
	v_mul_f32_e32 v100, 0x3fb8aa3b, v99
	v_rndne_f32_e32 v101, v100
	v_sub_f32_e32 v102, v100, v101
	v_fma_f32 v100, v99, s62, -v100
	v_fmac_f32_e32 v100, 0x32a5705f, v99
	v_add_f32_e32 v100, v102, v100
	v_cvt_i32_f32_e32 v101, v101
	v_exp_f32_e32 v100, v100
	v_cmp_ngt_f32_e32 vcc, s63, v99
	v_ldexp_f32 v100, v100, v101
	s_nop 0
	v_cndmask_b32_e32 v100, 0, v100, vcc
	v_cmp_nlt_f32_e32 vcc, s67, v99
	s_nop 1
	v_cndmask_b32_e32 v99, v97, v100, vcc
	v_add_f32_e32 v99, 1.0, v99
	v_rcp_f32_e32 v99, v99
	s_nop 0
	v_fma_f32 v99, v99, -2.0, 1.0

.LBB0_937:
	s_andn2_saveexec_b64 s[30:31], s[30:31]
	v_mul_f32_e32 v107, v106, v106
	v_fmamk_f32 v108, v107, 0xbbbac73d, v96
	v_fmaak_f32 v108, v107, v108, 0xbd5c1c4e
	v_fmaak_f32 v108, v107, v108, 0x3e088382
	v_fmaak_f32 v108, v107, v108, 0xbeaaaa99
	v_mul_f32_e64 v108, |v106|, v108
	v_fma_f32 v107, v107, v108, |v106|
	s_or_b64 exec, exec, s[30:31]
	v_bfi_b32 v66, s68, v67, v66
	v_mul_f32_e32 v60, 0.5, v60
	v_add_f32_e32 v66, 1.0, v66
	v_mul_f32_e32 v60, v60, v66
	v_bfi_b32 v66, s68, v71, v70
	v_mul_f32_e32 v61, 0.5, v61
	v_add_f32_e32 v66, 1.0, v66
	v_mul_f32_e32 v61, v61, v66
	v_bfi_b32 v66, s68, v101, v100
	v_mul_f32_e32 v62, 0.5, v62
	v_add_f32_e32 v66, 1.0, v66
	v_mul_f32_e32 v62, v62, v66
	v_bfi_b32 v66, s68, v105, v104
	v_mul_f32_e32 v63, 0.5, v63
	v_add_f32_e32 v66, 1.0, v66
	v_mul_f32_e32 v63, v63, v66
	v_bfi_b32 v66, s68, v69, v68
	v_mul_f32_e32 v56, 0.5, v56
	v_add_f32_e32 v66, 1.0, v66
	v_mul_f32_e32 v56, v56, v66
	v_bfi_b32 v66, s68, v99, v98
	v_mul_f32_e32 v57, 0.5, v57
	v_add_f32_e32 v66, 1.0, v66
	v_mul_f32_e32 v57, v57, v66
	v_bfi_b32 v66, s68, v103, v102
	v_mul_f32_e32 v58, 0.5, v58
	v_add_f32_e32 v66, 1.0, v66
	v_mul_f32_e32 v58, v58, v66
	v_bfi_b32 v66, s68, v107, v106
	v_mul_f32_e32 v59, 0.5, v59
	v_add_f32_e32 v66, 1.0, v66
	v_mul_f32_e32 v59, v59, v66
	v_or_b32_e32 v66, 16, v64
	v_ashrrev_i32_e32 v67, 31, v66
	v_lshlrev_b64 v[66:67], 9, v[66:67]
	v_lshl_add_u64 v[66:67], s[0:1], 0, v[66:67]
	v_lshl_add_u64 v[66:67], v[66:67], 0, v[80:81]
	v_add_f32_e32 v52, v52, v16
	v_add_f32_e32 v53, v53, v17
	global_store_dwordx4 v[66:67], v[60:63], off
	global_store_dwordx4 v[66:67], v[56:59], off offset:16
	s_nop 1
	v_mul_f32_e32 v56, 0x3d372713, v52
	v_mul_f32_e32 v56, v52, v56
	v_fma_f32 v56, v52, v56, v52
	v_mul_f32_e32 v56, 0x3f4c422a, v56
	v_cmp_nlt_f32_e64 s[30:31], |v56|, s61
	s_and_saveexec_b64 s[34:35], s[30:31]
	s_xor_b64 s[30:31], exec, s[34:35]
	s_cbranch_execz .LBB0_941
	v_add_f32_e64 v57, |v56|, |v56|
	v_mul_f32_e32 v58, 0x3fb8aa3b, v57
	v_rndne_f32_e32 v59, v58
	v_sub_f32_e32 v60, v58, v59
	v_fma_f32 v58, v57, s62, -v58
	v_fmac_f32_e32 v58, 0x32a5705f, v57
	v_add_f32_e32 v58, v60, v58
	v_cvt_i32_f32_e32 v59, v59
	v_exp_f32_e32 v58, v58
	v_cmp_ngt_f32_e32 vcc, s63, v57
	v_ldexp_f32 v58, v58, v59
	s_nop 0
	v_cndmask_b32_e32 v58, 0, v58, vcc
	v_cmp_nlt_f32_e32 vcc, s67, v57
	s_nop 1
	v_cndmask_b32_e32 v57, v97, v58, vcc
	v_add_f32_e32 v57, 1.0, v57
	v_rcp_f32_e32 v57, v57
	s_nop 0
	v_fma_f32 v57, v57, -2.0, 1.0
.LBB0_941:
	s_andn2_saveexec_b64 s[30:31], s[30:31]
	v_mul_f32_e32 v57, v56, v56
	v_fmamk_f32 v58, v57, 0xbbbac73d, v96
	v_fmaak_f32 v58, v57, v58, 0xbd5c1c4e
	v_fmaak_f32 v58, v57, v58, 0x3e088382
	v_fmaak_f32 v58, v57, v58, 0xbeaaaa99
	v_mul_f32_e64 v58, |v56|, v58
	v_fma_f32 v57, v57, v58, |v56|
	s_or_b64 exec, exec, s[30:31]
	v_add_f32_e32 v48, v48, v8
	v_add_f32_e32 v49, v49, v9
	s_nop 0
	v_mul_f32_e32 v58, 0x3d372713, v48
	v_mul_f32_e32 v58, v48, v58
	v_fma_f32 v58, v48, v58, v48
	v_mul_f32_e32 v58, 0x3f4c422a, v58
	v_cmp_nlt_f32_e64 s[30:31], |v58|, s61
	s_and_saveexec_b64 s[34:35], s[30:31]
	s_xor_b64 s[30:31], exec, s[34:35]
	s_cbranch_execz .LBB0_945
	v_add_f32_e64 v59, |v58|, |v58|
	v_mul_f32_e32 v60, 0x3fb8aa3b, v59
	v_rndne_f32_e32 v61, v60
	v_sub_f32_e32 v62, v60, v61
	v_fma_f32 v60, v59, s62, -v60
	v_fmac_f32_e32 v60, 0x32a5705f, v59
	v_add_f32_e32 v60, v62, v60
	v_cvt_i32_f32_e32 v61, v61
	v_exp_f32_e32 v60, v60
	v_cmp_ngt_f32_e32 vcc, s63, v59
	v_ldexp_f32 v60, v60, v61
	s_nop 0
	v_cndmask_b32_e32 v60, 0, v60, vcc
	v_cmp_nlt_f32_e32 vcc, s67, v59
	s_nop 1
	v_cndmask_b32_e32 v59, v97, v60, vcc
	v_add_f32_e32 v59, 1.0, v59
	v_rcp_f32_e32 v59, v59
	s_nop 0
	v_fma_f32 v59, v59, -2.0, 1.0
.LBB0_945:
	s_andn2_saveexec_b64 s[30:31], s[30:31]
	v_mul_f32_e32 v59, v58, v58
	v_fmamk_f32 v60, v59, 0xbbbac73d, v96
	v_fmaak_f32 v60, v59, v60, 0xbd5c1c4e
	v_fmaak_f32 v60, v59, v60, 0x3e088382
	v_fmaak_f32 v60, v59, v60, 0xbeaaaa99
	v_mul_f32_e64 v60, |v58|, v60
	v_fma_f32 v59, v59, v60, |v58|
	s_or_b64 exec, exec, s[30:31]
	v_mul_f32_e32 v60, 0x3d372713, v53
	v_mul_f32_e32 v60, v53, v60
	v_fma_f32 v60, v53, v60, v53
	v_mul_f32_e32 v60, 0x3f4c422a, v60
	v_add_f32_e32 v54, v54, v18
	v_add_f32_e32 v55, v55, v19
	v_cmp_nlt_f32_e64 s[30:31], |v60|, s61
	s_and_saveexec_b64 s[34:35], s[30:31]
	s_xor_b64 s[30:31], exec, s[34:35]
	s_cbranch_execz .LBB0_949
	v_add_f32_e64 v61, |v60|, |v60|
	v_mul_f32_e32 v62, 0x3fb8aa3b, v61
	v_rndne_f32_e32 v63, v62
	v_sub_f32_e32 v66, v62, v63
	v_fma_f32 v62, v61, s62, -v62
	v_fmac_f32_e32 v62, 0x32a5705f, v61
	v_add_f32_e32 v62, v66, v62
	v_cvt_i32_f32_e32 v63, v63
	v_exp_f32_e32 v62, v62
	v_cmp_ngt_f32_e32 vcc, s63, v61
	v_ldexp_f32 v62, v62, v63
	s_nop 0
	v_cndmask_b32_e32 v62, 0, v62, vcc
	v_cmp_nlt_f32_e32 vcc, s67, v61
	s_nop 1
	v_cndmask_b32_e32 v61, v97, v62, vcc
	v_add_f32_e32 v61, 1.0, v61
	v_rcp_f32_e32 v61, v61
	s_nop 0
	v_fma_f32 v61, v61, -2.0, 1.0
.LBB0_949:
	s_andn2_saveexec_b64 s[30:31], s[30:31]
	v_mul_f32_e32 v61, v60, v60
	v_fmamk_f32 v62, v61, 0xbbbac73d, v96
	v_fmaak_f32 v62, v61, v62, 0xbd5c1c4e
	v_fmaak_f32 v62, v61, v62, 0x3e088382
	v_fmaak_f32 v62, v61, v62, 0xbeaaaa99
	v_mul_f32_e64 v62, |v60|, v62
	v_fma_f32 v61, v61, v62, |v60|
	s_or_b64 exec, exec, s[30:31]
	v_mul_f32_e32 v62, 0x3d372713, v49
	v_mul_f32_e32 v62, v49, v62
	v_fma_f32 v62, v49, v62, v49
	v_mul_f32_e32 v62, 0x3f4c422a, v62
	v_add_f32_e32 v50, v50, v10
	v_add_f32_e32 v51, v51, v11
	v_cmp_nlt_f32_e64 s[30:31], |v62|, s61
	s_and_saveexec_b64 s[34:35], s[30:31]
	s_xor_b64 s[30:31], exec, s[34:35]
	s_cbranch_execz .LBB0_953
	v_add_f32_e64 v63, |v62|, |v62|
	v_mul_f32_e32 v66, 0x3fb8aa3b, v63
	v_rndne_f32_e32 v67, v66
	v_sub_f32_e32 v68, v66, v67
	v_fma_f32 v66, v63, s62, -v66
	v_fmac_f32_e32 v66, 0x32a5705f, v63
	v_add_f32_e32 v66, v68, v66
	v_cvt_i32_f32_e32 v67, v67
	v_exp_f32_e32 v66, v66
	v_cmp_ngt_f32_e32 vcc, s63, v63
	v_ldexp_f32 v66, v66, v67
	s_nop 0
	v_cndmask_b32_e32 v66, 0, v66, vcc
	v_cmp_nlt_f32_e32 vcc, s67, v63
	s_nop 1
	v_cndmask_b32_e32 v63, v97, v66, vcc
	v_add_f32_e32 v63, 1.0, v63
	v_rcp_f32_e32 v63, v63
	s_nop 0
	v_fma_f32 v63, v63, -2.0, 1.0

.LBB0_969:
	s_andn2_saveexec_b64 s[30:31], s[30:31]
	v_mul_f32_e32 v99, v98, v98
	v_fmamk_f32 v100, v99, 0xbbbac73d, v96
	v_fmaak_f32 v100, v99, v100, 0xbd5c1c4e
	v_fmaak_f32 v100, v99, v100, 0x3e088382
	v_fmaak_f32 v100, v99, v100, 0xbeaaaa99
	v_mul_f32_e64 v100, |v98|, v100
	v_fma_f32 v99, v99, v100, |v98|
	s_or_b64 exec, exec, s[30:31]
	v_bfi_b32 v56, s68, v57, v56
	v_mul_f32_e32 v52, 0.5, v52
	v_add_f32_e32 v56, 1.0, v56
	v_mul_f32_e32 v52, v52, v56
	v_bfi_b32 v56, s68, v61, v60
	v_mul_f32_e32 v53, 0.5, v53
	v_add_f32_e32 v56, 1.0, v56
	v_mul_f32_e32 v53, v53, v56
	v_bfi_b32 v56, s68, v67, v66
	v_mul_f32_e32 v54, 0.5, v54
	v_add_f32_e32 v56, 1.0, v56
	v_mul_f32_e32 v54, v54, v56
	v_bfi_b32 v56, s68, v71, v70
	v_mul_f32_e32 v55, 0.5, v55
	v_add_f32_e32 v56, 1.0, v56
	v_mul_f32_e32 v55, v55, v56
	v_bfi_b32 v56, s68, v59, v58
	v_mul_f32_e32 v48, 0.5, v48
	v_add_f32_e32 v56, 1.0, v56
	v_mul_f32_e32 v48, v48, v56
	v_bfi_b32 v56, s68, v63, v62
	v_mul_f32_e32 v49, 0.5, v49
	v_add_f32_e32 v56, 1.0, v56
	v_mul_f32_e32 v49, v49, v56
	v_bfi_b32 v56, s68, v69, v68
	v_mul_f32_e32 v50, 0.5, v50
	v_add_f32_e32 v56, 1.0, v56
	v_mul_f32_e32 v50, v50, v56
	v_bfi_b32 v56, s68, v99, v98
	v_mul_f32_e32 v51, 0.5, v51
	v_add_f32_e32 v56, 1.0, v56
	v_mul_f32_e32 v51, v51, v56
	v_or_b32_e32 v56, 32, v64
	v_ashrrev_i32_e32 v57, 31, v56
	v_lshlrev_b64 v[56:57], 9, v[56:57]
	v_lshl_add_u64 v[56:57], s[0:1], 0, v[56:57]
	v_lshl_add_u64 v[56:57], v[56:57], 0, v[80:81]
	v_add_f32_e32 v44, v44, v16
	v_add_f32_e32 v45, v45, v17
	global_store_dwordx4 v[56:57], v[52:55], off
	global_store_dwordx4 v[56:57], v[48:51], off offset:16
	s_nop 1
	v_mul_f32_e32 v48, 0x3d372713, v44
	v_mul_f32_e32 v48, v44, v48
	v_fma_f32 v48, v44, v48, v44
	v_mul_f32_e32 v48, 0x3f4c422a, v48
	v_cmp_nlt_f32_e64 s[30:31], |v48|, s61
	s_and_saveexec_b64 s[34:35], s[30:31]
	s_xor_b64 s[30:31], exec, s[34:35]
	s_cbranch_execz .LBB0_973
	v_add_f32_e64 v49, |v48|, |v48|
	v_mul_f32_e32 v50, 0x3fb8aa3b, v49
	v_rndne_f32_e32 v51, v50
	v_sub_f32_e32 v52, v50, v51
	v_fma_f32 v50, v49, s62, -v50
	v_fmac_f32_e32 v50, 0x32a5705f, v49
	v_add_f32_e32 v50, v52, v50
	v_cvt_i32_f32_e32 v51, v51
	v_exp_f32_e32 v50, v50
	v_cmp_ngt_f32_e32 vcc, s63, v49
	v_ldexp_f32 v50, v50, v51
	s_nop 0
	v_cndmask_b32_e32 v50, 0, v50, vcc
	v_cmp_nlt_f32_e32 vcc, s67, v49
	s_nop 1
	v_cndmask_b32_e32 v49, v97, v50, vcc
	v_add_f32_e32 v49, 1.0, v49
	v_rcp_f32_e32 v49, v49
	s_nop 0
	v_fma_f32 v49, v49, -2.0, 1.0
.LBB0_973:
	s_andn2_saveexec_b64 s[30:31], s[30:31]
	v_mul_f32_e32 v49, v48, v48
	v_fmamk_f32 v50, v49, 0xbbbac73d, v96
	v_fmaak_f32 v50, v49, v50, 0xbd5c1c4e
	v_fmaak_f32 v50, v49, v50, 0x3e088382
	v_fmaak_f32 v50, v49, v50, 0xbeaaaa99
	v_mul_f32_e64 v50, |v48|, v50
	v_fma_f32 v49, v49, v50, |v48|
	s_or_b64 exec, exec, s[30:31]
	v_add_f32_e32 v40, v40, v8
	v_add_f32_e32 v41, v41, v9
	s_nop 0
	v_mul_f32_e32 v50, 0x3d372713, v40
	v_mul_f32_e32 v50, v40, v50
	v_fma_f32 v50, v40, v50, v40
	v_mul_f32_e32 v50, 0x3f4c422a, v50
	v_cmp_nlt_f32_e64 s[30:31], |v50|, s61
	s_and_saveexec_b64 s[34:35], s[30:31]
	s_xor_b64 s[30:31], exec, s[34:35]
	s_cbranch_execz .LBB0_977
	v_add_f32_e64 v51, |v50|, |v50|
	v_mul_f32_e32 v52, 0x3fb8aa3b, v51
	v_rndne_f32_e32 v53, v52
	v_sub_f32_e32 v54, v52, v53
	v_fma_f32 v52, v51, s62, -v52
	v_fmac_f32_e32 v52, 0x32a5705f, v51
	v_add_f32_e32 v52, v54, v52
	v_cvt_i32_f32_e32 v53, v53
	v_exp_f32_e32 v52, v52
	v_cmp_ngt_f32_e32 vcc, s63, v51
	v_ldexp_f32 v52, v52, v53
	s_nop 0
	v_cndmask_b32_e32 v52, 0, v52, vcc
	v_cmp_nlt_f32_e32 vcc, s67, v51
	s_nop 1
	v_cndmask_b32_e32 v51, v97, v52, vcc
	v_add_f32_e32 v51, 1.0, v51
	v_rcp_f32_e32 v51, v51
	s_nop 0
	v_fma_f32 v51, v51, -2.0, 1.0
.LBB0_977:
	s_andn2_saveexec_b64 s[30:31], s[30:31]
	v_mul_f32_e32 v51, v50, v50
	v_fmamk_f32 v52, v51, 0xbbbac73d, v96
	v_fmaak_f32 v52, v51, v52, 0xbd5c1c4e
	v_fmaak_f32 v52, v51, v52, 0x3e088382
	v_fmaak_f32 v52, v51, v52, 0xbeaaaa99
	v_mul_f32_e64 v52, |v50|, v52
	v_fma_f32 v51, v51, v52, |v50|
	s_or_b64 exec, exec, s[30:31]
	v_mul_f32_e32 v52, 0x3d372713, v45
	v_mul_f32_e32 v52, v45, v52
	v_fma_f32 v52, v45, v52, v45
	v_mul_f32_e32 v52, 0x3f4c422a, v52
	v_add_f32_e32 v46, v46, v18
	v_add_f32_e32 v47, v47, v19
	v_cmp_nlt_f32_e64 s[30:31], |v52|, s61
	s_and_saveexec_b64 s[34:35], s[30:31]
	s_xor_b64 s[30:31], exec, s[34:35]
	s_cbranch_execz .LBB0_981
	v_add_f32_e64 v53, |v52|, |v52|
	v_mul_f32_e32 v54, 0x3fb8aa3b, v53
	v_rndne_f32_e32 v55, v54
	v_sub_f32_e32 v56, v54, v55
	v_fma_f32 v54, v53, s62, -v54
	v_fmac_f32_e32 v54, 0x32a5705f, v53
	v_add_f32_e32 v54, v56, v54
	v_cvt_i32_f32_e32 v55, v55
	v_exp_f32_e32 v54, v54
	v_cmp_ngt_f32_e32 vcc, s63, v53
	v_ldexp_f32 v54, v54, v55
	s_nop 0
	v_cndmask_b32_e32 v54, 0, v54, vcc
	v_cmp_nlt_f32_e32 vcc, s67, v53
	s_nop 1
	v_cndmask_b32_e32 v53, v97, v54, vcc
	v_add_f32_e32 v53, 1.0, v53
	v_rcp_f32_e32 v53, v53
	s_nop 0
	v_fma_f32 v53, v53, -2.0, 1.0
.LBB0_981:
	s_andn2_saveexec_b64 s[30:31], s[30:31]
	v_mul_f32_e32 v53, v52, v52
	v_fmamk_f32 v54, v53, 0xbbbac73d, v96
	v_fmaak_f32 v54, v53, v54, 0xbd5c1c4e
	v_fmaak_f32 v54, v53, v54, 0x3e088382
	v_fmaak_f32 v54, v53, v54, 0xbeaaaa99
	v_mul_f32_e64 v54, |v52|, v54
	v_fma_f32 v53, v53, v54, |v52|
	s_or_b64 exec, exec, s[30:31]
	v_mul_f32_e32 v54, 0x3d372713, v41
	v_mul_f32_e32 v54, v41, v54
	v_fma_f32 v54, v41, v54, v41
	v_mul_f32_e32 v54, 0x3f4c422a, v54
	v_add_f32_e32 v42, v42, v10
	v_add_f32_e32 v43, v43, v11
	v_cmp_nlt_f32_e64 s[30:31], |v54|, s61
	s_and_saveexec_b64 s[34:35], s[30:31]
	s_xor_b64 s[30:31], exec, s[34:35]
	s_cbranch_execz .LBB0_985
	v_add_f32_e64 v55, |v54|, |v54|
	v_mul_f32_e32 v56, 0x3fb8aa3b, v55
	v_rndne_f32_e32 v57, v56
	v_sub_f32_e32 v58, v56, v57
	v_fma_f32 v56, v55, s62, -v56
	v_fmac_f32_e32 v56, 0x32a5705f, v55
	v_add_f32_e32 v56, v58, v56
	v_cvt_i32_f32_e32 v57, v57
	v_exp_f32_e32 v56, v56
	v_cmp_ngt_f32_e32 vcc, s63, v55
	v_ldexp_f32 v56, v56, v57
	s_nop 0
	v_cndmask_b32_e32 v56, 0, v56, vcc
	v_cmp_nlt_f32_e32 vcc, s67, v55
	s_nop 1
	v_cndmask_b32_e32 v55, v97, v56, vcc
	v_add_f32_e32 v55, 1.0, v55
	v_rcp_f32_e32 v55, v55
	s_nop 0
	v_fma_f32 v55, v55, -2.0, 1.0

.LBB0_1001:
	s_andn2_saveexec_b64 s[30:31], s[30:31]
	v_mul_f32_e32 v63, v62, v62
	v_fmamk_f32 v66, v63, 0xbbbac73d, v96
	v_fmaak_f32 v66, v63, v66, 0xbd5c1c4e
	v_fmaak_f32 v66, v63, v66, 0x3e088382
	v_fmaak_f32 v66, v63, v66, 0xbeaaaa99
	v_mul_f32_e64 v66, |v62|, v66
	v_fma_f32 v63, v63, v66, |v62|
	s_or_b64 exec, exec, s[30:31]
	v_bfi_b32 v48, s68, v49, v48
	v_mul_f32_e32 v44, 0.5, v44
	v_add_f32_e32 v48, 1.0, v48
	v_mul_f32_e32 v44, v44, v48
	v_bfi_b32 v48, s68, v53, v52
	v_mul_f32_e32 v45, 0.5, v45
	v_add_f32_e32 v48, 1.0, v48
	v_mul_f32_e32 v45, v45, v48
	v_bfi_b32 v48, s68, v57, v56
	v_mul_f32_e32 v46, 0.5, v46
	v_add_f32_e32 v48, 1.0, v48
	v_mul_f32_e32 v46, v46, v48
	v_bfi_b32 v48, s68, v61, v60
	v_mul_f32_e32 v47, 0.5, v47
	v_add_f32_e32 v48, 1.0, v48
	v_mul_f32_e32 v47, v47, v48
	v_bfi_b32 v48, s68, v51, v50
	v_mul_f32_e32 v40, 0.5, v40
	v_add_f32_e32 v48, 1.0, v48
	v_mul_f32_e32 v40, v40, v48
	v_bfi_b32 v48, s68, v55, v54
	v_mul_f32_e32 v41, 0.5, v41
	v_add_f32_e32 v48, 1.0, v48
	v_mul_f32_e32 v41, v41, v48
	v_bfi_b32 v48, s68, v59, v58
	v_mul_f32_e32 v42, 0.5, v42
	v_add_f32_e32 v48, 1.0, v48
	v_mul_f32_e32 v42, v42, v48
	v_bfi_b32 v48, s68, v63, v62
	v_mul_f32_e32 v43, 0.5, v43
	v_add_f32_e32 v48, 1.0, v48
	v_mul_f32_e32 v43, v43, v48
	v_or_b32_e32 v48, 48, v64
	v_ashrrev_i32_e32 v49, 31, v48
	v_lshlrev_b64 v[48:49], 9, v[48:49]
	v_lshl_add_u64 v[48:49], s[0:1], 0, v[48:49]
	v_lshl_add_u64 v[48:49], v[48:49], 0, v[80:81]
	v_add_f32_e32 v36, v36, v16
	v_add_f32_e32 v37, v37, v17
	global_store_dwordx4 v[48:49], v[44:47], off
	global_store_dwordx4 v[48:49], v[40:43], off offset:16
	s_nop 1
	v_mul_f32_e32 v40, 0x3d372713, v36
	v_mul_f32_e32 v40, v36, v40
	v_fma_f32 v40, v36, v40, v36
	v_mul_f32_e32 v40, 0x3f4c422a, v40
	v_cmp_nlt_f32_e64 s[30:31], |v40|, s61
	s_and_saveexec_b64 s[34:35], s[30:31]
	s_xor_b64 s[30:31], exec, s[34:35]
	s_cbranch_execz .LBB0_1005
	v_add_f32_e64 v41, |v40|, |v40|
	v_mul_f32_e32 v42, 0x3fb8aa3b, v41
	v_rndne_f32_e32 v43, v42
	v_sub_f32_e32 v44, v42, v43
	v_fma_f32 v42, v41, s62, -v42
	v_fmac_f32_e32 v42, 0x32a5705f, v41
	v_add_f32_e32 v42, v44, v42
	v_cvt_i32_f32_e32 v43, v43
	v_exp_f32_e32 v42, v42
	v_cmp_ngt_f32_e32 vcc, s63, v41
	v_ldexp_f32 v42, v42, v43
	s_nop 0
	v_cndmask_b32_e32 v42, 0, v42, vcc
	v_cmp_nlt_f32_e32 vcc, s67, v41
	s_nop 1
	v_cndmask_b32_e32 v41, v97, v42, vcc
	v_add_f32_e32 v41, 1.0, v41
	v_rcp_f32_e32 v41, v41
	s_nop 0
	v_fma_f32 v41, v41, -2.0, 1.0
.LBB0_1005:
	s_andn2_saveexec_b64 s[30:31], s[30:31]
	v_mul_f32_e32 v41, v40, v40
	v_fmamk_f32 v42, v41, 0xbbbac73d, v96
	v_fmaak_f32 v42, v41, v42, 0xbd5c1c4e
	v_fmaak_f32 v42, v41, v42, 0x3e088382
	v_fmaak_f32 v42, v41, v42, 0xbeaaaa99
	v_mul_f32_e64 v42, |v40|, v42
	v_fma_f32 v41, v41, v42, |v40|
	s_or_b64 exec, exec, s[30:31]
	v_add_f32_e32 v32, v32, v8
	v_add_f32_e32 v33, v33, v9
	s_nop 0
	v_mul_f32_e32 v42, 0x3d372713, v32
	v_mul_f32_e32 v42, v32, v42
	v_fma_f32 v42, v32, v42, v32
	v_mul_f32_e32 v42, 0x3f4c422a, v42
	v_cmp_nlt_f32_e64 s[30:31], |v42|, s61
	s_and_saveexec_b64 s[34:35], s[30:31]
	s_xor_b64 s[30:31], exec, s[34:35]
	s_cbranch_execz .LBB0_1009
	v_add_f32_e64 v43, |v42|, |v42|
	v_mul_f32_e32 v44, 0x3fb8aa3b, v43
	v_rndne_f32_e32 v45, v44
	v_sub_f32_e32 v46, v44, v45
	v_fma_f32 v44, v43, s62, -v44
	v_fmac_f32_e32 v44, 0x32a5705f, v43
	v_add_f32_e32 v44, v46, v44
	v_cvt_i32_f32_e32 v45, v45
	v_exp_f32_e32 v44, v44
	v_cmp_ngt_f32_e32 vcc, s63, v43
	v_ldexp_f32 v44, v44, v45
	s_nop 0
	v_cndmask_b32_e32 v44, 0, v44, vcc
	v_cmp_nlt_f32_e32 vcc, s67, v43
	s_nop 1
	v_cndmask_b32_e32 v43, v97, v44, vcc
	v_add_f32_e32 v43, 1.0, v43
	v_rcp_f32_e32 v43, v43
	s_nop 0
	v_fma_f32 v43, v43, -2.0, 1.0
.LBB0_1009:
	s_andn2_saveexec_b64 s[30:31], s[30:31]
	v_mul_f32_e32 v43, v42, v42
	v_fmamk_f32 v44, v43, 0xbbbac73d, v96
	v_fmaak_f32 v44, v43, v44, 0xbd5c1c4e
	v_fmaak_f32 v44, v43, v44, 0x3e088382
	v_fmaak_f32 v44, v43, v44, 0xbeaaaa99
	v_mul_f32_e64 v44, |v42|, v44
	v_fma_f32 v43, v43, v44, |v42|
	s_or_b64 exec, exec, s[30:31]
	v_mul_f32_e32 v44, 0x3d372713, v37
	v_mul_f32_e32 v44, v37, v44
	v_fma_f32 v44, v37, v44, v37
	v_mul_f32_e32 v44, 0x3f4c422a, v44
	v_add_f32_e32 v38, v38, v18
	v_add_f32_e32 v39, v39, v19
	v_cmp_nlt_f32_e64 s[30:31], |v44|, s61
	s_and_saveexec_b64 s[34:35], s[30:31]
	s_xor_b64 s[30:31], exec, s[34:35]
	s_cbranch_execz .LBB0_1013
	v_add_f32_e64 v45, |v44|, |v44|
	v_mul_f32_e32 v46, 0x3fb8aa3b, v45
	v_rndne_f32_e32 v47, v46
	v_sub_f32_e32 v48, v46, v47
	v_fma_f32 v46, v45, s62, -v46
	v_fmac_f32_e32 v46, 0x32a5705f, v45
	v_add_f32_e32 v46, v48, v46
	v_cvt_i32_f32_e32 v47, v47
	v_exp_f32_e32 v46, v46
	v_cmp_ngt_f32_e32 vcc, s63, v45
	v_ldexp_f32 v46, v46, v47
	s_nop 0
	v_cndmask_b32_e32 v46, 0, v46, vcc
	v_cmp_nlt_f32_e32 vcc, s67, v45
	s_nop 1
	v_cndmask_b32_e32 v45, v97, v46, vcc
	v_add_f32_e32 v45, 1.0, v45
	v_rcp_f32_e32 v45, v45
	s_nop 0
	v_fma_f32 v45, v45, -2.0, 1.0
.LBB0_1013:
	s_andn2_saveexec_b64 s[30:31], s[30:31]
	v_mul_f32_e32 v45, v44, v44
	v_fmamk_f32 v46, v45, 0xbbbac73d, v96
	v_fmaak_f32 v46, v45, v46, 0xbd5c1c4e
	v_fmaak_f32 v46, v45, v46, 0x3e088382
	v_fmaak_f32 v46, v45, v46, 0xbeaaaa99
	v_mul_f32_e64 v46, |v44|, v46
	v_fma_f32 v45, v45, v46, |v44|
	s_or_b64 exec, exec, s[30:31]
	v_mul_f32_e32 v46, 0x3d372713, v33
	v_mul_f32_e32 v46, v33, v46
	v_fma_f32 v46, v33, v46, v33
	v_mul_f32_e32 v46, 0x3f4c422a, v46
	v_add_f32_e32 v34, v34, v10
	v_add_f32_e32 v35, v35, v11
	v_cmp_nlt_f32_e64 s[30:31], |v46|, s61
	s_and_saveexec_b64 s[34:35], s[30:31]
	s_xor_b64 s[30:31], exec, s[34:35]
	s_cbranch_execz .LBB0_1017
	v_add_f32_e64 v47, |v46|, |v46|
	v_mul_f32_e32 v48, 0x3fb8aa3b, v47
	v_rndne_f32_e32 v49, v48
	v_sub_f32_e32 v50, v48, v49
	v_fma_f32 v48, v47, s62, -v48
	v_fmac_f32_e32 v48, 0x32a5705f, v47
	v_add_f32_e32 v48, v50, v48
	v_cvt_i32_f32_e32 v49, v49
	v_exp_f32_e32 v48, v48
	v_cmp_ngt_f32_e32 vcc, s63, v47
	v_ldexp_f32 v48, v48, v49
	s_nop 0
	v_cndmask_b32_e32 v48, 0, v48, vcc
	v_cmp_nlt_f32_e32 vcc, s67, v47
	s_nop 1
	v_cndmask_b32_e32 v47, v97, v48, vcc
	v_add_f32_e32 v47, 1.0, v47
	v_rcp_f32_e32 v47, v47
	s_nop 0
	v_fma_f32 v47, v47, -2.0, 1.0

.LBB0_1033:
	s_andn2_saveexec_b64 s[30:31], s[30:31]
	v_mul_f32_e32 v55, v54, v54
	v_fmamk_f32 v56, v55, 0xbbbac73d, v96
	v_fmaak_f32 v56, v55, v56, 0xbd5c1c4e
	v_fmaak_f32 v56, v55, v56, 0x3e088382
	v_fmaak_f32 v56, v55, v56, 0xbeaaaa99
	v_mul_f32_e64 v56, |v54|, v56
	v_fma_f32 v55, v55, v56, |v54|
	s_or_b64 exec, exec, s[30:31]
	v_bfi_b32 v40, s68, v41, v40
	v_mul_f32_e32 v36, 0.5, v36
	v_add_f32_e32 v40, 1.0, v40
	v_mul_f32_e32 v36, v36, v40
	v_bfi_b32 v40, s68, v45, v44
	v_mul_f32_e32 v37, 0.5, v37
	v_add_f32_e32 v40, 1.0, v40
	v_mul_f32_e32 v37, v37, v40
	v_bfi_b32 v40, s68, v49, v48
	v_mul_f32_e32 v38, 0.5, v38
	v_add_f32_e32 v40, 1.0, v40
	v_mul_f32_e32 v38, v38, v40
	v_bfi_b32 v40, s68, v53, v52
	v_mul_f32_e32 v39, 0.5, v39
	v_add_f32_e32 v40, 1.0, v40
	v_mul_f32_e32 v39, v39, v40
	v_bfi_b32 v40, s68, v43, v42
	v_mul_f32_e32 v32, 0.5, v32
	v_add_f32_e32 v40, 1.0, v40
	v_mul_f32_e32 v32, v32, v40
	v_bfi_b32 v40, s68, v47, v46
	v_mul_f32_e32 v33, 0.5, v33
	v_add_f32_e32 v40, 1.0, v40
	v_mul_f32_e32 v33, v33, v40
	v_bfi_b32 v40, s68, v51, v50
	v_mul_f32_e32 v34, 0.5, v34
	v_add_f32_e32 v40, 1.0, v40
	v_mul_f32_e32 v34, v34, v40
	v_bfi_b32 v40, s68, v55, v54
	v_mul_f32_e32 v35, 0.5, v35
	v_add_f32_e32 v40, 1.0, v40
	v_mul_f32_e32 v35, v35, v40
	v_lshlrev_b64 v[40:41], 9, v[64:65]
	v_lshl_add_u64 v[40:41], s[0:1], 0, v[40:41]
	v_lshl_add_u64 v[40:41], v[40:41], 0, v[80:81]
	v_lshl_add_u64 v[42:43], v[40:41], 0, s[10:11]
	v_add_co_u32_e32 v40, vcc, s49, v40
	v_add_f32_e32 v28, v28, v16
	v_add_f32_e32 v29, v29, v17
	s_nop 0
	v_addc_co_u32_e32 v41, vcc, 0, v41, vcc
	global_store_dwordx4 v[40:41], v[36:39], off
	global_store_dwordx4 v[42:43], v[32:35], off offset:16
	s_nop 1
	v_mul_f32_e32 v32, 0x3d372713, v28
	v_mul_f32_e32 v32, v28, v32
	v_fma_f32 v32, v28, v32, v28
	v_mul_f32_e32 v32, 0x3f4c422a, v32
	v_cmp_nlt_f32_e64 s[30:31], |v32|, s61
	s_and_saveexec_b64 s[34:35], s[30:31]
	s_xor_b64 s[30:31], exec, s[34:35]
	s_cbranch_execz .LBB0_1037
	v_add_f32_e64 v33, |v32|, |v32|
	v_mul_f32_e32 v34, 0x3fb8aa3b, v33
	v_rndne_f32_e32 v35, v34
	v_sub_f32_e32 v36, v34, v35
	v_fma_f32 v34, v33, s62, -v34
	v_fmac_f32_e32 v34, 0x32a5705f, v33
	v_add_f32_e32 v34, v36, v34
	v_cvt_i32_f32_e32 v35, v35
	v_exp_f32_e32 v34, v34
	v_cmp_ngt_f32_e32 vcc, s63, v33
	v_ldexp_f32 v34, v34, v35
	s_nop 0
	v_cndmask_b32_e32 v34, 0, v34, vcc
	v_cmp_nlt_f32_e32 vcc, s67, v33
	s_nop 1
	v_cndmask_b32_e32 v33, v97, v34, vcc
	v_add_f32_e32 v33, 1.0, v33
	v_rcp_f32_e32 v33, v33
	s_nop 0
	v_fma_f32 v33, v33, -2.0, 1.0
.LBB0_1037:
	s_andn2_saveexec_b64 s[30:31], s[30:31]
	v_mul_f32_e32 v33, v32, v32
	v_fmamk_f32 v34, v33, 0xbbbac73d, v96
	v_fmaak_f32 v34, v33, v34, 0xbd5c1c4e
	v_fmaak_f32 v34, v33, v34, 0x3e088382
	v_fmaak_f32 v34, v33, v34, 0xbeaaaa99
	v_mul_f32_e64 v34, |v32|, v34
	v_fma_f32 v33, v33, v34, |v32|
	s_or_b64 exec, exec, s[30:31]
	v_add_f32_e32 v24, v24, v8
	v_add_f32_e32 v25, v25, v9
	s_nop 0
	v_mul_f32_e32 v34, 0x3d372713, v24
	v_mul_f32_e32 v34, v24, v34
	v_fma_f32 v34, v24, v34, v24
	v_mul_f32_e32 v34, 0x3f4c422a, v34
	v_cmp_nlt_f32_e64 s[30:31], |v34|, s61
	s_and_saveexec_b64 s[34:35], s[30:31]
	s_xor_b64 s[30:31], exec, s[34:35]
	s_cbranch_execz .LBB0_1041
	v_add_f32_e64 v35, |v34|, |v34|
	v_mul_f32_e32 v36, 0x3fb8aa3b, v35
	v_rndne_f32_e32 v37, v36
	v_sub_f32_e32 v38, v36, v37
	v_fma_f32 v36, v35, s62, -v36
	v_fmac_f32_e32 v36, 0x32a5705f, v35
	v_add_f32_e32 v36, v38, v36
	v_cvt_i32_f32_e32 v37, v37
	v_exp_f32_e32 v36, v36
	v_cmp_ngt_f32_e32 vcc, s63, v35
	v_ldexp_f32 v36, v36, v37
	s_nop 0
	v_cndmask_b32_e32 v36, 0, v36, vcc
	v_cmp_nlt_f32_e32 vcc, s67, v35
	s_nop 1
	v_cndmask_b32_e32 v35, v97, v36, vcc
	v_add_f32_e32 v35, 1.0, v35
	v_rcp_f32_e32 v35, v35
	s_nop 0
	v_fma_f32 v35, v35, -2.0, 1.0
.LBB0_1041:
	s_andn2_saveexec_b64 s[30:31], s[30:31]
	v_mul_f32_e32 v35, v34, v34
	v_fmamk_f32 v36, v35, 0xbbbac73d, v96
	v_fmaak_f32 v36, v35, v36, 0xbd5c1c4e
	v_fmaak_f32 v36, v35, v36, 0x3e088382
	v_fmaak_f32 v36, v35, v36, 0xbeaaaa99
	v_mul_f32_e64 v36, |v34|, v36
	v_fma_f32 v35, v35, v36, |v34|
	s_or_b64 exec, exec, s[30:31]
	v_mul_f32_e32 v36, 0x3d372713, v29
	v_mul_f32_e32 v36, v29, v36
	v_fma_f32 v36, v29, v36, v29
	v_mul_f32_e32 v36, 0x3f4c422a, v36
	v_add_f32_e32 v30, v30, v18
	v_add_f32_e32 v31, v31, v19
	v_cmp_nlt_f32_e64 s[30:31], |v36|, s61
	s_and_saveexec_b64 s[34:35], s[30:31]
	s_xor_b64 s[30:31], exec, s[34:35]
	s_cbranch_execz .LBB0_1045
	v_add_f32_e64 v37, |v36|, |v36|
	v_mul_f32_e32 v38, 0x3fb8aa3b, v37
	v_rndne_f32_e32 v39, v38
	v_sub_f32_e32 v40, v38, v39
	v_fma_f32 v38, v37, s62, -v38
	v_fmac_f32_e32 v38, 0x32a5705f, v37
	v_add_f32_e32 v38, v40, v38
	v_cvt_i32_f32_e32 v39, v39
	v_exp_f32_e32 v38, v38
	v_cmp_ngt_f32_e32 vcc, s63, v37
	v_ldexp_f32 v38, v38, v39
	s_nop 0
	v_cndmask_b32_e32 v38, 0, v38, vcc
	v_cmp_nlt_f32_e32 vcc, s67, v37
	s_nop 1
	v_cndmask_b32_e32 v37, v97, v38, vcc
	v_add_f32_e32 v37, 1.0, v37
	v_rcp_f32_e32 v37, v37
	s_nop 0
	v_fma_f32 v37, v37, -2.0, 1.0
.LBB0_1045:
	s_andn2_saveexec_b64 s[30:31], s[30:31]
	v_mul_f32_e32 v37, v36, v36
	v_fmamk_f32 v38, v37, 0xbbbac73d, v96
	v_fmaak_f32 v38, v37, v38, 0xbd5c1c4e
	v_fmaak_f32 v38, v37, v38, 0x3e088382
	v_fmaak_f32 v38, v37, v38, 0xbeaaaa99
	v_mul_f32_e64 v38, |v36|, v38
	v_fma_f32 v37, v37, v38, |v36|
	s_or_b64 exec, exec, s[30:31]
	v_mul_f32_e32 v38, 0x3d372713, v25
	v_mul_f32_e32 v38, v25, v38
	v_fma_f32 v38, v25, v38, v25
	v_mul_f32_e32 v38, 0x3f4c422a, v38
	v_add_f32_e32 v26, v26, v10
	v_add_f32_e32 v27, v27, v11
	v_cmp_nlt_f32_e64 s[30:31], |v38|, s61
	s_and_saveexec_b64 s[34:35], s[30:31]
	s_xor_b64 s[30:31], exec, s[34:35]
	s_cbranch_execz .LBB0_1049
	v_add_f32_e64 v39, |v38|, |v38|
	v_mul_f32_e32 v40, 0x3fb8aa3b, v39
	v_rndne_f32_e32 v41, v40
	v_sub_f32_e32 v42, v40, v41
	v_fma_f32 v40, v39, s62, -v40
	v_fmac_f32_e32 v40, 0x32a5705f, v39
	v_add_f32_e32 v40, v42, v40
	v_cvt_i32_f32_e32 v41, v41
	v_exp_f32_e32 v40, v40
	v_cmp_ngt_f32_e32 vcc, s63, v39
	v_ldexp_f32 v40, v40, v41
	s_nop 0
	v_cndmask_b32_e32 v40, 0, v40, vcc
	v_cmp_nlt_f32_e32 vcc, s67, v39
	s_nop 1
	v_cndmask_b32_e32 v39, v97, v40, vcc
	v_add_f32_e32 v39, 1.0, v39
	v_rcp_f32_e32 v39, v39
	s_nop 0
	v_fma_f32 v39, v39, -2.0, 1.0

.LBB0_1065:
	s_andn2_saveexec_b64 s[30:31], s[30:31]
	v_mul_f32_e32 v47, v46, v46
	v_fmamk_f32 v48, v47, 0xbbbac73d, v96
	v_fmaak_f32 v48, v47, v48, 0xbd5c1c4e
	v_fmaak_f32 v48, v47, v48, 0x3e088382
	v_fmaak_f32 v48, v47, v48, 0xbeaaaa99
	v_mul_f32_e64 v48, |v46|, v48
	v_fma_f32 v47, v47, v48, |v46|
	s_or_b64 exec, exec, s[30:31]
	v_bfi_b32 v32, s68, v33, v32
	v_mul_f32_e32 v28, 0.5, v28
	v_add_f32_e32 v32, 1.0, v32
	v_mul_f32_e32 v28, v28, v32
	v_bfi_b32 v32, s68, v37, v36
	v_mul_f32_e32 v29, 0.5, v29
	v_add_f32_e32 v32, 1.0, v32
	v_mul_f32_e32 v29, v29, v32
	v_bfi_b32 v32, s68, v41, v40
	v_mul_f32_e32 v30, 0.5, v30
	v_add_f32_e32 v32, 1.0, v32
	v_mul_f32_e32 v30, v30, v32
	v_bfi_b32 v32, s68, v45, v44
	v_mul_f32_e32 v31, 0.5, v31
	v_add_f32_e32 v32, 1.0, v32
	v_mul_f32_e32 v31, v31, v32
	v_bfi_b32 v32, s68, v35, v34
	v_mul_f32_e32 v24, 0.5, v24
	v_add_f32_e32 v32, 1.0, v32
	v_mul_f32_e32 v24, v24, v32
	v_bfi_b32 v32, s68, v39, v38
	v_mul_f32_e32 v25, 0.5, v25
	v_add_f32_e32 v32, 1.0, v32
	v_mul_f32_e32 v25, v25, v32
	v_bfi_b32 v32, s68, v43, v42
	v_mul_f32_e32 v26, 0.5, v26
	v_add_f32_e32 v32, 1.0, v32
	v_mul_f32_e32 v26, v26, v32
	v_bfi_b32 v32, s68, v47, v46
	v_mul_f32_e32 v27, 0.5, v27
	v_add_f32_e32 v32, 1.0, v32
	v_mul_f32_e32 v27, v27, v32
	v_lshlrev_b64 v[32:33], 9, v[64:65]
	v_lshl_add_u64 v[32:33], s[0:1], 0, v[32:33]
	v_lshl_add_u64 v[32:33], v[32:33], 0, v[80:81]
	v_lshl_add_u64 v[34:35], v[32:33], 0, s[12:13]
	v_add_co_u32_e32 v32, vcc, s50, v32
	v_add_f32_e32 v20, v20, v16
	v_add_f32_e32 v21, v21, v17
	s_nop 0
	v_addc_co_u32_e32 v33, vcc, 0, v33, vcc
	global_store_dwordx4 v[32:33], v[28:31], off
	global_store_dwordx4 v[34:35], v[24:27], off offset:16
	s_nop 1
	v_mul_f32_e32 v24, 0x3d372713, v20
	v_mul_f32_e32 v24, v20, v24
	v_fma_f32 v24, v20, v24, v20
	v_mul_f32_e32 v24, 0x3f4c422a, v24
	v_cmp_nlt_f32_e64 s[30:31], |v24|, s61
	s_and_saveexec_b64 s[34:35], s[30:31]
	s_xor_b64 s[30:31], exec, s[34:35]
	s_cbranch_execz .LBB0_1069
	v_add_f32_e64 v25, |v24|, |v24|
	v_mul_f32_e32 v26, 0x3fb8aa3b, v25
	v_rndne_f32_e32 v27, v26
	v_sub_f32_e32 v28, v26, v27
	v_fma_f32 v26, v25, s62, -v26
	v_fmac_f32_e32 v26, 0x32a5705f, v25
	v_add_f32_e32 v26, v28, v26
	v_cvt_i32_f32_e32 v27, v27
	v_exp_f32_e32 v26, v26
	v_cmp_ngt_f32_e32 vcc, s63, v25
	v_ldexp_f32 v26, v26, v27
	s_nop 0
	v_cndmask_b32_e32 v26, 0, v26, vcc
	v_cmp_nlt_f32_e32 vcc, s67, v25
	s_nop 1
	v_cndmask_b32_e32 v25, v97, v26, vcc
	v_add_f32_e32 v25, 1.0, v25
	v_rcp_f32_e32 v25, v25
	s_nop 0
	v_fma_f32 v25, v25, -2.0, 1.0
.LBB0_1069:
	s_andn2_saveexec_b64 s[30:31], s[30:31]
	v_mul_f32_e32 v25, v24, v24
	v_fmamk_f32 v26, v25, 0xbbbac73d, v96
	v_fmaak_f32 v26, v25, v26, 0xbd5c1c4e
	v_fmaak_f32 v26, v25, v26, 0x3e088382
	v_fmaak_f32 v26, v25, v26, 0xbeaaaa99
	v_mul_f32_e64 v26, |v24|, v26
	v_fma_f32 v25, v25, v26, |v24|
	s_or_b64 exec, exec, s[30:31]
	v_add_f32_e32 v12, v12, v8
	v_add_f32_e32 v13, v13, v9
	s_nop 0
	v_mul_f32_e32 v26, 0x3d372713, v12
	v_mul_f32_e32 v26, v12, v26
	v_fma_f32 v26, v12, v26, v12
	v_mul_f32_e32 v26, 0x3f4c422a, v26
	v_cmp_nlt_f32_e64 s[30:31], |v26|, s61
	s_and_saveexec_b64 s[34:35], s[30:31]
	s_xor_b64 s[30:31], exec, s[34:35]
	s_cbranch_execz .LBB0_1073
	v_add_f32_e64 v27, |v26|, |v26|
	v_mul_f32_e32 v28, 0x3fb8aa3b, v27
	v_rndne_f32_e32 v29, v28
	v_sub_f32_e32 v30, v28, v29
	v_fma_f32 v28, v27, s62, -v28
	v_fmac_f32_e32 v28, 0x32a5705f, v27
	v_add_f32_e32 v28, v30, v28
	v_cvt_i32_f32_e32 v29, v29
	v_exp_f32_e32 v28, v28
	v_cmp_ngt_f32_e32 vcc, s63, v27
	v_ldexp_f32 v28, v28, v29
	s_nop 0
	v_cndmask_b32_e32 v28, 0, v28, vcc
	v_cmp_nlt_f32_e32 vcc, s67, v27
	s_nop 1
	v_cndmask_b32_e32 v27, v97, v28, vcc
	v_add_f32_e32 v27, 1.0, v27
	v_rcp_f32_e32 v27, v27
	s_nop 0
	v_fma_f32 v27, v27, -2.0, 1.0
.LBB0_1073:
	s_andn2_saveexec_b64 s[30:31], s[30:31]
	v_mul_f32_e32 v27, v26, v26
	v_fmamk_f32 v28, v27, 0xbbbac73d, v96
	v_fmaak_f32 v28, v27, v28, 0xbd5c1c4e
	v_fmaak_f32 v28, v27, v28, 0x3e088382
	v_fmaak_f32 v28, v27, v28, 0xbeaaaa99
	v_mul_f32_e64 v28, |v26|, v28
	v_fma_f32 v27, v27, v28, |v26|
	s_or_b64 exec, exec, s[30:31]
	v_mul_f32_e32 v28, 0x3d372713, v21
	v_mul_f32_e32 v28, v21, v28
	v_fma_f32 v28, v21, v28, v21
	v_mul_f32_e32 v28, 0x3f4c422a, v28
	v_add_f32_e32 v22, v22, v18
	v_add_f32_e32 v23, v23, v19
	v_cmp_nlt_f32_e64 s[30:31], |v28|, s61
	s_and_saveexec_b64 s[34:35], s[30:31]
	s_xor_b64 s[30:31], exec, s[34:35]
	s_cbranch_execz .LBB0_1077
	v_add_f32_e64 v29, |v28|, |v28|
	v_mul_f32_e32 v30, 0x3fb8aa3b, v29
	v_rndne_f32_e32 v31, v30
	v_sub_f32_e32 v32, v30, v31
	v_fma_f32 v30, v29, s62, -v30
	v_fmac_f32_e32 v30, 0x32a5705f, v29
	v_add_f32_e32 v30, v32, v30
	v_cvt_i32_f32_e32 v31, v31
	v_exp_f32_e32 v30, v30
	v_cmp_ngt_f32_e32 vcc, s63, v29
	v_ldexp_f32 v30, v30, v31
	s_nop 0
	v_cndmask_b32_e32 v30, 0, v30, vcc
	v_cmp_nlt_f32_e32 vcc, s67, v29
	s_nop 1
	v_cndmask_b32_e32 v29, v97, v30, vcc
	v_add_f32_e32 v29, 1.0, v29
	v_rcp_f32_e32 v29, v29
	s_nop 0
	v_fma_f32 v29, v29, -2.0, 1.0
.LBB0_1077:
	s_andn2_saveexec_b64 s[30:31], s[30:31]
	v_mul_f32_e32 v29, v28, v28
	v_fmamk_f32 v30, v29, 0xbbbac73d, v96
	v_fmaak_f32 v30, v29, v30, 0xbd5c1c4e
	v_fmaak_f32 v30, v29, v30, 0x3e088382
	v_fmaak_f32 v30, v29, v30, 0xbeaaaa99
	v_mul_f32_e64 v30, |v28|, v30
	v_fma_f32 v29, v29, v30, |v28|
	s_or_b64 exec, exec, s[30:31]
	v_mul_f32_e32 v30, 0x3d372713, v13
	v_mul_f32_e32 v30, v13, v30
	v_fma_f32 v30, v13, v30, v13
	v_mul_f32_e32 v30, 0x3f4c422a, v30
	v_add_f32_e32 v14, v14, v10
	v_add_f32_e32 v15, v15, v11
	v_cmp_nlt_f32_e64 s[30:31], |v30|, s61
	s_and_saveexec_b64 s[34:35], s[30:31]
	s_xor_b64 s[30:31], exec, s[34:35]
	s_cbranch_execz .LBB0_1081
	v_add_f32_e64 v31, |v30|, |v30|
	v_mul_f32_e32 v32, 0x3fb8aa3b, v31
	v_rndne_f32_e32 v33, v32
	v_sub_f32_e32 v34, v32, v33
	v_fma_f32 v32, v31, s62, -v32
	v_fmac_f32_e32 v32, 0x32a5705f, v31
	v_add_f32_e32 v32, v34, v32
	v_cvt_i32_f32_e32 v33, v33
	v_exp_f32_e32 v32, v32
	v_cmp_ngt_f32_e32 vcc, s63, v31
	v_ldexp_f32 v32, v32, v33
	s_nop 0
	v_cndmask_b32_e32 v32, 0, v32, vcc
	v_cmp_nlt_f32_e32 vcc, s67, v31
	s_nop 1
	v_cndmask_b32_e32 v31, v97, v32, vcc
	v_add_f32_e32 v31, 1.0, v31
	v_rcp_f32_e32 v31, v31
	s_nop 0
	v_fma_f32 v31, v31, -2.0, 1.0

.LBB0_1097:
	s_andn2_saveexec_b64 s[30:31], s[30:31]
	v_mul_f32_e32 v39, v38, v38
	v_fmamk_f32 v40, v39, 0xbbbac73d, v96
	v_fmaak_f32 v40, v39, v40, 0xbd5c1c4e
	v_fmaak_f32 v40, v39, v40, 0x3e088382
	v_fmaak_f32 v40, v39, v40, 0xbeaaaa99
	v_mul_f32_e64 v40, |v38|, v40
	v_fma_f32 v39, v39, v40, |v38|
	s_or_b64 exec, exec, s[30:31]
	v_bfi_b32 v24, s68, v25, v24
	v_mul_f32_e32 v20, 0.5, v20
	v_add_f32_e32 v24, 1.0, v24
	v_mul_f32_e32 v20, v20, v24
	v_bfi_b32 v24, s68, v29, v28
	v_mul_f32_e32 v21, 0.5, v21
	v_add_f32_e32 v24, 1.0, v24
	v_mul_f32_e32 v21, v21, v24
	v_bfi_b32 v24, s68, v33, v32
	v_mul_f32_e32 v22, 0.5, v22
	v_add_f32_e32 v24, 1.0, v24
	v_mul_f32_e32 v22, v22, v24
	v_bfi_b32 v24, s68, v37, v36
	v_mul_f32_e32 v23, 0.5, v23
	v_add_f32_e32 v24, 1.0, v24
	v_mul_f32_e32 v23, v23, v24
	v_bfi_b32 v24, s68, v27, v26
	v_mul_f32_e32 v12, 0.5, v12
	v_add_f32_e32 v24, 1.0, v24
	v_mul_f32_e32 v12, v12, v24
	v_bfi_b32 v24, s68, v31, v30
	v_mul_f32_e32 v13, 0.5, v13
	v_add_f32_e32 v24, 1.0, v24
	v_mul_f32_e32 v13, v13, v24
	v_bfi_b32 v24, s68, v35, v34
	v_mul_f32_e32 v14, 0.5, v14
	v_add_f32_e32 v24, 1.0, v24
	v_mul_f32_e32 v14, v14, v24
	v_bfi_b32 v24, s68, v39, v38
	v_mul_f32_e32 v15, 0.5, v15
	v_add_f32_e32 v24, 1.0, v24
	v_mul_f32_e32 v15, v15, v24
	v_lshlrev_b64 v[24:25], 9, v[64:65]
	v_lshl_add_u64 v[24:25], s[0:1], 0, v[24:25]
	v_lshl_add_u64 v[24:25], v[24:25], 0, v[80:81]
	v_lshl_add_u64 v[26:27], v[24:25], 0, s[14:15]
	v_add_co_u32_e32 v24, vcc, s51, v24
	v_add_f32_e32 v4, v4, v16
	v_add_f32_e32 v5, v5, v17
	s_nop 0
	v_addc_co_u32_e32 v25, vcc, 0, v25, vcc
	global_store_dwordx4 v[24:25], v[20:23], off
	global_store_dwordx4 v[26:27], v[12:15], off offset:16
	s_nop 1
	v_mul_f32_e32 v12, 0x3d372713, v4
	v_mul_f32_e32 v12, v4, v12
	v_fma_f32 v12, v4, v12, v4
	v_mul_f32_e32 v12, 0x3f4c422a, v12
	v_cmp_nlt_f32_e64 s[30:31], |v12|, s61
	s_and_saveexec_b64 s[34:35], s[30:31]
	s_xor_b64 s[30:31], exec, s[34:35]
	s_cbranch_execz .LBB0_1101
	v_add_f32_e64 v13, |v12|, |v12|
	v_mul_f32_e32 v14, 0x3fb8aa3b, v13
	v_rndne_f32_e32 v15, v14
	v_sub_f32_e32 v16, v14, v15
	v_fma_f32 v14, v13, s62, -v14
	v_fmac_f32_e32 v14, 0x32a5705f, v13
	v_add_f32_e32 v14, v16, v14
	v_cvt_i32_f32_e32 v15, v15
	v_exp_f32_e32 v14, v14
	v_cmp_ngt_f32_e32 vcc, s63, v13
	v_ldexp_f32 v14, v14, v15
	s_nop 0
	v_cndmask_b32_e32 v14, 0, v14, vcc
	v_cmp_nlt_f32_e32 vcc, s67, v13
	s_nop 1
	v_cndmask_b32_e32 v13, v97, v14, vcc
	v_add_f32_e32 v13, 1.0, v13
	v_rcp_f32_e32 v13, v13
	s_nop 0
	v_fma_f32 v13, v13, -2.0, 1.0
.LBB0_1101:
	s_andn2_saveexec_b64 s[30:31], s[30:31]
	v_mul_f32_e32 v13, v12, v12
	v_fmamk_f32 v14, v13, 0xbbbac73d, v96
	v_fmaak_f32 v14, v13, v14, 0xbd5c1c4e
	v_fmaak_f32 v14, v13, v14, 0x3e088382
	v_fmaak_f32 v14, v13, v14, 0xbeaaaa99
	v_mul_f32_e64 v14, |v12|, v14
	v_fma_f32 v13, v13, v14, |v12|
	s_or_b64 exec, exec, s[30:31]
	v_add_f32_e32 v0, v0, v8
	v_add_f32_e32 v1, v1, v9
	s_nop 0
	v_mul_f32_e32 v8, 0x3d372713, v0
	v_mul_f32_e32 v8, v0, v8
	v_fma_f32 v8, v0, v8, v0
	v_mul_f32_e32 v8, 0x3f4c422a, v8
	v_cmp_nlt_f32_e64 s[30:31], |v8|, s61
	s_and_saveexec_b64 s[34:35], s[30:31]
	s_xor_b64 s[30:31], exec, s[34:35]
	s_cbranch_execz .LBB0_1105
	v_add_f32_e64 v9, |v8|, |v8|
	v_mul_f32_e32 v14, 0x3fb8aa3b, v9
	v_rndne_f32_e32 v15, v14
	v_sub_f32_e32 v16, v14, v15
	v_fma_f32 v14, v9, s62, -v14
	v_fmac_f32_e32 v14, 0x32a5705f, v9
	v_add_f32_e32 v14, v16, v14
	v_cvt_i32_f32_e32 v15, v15
	v_exp_f32_e32 v14, v14
	v_cmp_ngt_f32_e32 vcc, s63, v9
	v_ldexp_f32 v14, v14, v15
	s_nop 0
	v_cndmask_b32_e32 v14, 0, v14, vcc
	v_cmp_nlt_f32_e32 vcc, s67, v9
	s_nop 1
	v_cndmask_b32_e32 v9, v97, v14, vcc
	v_add_f32_e32 v9, 1.0, v9
	v_rcp_f32_e32 v9, v9
	s_nop 0
	v_fma_f32 v9, v9, -2.0, 1.0
.LBB0_1105:
	s_andn2_saveexec_b64 s[30:31], s[30:31]
	v_mul_f32_e32 v9, v8, v8
	v_fmamk_f32 v14, v9, 0xbbbac73d, v96
	v_fmaak_f32 v14, v9, v14, 0xbd5c1c4e
	v_fmaak_f32 v14, v9, v14, 0x3e088382
	v_fmaak_f32 v14, v9, v14, 0xbeaaaa99
	v_mul_f32_e64 v14, |v8|, v14
	v_fma_f32 v9, v9, v14, |v8|
	s_or_b64 exec, exec, s[30:31]
	v_mul_f32_e32 v14, 0x3d372713, v5
	v_mul_f32_e32 v14, v5, v14
	v_mov_b32_e32 v15, v5
	v_fmac_f32_e32 v15, v15, v14
	v_mul_f32_e32 v14, 0x3f4c422a, v15
	v_add_f32_e32 v6, v6, v18
	v_add_f32_e32 v7, v7, v19
	v_cmp_nlt_f32_e64 s[30:31], |v14|, s61
	s_and_saveexec_b64 s[34:35], s[30:31]
	s_xor_b64 s[30:31], exec, s[34:35]
	s_cbranch_execz .LBB0_1109
	v_add_f32_e64 v15, |v14|, |v14|
	v_mul_f32_e32 v16, 0x3fb8aa3b, v15
	v_rndne_f32_e32 v17, v16
	v_sub_f32_e32 v18, v16, v17
	v_fma_f32 v16, v15, s62, -v16
	v_fmac_f32_e32 v16, 0x32a5705f, v15
	v_add_f32_e32 v16, v18, v16
	v_cvt_i32_f32_e32 v17, v17
	v_exp_f32_e32 v16, v16
	v_cmp_ngt_f32_e32 vcc, s63, v15
	v_ldexp_f32 v16, v16, v17
	s_nop 0
	v_cndmask_b32_e32 v16, 0, v16, vcc
	v_cmp_nlt_f32_e32 vcc, s67, v15
	s_nop 1
	v_cndmask_b32_e32 v15, v97, v16, vcc
	v_add_f32_e32 v15, 1.0, v15
	v_rcp_f32_e32 v15, v15
	s_nop 0
	v_fma_f32 v15, v15, -2.0, 1.0
.LBB0_1109:
	s_andn2_saveexec_b64 s[30:31], s[30:31]
	v_mul_f32_e32 v15, v14, v14
	v_fmamk_f32 v16, v15, 0xbbbac73d, v96
	v_fmaak_f32 v16, v15, v16, 0xbd5c1c4e
	v_fmaak_f32 v16, v15, v16, 0x3e088382
	v_fmaak_f32 v16, v15, v16, 0xbeaaaa99
	v_mul_f32_e64 v16, |v14|, v16
	v_fma_f32 v15, v15, v16, |v14|
	s_or_b64 exec, exec, s[30:31]
	v_add_f32_e32 v2, v2, v10
	v_add_f32_e32 v3, v3, v11
	v_mul_f32_e32 v10, 0x3d372713, v1
	v_mul_f32_e32 v10, v1, v10
	v_mov_b32_e32 v11, v1
	v_fmac_f32_e32 v11, v11, v10
	v_mul_f32_e32 v10, 0x3f4c422a, v11
	v_cmp_nlt_f32_e64 s[30:31], |v10|, s61
	s_and_saveexec_b64 s[34:35], s[30:31]
	s_xor_b64 s[30:31], exec, s[34:35]
	s_cbranch_execz .LBB0_1113
	v_add_f32_e64 v11, |v10|, |v10|
	v_mul_f32_e32 v16, 0x3fb8aa3b, v11
	v_rndne_f32_e32 v17, v16
	v_sub_f32_e32 v18, v16, v17
	v_fma_f32 v16, v11, s62, -v16
	v_fmac_f32_e32 v16, 0x32a5705f, v11
	v_add_f32_e32 v16, v18, v16
	v_cvt_i32_f32_e32 v17, v17
	v_exp_f32_e32 v16, v16
	v_cmp_ngt_f32_e32 vcc, s63, v11
	v_ldexp_f32 v16, v16, v17
	s_nop 0
	v_cndmask_b32_e32 v16, 0, v16, vcc
	v_cmp_nlt_f32_e32 vcc, s67, v11
	s_nop 1
	v_cndmask_b32_e32 v11, v97, v16, vcc
	v_add_f32_e32 v11, 1.0, v11
	v_rcp_f32_e32 v11, v11
	s_nop 0
	v_fma_f32 v11, v11, -2.0, 1.0

.LBB0_1269:
	ds_bpermute_b32 v0, v155, v121
	v_mov_b32_e32 v123, v32
	v_mov_b32_e32 v125, v32
	v_mov_b32_e32 v127, v32
	v_mov_b32_e32 v129, v32
	s_waitcnt lgkmcnt(0)
	v_add_f32_e32 v0, v121, v0
	v_div_scale_f32 v1, s[0:1], v0, v0, v106
	v_rcp_f32_e32 v2, v1
	s_ashr_i32 s1, s39, 31
	s_add_u32 s0, s46, s39
	s_addc_u32 s1, s47, s1
	v_fma_f32 v3, -v1, v2, 1.0
	v_fmac_f32_e32 v2, v3, v2
	v_div_scale_f32 v3, vcc, v106, v0, v106
	v_mul_f32_e32 v4, v3, v2
	v_fma_f32 v5, -v1, v4, v3
	v_fmac_f32_e32 v4, v5, v2
	v_fma_f32 v1, -v1, v4, v3
	v_div_fmas_f32 v1, v1, v2, v4
	ds_read_b128 v[2:5], v210
	v_div_fixup_f32 v0, v1, v0, v106
	s_or_b64 s[0:1], s[0:1], s[60:61]
	s_lshl_b64 s[0:1], s[0:1], 11
	s_add_u32 s2, s26, s0
	s_waitcnt lgkmcnt(0)
	v_fmac_f32_e32 v2, v64, v0
	v_fmac_f32_e32 v3, v65, v0
	v_fmac_f32_e32 v4, v66, v0
	v_fmac_f32_e32 v5, v67, v0
	v_cvt_pk_bf16_f32 v2, v2, v3
	v_cvt_pk_bf16_f32 v3, v4, v5
	ds_read_b128 v[4:7], v210 offset:1024
	s_addc_u32 s3, s27, s1
	s_lshl_b64 s[0:1], s[48:49], 1
	s_add_u32 s0, s2, s0
	s_addc_u32 s1, s3, s1
	s_waitcnt lgkmcnt(0)
	v_fmac_f32_e32 v4, v68, v0
	v_fmac_f32_e32 v5, v69, v0
	v_mov_b32_e32 v121, v32
	v_cvt_pk_bf16_f32 v8, v4, v5
	v_fma_f32 v4, v70, v0, v6
	v_fma_f32 v5, v71, v0, v7
	s_add_i32 s38, s38, 1
	v_cvt_pk_bf16_f32 v9, v4, v5
	ds_read_b128 v[4:7], v210 offset:2048
	s_cmp_eq_u32 s38, s72
	s_waitcnt lgkmcnt(0)
	v_fmac_f32_e32 v4, v72, v0
	v_fmac_f32_e32 v5, v73, v0
	s_nop 0
	v_cvt_pk_bf16_f32 v10, v4, v5
	v_fma_f32 v4, v74, v0, v6
	v_fma_f32 v5, v75, v0, v7
	s_nop 0
	v_cvt_pk_bf16_f32 v11, v4, v5
	ds_read_b128 v[4:7], v210 offset:3072
	s_waitcnt lgkmcnt(0)
	v_fmac_f32_e32 v4, v76, v0
	v_fmac_f32_e32 v5, v77, v0
	s_nop 0
	v_cvt_pk_bf16_f32 v12, v4, v5
	v_fma_f32 v4, v78, v0, v6
	v_fma_f32 v5, v79, v0, v7
	s_nop 0
	v_cvt_pk_bf16_f32 v13, v4, v5
	ds_read_b128 v[4:7], v210 offset:4096
	s_waitcnt lgkmcnt(0)
	v_fmac_f32_e32 v4, v48, v0
	v_fmac_f32_e32 v5, v49, v0
	s_nop 0
	v_cvt_pk_bf16_f32 v14, v4, v5
	v_fma_f32 v4, v50, v0, v6
	v_fma_f32 v5, v51, v0, v7
	s_nop 0
	v_cvt_pk_bf16_f32 v15, v4, v5
	ds_read_b128 v[4:7], v210 offset:5120
	s_waitcnt lgkmcnt(0)
	v_fmac_f32_e32 v4, v52, v0
	v_fmac_f32_e32 v5, v53, v0
	s_nop 0
	v_cvt_pk_bf16_f32 v16, v4, v5
	v_fma_f32 v4, v54, v0, v6
	v_fma_f32 v5, v55, v0, v7
	s_nop 0
	v_cvt_pk_bf16_f32 v17, v4, v5
	ds_read_b128 v[4:7], v210 offset:6144
	s_waitcnt lgkmcnt(0)
	v_fmac_f32_e32 v4, v56, v0
	v_fmac_f32_e32 v5, v57, v0
	s_nop 0
	v_cvt_pk_bf16_f32 v18, v4, v5
	v_fma_f32 v4, v58, v0, v6
	v_fma_f32 v5, v59, v0, v7
	s_nop 0
	v_cvt_pk_bf16_f32 v19, v4, v5
	ds_read_b128 v[4:7], v210 offset:7168
	s_waitcnt lgkmcnt(0)
	v_fmac_f32_e32 v4, v60, v0
	v_fmac_f32_e32 v5, v61, v0
	v_fma_f32 v1, v63, v0, v7
	v_fma_f32 v0, v62, v0, v6
	v_cvt_pk_bf16_f32 v4, v4, v5
	v_cvt_pk_bf16_f32 v5, v0, v1
	ds_write2_b64 v206, v[2:3], v[8:9] offset1:2
	ds_write2_b64 v206, v[10:11], v[12:13] offset0:4 offset1:6
	ds_write2_b64 v206, v[14:15], v[16:17] offset0:8 offset1:10
	ds_write2_b64 v206, v[18:19], v[4:5] offset0:12 offset1:14
	s_waitcnt lgkmcnt(0)
	ds_read_b128 v[0:3], v207
	v_lshl_add_u64 v[4:5], s[0:1], 0, v[120:121]
	v_lshl_add_u64 v[6:7], v[4:5], 0, v[122:123]
	s_waitcnt lgkmcnt(0)
	global_store_dwordx4 v[6:7], v[0:3], off
	ds_read_b128 v[0:3], v208
	v_lshl_add_u64 v[6:7], v[4:5], 0, v[124:125]
	s_waitcnt lgkmcnt(0)
	global_store_dwordx4 v[6:7], v[0:3], off
	ds_read_b128 v[0:3], v208 offset:1152
	v_lshl_add_u64 v[6:7], v[4:5], 0, v[126:127]
	v_lshl_add_u64 v[4:5], v[4:5], 0, v[128:129]
	s_waitcnt lgkmcnt(0)
	global_store_dwordx4 v[6:7], v[0:3], off
	ds_read_b128 v[0:3], v208 offset:2304
	s_waitcnt lgkmcnt(0)
	global_store_dwordx4 v[4:5], v[0:3], off
	s_cbranch_scc1 .LBB0_1476

.LBB0_1285:
	s_mul_i32 s2, s3, 0x2400
	v_add_u32_e32 v33, s2, v156
	v_add_u32_e32 v42, v33, v157
	ds_read_b128 v[34:37], v42
	ds_read_b128 v[38:41], v42 offset:32
	v_add_u32_e32 v33, v33, v158
	v_mov_b32_e32 v68, v48
	s_lshl_b32 s3, s3, 6
	s_waitcnt lgkmcnt(1)
	v_mfma_f32_32x32x16_bf16 v[50:65], v[34:37], v[80:83], 0
	ds_read_b128 v[34:37], v42 offset:64
	s_waitcnt lgkmcnt(1)
	v_mfma_f32_32x32x16_bf16 v[50:65], v[38:41], v[84:87], v[50:65]
	s_waitcnt lgkmcnt(0)
	v_mfma_f32_32x32x16_bf16 v[50:65], v[34:37], v[88:91], v[50:65]
	ds_read_b128 v[34:37], v42 offset:96
	s_waitcnt lgkmcnt(0)
	v_mfma_f32_32x32x16_bf16 v[50:65], v[34:37], v[92:95], v[50:65]
	ds_read_b128 v[34:37], v33
	ds_read_b128 v[70:73], v33 offset:32
	s_waitcnt lgkmcnt(1)
	v_mfma_f32_32x32x16_bf16 v[34:49], v[34:37], v[80:83], 0
	s_waitcnt lgkmcnt(0)
	v_mfma_f32_32x32x16_bf16 v[34:49], v[70:73], v[84:87], v[34:49]
	ds_read_b128 v[70:73], v33 offset:64
	s_waitcnt lgkmcnt(0)
	v_mfma_f32_32x32x16_bf16 v[34:49], v[70:73], v[88:91], v[34:49]
	ds_read_b128 v[70:73], v33 offset:96
	v_subrev_u32_e32 v33, s3, v159
	v_lshl_add_u32 v33, v33, 4, v66
	v_med3_i32 v33, v33, -1, v209
	v_lshl_add_u32 v33, v33, 2, s69
	ds_read_b32 v69, v33 offset:256
	v_xad_u32 v33, s3, -1, v159
	v_lshl_add_u32 v33, v33, 4, v66
	v_med3_i32 v33, v33, -1, v209
	v_lshl_add_u32 v33, v33, 2, s69
	s_waitcnt lgkmcnt(1)
	v_mfma_f32_32x32x16_bf16 v[34:49], v[70:73], v[92:95], v[34:49]
	ds_read_b32 v70, v33 offset:256
	v_subrev_u32_e32 v33, s3, v160
	v_lshl_add_u32 v33, v33, 4, v66
	v_med3_i32 v33, v33, -1, v209
	v_lshl_add_u32 v33, v33, 2, s69
	ds_read_b32 v71, v33 offset:256
	v_subrev_u32_e32 v33, s3, v161
	v_lshl_add_u32 v33, v33, 4, v66
	v_med3_i32 v33, v33, -1, v209
	v_lshl_add_u32 v33, v33, 2, s69
	ds_read_b32 v72, v33 offset:256
	v_subrev_u32_e32 v33, s3, v162
	v_lshl_add_u32 v33, v33, 4, v66
	v_med3_i32 v33, v33, -1, v209
	v_lshl_add_u32 v33, v33, 2, s69
	ds_read_b32 v75, v33 offset:256
	v_subrev_u32_e32 v33, s3, v163
	v_lshl_add_u32 v33, v33, 4, v66
	v_med3_i32 v33, v33, -1, v209
	v_lshl_add_u32 v33, v33, 2, s69
	ds_read_b32 v73, v33 offset:256
	v_subrev_u32_e32 v33, s3, v164
	v_lshl_add_u32 v33, v33, 4, v66
	v_med3_i32 v33, v33, -1, v209
	v_lshl_add_u32 v33, v33, 2, s69
	ds_read_b32 v74, v33 offset:256
	v_subrev_u32_e32 v33, s3, v165
	v_lshl_add_u32 v33, v33, 4, v66
	v_med3_i32 v33, v33, -1, v209
	v_lshl_add_u32 v33, v33, 2, s69
	ds_read_b32 v76, v33 offset:256
	s_waitcnt lgkmcnt(7)
	v_fmac_f32_e32 v69, 0x3fb8aa3b, v50
	s_waitcnt lgkmcnt(6)
	v_fmac_f32_e32 v70, 0x3fb8aa3b, v51
	v_max3_f32 v33, v69, s70, v70
	s_waitcnt lgkmcnt(5)
	v_fmac_f32_e32 v71, 0x3fb8aa3b, v52
	s_waitcnt lgkmcnt(4)
	v_fmac_f32_e32 v72, 0x3fb8aa3b, v53
	v_max3_f32 v33, v33, v71, v72
	s_waitcnt lgkmcnt(3)
	v_fmac_f32_e32 v75, 0x3fb8aa3b, v54
	s_waitcnt lgkmcnt(2)
	v_fmac_f32_e32 v73, 0x3fb8aa3b, v55
	v_max3_f32 v33, v33, v75, v73
	s_waitcnt lgkmcnt(1)
	v_fmac_f32_e32 v74, 0x3fb8aa3b, v56
	s_waitcnt lgkmcnt(0)
	v_fmac_f32_e32 v76, 0x3fb8aa3b, v57
	v_max3_f32 v33, v33, v74, v76
	v_subrev_u32_e32 v50, s3, v166
	v_subrev_u32_e32 v51, s3, v167
	v_subrev_u32_e32 v53, s3, v169
	v_subrev_u32_e32 v55, s3, v171
	v_lshl_add_u32 v50, v50, 4, v66
	v_lshl_add_u32 v51, v51, 4, v66
	v_subrev_u32_e32 v52, s3, v168
	v_lshl_add_u32 v53, v53, 4, v66
	v_subrev_u32_e32 v54, s3, v170
	v_lshl_add_u32 v55, v55, 4, v66
	v_subrev_u32_e32 v56, s3, v172
	v_subrev_u32_e32 v57, s3, v173
	v_med3_i32 v50, v50, -1, v209
	v_med3_i32 v51, v51, -1, v209
	v_lshl_add_u32 v52, v52, 4, v66
	v_med3_i32 v53, v53, -1, v209
	v_lshl_add_u32 v54, v54, 4, v66
	v_med3_i32 v55, v55, -1, v209
	v_lshl_add_u32 v56, v56, 4, v66
	v_lshl_add_u32 v57, v57, 4, v66
	v_lshl_add_u32 v50, v50, 2, s69
	v_lshl_add_u32 v51, v51, 2, s69
	v_med3_i32 v52, v52, -1, v209
	v_lshl_add_u32 v53, v53, 2, s69
	v_med3_i32 v54, v54, -1, v209
	v_lshl_add_u32 v55, v55, 2, s69
	v_med3_i32 v56, v56, -1, v209
	v_med3_i32 v57, v57, -1, v209
	v_lshl_add_u32 v52, v52, 2, s69
	v_lshl_add_u32 v54, v54, 2, s69
	v_lshl_add_u32 v56, v56, 2, s69
	v_lshl_add_u32 v97, v57, 2, s69
	ds_read_b32 v96, v50 offset:256
	ds_read_b32 v79, v51 offset:256
	ds_read_b32 v78, v52 offset:256
	ds_read_b32 v77, v53 offset:256
	ds_read_b32 v57, v54 offset:256
	ds_read_b32 v55, v55 offset:256
	ds_read_b32 v53, v56 offset:256
	ds_read_b32 v51, v97 offset:256
	s_waitcnt lgkmcnt(7)
	v_fmac_f32_e32 v96, 0x3fb8aa3b, v58
	s_waitcnt lgkmcnt(6)
	v_fmac_f32_e32 v79, 0x3fb8aa3b, v59
	v_max3_f32 v33, v33, v96, v79
	s_waitcnt lgkmcnt(5)
	v_fmac_f32_e32 v78, 0x3fb8aa3b, v60
	s_waitcnt lgkmcnt(4)
	v_fmac_f32_e32 v77, 0x3fb8aa3b, v61
	v_max3_f32 v33, v33, v78, v77
	s_waitcnt lgkmcnt(3)
	v_fmac_f32_e32 v57, 0x3fb8aa3b, v62
	s_waitcnt lgkmcnt(2)
	v_fmac_f32_e32 v55, 0x3fb8aa3b, v63
	v_max3_f32 v33, v33, v57, v55
	s_waitcnt lgkmcnt(1)
	v_fmac_f32_e32 v53, 0x3fb8aa3b, v64
	s_waitcnt lgkmcnt(0)
	v_fmac_f32_e32 v51, 0x3fb8aa3b, v65
	v_max3_f32 v33, v33, v53, v51
	v_subrev_u32_e32 v58, s3, v178
	v_lshl_add_u32 v58, v58, 4, v66
	v_med3_i32 v58, v58, -1, v209
	v_lshl_add_u32 v61, v58, 2, s69
	v_subrev_u32_e32 v58, s3, v179
	v_lshl_add_u32 v58, v58, 4, v66
	v_med3_i32 v58, v58, -1, v209
	v_lshl_add_u32 v63, v58, 2, s69
	v_subrev_u32_e32 v58, s3, v180
	v_lshl_add_u32 v58, v58, 4, v66
	v_subrev_u32_e32 v50, s3, v174
	v_subrev_u32_e32 v52, s3, v175
	v_subrev_u32_e32 v54, s3, v176
	v_subrev_u32_e32 v56, s3, v177
	v_med3_i32 v58, v58, -1, v209
	v_lshl_add_u32 v50, v50, 4, v66
	v_lshl_add_u32 v52, v52, 4, v66
	v_lshl_add_u32 v54, v54, 4, v66
	v_lshl_add_u32 v56, v56, 4, v66
	v_lshl_add_u32 v64, v58, 2, s69
	v_subrev_u32_e32 v58, s3, v181
	v_med3_i32 v50, v50, -1, v209
	v_med3_i32 v52, v52, -1, v209
	v_med3_i32 v54, v54, -1, v209
	v_med3_i32 v56, v56, -1, v209
	v_lshl_add_u32 v58, v58, 4, v66
	v_lshl_add_u32 v50, v50, 2, s69
	v_lshl_add_u32 v52, v52, 2, s69
	v_lshl_add_u32 v54, v54, 2, s69
	v_lshl_add_u32 v56, v56, 2, s69
	v_med3_i32 v58, v58, -1, v209
	v_lshl_add_u32 v65, v58, 2, s69
	ds_read_b32 v62, v50 offset:256
	ds_read_b32 v60, v52 offset:256
	ds_read_b32 v59, v54 offset:256
	ds_read_b32 v58, v56 offset:256
	ds_read_b32 v56, v61 offset:256
	ds_read_b32 v54, v63 offset:256
	ds_read_b32 v52, v64 offset:256
	ds_read_b32 v50, v65 offset:256
	s_waitcnt lgkmcnt(7)
	v_fmac_f32_e32 v62, 0x3fb8aa3b, v34
	s_waitcnt lgkmcnt(6)
	v_fmac_f32_e32 v60, 0x3fb8aa3b, v35
	v_max3_f32 v33, v33, v62, v60
	s_waitcnt lgkmcnt(5)
	v_fmac_f32_e32 v59, 0x3fb8aa3b, v36
	s_waitcnt lgkmcnt(4)
	v_fmac_f32_e32 v58, 0x3fb8aa3b, v37
	v_max3_f32 v33, v33, v59, v58
	s_waitcnt lgkmcnt(3)
	v_fmac_f32_e32 v56, 0x3fb8aa3b, v38
	s_waitcnt lgkmcnt(2)
	v_fmac_f32_e32 v54, 0x3fb8aa3b, v39
	v_max3_f32 v33, v33, v56, v54
	s_waitcnt lgkmcnt(1)
	v_fmac_f32_e32 v52, 0x3fb8aa3b, v40
	s_waitcnt lgkmcnt(0)
	v_fmac_f32_e32 v50, 0x3fb8aa3b, v41
	v_max3_f32 v33, v33, v52, v50
	v_subrev_u32_e32 v39, s3, v187
	v_lshl_add_u32 v39, v39, 4, v66
	v_med3_i32 v39, v39, -1, v209
	v_lshl_add_u32 v63, v39, 2, s69
	v_subrev_u32_e32 v39, s3, v189
	v_lshl_add_u32 v39, v39, 4, v66
	v_subrev_u32_e32 v34, s3, v182
	v_subrev_u32_e32 v35, s3, v183
	v_subrev_u32_e32 v36, s3, v184
	v_subrev_u32_e32 v37, s3, v185
	v_subrev_u32_e32 v38, s3, v186
	v_med3_i32 v39, v39, -1, v209
	v_lshl_add_u32 v34, v34, 4, v66
	v_lshl_add_u32 v35, v35, 4, v66
	v_lshl_add_u32 v36, v36, 4, v66
	v_lshl_add_u32 v37, v37, 4, v66
	v_lshl_add_u32 v38, v38, 4, v66
	v_lshl_add_u32 v64, v39, 2, s69
	v_subrev_u32_e32 v39, s3, v190
	v_med3_i32 v34, v34, -1, v209
	v_med3_i32 v35, v35, -1, v209
	v_med3_i32 v36, v36, -1, v209
	v_med3_i32 v37, v37, -1, v209
	v_med3_i32 v38, v38, -1, v209
	v_lshl_add_u32 v39, v39, 4, v66
	v_lshl_add_u32 v34, v34, 2, s69
	v_lshl_add_u32 v35, v35, 2, s69
	v_lshl_add_u32 v36, v36, 2, s69
	v_lshl_add_u32 v37, v37, 2, s69
	v_lshl_add_u32 v38, v38, 2, s69
	v_med3_i32 v39, v39, -1, v209
	v_lshl_add_u32 v65, v39, 2, s69
	ds_read_b32 v61, v34 offset:256
	ds_read_b32 v41, v35 offset:256
	ds_read_b32 v40, v36 offset:256
	ds_read_b32 v39, v37 offset:256
	ds_read_b32 v38, v38 offset:256
	ds_read_b32 v37, v63 offset:256
	ds_read_b32 v36, v64 offset:256
	ds_read_b32 v35, v65 offset:256
	s_waitcnt lgkmcnt(7)
	v_fmac_f32_e32 v61, 0x3fb8aa3b, v42
	s_waitcnt lgkmcnt(6)
	v_fmac_f32_e32 v41, 0x3fb8aa3b, v43
	v_max3_f32 v33, v33, v61, v41
	s_waitcnt lgkmcnt(5)
	v_fmac_f32_e32 v40, 0x3fb8aa3b, v44
	s_waitcnt lgkmcnt(4)
	v_fmac_f32_e32 v39, 0x3fb8aa3b, v45
	v_max3_f32 v33, v33, v40, v39
	s_waitcnt lgkmcnt(3)
	v_fmac_f32_e32 v38, 0x3fb8aa3b, v46
	s_waitcnt lgkmcnt(2)
	v_fmac_f32_e32 v37, 0x3fb8aa3b, v47
	v_max3_f32 v33, v33, v38, v37
	s_waitcnt lgkmcnt(1)
	v_fmac_f32_e32 v36, 0x3fb8aa3b, v48
	s_waitcnt lgkmcnt(0)
	v_fmac_f32_e32 v35, 0x3fb8aa3b, v49
	v_max3_f32 v33, v33, v36, v35
	ds_bpermute_b32 v34, v155, v33
	s_waitcnt lgkmcnt(0)
	v_max3_f32 v48, v68, v33, v34
	v_cmp_neq_f32_e32 vcc, s70, v48
	s_nop 1
	v_cndmask_b32_e32 v33, 0, v48, vcc
	v_sub_f32_e32 v34, v68, v33
	v_exp_f32_e32 v34, v34
	s_nop 0
	v_cmp_neq_f32_e32 vcc, 1.0, v34
	s_cbranch_vccz .LBB0_1287
	v_mul_f32_e32 v30, v30, v34
	v_mul_f32_e32 v31, v31, v34
	v_mul_f32_e32 v28, v28, v34
	v_mul_f32_e32 v29, v29, v34
	v_mul_f32_e32 v26, v26, v34
	v_mul_f32_e32 v27, v27, v34
	v_mul_f32_e32 v24, v24, v34
	v_mul_f32_e32 v25, v25, v34
	v_mul_f32_e32 v22, v22, v34
	v_mul_f32_e32 v23, v23, v34
	v_mul_f32_e32 v20, v20, v34
	v_mul_f32_e32 v21, v21, v34
	v_mul_f32_e32 v18, v18, v34
	v_mul_f32_e32 v19, v19, v34
	v_mul_f32_e32 v16, v16, v34
	v_mul_f32_e32 v17, v17, v34
	v_mul_f32_e32 v14, v14, v34
	v_mul_f32_e32 v15, v15, v34
	v_mul_f32_e32 v12, v12, v34
	v_mul_f32_e32 v13, v13, v34
	v_mul_f32_e32 v10, v10, v34
	v_mul_f32_e32 v11, v11, v34
	v_mul_f32_e32 v8, v8, v34
	v_mul_f32_e32 v9, v9, v34
	v_mul_f32_e32 v6, v6, v34
	v_mul_f32_e32 v7, v7, v34
	v_mul_f32_e32 v4, v4, v34
	v_mul_f32_e32 v5, v5, v34
	v_mul_f32_e32 v2, v2, v34
	v_mul_f32_e32 v3, v3, v34
	v_mul_f32_e32 v0, v0, v34
	v_mul_f32_e32 v1, v1, v34

.LBB0_1289:
	ds_bpermute_b32 v34, v155, v35
	s_waitcnt lgkmcnt(0)
	v_add_f32_e32 v34, v35, v34
	v_div_scale_f32 v35, s[2:3], v34, v34, 1.0
	v_rcp_f32_e32 v36, v35
	v_div_scale_f32 v37, vcc, 1.0, v34, 1.0
	v_fma_f32 v38, -v35, v36, 1.0
	v_fmac_f32_e32 v36, v38, v36
	v_mul_f32_e32 v38, v37, v36
	v_fma_f32 v39, -v35, v38, v37
	v_fmac_f32_e32 v38, v39, v36
	v_fma_f32 v35, -v35, v38, v37
	v_div_fmas_f32 v35, v35, v36, v38
	v_div_fixup_f32 v35, v35, v34, 1.0
	v_cmp_lt_f32_e32 vcc, 0, v34
	s_nop 1
	v_cndmask_b32_e32 v34, 0, v35, vcc
	v_mul_f32_e32 v36, v104, v34
	v_mul_f32_e32 v0, v0, v36
	v_mul_f32_e32 v1, v1, v36
	v_mul_f32_e32 v2, v2, v36
	v_mul_f32_e32 v3, v3, v36
	v_mul_f32_e32 v16, v16, v36
	v_mul_f32_e32 v17, v17, v36
	v_mul_f32_e32 v18, v18, v36
	v_mul_f32_e32 v19, v19, v36
	ds_write_b128 v210, v[0:3] offset:4096
	v_mul_f32_e32 v0, v4, v36
	v_mul_f32_e32 v1, v5, v36
	v_mul_f32_e32 v2, v6, v36
	v_mul_f32_e32 v3, v7, v36
	ds_write_b128 v210, v[16:19]
	v_mul_f32_e32 v16, v24, v36
	v_mul_f32_e32 v17, v25, v36
	v_mul_f32_e32 v18, v26, v36
	v_mul_f32_e32 v19, v27, v36
	ds_write_b128 v210, v[0:3] offset:5120
	v_mul_f32_e32 v0, v8, v36
	v_mul_f32_e32 v1, v9, v36
	v_mul_f32_e32 v2, v10, v36
	v_mul_f32_e32 v3, v11, v36
	v_mul_f32_e32 v20, v20, v36
	v_mul_f32_e32 v21, v21, v36
	v_mul_f32_e32 v22, v22, v36
	v_mul_f32_e32 v23, v23, v36
	ds_write_b128 v210, v[16:19] offset:2048
	v_mul_f32_e32 v16, v28, v36
	v_mul_f32_e32 v17, v29, v36
	v_mul_f32_e32 v18, v30, v36
	v_mul_f32_e32 v19, v31, v36
	ds_write_b128 v210, v[0:3] offset:6144
	v_mul_f32_e32 v0, v12, v36
	v_mul_f32_e32 v1, v13, v36
	v_mul_f32_e32 v2, v14, v36
	v_mul_f32_e32 v3, v15, v36
	s_andn2_b64 vcc, exec, s[30:31]
	ds_write_b128 v210, v[20:23] offset:1024
	ds_write_b128 v210, v[16:19] offset:3072
	ds_write_b128 v210, v[0:3] offset:7168
	s_cbranch_vccnz .LBB0_1292
	v_mov_b32_e32 v35, 0
	s_mov_b32 s2, 0
	s_mov_b64 s[30:31], -1

.LBB0_1296:
	s_andn2_b64 vcc, exec, s[2:3]
	s_cbranch_vccnz .LBB0_1449
	v_add_u32_e32 v14, 0x9000, v109
	v_add_u32_e32 v2, 0xb100, v109
	ds_read2_b32 v[0:1], v14 offset1:1
	ds_read2_b32 v[2:3], v2 offset1:1
	v_add_u32_e32 v4, 0xd200, v109
	v_add_u32_e32 v6, 0xf300, v109
	ds_read2_b32 v[4:5], v4 offset1:1
	ds_read2_b32 v[6:7], v6 offset1:1
	v_add_u32_e32 v15, 0x9008, v109
	v_add_u32_e32 v8, 0xb108, v109
	v_add_u32_e32 v10, 0xd208, v109
	v_add_u32_e32 v12, 0xf308, v109
	s_waitcnt lgkmcnt(2)
	v_add_f32_e32 v0, v0, v2
	v_add_f32_e32 v1, v1, v3
	ds_read2_b32 v[2:3], v15 offset1:1
	ds_read2_b32 v[8:9], v8 offset1:1
	ds_read2_b32 v[10:11], v10 offset1:1
	ds_read2_b32 v[12:13], v12 offset1:1
	s_waitcnt lgkmcnt(4)
	v_add_f32_e32 v4, v4, v6
	v_add_f32_e32 v5, v5, v7
	v_add_u32_e32 v6, 0x9034, v192
	v_add_f32_e32 v0, v0, v4
	v_add_f32_e32 v1, v1, v5
	ds_write2_b32 v14, v0, v1 offset1:1
	s_waitcnt lgkmcnt(3)
	v_add_f32_e32 v0, v2, v8
	v_add_f32_e32 v1, v3, v9
	s_waitcnt lgkmcnt(1)
	v_add_f32_e32 v2, v10, v12
	v_add_f32_e32 v3, v11, v13
	v_add_u32_e32 v4, 0x9024, v192
	v_add_f32_e32 v0, v0, v2
	v_add_f32_e32 v1, v1, v3
	ds_write2_b32 v15, v0, v1 offset1:1
	v_add_u32_e32 v0, 0x9004, v192
	s_waitcnt lgkmcnt(0)
	s_barrier
	v_add_u32_e32 v1, 0x900c, v192
	v_add_u32_e32 v2, 0x9014, v192
	v_add_u32_e32 v3, 0x901c, v192
	v_add_u32_e32 v5, 0x902c, v192
	ds_read2_b32 v[26:27], v0 offset1:1
	ds_read2_b32 v[22:23], v1 offset1:1
	ds_read2_b32 v[20:21], v2 offset1:1
	ds_read_b32 v30, v109 offset:36864
	ds_read2_b32 v[18:19], v3 offset1:1
	ds_read2_b32 v[14:15], v4 offset1:1
	ds_read2_b32 v[12:13], v5 offset1:1
	ds_read2_b32 v[10:11], v6 offset1:1
	s_cmp_lg_u32 s45, 16
	s_waitcnt lgkmcnt(4)
	v_cmp_eq_f32_e64 s[0:1], v26, v30
	s_cselect_b64 s[34:35], -1, 0
	v_cmp_gt_f32_e32 vcc, v26, v30
	s_and_b64 s[2:3], s[0:1], s[10:11]
	v_cmp_eq_f32_e64 s[30:31], v27, v30
	v_cmp_gt_f32_e64 s[0:1], v27, v30
	s_and_b64 s[6:7], s[30:31], s[10:11]
	s_or_b64 s[2:3], vcc, s[2:3]
	v_cmp_eq_f32_e64 s[30:31], v22, v30
	v_cndmask_b32_e64 v31, 0, 1, s[2:3]
	v_cndmask_b32_e64 v33, 1, 2, s[2:3]
	s_or_b64 vcc, s[0:1], s[6:7]
	v_cmp_gt_f32_e64 s[0:1], v22, v30
	s_and_b64 s[2:3], s[30:31], s[10:11]
	v_cmp_eq_f32_e64 s[30:31], v23, v30
	s_or_b64 s[2:3], s[0:1], s[2:3]
	v_cmp_gt_f32_e64 s[0:1], v23, v30
	s_and_b64 s[6:7], s[30:31], s[12:13]
	v_cmp_eq_f32_e64 s[30:31], v20, v30
	s_or_b64 s[6:7], s[0:1], s[6:7]
	v_cmp_gt_f32_e64 s[0:1], v20, v30
	s_and_b64 s[8:9], s[30:31], s[12:13]
	v_cmp_eq_f32_e64 s[30:31], v21, v30
	s_or_b64 s[8:9], s[0:1], s[8:9]
	v_cmp_gt_f32_e64 s[0:1], v21, v30
	s_and_b64 s[28:29], s[30:31], s[12:13]
	s_waitcnt lgkmcnt(3)
	v_cmp_eq_f32_e64 s[30:31], v18, v30
	s_or_b64 s[28:29], s[0:1], s[28:29]
	v_cmp_gt_f32_e64 s[0:1], v18, v30
	s_and_b64 s[30:31], s[30:31], s[12:13]
	s_or_b64 s[36:37], s[0:1], s[30:31]
	v_cmp_eq_f32_e64 s[30:31], v19, v30
	v_cmp_gt_f32_e64 s[0:1], v19, v30
	s_and_b64 s[30:31], s[30:31], s[14:15]
	s_or_b64 s[52:53], s[0:1], s[30:31]
	s_waitcnt lgkmcnt(2)
	v_cmp_eq_f32_e64 s[30:31], v14, v30
	v_cmp_gt_f32_e64 s[0:1], v14, v30
	s_and_b64 s[30:31], s[30:31], s[14:15]
	s_or_b64 s[54:55], s[0:1], s[30:31]
	v_cmp_eq_f32_e64 s[30:31], v15, v30
	v_cmp_gt_f32_e64 s[0:1], v15, v30
	s_and_b64 s[30:31], s[30:31], s[14:15]
	s_mov_b32 s20, s33
	s_mov_b32 s33, s19
	s_mov_b64 s[18:19], s[24:25]
	s_mov_b64 s[24:25], s[26:27]
	s_mov_b64 s[26:27], s[74:75]
	s_mov_b64 s[74:75], s[56:57]
	s_or_b64 s[56:57], s[0:1], s[30:31]
	s_waitcnt lgkmcnt(1)
	v_cmp_eq_f32_e64 s[30:31], v12, v30
	v_cmp_gt_f32_e64 s[0:1], v12, v30
	s_and_b64 s[30:31], s[30:31], s[14:15]
	s_mov_b64 s[42:43], s[58:59]
	v_add_u32_e32 v0, 0x903c, v192
	s_or_b64 s[58:59], s[0:1], s[30:31]
	v_cmp_eq_f32_e64 s[30:31], v13, v30
	v_add_u32_e32 v1, 0x9044, v192
	v_add_u32_e32 v2, 0x904c, v192
	v_writelane_b32 v234, s46, 55
	v_cmp_gt_f32_e64 s[0:1], v13, v30
	s_and_b64 s[30:31], s[30:31], s[16:17]
	v_add_u32_e32 v3, 0x9054, v192
	ds_read2_b32 v[28:29], v0 offset1:1
	ds_read2_b32 v[24:25], v1 offset1:1
	ds_read2_b32 v[16:17], v2 offset1:1
	ds_read2_b32 v[8:9], v3 offset1:1
	v_add_u32_e32 v0, 0x905c, v192
	v_add_u32_e32 v1, 0x9064, v192
	v_add_u32_e32 v2, 0x906c, v192
	v_add_u32_e32 v34, 0x9074, v192
	v_writelane_b32 v234, s47, 56
	s_mov_b64 s[46:47], s[22:23]
	s_mov_b64 s[22:23], s[60:61]
	s_or_b64 s[60:61], s[0:1], s[30:31]
	s_waitcnt lgkmcnt(4)
	v_cmp_eq_f32_e64 s[30:31], v10, v30
	ds_read2_b32 v[6:7], v0 offset1:1
	ds_read2_b32 v[4:5], v1 offset1:1
	ds_read2_b32 v[2:3], v2 offset1:1
	ds_read2_b32 v[0:1], v34 offset1:1
	v_cndmask_b32_e32 v31, v31, v33, vcc
	v_cndmask_b32_e64 v33, 0, 1, s[2:3]
	v_cndmask_b32_e64 v34, 0, 1, s[6:7]
	v_cmp_gt_f32_e64 s[0:1], v10, v30
	s_and_b64 s[30:31], s[30:31], s[16:17]
	v_add3_u32 v31, v31, v33, v34
	v_cndmask_b32_e64 v33, 0, 1, s[8:9]
	v_cndmask_b32_e64 v34, 0, 1, s[28:29]
	s_or_b64 s[62:63], s[0:1], s[30:31]
	v_cmp_eq_f32_e64 s[30:31], v11, v30
	v_add3_u32 v31, v31, v33, v34
	v_cndmask_b32_e64 v33, 0, 1, s[36:37]
	v_cndmask_b32_e64 v34, 0, 1, s[52:53]
	v_cmp_gt_f32_e64 s[0:1], v11, v30
	s_and_b64 s[30:31], s[30:31], s[16:17]
	v_add3_u32 v31, v31, v33, v34
	v_cndmask_b32_e64 v33, 0, 1, s[54:55]
	v_cndmask_b32_e64 v34, 0, 1, s[56:57]
	s_or_b64 s[0:1], s[0:1], s[30:31]
	v_add3_u32 v31, v31, v33, v34
	v_cndmask_b32_e64 v33, 0, 1, s[58:59]
	v_cndmask_b32_e64 v34, 0, 1, s[60:61]
	v_add3_u32 v31, v31, v33, v34
	v_cndmask_b32_e64 v33, 0, 1, s[62:63]
	v_cndmask_b32_e64 v34, 0, 1, s[0:1]
	s_cmp_eq_u32 s45, 16
	v_add3_u32 v31, v31, v33, v34
	s_cbranch_scc1 .LBB0_1333
	s_waitcnt lgkmcnt(7)
	v_cmp_eq_f32_e64 s[0:1], v28, v30
	v_cmp_gt_f32_e32 vcc, v28, v30
	s_and_b64 s[0:1], s[0:1], s[16:17]
	s_or_b64 s[0:1], vcc, s[0:1]
	v_cndmask_b32_e64 v33, 0, 1, s[0:1]
	v_add_u32_e32 v31, v31, v33
	s_cmp_gt_u32 s45, 17
	s_cselect_b64 s[36:37], -1, 0
	s_cmp_lt_u32 s45, 18
	s_cbranch_scc0 .LBB0_1334

.LBB0_1453:
	s_cmp_lg_u32 s6, s2
	s_cbranch_scc1 .LBB0_1455
	ds_bpermute_b32 v0, v155, v121
	v_mov_b32_e32 v46, v32
	v_mov_b32_e32 v47, v32
	v_mov_b32_e32 v33, v32
	v_mov_b32_e32 v34, v32
	s_waitcnt lgkmcnt(0)
	v_add_f32_e32 v0, v121, v0
	v_div_scale_f32 v1, s[0:1], v0, v0, v105
	v_rcp_f32_e32 v2, v1
	v_mov_b32_e32 v35, v32
	v_mov_b32_e32 v36, v32
	v_mov_b32_e32 v37, v32
	v_fma_f32 v3, -v1, v2, 1.0
	v_fmac_f32_e32 v2, v3, v2
	v_div_scale_f32 v3, vcc, v105, v0, v105
	v_mul_f32_e32 v4, v3, v2
	v_fma_f32 v5, -v1, v4, v3
	v_fmac_f32_e32 v4, v5, v2
	v_fma_f32 v1, -v1, v4, v3
	v_div_fmas_f32 v1, v1, v2, v4
	ds_read_b128 v[2:5], v210
	v_div_fixup_f32 v0, v1, v0, v105
	v_mov_b32_e32 v38, v32
	v_mov_b32_e32 v39, v32
	v_mov_b32_e32 v40, v32
	s_waitcnt lgkmcnt(0)
	v_fmac_f32_e32 v2, v64, v0
	v_fmac_f32_e32 v3, v65, v0
	v_fmac_f32_e32 v4, v66, v0
	v_fmac_f32_e32 v5, v67, v0
	ds_write_b128 v210, v[2:5]
	ds_read_b128 v[2:5], v210 offset:1024
	v_mov_b32_e32 v41, v32
	v_mov_b32_e32 v42, v32
	v_mov_b32_e32 v43, v32
	v_mov_b32_e32 v44, v32
	s_waitcnt lgkmcnt(0)
	v_fmac_f32_e32 v2, v68, v0
	v_fmac_f32_e32 v3, v69, v0
	v_fmac_f32_e32 v4, v70, v0
	v_fmac_f32_e32 v5, v71, v0
	ds_write_b128 v210, v[2:5] offset:1024
	ds_read_b128 v[2:5], v210 offset:2048
	v_mov_b32_e32 v45, v32
	v_mov_b32_e32 v121, 0
	v_mov_b32_e32 v123, 0xff800000
	s_waitcnt lgkmcnt(0)
	v_fmac_f32_e32 v2, v72, v0
	v_fmac_f32_e32 v3, v73, v0
	v_fmac_f32_e32 v4, v74, v0
	v_fmac_f32_e32 v5, v75, v0
	ds_write_b128 v210, v[2:5] offset:2048
	ds_read_b128 v[2:5], v210 offset:3072
	s_waitcnt lgkmcnt(0)
	v_fmac_f32_e32 v2, v76, v0
	v_fmac_f32_e32 v3, v77, v0
	v_fmac_f32_e32 v4, v78, v0
	v_fmac_f32_e32 v5, v79, v0
	ds_write_b128 v210, v[2:5] offset:3072
	ds_read_b128 v[2:5], v210 offset:4096
	v_mov_b64_e32 v[78:79], v[46:47]
	v_mov_b64_e32 v[76:77], v[44:45]
	v_mov_b64_e32 v[74:75], v[42:43]
	v_mov_b64_e32 v[72:73], v[40:41]
	s_waitcnt lgkmcnt(0)
	v_fmac_f32_e32 v2, v48, v0
	v_fmac_f32_e32 v3, v49, v0
	v_fmac_f32_e32 v4, v50, v0
	v_fmac_f32_e32 v5, v51, v0
	ds_write_b128 v210, v[2:5] offset:4096
	ds_read_b128 v[2:5], v210 offset:5120
	v_mov_b64_e32 v[70:71], v[38:39]
	v_mov_b64_e32 v[68:69], v[36:37]
	v_mov_b64_e32 v[66:67], v[34:35]
	v_mov_b64_e32 v[64:65], v[32:33]
	s_waitcnt lgkmcnt(0)
	v_fmac_f32_e32 v2, v52, v0
	v_fmac_f32_e32 v3, v53, v0
	v_fmac_f32_e32 v4, v54, v0
	v_fmac_f32_e32 v5, v55, v0
	ds_write_b128 v210, v[2:5] offset:5120
	ds_read_b128 v[2:5], v210 offset:6144
	s_waitcnt lgkmcnt(0)
	v_fmac_f32_e32 v2, v56, v0
	v_fmac_f32_e32 v3, v57, v0
	v_fmac_f32_e32 v4, v58, v0
	v_fmac_f32_e32 v5, v59, v0
	ds_write_b128 v210, v[2:5] offset:6144
	ds_read_b128 v[2:5], v210 offset:7168
	s_waitcnt lgkmcnt(0)
	v_fmac_f32_e32 v2, v60, v0
	v_fmac_f32_e32 v3, v61, v0
	v_fmac_f32_e32 v4, v62, v0
	v_fmac_f32_e32 v5, v63, v0
	v_mov_b64_e32 v[62:63], v[46:47]
	v_mov_b64_e32 v[60:61], v[44:45]
	v_mov_b64_e32 v[58:59], v[42:43]
	v_mov_b64_e32 v[56:57], v[40:41]
	v_mov_b64_e32 v[54:55], v[38:39]
	v_mov_b64_e32 v[52:53], v[36:37]
	v_mov_b64_e32 v[50:51], v[34:35]
	v_mov_b64_e32 v[48:49], v[32:33]
	ds_write_b128 v210, v[2:5] offset:7168

.LBB0_1551:
	ds_read_b128 v[128:131], v190
	ds_read_b128 v[132:135], v190 offset:1024
	ds_read_b128 v[136:139], v190 offset:2048
	ds_read_b128 v[140:143], v190 offset:3072
	s_add_u32 s22, s20, 0xfffc0080
	s_addc_u32 s23, s21, -1
	s_cmp_eq_u32 s51, 12
	s_cselect_b32 s29, s13, s23
	s_cselect_b32 s28, s19, s22
	s_cselect_b32 s23, s11, s50
	s_cselect_b32 s22, s48, s49
	v_lshl_add_u64 v[184:185], s[20:21], 0, v[160:161]
	s_add_i32 m0, s36, 0xc000
	ds_read_b128 v[144:147], v191
	ds_read_b128 v[148:151], v191 offset:1024
	ds_read_b128 v[168:171], v191 offset:2048
	ds_read_b128 v[172:175], v191 offset:3072
	ds_read_b128 v[176:179], v191 offset:4096
	ds_read_b128 v[180:183], v191 offset:5120
	ds_read_b128 v[194:197], v191 offset:6144
	ds_read_b128 v[198:201], v191 offset:7168
	global_load_lds_dwordx4 v[184:185], off
	v_lshl_add_u64 v[184:185], s[20:21], 0, v[162:163]
	s_add_i32 m0, s36, 0xe000
	s_nop 0
	global_load_lds_dwordx4 v[184:185], off
	s_waitcnt lgkmcnt(8)
	s_barrier
	s_waitcnt lgkmcnt(0)
	s_setprio 1
	s_waitcnt lgkmcnt(0)
	v_mfma_f32_16x16x32_bf16 v[124:127], v[128:131], v[144:147], v[124:127]
	v_mfma_f32_16x16x32_bf16 v[120:123], v[136:139], v[144:147], v[120:123]
	v_mfma_f32_16x16x32_bf16 v[108:111], v[128:131], v[168:171], v[108:111]
	v_mfma_f32_16x16x32_bf16 v[104:107], v[136:139], v[168:171], v[104:107]
	v_mfma_f32_16x16x32_bf16 v[92:95], v[128:131], v[176:179], v[92:95]
	v_mfma_f32_16x16x32_bf16 v[88:91], v[136:139], v[176:179], v[88:91]
	v_mfma_f32_16x16x32_bf16 v[76:79], v[128:131], v[194:197], v[76:79]
	v_mfma_f32_16x16x32_bf16 v[72:75], v[136:139], v[194:197], v[72:75]
	v_mfma_f32_16x16x32_bf16 v[124:127], v[132:135], v[148:151], v[124:127]
	v_mfma_f32_16x16x32_bf16 v[120:123], v[140:143], v[148:151], v[120:123]
	v_mfma_f32_16x16x32_bf16 v[108:111], v[132:135], v[172:175], v[108:111]
	v_mfma_f32_16x16x32_bf16 v[104:107], v[140:143], v[172:175], v[104:107]
	v_mfma_f32_16x16x32_bf16 v[92:95], v[132:135], v[180:183], v[92:95]
	v_mfma_f32_16x16x32_bf16 v[88:91], v[140:143], v[180:183], v[88:91]
	v_mfma_f32_16x16x32_bf16 v[76:79], v[132:135], v[198:201], v[76:79]
	v_mfma_f32_16x16x32_bf16 v[72:75], v[140:143], v[198:201], v[72:75]
	s_setprio 0
	s_barrier
	s_add_i32 s52, s45, s35
	v_lshl_add_u64 v[184:185], s[22:23], 0, v[154:155]
	s_mov_b32 m0, s52
	ds_read_b128 v[202:205], v192
	ds_read_b128 v[206:209], v192 offset:1024
	ds_read_b128 v[210:213], v192 offset:2048
	ds_read_b128 v[214:217], v192 offset:3072
	global_load_lds_dwordx4 v[184:185], off
	v_lshl_add_u64 v[218:219], s[22:23], 0, v[158:159]
	s_add_i32 m0, s52, 0x2000
	s_nop 0
	global_load_lds_dwordx4 v[218:219], off
	s_barrier
	s_waitcnt lgkmcnt(0)
	s_setprio 1
	s_waitcnt lgkmcnt(0)
	v_mfma_f32_16x16x32_bf16 v[116:119], v[202:205], v[144:147], v[116:119]
	v_mfma_f32_16x16x32_bf16 v[112:115], v[210:213], v[144:147], v[112:115]
	v_mfma_f32_16x16x32_bf16 v[100:103], v[202:205], v[168:171], v[100:103]
	v_mfma_f32_16x16x32_bf16 v[96:99], v[210:213], v[168:171], v[96:99]
	v_mfma_f32_16x16x32_bf16 v[84:87], v[202:205], v[176:179], v[84:87]
	v_mfma_f32_16x16x32_bf16 v[80:83], v[210:213], v[176:179], v[80:83]
	v_mfma_f32_16x16x32_bf16 v[68:71], v[202:205], v[194:197], v[68:71]
	v_mfma_f32_16x16x32_bf16 v[64:67], v[210:213], v[194:197], v[64:67]
	v_mfma_f32_16x16x32_bf16 v[116:119], v[206:209], v[148:151], v[116:119]
	v_mfma_f32_16x16x32_bf16 v[112:115], v[214:217], v[148:151], v[112:115]
	v_mfma_f32_16x16x32_bf16 v[100:103], v[206:209], v[172:175], v[100:103]
	v_mfma_f32_16x16x32_bf16 v[96:99], v[214:217], v[172:175], v[96:99]
	v_mfma_f32_16x16x32_bf16 v[84:87], v[206:209], v[180:183], v[84:87]
	v_mfma_f32_16x16x32_bf16 v[80:83], v[214:217], v[180:183], v[80:83]
	v_mfma_f32_16x16x32_bf16 v[68:71], v[206:209], v[198:201], v[68:71]
	v_mfma_f32_16x16x32_bf16 v[64:67], v[214:217], v[198:201], v[64:67]
	s_setprio 0
	s_mov_b32 m0, s36
	v_lshl_add_u64 v[220:221], s[28:29], 0, v[152:153]
	s_barrier
	ds_read_b128 v[144:147], v191 offset:16384
	ds_read_b128 v[148:151], v191 offset:17408
	ds_read_b128 v[168:171], v191 offset:18432
	ds_read_b128 v[172:175], v191 offset:19456
	ds_read_b128 v[176:179], v191 offset:20480
	ds_read_b128 v[180:183], v191 offset:21504
	ds_read_b128 v[194:197], v191 offset:22528
	ds_read_b128 v[198:201], v191 offset:23552
	global_load_lds_dwordx4 v[220:221], off
	v_lshl_add_u64 v[222:223], s[28:29], 0, v[156:157]
	s_mov_b32 m0, s37
	s_nop 0
	global_load_lds_dwordx4 v[222:223], off
	s_barrier
	s_waitcnt lgkmcnt(0)
	s_setprio 1
	s_waitcnt lgkmcnt(0)
	v_mfma_f32_16x16x32_bf16 v[60:63], v[128:131], v[144:147], v[60:63]
	v_mfma_f32_16x16x32_bf16 v[56:59], v[136:139], v[144:147], v[56:59]
	v_mfma_f32_16x16x32_bf16 v[44:47], v[128:131], v[168:171], v[44:47]
	v_mfma_f32_16x16x32_bf16 v[40:43], v[136:139], v[168:171], v[40:43]
	v_mfma_f32_16x16x32_bf16 v[28:31], v[128:131], v[176:179], v[28:31]
	v_mfma_f32_16x16x32_bf16 v[24:27], v[136:139], v[176:179], v[24:27]
	v_mfma_f32_16x16x32_bf16 v[12:15], v[128:131], v[194:197], v[12:15]
	v_mfma_f32_16x16x32_bf16 v[8:11], v[136:139], v[194:197], v[8:11]
	v_mfma_f32_16x16x32_bf16 v[60:63], v[132:135], v[148:151], v[60:63]
	v_mfma_f32_16x16x32_bf16 v[56:59], v[140:143], v[148:151], v[56:59]
	v_mfma_f32_16x16x32_bf16 v[44:47], v[132:135], v[172:175], v[44:47]
	v_mfma_f32_16x16x32_bf16 v[40:43], v[140:143], v[172:175], v[40:43]
	v_mfma_f32_16x16x32_bf16 v[28:31], v[132:135], v[180:183], v[28:31]
	v_mfma_f32_16x16x32_bf16 v[24:27], v[140:143], v[180:183], v[24:27]
	v_mfma_f32_16x16x32_bf16 v[12:15], v[132:135], v[198:201], v[12:15]
	v_mfma_f32_16x16x32_bf16 v[8:11], v[140:143], v[198:201], v[8:11]
	s_setprio 0
	s_barrier
	s_add_u32 s52, s22, 0x40000
	s_addc_u32 s53, s23, 0
	s_add_i32 s54, s46, s35
	v_lshl_add_u64 v[128:129], s[52:53], 0, v[154:155]
	s_mov_b32 m0, s54
	s_nop 0
	global_load_lds_dwordx4 v[128:129], off
	v_lshl_add_u64 v[128:129], s[52:53], 0, v[158:159]
	s_add_i32 m0, s54, 0x2000
	s_nop 0
	global_load_lds_dwordx4 v[128:129], off
	s_waitcnt vmcnt(6)
	s_barrier
	s_setprio 1
	v_mfma_f32_16x16x32_bf16 v[52:55], v[202:205], v[144:147], v[52:55]
	v_mfma_f32_16x16x32_bf16 v[48:51], v[210:213], v[144:147], v[48:51]
	v_mfma_f32_16x16x32_bf16 v[36:39], v[202:205], v[168:171], v[36:39]
	v_mfma_f32_16x16x32_bf16 v[32:35], v[210:213], v[168:171], v[32:35]
	v_mfma_f32_16x16x32_bf16 v[20:23], v[202:205], v[176:179], v[20:23]
	v_mfma_f32_16x16x32_bf16 v[16:19], v[210:213], v[176:179], v[16:19]
	v_mfma_f32_16x16x32_bf16 v[4:7], v[202:205], v[194:197], v[4:7]
	v_mfma_f32_16x16x32_bf16 v[0:3], v[210:213], v[194:197], v[0:3]
	v_mfma_f32_16x16x32_bf16 v[52:55], v[206:209], v[148:151], v[52:55]
	v_mfma_f32_16x16x32_bf16 v[48:51], v[214:217], v[148:151], v[48:51]
	v_mfma_f32_16x16x32_bf16 v[36:39], v[206:209], v[172:175], v[36:39]
	v_mfma_f32_16x16x32_bf16 v[32:35], v[214:217], v[172:175], v[32:35]
	v_mfma_f32_16x16x32_bf16 v[20:23], v[206:209], v[180:183], v[20:23]
	v_mfma_f32_16x16x32_bf16 v[16:19], v[214:217], v[180:183], v[16:19]
	v_mfma_f32_16x16x32_bf16 v[4:7], v[206:209], v[198:201], v[4:7]
	v_mfma_f32_16x16x32_bf16 v[0:3], v[214:217], v[198:201], v[0:3]
	s_setprio 0
	s_add_i32 s52, 0, 0x18000
	v_add_u32_e32 v140, s52, v187
	s_barrier
	ds_read_b128 v[128:131], v140
	ds_read_b128 v[132:135], v140 offset:1024
	ds_read_b128 v[136:139], v140 offset:2048
	ds_read_b128 v[140:143], v140 offset:3072
	s_add_u32 s28, s28, 0x40000
	s_addc_u32 s29, s29, 0
	s_mov_b32 m0, s38
	v_lshl_add_u64 v[202:203], s[28:29], 0, v[152:153]
	ds_read_b128 v[144:147], v191 offset:32768
	ds_read_b128 v[148:151], v191 offset:33792
	ds_read_b128 v[168:171], v191 offset:34816
	ds_read_b128 v[172:175], v191 offset:35840
	ds_read_b128 v[176:179], v191 offset:36864
	ds_read_b128 v[180:183], v191 offset:37888
	ds_read_b128 v[194:197], v191 offset:38912
	ds_read_b128 v[198:201], v191 offset:39936
	global_load_lds_dwordx4 v[202:203], off
	v_lshl_add_u64 v[202:203], s[28:29], 0, v[156:157]
	s_mov_b32 m0, s39
	s_nop 0
	global_load_lds_dwordx4 v[202:203], off
	s_waitcnt lgkmcnt(8)
	s_barrier
	s_waitcnt lgkmcnt(0)
	s_setprio 1
	s_waitcnt lgkmcnt(0)
	v_mfma_f32_16x16x32_bf16 v[124:127], v[128:131], v[144:147], v[124:127]
	v_mfma_f32_16x16x32_bf16 v[120:123], v[136:139], v[144:147], v[120:123]
	v_mfma_f32_16x16x32_bf16 v[108:111], v[128:131], v[168:171], v[108:111]
	v_mfma_f32_16x16x32_bf16 v[104:107], v[136:139], v[168:171], v[104:107]
	v_mfma_f32_16x16x32_bf16 v[92:95], v[128:131], v[176:179], v[92:95]
	v_mfma_f32_16x16x32_bf16 v[88:91], v[136:139], v[176:179], v[88:91]
	v_mfma_f32_16x16x32_bf16 v[76:79], v[128:131], v[194:197], v[76:79]
	v_mfma_f32_16x16x32_bf16 v[72:75], v[136:139], v[194:197], v[72:75]
	v_mfma_f32_16x16x32_bf16 v[124:127], v[132:135], v[148:151], v[124:127]
	v_mfma_f32_16x16x32_bf16 v[120:123], v[140:143], v[148:151], v[120:123]
	v_mfma_f32_16x16x32_bf16 v[108:111], v[132:135], v[172:175], v[108:111]
	v_mfma_f32_16x16x32_bf16 v[104:107], v[140:143], v[172:175], v[104:107]
	v_mfma_f32_16x16x32_bf16 v[92:95], v[132:135], v[180:183], v[92:95]
	v_mfma_f32_16x16x32_bf16 v[88:91], v[140:143], v[180:183], v[88:91]
	v_mfma_f32_16x16x32_bf16 v[76:79], v[132:135], v[198:201], v[76:79]
	v_mfma_f32_16x16x32_bf16 v[72:75], v[140:143], v[198:201], v[72:75]
	s_setprio 0
	s_barrier
	s_add_i32 s28, 0, 0x1c000
	s_add_i32 s29, s52, s35
	v_add_u32_e32 v214, s28, v187
	v_lshl_add_u64 v[184:185], v[184:185], 0, s[8:9]
	s_mov_b32 m0, s29
	ds_read_b128 v[202:205], v214
	ds_read_b128 v[206:209], v214 offset:1024
	ds_read_b128 v[210:213], v214 offset:2048
	ds_read_b128 v[214:217], v214 offset:3072
	global_load_lds_dwordx4 v[184:185], off
	v_lshl_add_u64 v[184:185], v[218:219], 0, s[8:9]
	s_add_i32 m0, s29, 0x2000
	s_nop 0
	global_load_lds_dwordx4 v[184:185], off
	s_barrier
	s_waitcnt lgkmcnt(0)
	s_setprio 1
	s_waitcnt lgkmcnt(0)
	v_mfma_f32_16x16x32_bf16 v[116:119], v[202:205], v[144:147], v[116:119]
	v_mfma_f32_16x16x32_bf16 v[112:115], v[210:213], v[144:147], v[112:115]
	v_mfma_f32_16x16x32_bf16 v[100:103], v[202:205], v[168:171], v[100:103]
	v_mfma_f32_16x16x32_bf16 v[96:99], v[210:213], v[168:171], v[96:99]
	v_mfma_f32_16x16x32_bf16 v[84:87], v[202:205], v[176:179], v[84:87]
	v_mfma_f32_16x16x32_bf16 v[80:83], v[210:213], v[176:179], v[80:83]
	v_mfma_f32_16x16x32_bf16 v[68:71], v[202:205], v[194:197], v[68:71]
	v_mfma_f32_16x16x32_bf16 v[64:67], v[210:213], v[194:197], v[64:67]
	v_mfma_f32_16x16x32_bf16 v[116:119], v[206:209], v[148:151], v[116:119]
	v_mfma_f32_16x16x32_bf16 v[112:115], v[214:217], v[148:151], v[112:115]
	v_mfma_f32_16x16x32_bf16 v[100:103], v[206:209], v[172:175], v[100:103]
	v_mfma_f32_16x16x32_bf16 v[96:99], v[214:217], v[172:175], v[96:99]
	v_mfma_f32_16x16x32_bf16 v[84:87], v[206:209], v[180:183], v[84:87]
	v_mfma_f32_16x16x32_bf16 v[80:83], v[214:217], v[180:183], v[80:83]
	v_mfma_f32_16x16x32_bf16 v[68:71], v[206:209], v[198:201], v[68:71]
	v_mfma_f32_16x16x32_bf16 v[64:67], v[214:217], v[198:201], v[64:67]
	s_setprio 0
	s_mov_b32 m0, s41
	v_lshl_add_u64 v[184:185], v[220:221], 0, s[8:9]
	s_barrier
	ds_read_b128 v[144:147], v191 offset:49152
	ds_read_b128 v[148:151], v191 offset:50176
	ds_read_b128 v[168:171], v191 offset:51200
	ds_read_b128 v[172:175], v191 offset:52224
	ds_read_b128 v[176:179], v191 offset:53248
	ds_read_b128 v[180:183], v191 offset:54272
	ds_read_b128 v[194:197], v191 offset:55296
	ds_read_b128 v[198:201], v191 offset:56320
	global_load_lds_dwordx4 v[184:185], off
	v_lshl_add_u64 v[184:185], v[222:223], 0, s[8:9]
	s_mov_b32 m0, s42
	s_nop 0
	global_load_lds_dwordx4 v[184:185], off
	s_barrier
	s_waitcnt lgkmcnt(0)
	s_setprio 1
	s_waitcnt lgkmcnt(0)
	v_mfma_f32_16x16x32_bf16 v[60:63], v[128:131], v[144:147], v[60:63]
	v_mfma_f32_16x16x32_bf16 v[56:59], v[136:139], v[144:147], v[56:59]
	v_mfma_f32_16x16x32_bf16 v[44:47], v[128:131], v[168:171], v[44:47]
	v_mfma_f32_16x16x32_bf16 v[40:43], v[136:139], v[168:171], v[40:43]
	v_mfma_f32_16x16x32_bf16 v[28:31], v[128:131], v[176:179], v[28:31]
	v_mfma_f32_16x16x32_bf16 v[24:27], v[136:139], v[176:179], v[24:27]
	v_mfma_f32_16x16x32_bf16 v[12:15], v[128:131], v[194:197], v[12:15]
	v_mfma_f32_16x16x32_bf16 v[8:11], v[136:139], v[194:197], v[8:11]
	v_mfma_f32_16x16x32_bf16 v[60:63], v[132:135], v[148:151], v[60:63]
	v_mfma_f32_16x16x32_bf16 v[56:59], v[140:143], v[148:151], v[56:59]
	v_mfma_f32_16x16x32_bf16 v[44:47], v[132:135], v[172:175], v[44:47]
	v_mfma_f32_16x16x32_bf16 v[40:43], v[140:143], v[172:175], v[40:43]
	v_mfma_f32_16x16x32_bf16 v[28:31], v[132:135], v[180:183], v[28:31]
	v_mfma_f32_16x16x32_bf16 v[24:27], v[140:143], v[180:183], v[24:27]
	v_mfma_f32_16x16x32_bf16 v[12:15], v[132:135], v[198:201], v[12:15]
	v_mfma_f32_16x16x32_bf16 v[8:11], v[140:143], v[198:201], v[8:11]
	s_setprio 0
	s_barrier
	s_add_u32 s22, s22, 0x40080
	s_addc_u32 s23, s23, 0
	s_add_i32 s28, s28, s35
	v_lshl_add_u64 v[128:129], s[22:23], 0, v[154:155]
	s_mov_b32 m0, s28
	s_nop 0
	global_load_lds_dwordx4 v[128:129], off
	v_lshl_add_u64 v[128:129], s[22:23], 0, v[158:159]
	s_add_i32 m0, s28, 0x2000
	s_nop 0
	global_load_lds_dwordx4 v[128:129], off
	s_waitcnt vmcnt(6)
	s_barrier
	s_setprio 1
	v_mfma_f32_16x16x32_bf16 v[52:55], v[202:205], v[144:147], v[52:55]
	v_mfma_f32_16x16x32_bf16 v[48:51], v[210:213], v[144:147], v[48:51]
	v_mfma_f32_16x16x32_bf16 v[36:39], v[202:205], v[168:171], v[36:39]
	v_mfma_f32_16x16x32_bf16 v[32:35], v[210:213], v[168:171], v[32:35]
	v_mfma_f32_16x16x32_bf16 v[20:23], v[202:205], v[176:179], v[20:23]
	v_mfma_f32_16x16x32_bf16 v[16:19], v[210:213], v[176:179], v[16:19]
	v_mfma_f32_16x16x32_bf16 v[4:7], v[202:205], v[194:197], v[4:7]
	v_mfma_f32_16x16x32_bf16 v[0:3], v[210:213], v[194:197], v[0:3]
	v_mfma_f32_16x16x32_bf16 v[52:55], v[206:209], v[148:151], v[52:55]
	v_mfma_f32_16x16x32_bf16 v[48:51], v[214:217], v[148:151], v[48:51]
	v_mfma_f32_16x16x32_bf16 v[36:39], v[206:209], v[172:175], v[36:39]
	v_mfma_f32_16x16x32_bf16 v[32:35], v[214:217], v[172:175], v[32:35]
	v_mfma_f32_16x16x32_bf16 v[20:23], v[206:209], v[180:183], v[20:23]
	v_mfma_f32_16x16x32_bf16 v[16:19], v[214:217], v[180:183], v[16:19]
	v_mfma_f32_16x16x32_bf16 v[4:7], v[206:209], v[198:201], v[4:7]
	v_mfma_f32_16x16x32_bf16 v[0:3], v[214:217], v[198:201], v[0:3]
	s_setprio 0
	s_add_i32 s51, s51, 2
	s_add_u32 s20, s20, 0x100
	s_addc_u32 s21, s21, 0
	s_add_u32 s49, s49, 0x100
	s_addc_u32 s50, s50, 0
	s_cmp_gt_u32 s51, 13
	s_barrier
	s_cbranch_scc0 .LBB0_1551
	v_lshl_or_b32 v168, s6, 8, v189
	v_lshl_add_u32 v170, s18, 8, v186
	v_ashrrev_i32_e32 v169, 31, v168
	v_lshlrev_b64 v[202:203], 1, v[168:169]
	v_ashrrev_i32_e32 v171, 31, v170
	v_or_b32_e32 v182, 16, v170
	v_lshl_add_u64 v[172:173], s[64:65], 0, v[202:203]
	v_lshlrev_b64 v[204:205], 11, v[170:171]
	v_ashrrev_i32_e32 v183, 31, v182
	v_or_b32_e32 v178, 32, v170
	v_lshl_add_u64 v[128:129], v[172:173], 0, v[204:205]
	v_lshlrev_b64 v[184:185], 11, v[182:183]
	v_ashrrev_i32_e32 v179, 31, v178
	v_or_b32_e32 v174, 48, v170
	global_load_dwordx4 v[194:197], v[128:129], off
	global_load_dwordx4 v[198:201], v[128:129], off offset:256
	v_lshl_add_u64 v[128:129], v[172:173], 0, v[184:185]
	v_lshlrev_b64 v[180:181], 11, v[178:179]
	v_ashrrev_i32_e32 v175, 31, v174
	global_load_dwordx4 v[148:151], v[128:129], off
	global_load_dwordx4 v[144:147], v[128:129], off offset:256
	v_lshl_add_u64 v[128:129], v[172:173], 0, v[180:181]
	v_lshlrev_b64 v[176:177], 11, v[174:175]
	global_load_dwordx4 v[140:143], v[128:129], off
	global_load_dwordx4 v[136:139], v[128:129], off offset:256
	v_lshl_add_u64 v[128:129], v[172:173], 0, v[176:177]
	global_load_dwordx4 v[132:135], v[128:129], off
	s_nop 0
	global_load_dwordx4 v[128:131], v[128:129], off offset:256
	s_lshl_b32 s18, s6, 2
	s_ashr_i32 s19, s18, 31
	v_add_u32_e32 v252, 0x80, v170
	v_ashrrev_i32_e32 v253, 31, v252
	v_lshlrev_b64 v[252:253], 11, v[252:253]
	v_lshl_add_u64 v[252:253], v[172:173], 0, v[252:253]
	global_load_dwordx4 v[236:239], v[252:253], off
	global_load_dwordx4 v[240:243], v[252:253], off offset:256
	v_add_u32_e32 v252, 0x90, v170
	v_ashrrev_i32_e32 v253, 31, v252
	v_lshlrev_b64 v[252:253], 11, v[252:253]
	v_lshl_add_u64 v[252:253], v[172:173], 0, v[252:253]
	global_load_dwordx4 v[244:247], v[252:253], off
	global_load_dwordx4 v[248:251], v[252:253], off offset:256
	v_add_u32_e32 v252, 0xa0, v170
	v_ashrrev_i32_e32 v253, 31, v252
	v_lshlrev_b64 v[252:253], 11, v[252:253]
	v_lshl_add_u64 v[252:253], v[172:173], 0, v[252:253]
	global_load_dwordx4 v[210:213], v[252:253], off
	global_load_dwordx4 v[214:217], v[252:253], off offset:256
	s_waitcnt vmcnt(6)
	v_lshlrev_b32_e32 v206, 16, v194
	v_and_b32_e32 v207, 0xffff0000, v194
	v_lshlrev_b32_e32 v194, 16, v195
	v_and_b32_e32 v195, 0xffff0000, v195
	v_lshlrev_b32_e32 v208, 16, v196
	v_and_b32_e32 v209, 0xffff0000, v196
	v_lshlrev_b32_e32 v196, 16, v197
	v_and_b32_e32 v197, 0xffff0000, v197
	v_add_f32_e32 v126, v126, v194
	v_add_f32_e32 v127, v127, v195
	v_add_f32_e32 v124, v124, v206
	v_add_f32_e32 v125, v125, v207
	v_add_f32_e32 v194, v122, v196
	v_add_f32_e32 v195, v123, v197
	v_add_f32_e32 v122, v120, v208
	v_add_f32_e32 v123, v121, v209
	v_mul_f32_e32 v120, v125, v125
	v_mul_f32_e32 v121, v127, v127
	v_fmac_f32_e32 v120, v124, v124
	v_fmac_f32_e32 v121, v126, v126
	v_add_f32_e32 v120, v120, v121
	v_mul_f32_e32 v121, v123, v123
	v_mul_f32_e32 v196, v195, v195
	v_fmac_f32_e32 v121, v122, v122
	v_fmac_f32_e32 v196, v194, v194
	v_add_f32_e32 v121, v121, v196
	v_add_f32_e32 v206, v120, v121
	v_cvt_pk_bf16_f32 v120, v124, v125
	v_cvt_pk_bf16_f32 v121, v126, v127
	v_lshlrev_b32_e32 v124, 16, v198
	v_and_b32_e32 v125, 0xffff0000, v198
	v_lshlrev_b32_e32 v126, 16, v199
	v_and_b32_e32 v127, 0xffff0000, v199
	v_cvt_pk_bf16_f32 v122, v122, v123
	v_cvt_pk_bf16_f32 v123, v194, v195
	v_lshlrev_b32_e32 v194, 16, v200
	v_and_b32_e32 v195, 0xffff0000, v200
	v_add_f32_e32 v118, v118, v126
	v_add_f32_e32 v119, v119, v127
	v_add_f32_e32 v116, v116, v124
	v_add_f32_e32 v117, v117, v125
	v_lshlrev_b32_e32 v196, 16, v201
	v_and_b32_e32 v197, 0xffff0000, v201
	v_add_f32_e32 v126, v112, v194
	v_add_f32_e32 v127, v113, v195
	v_mul_f32_e32 v112, v117, v117
	v_mul_f32_e32 v113, v119, v119
	v_add_f32_e32 v124, v114, v196
	v_add_f32_e32 v125, v115, v197
	v_fmac_f32_e32 v112, v116, v116
	v_fmac_f32_e32 v113, v118, v118
	v_add_f32_e32 v112, v112, v113
	v_mul_f32_e32 v113, v127, v127
	v_mul_f32_e32 v114, v125, v125
	v_fmac_f32_e32 v113, v126, v126
	v_fmac_f32_e32 v114, v124, v124
	v_add_f32_e32 v113, v113, v114
	v_add_f32_e32 v112, v112, v113
	v_and_b32_e32 v114, 64, v193
	v_add_f32_e32 v113, v206, v112
	v_xor_b32_e32 v112, 16, v193
	v_add_u32_e32 v196, 64, v114
	v_cmp_lt_i32_e32 vcc, v112, v196
	v_lshl_add_u64 v[114:115], s[64:65], 0, v[204:205]
	v_lshl_add_u64 v[194:195], v[114:115], 0, v[202:203]
	v_cndmask_b32_e32 v112, v193, v112, vcc
	v_lshlrev_b32_e32 v112, 2, v112
	ds_bpermute_b32 v197, v112, v113
	global_store_dwordx4 v[194:195], v[120:123], off
	v_cvt_pk_bf16_f32 v116, v116, v117
	v_cvt_pk_bf16_f32 v117, v118, v119
	v_cvt_pk_bf16_f32 v118, v126, v127
	s_waitcnt lgkmcnt(0)
	v_add_f32_e32 v114, v113, v197
	v_xor_b32_e32 v113, 32, v193
	v_cmp_lt_i32_e32 vcc, v113, v196
	v_cvt_pk_bf16_f32 v119, v124, v125
	global_store_dwordx4 v[194:195], v[116:119], off offset:256
	s_nop 0
	v_cndmask_b32_e32 v113, v193, v113, vcc
	v_lshlrev_b32_e32 v113, 2, v113
	ds_bpermute_b32 v115, v113, v114
	s_and_saveexec_b64 s[20:21], s[2:3]
	s_cbranch_execz .LBB0_1554
	s_waitcnt lgkmcnt(0)
	v_add_f32_e32 v116, v114, v115
	v_lshlrev_b64 v[114:115], 6, v[170:171]
	v_lshl_add_u64 v[114:115], s[74:75], 0, v[114:115]
	v_lshl_add_u64 v[114:115], s[18:19], 2, v[114:115]
	s_lshl_b32 s6, s40, 2
	v_lshl_add_u64 v[114:115], v[114:115], 0, s[6:7]
	global_store_dword v[114:115], v116, off
.LBB0_1554:
	s_or_b64 exec, exec, s[20:21]
	v_lshlrev_b32_e32 v114, 16, v148
	s_waitcnt lgkmcnt(0)
	v_and_b32_e32 v115, 0xffff0000, v148
	v_lshlrev_b32_e32 v116, 16, v149
	v_and_b32_e32 v117, 0xffff0000, v149
	v_lshlrev_b32_e32 v118, 16, v150
	v_and_b32_e32 v119, 0xffff0000, v150
	v_lshlrev_b32_e32 v120, 16, v151
	v_and_b32_e32 v121, 0xffff0000, v151
	v_add_f32_e32 v110, v110, v116
	v_add_f32_e32 v111, v111, v117
	v_add_f32_e32 v108, v108, v114
	v_add_f32_e32 v109, v109, v115
	v_add_f32_e32 v114, v106, v120
	v_add_f32_e32 v115, v107, v121
	v_add_f32_e32 v106, v104, v118
	v_add_f32_e32 v107, v105, v119
	v_mul_f32_e32 v104, v109, v109
	v_mul_f32_e32 v105, v111, v111
	v_fmac_f32_e32 v104, v108, v108
	v_fmac_f32_e32 v105, v110, v110
	v_add_f32_e32 v104, v104, v105
	v_mul_f32_e32 v105, v107, v107
	v_mul_f32_e32 v116, v115, v115
	v_fmac_f32_e32 v105, v106, v106
	v_fmac_f32_e32 v116, v114, v114
	v_add_f32_e32 v105, v105, v116
	v_add_f32_e32 v118, v104, v105
	v_cvt_pk_bf16_f32 v104, v108, v109
	v_cvt_pk_bf16_f32 v105, v110, v111
	v_lshlrev_b32_e32 v108, 16, v144
	v_and_b32_e32 v109, 0xffff0000, v144
	v_lshlrev_b32_e32 v110, 16, v145
	v_and_b32_e32 v111, 0xffff0000, v145
	v_cvt_pk_bf16_f32 v106, v106, v107
	v_cvt_pk_bf16_f32 v107, v114, v115
	v_lshlrev_b32_e32 v114, 16, v146
	v_and_b32_e32 v115, 0xffff0000, v146
	v_add_f32_e32 v102, v102, v110
	v_add_f32_e32 v103, v103, v111
	v_add_f32_e32 v100, v100, v108
	v_add_f32_e32 v101, v101, v109
	v_lshlrev_b32_e32 v116, 16, v147
	v_and_b32_e32 v117, 0xffff0000, v147
	v_add_f32_e32 v110, v96, v114
	v_add_f32_e32 v111, v97, v115
	v_mul_f32_e32 v96, v101, v101
	v_mul_f32_e32 v97, v103, v103
	v_add_f32_e32 v108, v98, v116
	v_add_f32_e32 v109, v99, v117
	v_fmac_f32_e32 v96, v100, v100
	v_fmac_f32_e32 v97, v102, v102
	v_add_f32_e32 v96, v96, v97
	v_mul_f32_e32 v97, v111, v111
	v_mul_f32_e32 v98, v109, v109
	v_fmac_f32_e32 v97, v110, v110
	v_fmac_f32_e32 v98, v108, v108
	v_add_f32_e32 v97, v97, v98
	v_add_f32_e32 v96, v96, v97
	v_add_f32_e32 v99, v118, v96
	ds_bpermute_b32 v116, v112, v99
	v_lshl_add_u64 v[96:97], s[64:65], 0, v[184:185]
	v_lshl_add_u64 v[114:115], v[168:169], 1, v[96:97]
	global_store_dwordx4 v[114:115], v[104:107], off
	v_cvt_pk_bf16_f32 v98, v100, v101
	s_waitcnt lgkmcnt(0)
	v_add_f32_e32 v96, v99, v116
	ds_bpermute_b32 v97, v113, v96
	v_cvt_pk_bf16_f32 v99, v102, v103
	v_cvt_pk_bf16_f32 v100, v110, v111
	v_cvt_pk_bf16_f32 v101, v108, v109
	global_store_dwordx4 v[114:115], v[98:101], off offset:256
	s_and_saveexec_b64 s[20:21], s[2:3]
	s_cbranch_execz .LBB0_1556
	s_waitcnt lgkmcnt(0)
	v_add_f32_e32 v98, v96, v97
	v_lshlrev_b64 v[96:97], 6, v[182:183]
	v_lshl_add_u64 v[96:97], s[74:75], 0, v[96:97]
	v_lshl_add_u64 v[96:97], s[18:19], 2, v[96:97]
	s_lshl_b32 s6, s40, 2
	v_lshl_add_u64 v[96:97], v[96:97], 0, s[6:7]
	global_store_dword v[96:97], v98, off
.LBB0_1556:
	s_or_b64 exec, exec, s[20:21]
	v_lshlrev_b32_e32 v96, 16, v140
	s_waitcnt lgkmcnt(0)
	v_and_b32_e32 v97, 0xffff0000, v140
	v_lshlrev_b32_e32 v98, 16, v141
	v_and_b32_e32 v99, 0xffff0000, v141
	v_lshlrev_b32_e32 v100, 16, v142
	v_and_b32_e32 v101, 0xffff0000, v142
	v_lshlrev_b32_e32 v102, 16, v143
	v_and_b32_e32 v103, 0xffff0000, v143
	v_add_f32_e32 v94, v94, v98
	v_add_f32_e32 v95, v95, v99
	v_add_f32_e32 v92, v92, v96
	v_add_f32_e32 v93, v93, v97
	v_add_f32_e32 v96, v90, v102
	v_add_f32_e32 v97, v91, v103
	v_add_f32_e32 v90, v88, v100
	v_add_f32_e32 v91, v89, v101
	v_mul_f32_e32 v88, v93, v93
	v_mul_f32_e32 v89, v95, v95
	v_fmac_f32_e32 v88, v92, v92
	v_fmac_f32_e32 v89, v94, v94
	v_add_f32_e32 v88, v88, v89
	v_mul_f32_e32 v89, v91, v91
	v_mul_f32_e32 v98, v97, v97
	v_fmac_f32_e32 v89, v90, v90
	v_fmac_f32_e32 v98, v96, v96
	v_add_f32_e32 v89, v89, v98
	v_add_f32_e32 v100, v88, v89
	v_cvt_pk_bf16_f32 v88, v92, v93
	v_cvt_pk_bf16_f32 v89, v94, v95
	v_lshlrev_b32_e32 v92, 16, v136
	v_and_b32_e32 v93, 0xffff0000, v136
	v_lshlrev_b32_e32 v94, 16, v137
	v_and_b32_e32 v95, 0xffff0000, v137
	v_cvt_pk_bf16_f32 v90, v90, v91
	v_cvt_pk_bf16_f32 v91, v96, v97
	v_lshlrev_b32_e32 v96, 16, v138
	v_and_b32_e32 v97, 0xffff0000, v138
	v_add_f32_e32 v86, v86, v94
	v_add_f32_e32 v87, v87, v95
	v_add_f32_e32 v84, v84, v92
	v_add_f32_e32 v85, v85, v93
	v_lshlrev_b32_e32 v98, 16, v139
	v_and_b32_e32 v99, 0xffff0000, v139
	v_add_f32_e32 v94, v80, v96
	v_add_f32_e32 v95, v81, v97
	v_mul_f32_e32 v80, v85, v85
	v_mul_f32_e32 v81, v87, v87
	v_add_f32_e32 v92, v82, v98
	v_add_f32_e32 v93, v83, v99
	v_fmac_f32_e32 v80, v84, v84
	v_fmac_f32_e32 v81, v86, v86
	v_add_f32_e32 v80, v80, v81
	v_mul_f32_e32 v81, v95, v95
	v_mul_f32_e32 v82, v93, v93
	v_fmac_f32_e32 v81, v94, v94
	v_fmac_f32_e32 v82, v92, v92
	v_add_f32_e32 v81, v81, v82
	v_add_f32_e32 v80, v80, v81
	v_add_f32_e32 v83, v100, v80
	ds_bpermute_b32 v98, v112, v83
	v_lshl_add_u64 v[80:81], s[64:65], 0, v[180:181]
	v_lshl_add_u64 v[96:97], v[168:169], 1, v[80:81]
	global_store_dwordx4 v[96:97], v[88:91], off
	v_cvt_pk_bf16_f32 v82, v84, v85
	s_waitcnt lgkmcnt(0)
	v_add_f32_e32 v80, v83, v98
	ds_bpermute_b32 v81, v113, v80
	v_cvt_pk_bf16_f32 v83, v86, v87
	v_cvt_pk_bf16_f32 v84, v94, v95
	v_cvt_pk_bf16_f32 v85, v92, v93
	global_store_dwordx4 v[96:97], v[82:85], off offset:256
	s_and_saveexec_b64 s[20:21], s[2:3]
	s_cbranch_execz .LBB0_1558
	s_waitcnt lgkmcnt(0)
	v_add_f32_e32 v82, v80, v81
	v_lshlrev_b64 v[80:81], 6, v[178:179]
	v_lshl_add_u64 v[80:81], s[74:75], 0, v[80:81]
	v_lshl_add_u64 v[80:81], s[18:19], 2, v[80:81]
	s_lshl_b32 s6, s40, 2
	v_lshl_add_u64 v[80:81], v[80:81], 0, s[6:7]
	global_store_dword v[80:81], v82, off
.LBB0_1558:
	s_or_b64 exec, exec, s[20:21]
	v_lshlrev_b32_e32 v80, 16, v132
	s_waitcnt lgkmcnt(0)
	v_and_b32_e32 v81, 0xffff0000, v132
	v_lshlrev_b32_e32 v82, 16, v133
	v_and_b32_e32 v83, 0xffff0000, v133
	v_lshlrev_b32_e32 v84, 16, v134
	v_and_b32_e32 v85, 0xffff0000, v134
	v_lshlrev_b32_e32 v86, 16, v135
	v_and_b32_e32 v87, 0xffff0000, v135
	v_add_f32_e32 v78, v78, v82
	v_add_f32_e32 v79, v79, v83
	v_add_f32_e32 v76, v76, v80
	v_add_f32_e32 v77, v77, v81
	v_add_f32_e32 v80, v74, v86
	v_add_f32_e32 v81, v75, v87
	v_add_f32_e32 v74, v72, v84
	v_add_f32_e32 v75, v73, v85
	v_mul_f32_e32 v72, v77, v77
	v_mul_f32_e32 v73, v79, v79
	v_fmac_f32_e32 v72, v76, v76
	v_fmac_f32_e32 v73, v78, v78
	v_add_f32_e32 v72, v72, v73
	v_mul_f32_e32 v73, v75, v75
	v_mul_f32_e32 v82, v81, v81
	v_fmac_f32_e32 v73, v74, v74
	v_fmac_f32_e32 v82, v80, v80
	v_add_f32_e32 v73, v73, v82
	v_add_f32_e32 v84, v72, v73
	v_cvt_pk_bf16_f32 v72, v76, v77
	v_cvt_pk_bf16_f32 v73, v78, v79
	v_lshlrev_b32_e32 v76, 16, v128
	v_and_b32_e32 v77, 0xffff0000, v128
	v_lshlrev_b32_e32 v78, 16, v129
	v_and_b32_e32 v79, 0xffff0000, v129
	v_cvt_pk_bf16_f32 v74, v74, v75
	v_cvt_pk_bf16_f32 v75, v80, v81
	v_lshlrev_b32_e32 v80, 16, v130
	v_and_b32_e32 v81, 0xffff0000, v130
	v_add_f32_e32 v70, v70, v78
	v_add_f32_e32 v71, v71, v79
	v_add_f32_e32 v68, v68, v76
	v_add_f32_e32 v69, v69, v77
	v_lshlrev_b32_e32 v82, 16, v131
	v_and_b32_e32 v83, 0xffff0000, v131
	v_add_f32_e32 v78, v64, v80
	v_add_f32_e32 v79, v65, v81
	v_mul_f32_e32 v64, v69, v69
	v_mul_f32_e32 v65, v71, v71
	v_add_f32_e32 v76, v66, v82
	v_add_f32_e32 v77, v67, v83
	v_fmac_f32_e32 v64, v68, v68
	v_fmac_f32_e32 v65, v70, v70
	v_add_f32_e32 v64, v64, v65
	v_mul_f32_e32 v65, v79, v79
	v_mul_f32_e32 v66, v77, v77
	v_fmac_f32_e32 v65, v78, v78
	v_fmac_f32_e32 v66, v76, v76
	v_add_f32_e32 v65, v65, v66
	v_add_f32_e32 v64, v64, v65
	v_add_f32_e32 v67, v84, v64
	ds_bpermute_b32 v82, v112, v67
	v_lshl_add_u64 v[64:65], s[64:65], 0, v[176:177]
	v_lshl_add_u64 v[80:81], v[168:169], 1, v[64:65]
	global_store_dwordx4 v[80:81], v[72:75], off
	v_cvt_pk_bf16_f32 v66, v68, v69
	s_waitcnt lgkmcnt(0)
	v_add_f32_e32 v64, v67, v82
	ds_bpermute_b32 v65, v113, v64
	v_cvt_pk_bf16_f32 v67, v70, v71
	v_cvt_pk_bf16_f32 v68, v78, v79
	v_cvt_pk_bf16_f32 v69, v76, v77
	global_store_dwordx4 v[80:81], v[66:69], off offset:256
	s_and_saveexec_b64 s[20:21], s[2:3]
	s_cbranch_execz .LBB0_1560
	s_waitcnt lgkmcnt(0)
	v_add_f32_e32 v66, v64, v65
	v_lshlrev_b64 v[64:65], 6, v[174:175]
	v_lshl_add_u64 v[64:65], s[74:75], 0, v[64:65]
	v_lshl_add_u64 v[64:65], s[18:19], 2, v[64:65]
	s_lshl_b32 s6, s40, 2
	v_lshl_add_u64 v[64:65], v[64:65], 0, s[6:7]
	global_store_dword v[64:65], v66, off
.LBB0_1560:
	s_or_b64 exec, exec, s[20:21]
	v_add_u32_e32 v100, 0x80, v170
	v_ashrrev_i32_e32 v101, 31, v100
	v_add_u32_e32 v96, 0x90, v170
	v_lshlrev_b64 v[110:111], 11, v[100:101]
	v_ashrrev_i32_e32 v97, 31, v96
	v_add_u32_e32 v92, 0xa0, v170
	s_waitcnt lgkmcnt(0)
	v_lshl_add_u64 v[64:65], v[172:173], 0, v[110:111]
	v_lshlrev_b64 v[98:99], 11, v[96:97]
	v_ashrrev_i32_e32 v93, 31, v92
	v_add_u32_e32 v88, 0xb0, v170
	v_lshl_add_u64 v[64:65], v[172:173], 0, v[98:99]
	v_lshlrev_b64 v[94:95], 11, v[92:93]
	v_ashrrev_i32_e32 v89, 31, v88
	v_lshl_add_u64 v[64:65], v[172:173], 0, v[94:95]
	v_lshlrev_b64 v[90:91], 11, v[88:89]
	v_lshl_add_u64 v[64:65], v[172:173], 0, v[90:91]
	global_load_dwordx4 v[68:71], v[64:65], off
	s_nop 0
	global_load_dwordx4 v[64:67], v[64:65], off offset:256
	s_waitcnt vmcnt(15)
	v_lshlrev_b32_e32 v114, 16, v236
	v_and_b32_e32 v115, 0xffff0000, v236
	v_lshlrev_b32_e32 v236, 16, v237
	v_and_b32_e32 v237, 0xffff0000, v237
	v_lshlrev_b32_e32 v116, 16, v238
	v_and_b32_e32 v117, 0xffff0000, v238
	v_lshlrev_b32_e32 v238, 16, v239
	v_and_b32_e32 v239, 0xffff0000, v239
	v_add_f32_e32 v62, v62, v236
	v_add_f32_e32 v63, v63, v237
	v_add_f32_e32 v60, v60, v114
	v_add_f32_e32 v61, v61, v115
	v_add_f32_e32 v236, v58, v238
	v_add_f32_e32 v237, v59, v239
	v_add_f32_e32 v58, v56, v116
	v_add_f32_e32 v59, v57, v117
	v_mul_f32_e32 v56, v61, v61
	v_mul_f32_e32 v57, v63, v63
	v_fmac_f32_e32 v56, v60, v60
	v_fmac_f32_e32 v57, v62, v62
	v_add_f32_e32 v56, v56, v57
	v_mul_f32_e32 v57, v59, v59
	v_mul_f32_e32 v238, v237, v237
	v_fmac_f32_e32 v57, v58, v58
	v_fmac_f32_e32 v238, v236, v236
	v_add_f32_e32 v57, v57, v238
	v_add_f32_e32 v114, v56, v57
	v_cvt_pk_bf16_f32 v56, v60, v61
	v_cvt_pk_bf16_f32 v57, v62, v63
	s_waitcnt vmcnt(14)
	v_lshlrev_b32_e32 v60, 16, v240
	v_and_b32_e32 v61, 0xffff0000, v240
	v_lshlrev_b32_e32 v62, 16, v241
	v_and_b32_e32 v63, 0xffff0000, v241
	v_cvt_pk_bf16_f32 v58, v58, v59
	v_cvt_pk_bf16_f32 v59, v236, v237
	v_lshlrev_b32_e32 v236, 16, v242
	v_and_b32_e32 v237, 0xffff0000, v242
	v_add_f32_e32 v54, v54, v62
	v_add_f32_e32 v55, v55, v63
	v_add_f32_e32 v52, v52, v60
	v_add_f32_e32 v53, v53, v61
	v_lshlrev_b32_e32 v238, 16, v243
	v_and_b32_e32 v239, 0xffff0000, v243
	v_add_f32_e32 v62, v48, v236
	v_add_f32_e32 v63, v49, v237
	v_mul_f32_e32 v48, v53, v53
	v_mul_f32_e32 v49, v55, v55
	v_add_f32_e32 v60, v50, v238
	v_add_f32_e32 v61, v51, v239
	v_fmac_f32_e32 v48, v52, v52
	v_fmac_f32_e32 v49, v54, v54
	v_add_f32_e32 v48, v48, v49
	v_mul_f32_e32 v49, v63, v63
	v_mul_f32_e32 v50, v61, v61
	v_fmac_f32_e32 v49, v62, v62
	v_fmac_f32_e32 v50, v60, v60
	v_add_f32_e32 v49, v49, v50
	v_add_f32_e32 v48, v48, v49
	v_add_f32_e32 v51, v114, v48
	ds_bpermute_b32 v238, v112, v51
	v_lshl_add_u64 v[48:49], s[64:65], 0, v[110:111]
	v_lshl_add_u64 v[236:237], v[168:169], 1, v[48:49]
	global_store_dwordx4 v[236:237], v[56:59], off
	v_cvt_pk_bf16_f32 v50, v52, v53
	s_waitcnt lgkmcnt(0)
	v_add_f32_e32 v48, v51, v238
	ds_bpermute_b32 v49, v113, v48
	v_cvt_pk_bf16_f32 v51, v54, v55
	v_cvt_pk_bf16_f32 v52, v62, v63
	v_cvt_pk_bf16_f32 v53, v60, v61
	global_store_dwordx4 v[236:237], v[50:53], off offset:256
	s_and_saveexec_b64 s[20:21], s[2:3]
	s_cbranch_execz .LBB0_1562
	s_waitcnt lgkmcnt(0)
	v_add_f32_e32 v50, v48, v49
	v_lshlrev_b64 v[48:49], 6, v[100:101]
	v_lshl_add_u64 v[48:49], s[74:75], 0, v[48:49]
	v_lshl_add_u64 v[48:49], s[18:19], 2, v[48:49]
	s_lshl_b32 s6, s40, 2
	v_lshl_add_u64 v[48:49], v[48:49], 0, s[6:7]
	global_store_dword v[48:49], v50, off
.LBB0_1562:
	s_or_b64 exec, exec, s[20:21]
	s_waitcnt vmcnt(15)
	v_lshlrev_b32_e32 v48, 16, v244
	s_waitcnt lgkmcnt(0)
	v_and_b32_e32 v49, 0xffff0000, v244
	v_lshlrev_b32_e32 v50, 16, v245
	v_and_b32_e32 v51, 0xffff0000, v245
	v_lshlrev_b32_e32 v52, 16, v246
	v_and_b32_e32 v53, 0xffff0000, v246
	v_lshlrev_b32_e32 v54, 16, v247
	v_and_b32_e32 v55, 0xffff0000, v247
	v_add_f32_e32 v46, v46, v50
	v_add_f32_e32 v47, v47, v51
	v_add_f32_e32 v44, v44, v48
	v_add_f32_e32 v45, v45, v49
	v_add_f32_e32 v48, v42, v54
	v_add_f32_e32 v49, v43, v55
	v_add_f32_e32 v42, v40, v52
	v_add_f32_e32 v43, v41, v53
	v_mul_f32_e32 v40, v45, v45
	v_mul_f32_e32 v41, v47, v47
	v_fmac_f32_e32 v40, v44, v44
	v_fmac_f32_e32 v41, v46, v46
	v_add_f32_e32 v40, v40, v41
	v_mul_f32_e32 v41, v43, v43
	v_mul_f32_e32 v50, v49, v49
	v_fmac_f32_e32 v41, v42, v42
	v_fmac_f32_e32 v50, v48, v48
	v_add_f32_e32 v41, v41, v50
	v_add_f32_e32 v52, v40, v41
	v_cvt_pk_bf16_f32 v40, v44, v45
	v_cvt_pk_bf16_f32 v41, v46, v47
	s_waitcnt vmcnt(14)
	v_lshlrev_b32_e32 v44, 16, v248
	v_and_b32_e32 v45, 0xffff0000, v248
	v_lshlrev_b32_e32 v46, 16, v249
	v_and_b32_e32 v47, 0xffff0000, v249
	v_cvt_pk_bf16_f32 v42, v42, v43
	v_cvt_pk_bf16_f32 v43, v48, v49
	v_lshlrev_b32_e32 v48, 16, v250
	v_and_b32_e32 v49, 0xffff0000, v250
	v_add_f32_e32 v38, v38, v46
	v_add_f32_e32 v39, v39, v47
	v_add_f32_e32 v36, v36, v44
	v_add_f32_e32 v37, v37, v45
	v_lshlrev_b32_e32 v50, 16, v251
	v_and_b32_e32 v51, 0xffff0000, v251
	v_add_f32_e32 v46, v32, v48
	v_add_f32_e32 v47, v33, v49
	v_mul_f32_e32 v32, v37, v37
	v_mul_f32_e32 v33, v39, v39
	v_add_f32_e32 v44, v34, v50
	v_add_f32_e32 v45, v35, v51
	v_fmac_f32_e32 v32, v36, v36
	v_fmac_f32_e32 v33, v38, v38
	v_add_f32_e32 v32, v32, v33
	v_mul_f32_e32 v33, v47, v47
	v_mul_f32_e32 v34, v45, v45
	v_fmac_f32_e32 v33, v46, v46
	v_fmac_f32_e32 v34, v44, v44
	v_add_f32_e32 v33, v33, v34
	v_add_f32_e32 v32, v32, v33
	v_add_f32_e32 v35, v52, v32
	ds_bpermute_b32 v50, v112, v35
	v_lshl_add_u64 v[32:33], s[64:65], 0, v[98:99]
	v_lshl_add_u64 v[48:49], v[168:169], 1, v[32:33]
	global_store_dwordx4 v[48:49], v[40:43], off
	v_cvt_pk_bf16_f32 v34, v36, v37
	s_waitcnt lgkmcnt(0)
	v_add_f32_e32 v32, v35, v50
	ds_bpermute_b32 v33, v113, v32
	v_cvt_pk_bf16_f32 v35, v38, v39
	v_cvt_pk_bf16_f32 v36, v46, v47
	v_cvt_pk_bf16_f32 v37, v44, v45
	global_store_dwordx4 v[48:49], v[34:37], off offset:256
	s_and_saveexec_b64 s[20:21], s[2:3]
	s_cbranch_execz .LBB0_1564
	s_waitcnt lgkmcnt(0)
	v_add_f32_e32 v34, v32, v33
	v_lshlrev_b64 v[32:33], 6, v[96:97]
	v_lshl_add_u64 v[32:33], s[74:75], 0, v[32:33]
	v_lshl_add_u64 v[32:33], s[18:19], 2, v[32:33]
	s_lshl_b32 s6, s40, 2
	v_lshl_add_u64 v[32:33], v[32:33], 0, s[6:7]
	global_store_dword v[32:33], v34, off
.LBB0_1564:
	s_or_b64 exec, exec, s[20:21]
	s_waitcnt vmcnt(15)
	v_lshlrev_b32_e32 v32, 16, v210
	s_waitcnt lgkmcnt(0)
	v_and_b32_e32 v33, 0xffff0000, v210
	v_lshlrev_b32_e32 v34, 16, v211
	v_and_b32_e32 v35, 0xffff0000, v211
	v_lshlrev_b32_e32 v36, 16, v212
	v_and_b32_e32 v37, 0xffff0000, v212
	v_lshlrev_b32_e32 v38, 16, v213
	v_and_b32_e32 v39, 0xffff0000, v213
	v_add_f32_e32 v30, v30, v34
	v_add_f32_e32 v31, v31, v35
	v_add_f32_e32 v28, v28, v32
	v_add_f32_e32 v29, v29, v33
	v_add_f32_e32 v32, v26, v38
	v_add_f32_e32 v33, v27, v39
	v_add_f32_e32 v26, v24, v36
	v_add_f32_e32 v27, v25, v37
	v_mul_f32_e32 v24, v29, v29
	v_mul_f32_e32 v25, v31, v31
	v_fmac_f32_e32 v24, v28, v28
	v_fmac_f32_e32 v25, v30, v30
	v_add_f32_e32 v24, v24, v25
	v_mul_f32_e32 v25, v27, v27
	v_mul_f32_e32 v34, v33, v33
	v_fmac_f32_e32 v25, v26, v26
	v_fmac_f32_e32 v34, v32, v32
	v_add_f32_e32 v25, v25, v34
	v_add_f32_e32 v36, v24, v25
	v_cvt_pk_bf16_f32 v24, v28, v29
	v_cvt_pk_bf16_f32 v25, v30, v31
	s_waitcnt vmcnt(14)
	v_lshlrev_b32_e32 v28, 16, v214
	v_and_b32_e32 v29, 0xffff0000, v214
	v_lshlrev_b32_e32 v30, 16, v215
	v_and_b32_e32 v31, 0xffff0000, v215
	v_cvt_pk_bf16_f32 v26, v26, v27
	v_cvt_pk_bf16_f32 v27, v32, v33
	v_lshlrev_b32_e32 v32, 16, v216
	v_and_b32_e32 v33, 0xffff0000, v216
	v_add_f32_e32 v22, v22, v30
	v_add_f32_e32 v23, v23, v31
	v_add_f32_e32 v20, v20, v28
	v_add_f32_e32 v21, v21, v29
	v_lshlrev_b32_e32 v34, 16, v217
	v_and_b32_e32 v35, 0xffff0000, v217
	v_add_f32_e32 v30, v16, v32
	v_add_f32_e32 v31, v17, v33
	v_mul_f32_e32 v16, v21, v21
	v_mul_f32_e32 v17, v23, v23
	v_add_f32_e32 v28, v18, v34
	v_add_f32_e32 v29, v19, v35
	v_fmac_f32_e32 v16, v20, v20
	v_fmac_f32_e32 v17, v22, v22
	v_add_f32_e32 v16, v16, v17
	v_mul_f32_e32 v17, v31, v31
	v_mul_f32_e32 v18, v29, v29
	v_fmac_f32_e32 v17, v30, v30
	v_fmac_f32_e32 v18, v28, v28
	v_add_f32_e32 v17, v17, v18
	v_add_f32_e32 v16, v16, v17
	v_add_f32_e32 v19, v36, v16
	ds_bpermute_b32 v34, v112, v19
	v_lshl_add_u64 v[16:17], s[64:65], 0, v[94:95]
	v_lshl_add_u64 v[32:33], v[168:169], 1, v[16:17]
	global_store_dwordx4 v[32:33], v[24:27], off
	v_cvt_pk_bf16_f32 v18, v20, v21
	s_waitcnt lgkmcnt(0)
	v_add_f32_e32 v16, v19, v34
	ds_bpermute_b32 v17, v113, v16
	v_cvt_pk_bf16_f32 v19, v22, v23
	v_cvt_pk_bf16_f32 v20, v30, v31
	v_cvt_pk_bf16_f32 v21, v28, v29
	global_store_dwordx4 v[32:33], v[18:21], off offset:256
	s_and_saveexec_b64 s[20:21], s[2:3]
	s_cbranch_execz .LBB0_1566
	s_waitcnt lgkmcnt(0)
	v_add_f32_e32 v18, v16, v17
	v_lshlrev_b64 v[16:17], 6, v[92:93]
	v_lshl_add_u64 v[16:17], s[74:75], 0, v[16:17]
	v_lshl_add_u64 v[16:17], s[18:19], 2, v[16:17]
	s_lshl_b32 s6, s40, 2
	v_lshl_add_u64 v[16:17], v[16:17], 0, s[6:7]
	global_store_dword v[16:17], v18, off
.LBB0_1566:
	s_or_b64 exec, exec, s[20:21]
	s_waitcnt vmcnt(7)
	v_lshlrev_b32_e32 v16, 16, v68
	s_waitcnt lgkmcnt(0)
	v_and_b32_e32 v17, 0xffff0000, v68
	v_lshlrev_b32_e32 v18, 16, v69
	v_and_b32_e32 v19, 0xffff0000, v69
	v_lshlrev_b32_e32 v20, 16, v70
	v_and_b32_e32 v21, 0xffff0000, v70
	v_lshlrev_b32_e32 v22, 16, v71
	v_and_b32_e32 v23, 0xffff0000, v71
	v_add_f32_e32 v14, v14, v18
	v_add_f32_e32 v15, v15, v19
	v_add_f32_e32 v12, v12, v16
	v_add_f32_e32 v13, v13, v17
	v_add_f32_e32 v16, v10, v22
	v_add_f32_e32 v17, v11, v23
	v_add_f32_e32 v10, v8, v20
	v_add_f32_e32 v11, v9, v21
	v_mul_f32_e32 v8, v13, v13
	v_mul_f32_e32 v9, v15, v15
	v_fmac_f32_e32 v8, v12, v12
	v_fmac_f32_e32 v9, v14, v14
	v_add_f32_e32 v8, v8, v9
	v_mul_f32_e32 v9, v11, v11
	v_mul_f32_e32 v18, v17, v17
	v_fmac_f32_e32 v9, v10, v10
	v_fmac_f32_e32 v18, v16, v16
	v_add_f32_e32 v9, v9, v18
	v_add_f32_e32 v20, v8, v9
	v_cvt_pk_bf16_f32 v8, v12, v13
	v_cvt_pk_bf16_f32 v9, v14, v15
	s_waitcnt vmcnt(6)
	v_lshlrev_b32_e32 v12, 16, v64
	v_and_b32_e32 v13, 0xffff0000, v64
	v_lshlrev_b32_e32 v14, 16, v65
	v_and_b32_e32 v15, 0xffff0000, v65
	v_cvt_pk_bf16_f32 v10, v10, v11
	v_cvt_pk_bf16_f32 v11, v16, v17
	v_lshlrev_b32_e32 v16, 16, v66
	v_and_b32_e32 v17, 0xffff0000, v66
	v_add_f32_e32 v6, v6, v14
	v_add_f32_e32 v7, v7, v15
	v_add_f32_e32 v4, v4, v12
	v_add_f32_e32 v5, v5, v13
	v_lshlrev_b32_e32 v18, 16, v67
	v_and_b32_e32 v19, 0xffff0000, v67
	v_add_f32_e32 v14, v0, v16
	v_add_f32_e32 v15, v1, v17
	v_mul_f32_e32 v0, v5, v5
	v_mul_f32_e32 v1, v7, v7
	v_add_f32_e32 v12, v2, v18
	v_add_f32_e32 v13, v3, v19
	v_fmac_f32_e32 v0, v4, v4
	v_fmac_f32_e32 v1, v6, v6
	v_add_f32_e32 v0, v0, v1
	v_mul_f32_e32 v1, v15, v15
	v_mul_f32_e32 v2, v13, v13
	v_fmac_f32_e32 v1, v14, v14
	v_fmac_f32_e32 v2, v12, v12
	v_add_f32_e32 v1, v1, v2
	v_add_f32_e32 v0, v0, v1
	v_add_f32_e32 v3, v20, v0
	ds_bpermute_b32 v18, v112, v3
	v_lshl_add_u64 v[0:1], s[64:65], 0, v[90:91]
	v_lshl_add_u64 v[16:17], v[168:169], 1, v[0:1]
	global_store_dwordx4 v[16:17], v[8:11], off
	v_cvt_pk_bf16_f32 v2, v4, v5
	s_waitcnt lgkmcnt(0)
	v_add_f32_e32 v0, v3, v18
	ds_bpermute_b32 v1, v113, v0
	v_cvt_pk_bf16_f32 v3, v6, v7
	v_cvt_pk_bf16_f32 v4, v14, v15
	v_cvt_pk_bf16_f32 v5, v12, v13
	global_store_dwordx4 v[16:17], v[2:5], off offset:256
	s_and_saveexec_b64 s[20:21], s[2:3]
	s_cbranch_execz .LBB0_1543
	s_waitcnt lgkmcnt(0)
	v_add_f32_e32 v2, v0, v1
	v_lshlrev_b64 v[0:1], 6, v[88:89]
	v_lshl_add_u64 v[0:1], s[74:75], 0, v[0:1]
	v_lshl_add_u64 v[0:1], s[18:19], 2, v[0:1]
	s_lshl_b32 s6, s40, 2
	v_lshl_add_u64 v[0:1], v[0:1], 0, s[6:7]
	global_store_dword v[0:1], v2, off
	s_branch .LBB0_1543

.LBB0_1644:
	s_and_b32 s26, s58, 1
	s_lshl_b32 s11, s26, 12
	s_add_i32 s13, s11, 0
	s_add_i32 s13, s13, 0x24010
	s_lshl_b32 s27, s48, 2
	s_add_i32 s27, s13, s27
	v_lshl_add_u32 v68, v189, 2, s27
	ds_read_b128 v[96:99], v68 offset:3072
	ds_read_b128 v[68:71], v68 offset:3584
	s_lshl_b32 s28, s26, 13
	s_add_i32 s29, s28, 0
	s_add_i32 s29, s29, 0x20000
	s_waitcnt lgkmcnt(0)
	v_mul_f32_e32 v166, v146, v98
	v_mul_f32_e32 v167, v147, v98
	v_mul_f32_e32 v164, v144, v98
	v_mul_f32_e32 v165, v145, v98
	v_mul_f32_e32 v158, v82, v98
	v_mul_f32_e32 v159, v83, v98
	v_mul_f32_e32 v156, v80, v98
	v_mul_f32_e32 v157, v81, v98
	v_mul_f32_e32 v82, v142, v98
	v_mul_f32_e32 v83, v143, v98
	v_mul_f32_e32 v80, v140, v98
	v_mul_f32_e32 v81, v141, v98
	v_mul_f32_e32 v94, v94, v98
	v_mul_f32_e32 v95, v95, v98
	v_mul_f32_e32 v92, v92, v98
	v_mul_f32_e32 v93, v93, v98
	v_mov_b32_e32 v98, v99
	v_mul_f32_e32 v162, v86, v98
	v_mul_f32_e32 v163, v87, v98
	v_mul_f32_e32 v160, v84, v98
	v_mul_f32_e32 v161, v85, v98
	v_mul_f32_e32 v86, v134, v98
	v_mul_f32_e32 v87, v135, v98
	v_mul_f32_e32 v84, v132, v98
	v_mul_f32_e32 v85, v133, v98
	v_mul_f32_e32 v134, v130, v70
	v_mul_f32_e32 v135, v131, v70
	v_mul_f32_e32 v132, v128, v70
	v_mul_f32_e32 v133, v129, v70
	v_mul_f32_e32 v130, v46, v70
	v_mul_f32_e32 v131, v47, v70
	v_mul_f32_e32 v128, v44, v70
	v_mul_f32_e32 v129, v45, v70
	v_mul_f32_e32 v46, v126, v70
	v_mul_f32_e32 v47, v127, v70
	v_mul_f32_e32 v44, v124, v70
	v_mul_f32_e32 v45, v125, v70
	v_mul_f32_e32 v50, v50, v70
	v_mul_f32_e32 v51, v51, v70
	v_mul_f32_e32 v48, v48, v70
	v_mul_f32_e32 v49, v49, v70
	v_mov_b32_e32 v70, v71
	v_mul_f32_e32 v170, v138, v98
	v_mul_f32_e32 v171, v139, v98
	v_mul_f32_e32 v168, v136, v98
	v_mul_f32_e32 v169, v137, v98
	v_mul_f32_e32 v90, v90, v98
	v_mul_f32_e32 v91, v91, v98
	v_mul_f32_e32 v88, v88, v98
	v_mul_f32_e32 v89, v89, v98
	v_mul_f32_e32 v126, v122, v70
	v_mul_f32_e32 v127, v123, v70
	v_mul_f32_e32 v124, v120, v70
	v_mul_f32_e32 v125, v121, v70
	v_mul_f32_e32 v122, v54, v70
	v_mul_f32_e32 v123, v55, v70
	v_mul_f32_e32 v120, v52, v70
	v_mul_f32_e32 v121, v53, v70
	v_mul_f32_e32 v54, v118, v70
	v_mul_f32_e32 v55, v119, v70
	v_mul_f32_e32 v52, v116, v70
	v_mul_f32_e32 v53, v117, v70
	v_mul_f32_e32 v58, v58, v70
	v_mul_f32_e32 v59, v59, v70
	v_mul_f32_e32 v56, v56, v70
	v_mul_f32_e32 v57, v57, v70
	s_and_saveexec_b64 s[26:27], s[6:7]
	s_cbranch_execz .LBB0_1646
	s_add_i32 s30, s51, s29
	v_lshl_add_u32 v70, v210, 2, s30
	ds_write_b128 v70, v[164:167]
	ds_write_b128 v70, v[80:83] offset:16
	ds_write_b128 v70, v[156:159] offset:512
	ds_write_b128 v70, v[92:95] offset:528
	ds_write_b128 v70, v[168:171] offset:1024
	ds_write_b128 v70, v[84:87] offset:1040
	ds_write_b128 v70, v[160:163] offset:1536
	ds_write_b128 v70, v[88:91] offset:1552
	ds_write_b128 v70, v[132:135] offset:4096
	ds_write_b128 v70, v[44:47] offset:4112
	ds_write_b128 v70, v[128:131] offset:4608
	ds_write_b128 v70, v[48:51] offset:4624
	ds_write_b128 v70, v[124:127] offset:5120
	ds_write_b128 v70, v[52:55] offset:5136
	ds_write_b128 v70, v[120:123] offset:5632
	ds_write_b128 v70, v[56:59] offset:5648

.LBB0_1649:
	s_waitcnt lgkmcnt(0)
	v_mov_b32_dpp v180, v168 row_shr:1 row_mask:0xf bank_mask:0xf
	v_mul_f32_e32 v112, v112, v96
	v_mul_f32_e32 v113, v113, v96
	v_mul_f32_e32 v70, v102, v97
	v_mul_f32_e32 v71, v103, v97
	v_mul_f32_e32 v102, v148, v180
	v_mov_b32_dpp v184, v164 row_shr:1 row_mask:0xf bank_mask:0xf
	v_fmac_f32_e32 v102, v112, v152
	v_fmac_f32_e32 v102, v144, v184
	v_mul_f32_e32 v98, v106, v96
	v_mul_f32_e32 v99, v107, v96
	v_mul_f32_e32 v106, v104, v96
	v_mul_f32_e32 v107, v105, v96
	v_mul_f32_e32 v104, v110, v97
	v_mul_f32_e32 v105, v111, v97
	v_mul_f32_e32 v111, v168, v152
	v_mul_f32_e32 v168, 0xbfb8aa3b, v102
	v_mul_f32_e32 v108, v108, v97
	v_mul_f32_e32 v109, v109, v97
	v_mul_f32_e32 v110, v164, v152
	v_exp_f32_e32 v168, v168
	v_mul_f32_e32 v100, v100, v97
	v_mul_f32_e32 v101, v101, v97
	v_mul_f32_e32 v103, v108, v152
	v_fmac_f32_e32 v110, v108, v148
	v_fmac_f32_e32 v111, v164, v148
	v_mov_b32_dpp v172, v160 row_shr:1 row_mask:0xf bank_mask:0xf
	v_mul_f32_e32 v164, v156, v140
	v_fmac_f32_e32 v103, v112, v148
	v_fmac_f32_e32 v110, v112, v144
	v_fmac_f32_e32 v111, v108, v144
	v_mul_f32_e32 v108, v136, v172
	v_mul_f32_e32 v112, v100, v140
	v_fmac_f32_e32 v164, v100, v136
	v_fmac_f32_e32 v108, v106, v140
	v_fmac_f32_e32 v112, v106, v136
	v_fmac_f32_e32 v164, v106, v116
	v_mul_f32_e32 v106, v160, v140
	v_fmac_f32_e32 v103, v144, v180
	v_mov_b32_dpp v176, v156 row_shr:1 row_mask:0xf bank_mask:0xf
	v_fmac_f32_e32 v106, v156, v136
	v_add_f32_e32 v156, 1.0, v168
	v_rcp_f32_e32 v156, v156
	v_mul_f32_e32 v160, 0xbfb8aa3b, v103
	v_exp_f32_e32 v160, v160
	v_fmac_f32_e32 v108, v116, v176
	v_fmac_f32_e32 v106, v100, v116
	v_mul_f32_e32 v100, v102, v156
	v_mul_f32_e32 v100, v108, v100
	v_add_f32_e32 v102, 1.0, v160
	v_mul_f32_e32 v108, 0xbfb8aa3b, v110
	v_rcp_f32_e32 v102, v102
	v_exp_f32_e32 v108, v108
	v_mul_f32_e32 v156, 0xbfb8aa3b, v111
	v_exp_f32_e32 v156, v156
	v_mul_f32_e32 v102, v103, v102
	v_add_f32_e32 v103, 1.0, v108
	v_rcp_f32_e32 v103, v103
	v_add_f32_e32 v108, 1.0, v156
	v_rcp_f32_e32 v108, v108
	v_fmac_f32_e32 v112, v116, v172
	v_mul_f32_e32 v112, v112, v102
	v_mul_f32_e32 v102, v110, v103
	v_mul_f32_e32 v110, v164, v102
	v_mul_f32_e32 v102, v111, v108
	v_mov_b32_dpp v181, v169 row_shr:1 row_mask:0xf bank_mask:0xf
	v_mul_f32_e32 v106, v106, v102
	v_mul_f32_e32 v102, v149, v181
	v_mov_b32_dpp v185, v165 row_shr:1 row_mask:0xf bank_mask:0xf
	v_fmac_f32_e32 v102, v113, v153
	v_fmac_f32_e32 v102, v145, v185
	v_mul_f32_e32 v160, 0xbfb8aa3b, v102
	v_mul_f32_e32 v108, v165, v153
	v_mul_f32_e32 v111, v169, v153
	v_exp_f32_e32 v160, v160
	v_mul_f32_e32 v103, v109, v153
	v_fmac_f32_e32 v108, v109, v149
	v_fmac_f32_e32 v111, v165, v149
	v_mov_b32_dpp v173, v161 row_shr:1 row_mask:0xf bank_mask:0xf
	v_mul_f32_e32 v156, v157, v141
	v_fmac_f32_e32 v103, v113, v149
	v_fmac_f32_e32 v108, v113, v145
	v_fmac_f32_e32 v111, v109, v145
	v_mul_f32_e32 v109, v137, v173
	v_mul_f32_e32 v113, v101, v141
	v_fmac_f32_e32 v156, v101, v137
	v_fmac_f32_e32 v109, v107, v141
	v_fmac_f32_e32 v113, v107, v137
	v_fmac_f32_e32 v156, v107, v117
	v_mul_f32_e32 v107, v161, v141
	v_fmac_f32_e32 v103, v145, v181
	v_mov_b32_dpp v177, v157 row_shr:1 row_mask:0xf bank_mask:0xf
	v_fmac_f32_e32 v107, v157, v137
	v_add_f32_e32 v157, 1.0, v160
	v_rcp_f32_e32 v157, v157
	v_mul_f32_e32 v160, 0xbfb8aa3b, v103
	v_exp_f32_e32 v160, v160
	v_fmac_f32_e32 v109, v117, v177
	v_fmac_f32_e32 v107, v101, v117
	v_mul_f32_e32 v101, v102, v157
	v_mul_f32_e32 v101, v109, v101
	v_add_f32_e32 v102, 1.0, v160
	v_mul_f32_e32 v109, 0xbfb8aa3b, v108
	v_rcp_f32_e32 v102, v102
	v_exp_f32_e32 v109, v109
	v_mul_f32_e32 v157, 0xbfb8aa3b, v111
	v_exp_f32_e32 v157, v157
	v_mul_f32_e32 v102, v103, v102
	v_add_f32_e32 v103, 1.0, v109
	v_rcp_f32_e32 v103, v103
	v_add_f32_e32 v109, 1.0, v157
	v_rcp_f32_e32 v109, v109
	v_fmac_f32_e32 v113, v117, v173
	v_mul_f32_e32 v113, v113, v102
	v_mul_f32_e32 v102, v108, v103
	v_mul_f32_e32 v108, v156, v102
	v_mul_f32_e32 v102, v111, v109
	v_mov_b32_dpp v182, v170 row_shr:1 row_mask:0xf bank_mask:0xf
	v_mul_f32_e32 v114, v114, v96
	v_mul_f32_e32 v115, v115, v96
	v_mul_f32_e32 v107, v107, v102
	v_mul_f32_e32 v102, v150, v182
	v_mov_b32_dpp v186, v166 row_shr:1 row_mask:0xf bank_mask:0xf
	v_fmac_f32_e32 v102, v114, v154
	v_fmac_f32_e32 v102, v146, v186
	v_mul_f32_e32 v157, 0xbfb8aa3b, v102
	v_exp_f32_e32 v157, v157
	v_mul_f32_e32 v109, v166, v154
	v_mul_f32_e32 v111, v170, v154
	v_mul_f32_e32 v103, v104, v154
	v_fmac_f32_e32 v109, v104, v150
	v_fmac_f32_e32 v111, v166, v150
	v_mov_b32_dpp v174, v162 row_shr:1 row_mask:0xf bank_mask:0xf
	v_mul_f32_e32 v156, v158, v142
	v_fmac_f32_e32 v103, v114, v150
	v_fmac_f32_e32 v109, v114, v146
	v_fmac_f32_e32 v111, v104, v146
	v_mul_f32_e32 v104, v138, v174
	v_mul_f32_e32 v114, v70, v142
	v_fmac_f32_e32 v156, v70, v138
	v_fmac_f32_e32 v103, v146, v182
	v_fmac_f32_e32 v104, v98, v142
	v_fmac_f32_e32 v114, v98, v138
	v_fmac_f32_e32 v156, v98, v118
	v_mul_f32_e32 v98, v162, v142
	v_add_f32_e32 v157, 1.0, v157
	v_mov_b32_dpp v178, v158 row_shr:1 row_mask:0xf bank_mask:0xf
	v_fmac_f32_e32 v98, v158, v138
	v_rcp_f32_e32 v157, v157
	v_mul_f32_e32 v158, 0xbfb8aa3b, v103
	v_exp_f32_e32 v158, v158
	v_fmac_f32_e32 v104, v118, v178
	v_fmac_f32_e32 v98, v70, v118
	v_mul_f32_e32 v70, v102, v157
	v_mul_f32_e32 v70, v104, v70
	v_add_f32_e32 v102, 1.0, v158
	v_mul_f32_e32 v104, 0xbfb8aa3b, v109
	v_rcp_f32_e32 v102, v102
	v_exp_f32_e32 v104, v104
	v_mul_f32_e32 v157, 0xbfb8aa3b, v111
	v_exp_f32_e32 v157, v157
	v_mul_f32_e32 v102, v103, v102
	v_add_f32_e32 v103, 1.0, v104
	v_rcp_f32_e32 v103, v103
	v_add_f32_e32 v104, 1.0, v157
	v_rcp_f32_e32 v104, v104
	v_fmac_f32_e32 v114, v118, v174
	v_mul_f32_e32 v114, v114, v102
	v_mul_f32_e32 v102, v109, v103
	v_mul_f32_e32 v109, v156, v102
	v_mul_f32_e32 v102, v111, v104
	v_mov_b32_dpp v183, v171 row_shr:1 row_mask:0xf bank_mask:0xf
	v_mul_f32_e32 v104, v98, v102
	v_mul_f32_e32 v98, v151, v183
	v_mov_b32_dpp v187, v167 row_shr:1 row_mask:0xf bank_mask:0xf
	v_fmac_f32_e32 v98, v115, v155
	v_fmac_f32_e32 v98, v147, v187
	v_mul_f32_e32 v157, 0xbfb8aa3b, v98
	v_exp_f32_e32 v157, v157
	v_mul_f32_e32 v102, v105, v155
	v_fmac_f32_e32 v102, v115, v151
	v_fmac_f32_e32 v102, v147, v183
	v_mul_f32_e32 v103, v167, v155
	v_mul_f32_e32 v111, v171, v155
	v_add_f32_e32 v157, 1.0, v157
	v_fmac_f32_e32 v103, v105, v151
	v_fmac_f32_e32 v111, v167, v151
	v_mov_b32_dpp v175, v163 row_shr:1 row_mask:0xf bank_mask:0xf
	v_mul_f32_e32 v156, v159, v143
	v_rcp_f32_e32 v157, v157
	v_mul_f32_e32 v158, 0xbfb8aa3b, v102
	v_fmac_f32_e32 v103, v115, v147
	v_fmac_f32_e32 v111, v105, v147
	v_mul_f32_e32 v105, v139, v175
	v_mul_f32_e32 v115, v71, v143
	v_fmac_f32_e32 v156, v71, v139
	v_exp_f32_e32 v158, v158
	v_fmac_f32_e32 v105, v99, v143
	v_fmac_f32_e32 v115, v99, v139
	v_fmac_f32_e32 v156, v99, v119
	v_mul_f32_e32 v99, v163, v143
	v_mov_b32_dpp v179, v159 row_shr:1 row_mask:0xf bank_mask:0xf
	v_fmac_f32_e32 v99, v159, v139
	v_fmac_f32_e32 v105, v119, v179
	v_fmac_f32_e32 v99, v71, v119
	v_mul_f32_e32 v71, v98, v157
	v_mul_f32_e32 v71, v105, v71
	v_add_f32_e32 v98, 1.0, v158
	v_mul_f32_e32 v105, 0xbfb8aa3b, v103
	v_rcp_f32_e32 v98, v98
	v_exp_f32_e32 v105, v105
	v_mul_f32_e32 v157, 0xbfb8aa3b, v111
	v_exp_f32_e32 v157, v157
	v_mul_f32_e32 v98, v102, v98
	v_add_f32_e32 v102, 1.0, v105
	v_rcp_f32_e32 v102, v102
	v_add_f32_e32 v105, 1.0, v157
	v_rcp_f32_e32 v105, v105
	s_addk_i32 s13, 0x800
	s_and_b64 s[30:31], s[22:23], exec
	s_cselect_b32 s13, s13, s26
	v_fmac_f32_e32 v115, v119, v175
	v_mul_f32_e32 v102, v103, v102
	s_cmp_lg_u32 s13, 0
	v_mul_f32_e32 v98, v115, v98
	v_mul_f32_e32 v115, v156, v102
	v_mul_f32_e32 v102, v111, v105
	s_cselect_b64 s[26:27], -1, 0
	s_cmp_eq_u32 s13, 0
	v_lshl_add_u32 v160, v210, 2, s13
	v_mul_f32_e32 v105, v99, v102
	v_cvt_pk_bf16_f32 v102, v100, v101
	v_cvt_pk_bf16_f32 v103, v70, v71
	v_cvt_pk_bf16_f32 v100, v112, v113
	v_cvt_pk_bf16_f32 v101, v114, v98
	v_cvt_pk_bf16_f32 v98, v110, v108
	v_cvt_pk_bf16_f32 v99, v109, v115
	v_cvt_pk_bf16_f32 v70, v106, v107
	v_cvt_pk_bf16_f32 v71, v104, v105
	s_cbranch_scc1 .LBB0_1651
	ds_read_b128 v[156:159], v160
	ds_read_b128 v[108:111], v160 offset:512
	ds_read_b128 v[112:115], v160 offset:1024
	ds_read_b128 v[104:107], v160 offset:1536
	s_branch .LBB0_1652

.LBB0_1652:
	v_mul_f32_e32 v72, v72, v69
	v_mul_f32_e32 v73, v73, v69
	v_mul_f32_e32 v76, v76, v68
	v_mul_f32_e32 v77, v77, v68
	v_mul_f32_e32 v162, v64, v68
	v_mul_f32_e32 v163, v65, v68
	v_mul_f32_e32 v64, v74, v69
	v_mul_f32_e32 v65, v75, v69
	s_waitcnt lgkmcnt(0)
	v_mov_b32_dpp v112, v124 row_shr:1 row_mask:0xf bank_mask:0xf
	v_mul_f32_e32 v75, v72, v152
	v_mul_f32_e32 v74, v148, v112
	v_fmac_f32_e32 v75, v76, v148
	v_mov_b32_dpp v156, v132 row_shr:1 row_mask:0xf bank_mask:0xf
	v_fmac_f32_e32 v74, v76, v152
	v_fmac_f32_e32 v75, v144, v112
	v_mul_f32_e32 v112, v132, v152
	v_fmac_f32_e32 v74, v144, v156
	v_fmac_f32_e32 v112, v72, v148
	v_fmac_f32_e32 v112, v76, v144
	v_mul_f32_e32 v76, v124, v152
	v_mul_f32_e32 v124, 0xbfb8aa3b, v74
	v_fmac_f32_e32 v76, v132, v148
	v_mov_b32_dpp v104, v120 row_shr:1 row_mask:0xf bank_mask:0xf
	v_exp_f32_e32 v124, v124
	v_fmac_f32_e32 v76, v72, v144
	v_mul_f32_e32 v72, v136, v104
	v_mul_f32_e32 v60, v60, v69
	v_mul_f32_e32 v61, v61, v69
	v_mov_b32_dpp v108, v128 row_shr:1 row_mask:0xf bank_mask:0xf
	v_fmac_f32_e32 v72, v162, v140
	v_fmac_f32_e32 v72, v116, v108
	v_mul_f32_e32 v108, v60, v140
	v_fmac_f32_e32 v108, v162, v136
	v_mul_f32_e32 v120, v120, v140
	v_add_f32_e32 v124, 1.0, v124
	v_fmac_f32_e32 v108, v116, v104
	v_mul_f32_e32 v104, v128, v140
	v_fmac_f32_e32 v120, v128, v136
	v_rcp_f32_e32 v124, v124
	v_mul_f32_e32 v128, 0xbfb8aa3b, v75
	v_exp_f32_e32 v128, v128
	v_fmac_f32_e32 v104, v60, v136
	v_fmac_f32_e32 v120, v60, v116
	v_mul_f32_e32 v60, v74, v124
	v_fmac_f32_e32 v104, v162, v116
	v_mul_f32_e32 v60, v72, v60
	v_add_f32_e32 v72, 1.0, v128
	v_mul_f32_e32 v116, 0xbfb8aa3b, v76
	v_rcp_f32_e32 v72, v72
	v_exp_f32_e32 v116, v116
	v_mul_f32_e32 v74, 0xbfb8aa3b, v112
	v_exp_f32_e32 v74, v74
	v_mul_f32_e32 v72, v75, v72
	v_add_f32_e32 v75, 1.0, v116
	v_rcp_f32_e32 v75, v75
	v_add_f32_e32 v74, 1.0, v74
	v_rcp_f32_e32 v74, v74
	v_mov_b32_dpp v113, v125 row_shr:1 row_mask:0xf bank_mask:0xf
	v_mul_f32_e32 v75, v76, v75
	v_mul_f32_e32 v76, v149, v113
	v_mov_b32_dpp v157, v133 row_shr:1 row_mask:0xf bank_mask:0xf
	v_fmac_f32_e32 v76, v77, v153
	v_fmac_f32_e32 v76, v145, v157
	v_mul_f32_e32 v74, v112, v74
	v_mul_f32_e32 v112, 0xbfb8aa3b, v76
	v_mul_f32_e32 v72, v108, v72
	v_mul_f32_e32 v108, v133, v153
	v_exp_f32_e32 v112, v112
	v_mul_f32_e32 v74, v104, v74
	v_mul_f32_e32 v104, v73, v153
	v_fmac_f32_e32 v108, v73, v149
	v_fmac_f32_e32 v104, v77, v149
	v_fmac_f32_e32 v108, v77, v145
	v_mul_f32_e32 v77, v125, v153
	v_fmac_f32_e32 v77, v133, v149
	v_mov_b32_dpp v105, v121 row_shr:1 row_mask:0xf bank_mask:0xf
	v_fmac_f32_e32 v104, v145, v113
	v_fmac_f32_e32 v77, v73, v145
	v_mul_f32_e32 v73, v137, v105
	v_add_f32_e32 v112, 1.0, v112
	v_mov_b32_dpp v109, v129 row_shr:1 row_mask:0xf bank_mask:0xf
	v_fmac_f32_e32 v73, v163, v141
	v_rcp_f32_e32 v112, v112
	v_mul_f32_e32 v116, 0xbfb8aa3b, v104
	v_fmac_f32_e32 v73, v117, v109
	v_mul_f32_e32 v109, v61, v141
	v_exp_f32_e32 v116, v116
	v_fmac_f32_e32 v109, v163, v137
	v_mul_f32_e32 v113, v121, v141
	v_fmac_f32_e32 v109, v117, v105
	v_mul_f32_e32 v105, v129, v141
	v_fmac_f32_e32 v113, v129, v137
	v_fmac_f32_e32 v105, v61, v137
	v_fmac_f32_e32 v113, v61, v117
	v_mul_f32_e32 v61, v76, v112
	v_mul_f32_e32 v76, 0xbfb8aa3b, v108
	v_mul_f32_e32 v61, v73, v61
	v_add_f32_e32 v73, 1.0, v116
	v_exp_f32_e32 v76, v76
	v_mul_f32_e32 v112, 0xbfb8aa3b, v77
	v_rcp_f32_e32 v73, v73
	v_exp_f32_e32 v112, v112
	v_add_f32_e32 v76, 1.0, v76
	v_rcp_f32_e32 v76, v76
	v_mul_f32_e32 v73, v104, v73
	v_add_f32_e32 v104, 1.0, v112
	v_rcp_f32_e32 v104, v104
	v_fmac_f32_e32 v105, v163, v117
	v_mul_f32_e32 v76, v108, v76
	v_mov_b32_dpp v114, v126 row_shr:1 row_mask:0xf bank_mask:0xf
	v_mul_f32_e32 v108, v134, v154
	v_mul_f32_e32 v78, v78, v68
	v_mul_f32_e32 v79, v79, v68
	v_mul_f32_e32 v76, v105, v76
	v_mul_f32_e32 v77, v77, v104
	v_mul_f32_e32 v104, v150, v114
	v_mul_f32_e32 v105, v64, v154
	v_fmac_f32_e32 v108, v64, v150
	v_fmac_f32_e32 v104, v78, v154
	v_fmac_f32_e32 v105, v78, v150
	v_fmac_f32_e32 v108, v78, v146
	v_mul_f32_e32 v78, v126, v154
	v_fmac_f32_e32 v78, v134, v150
	v_mov_b32_dpp v106, v122 row_shr:1 row_mask:0xf bank_mask:0xf
	v_mul_f32_e32 v66, v66, v68
	v_mul_f32_e32 v67, v67, v68
	v_mov_b32_dpp v158, v134 row_shr:1 row_mask:0xf bank_mask:0xf
	v_fmac_f32_e32 v78, v64, v146
	v_mul_f32_e32 v64, v138, v106
	v_fmac_f32_e32 v104, v146, v158
	v_mov_b32_dpp v110, v130 row_shr:1 row_mask:0xf bank_mask:0xf
	v_fmac_f32_e32 v64, v66, v142
	v_fmac_f32_e32 v64, v118, v110
	v_mul_f32_e32 v110, 0xbfb8aa3b, v104
	v_exp_f32_e32 v110, v110
	v_mul_f32_e32 v62, v62, v69
	v_mul_f32_e32 v63, v63, v69
	v_mul_f32_e32 v73, v109, v73
	v_mul_f32_e32 v109, v62, v142
	v_fmac_f32_e32 v105, v146, v114
	v_fmac_f32_e32 v109, v66, v138
	v_add_f32_e32 v110, 1.0, v110
	v_fmac_f32_e32 v109, v118, v106
	v_mul_f32_e32 v106, v130, v142
	v_rcp_f32_e32 v110, v110
	v_mul_f32_e32 v112, 0xbfb8aa3b, v105
	v_fmac_f32_e32 v106, v62, v138
	v_exp_f32_e32 v112, v112
	v_fmac_f32_e32 v106, v66, v118
	v_mul_f32_e32 v66, v122, v142
	v_fmac_f32_e32 v66, v130, v138
	v_fmac_f32_e32 v66, v62, v118
	v_mul_f32_e32 v62, v104, v110
	v_mul_f32_e32 v104, 0xbfb8aa3b, v108
	v_mul_f32_e32 v62, v64, v62
	v_add_f32_e32 v64, 1.0, v112
	v_exp_f32_e32 v104, v104
	v_mul_f32_e32 v110, 0xbfb8aa3b, v78
	v_rcp_f32_e32 v64, v64
	v_exp_f32_e32 v110, v110
	v_add_f32_e32 v104, 1.0, v104
	v_rcp_f32_e32 v104, v104
	v_mul_f32_e32 v64, v105, v64
	v_add_f32_e32 v105, 1.0, v110
	v_rcp_f32_e32 v105, v105
	v_mul_f32_e32 v109, v109, v64
	v_mul_f32_e32 v64, v108, v104
	v_mul_f32_e32 v104, v106, v64
	v_mul_f32_e32 v64, v78, v105
	v_mov_b32_dpp v115, v127 row_shr:1 row_mask:0xf bank_mask:0xf
	v_mul_f32_e32 v78, v66, v64
	v_mul_f32_e32 v64, v151, v115
	v_mov_b32_dpp v159, v135 row_shr:1 row_mask:0xf bank_mask:0xf
	v_fmac_f32_e32 v64, v79, v155
	v_fmac_f32_e32 v64, v147, v159
	v_mul_f32_e32 v108, 0xbfb8aa3b, v64
	v_exp_f32_e32 v108, v108
	v_mul_f32_e32 v105, v135, v155
	v_mul_f32_e32 v66, v65, v155
	v_fmac_f32_e32 v105, v65, v151
	v_fmac_f32_e32 v66, v79, v151
	v_fmac_f32_e32 v105, v79, v147
	v_mul_f32_e32 v79, v127, v155
	v_mul_f32_e32 v106, v63, v143
	v_fmac_f32_e32 v79, v135, v151
	v_mov_b32_dpp v107, v123 row_shr:1 row_mask:0xf bank_mask:0xf
	v_fmac_f32_e32 v106, v67, v139
	v_add_f32_e32 v108, 1.0, v108
	v_fmac_f32_e32 v66, v147, v115
	v_fmac_f32_e32 v79, v65, v147
	v_mul_f32_e32 v65, v139, v107
	v_fmac_f32_e32 v106, v119, v107
	v_mul_f32_e32 v107, v131, v143
	v_rcp_f32_e32 v108, v108
	v_fmac_f32_e32 v107, v63, v139
	v_mul_f32_e32 v110, 0xbfb8aa3b, v66
	v_fmac_f32_e32 v65, v67, v143
	v_fmac_f32_e32 v107, v67, v119
	v_mul_f32_e32 v67, v123, v143
	v_exp_f32_e32 v110, v110
	v_mov_b32_dpp v111, v131 row_shr:1 row_mask:0xf bank_mask:0xf
	v_fmac_f32_e32 v67, v131, v139
	v_fmac_f32_e32 v65, v119, v111
	v_fmac_f32_e32 v67, v63, v119
	v_mul_f32_e32 v63, v64, v108
	v_mul_f32_e32 v63, v65, v63
	v_mul_f32_e32 v65, 0xbfb8aa3b, v105
	v_add_f32_e32 v64, 1.0, v110
	v_exp_f32_e32 v65, v65
	v_mul_f32_e32 v108, 0xbfb8aa3b, v79
	v_rcp_f32_e32 v64, v64
	v_exp_f32_e32 v108, v108
	v_add_f32_e32 v65, 1.0, v65
	v_rcp_f32_e32 v65, v65
	v_mul_f32_e32 v64, v66, v64
	v_add_f32_e32 v66, 1.0, v108
	v_rcp_f32_e32 v66, v66
	v_mul_f32_e32 v106, v106, v64
	v_mul_f32_e32 v64, v105, v65
	v_mul_f32_e32 v75, v120, v75
	v_mul_f32_e32 v77, v113, v77
	v_mul_f32_e32 v105, v107, v64
	v_mul_f32_e32 v64, v79, v66
	v_mul_f32_e32 v79, v67, v64
	v_cvt_pk_bf16_f32 v66, v60, v61
	v_cvt_pk_bf16_f32 v67, v62, v63
	v_cvt_pk_bf16_f32 v64, v72, v73
	v_cvt_pk_bf16_f32 v65, v109, v106
	v_cvt_pk_bf16_f32 v62, v74, v76
	v_cvt_pk_bf16_f32 v63, v104, v105
	v_cvt_pk_bf16_f32 v60, v75, v77
	v_cvt_pk_bf16_f32 v61, v78, v79
	ds_read_b128 v[74:77], v218 offset:16
	ds_read_b128 v[106:109], v218 offset:528
	ds_read_b128 v[114:117], v218 offset:1552
	ds_read_b128 v[110:113], v218 offset:1040
	ds_read_b128 v[118:121], v218 offset:2064
	ds_read_b128 v[122:125], v218 offset:2576
	v_mov_b32_e32 v78, 0
	s_andn2_b64 vcc, exec, s[28:29]
	v_mov_b32_e32 v126, 0
	v_mov_b32_e32 v142, 0
	v_mov_b32_e32 v128, 0
	v_mov_b32_e32 v104, 0
	v_mov_b32_e32 v130, 0
	v_mov_b32_e32 v144, 0
	v_mov_b32_e32 v132, 0
	v_mov_b32_e32 v134, 0
	v_mov_b32_e32 v127, 0
	v_mov_b32_e32 v143, 0
	v_mov_b32_e32 v129, 0
	v_mov_b32_e32 v105, 0
	v_mov_b32_e32 v131, 0
	v_mov_b32_e32 v145, 0
	v_mov_b32_e32 v133, 0
	v_mov_b32_e32 v135, 0
	s_cbranch_vccnz .LBB0_1654
	ds_read_b128 v[126:129], v217 offset:1552
	ds_read_b128 v[130:133], v217 offset:528
	ds_read_b128 v[136:139], v217 offset:16
	ds_read_b128 v[146:149], v217 offset:1040
	s_waitcnt lgkmcnt(0)
	v_mov_b32_e32 v142, v127
	v_mov_b32_e32 v104, v129
	v_mov_b32_e32 v144, v131
	v_mov_b32_e32 v134, v133
	v_mov_b32_e32 v127, v146
	v_mov_b32_e32 v143, v147
	v_mov_b32_e32 v129, v148
	v_mov_b32_e32 v105, v149
	v_mov_b32_e32 v131, v136
	v_mov_b32_e32 v145, v137
	v_mov_b32_e32 v133, v138
	v_mov_b32_e32 v135, v139
.LBB0_1654:
	v_mov_b32_e32 v136, v96
	v_mov_b32_e32 v137, v96
	v_mov_b32_e32 v148, v97
	v_mov_b32_e32 v149, v97
	v_mov_b32_e32 v140, v96
	v_mov_b32_e32 v141, v96
	v_mov_b32_e32 v96, v97
	v_mul_f32_e32 v138, v42, v140
	v_mul_f32_e32 v139, v43, v141
	v_mul_f32_e32 v40, v40, v136
	v_mul_f32_e32 v41, v41, v137
	v_mul_f32_e32 v42, v32, v136
	v_mul_f32_e32 v43, v33, v137
	v_mul_f32_e32 v136, v38, v96
	v_mul_f32_e32 v137, v39, v97
	v_mul_f32_e32 v38, v36, v148
	v_mul_f32_e32 v39, v37, v149
	v_mov_b32_dpp v127, v84 row_shr:1 row_mask:0xf bank_mask:0xf
	v_mov_b32_dpp v126, v88 row_shr:1 row_mask:0xf bank_mask:0xf
	s_waitcnt lgkmcnt(0)
	v_mov_b32_e32 v36, v118
	v_mov_b32_e32 v37, v106
	v_mul_f32_e32 v140, v34, v140
	v_mul_f32_e32 v141, v35, v141
	v_mul_f32_e32 v30, v30, v96
	v_mul_f32_e32 v31, v31, v97
	v_mov_b32_e32 v96, v42
	v_mov_b32_e32 v97, v40
	v_mov_b32_e32 v34, v122
	v_mov_b32_e32 v35, v110
	v_mul_f32_e32 v32, v36, v126
	v_mul_f32_e32 v33, v37, v127
	v_mul_f32_e32 v28, v28, v148
	v_mul_f32_e32 v29, v29, v149
	v_mov_b32_dpp v131, v80 row_shr:1 row_mask:0xf bank_mask:0xf
	v_mov_b32_dpp v130, v92 row_shr:1 row_mask:0xf bank_mask:0xf
	v_fma_f32 v148, v96, v34, v32
	v_fma_f32 v149, v97, v35, v33
	v_mov_b32_e32 v32, v114
	v_mov_b32_e32 v33, v74
	v_fma_f32 v130, v32, v130, v148
	v_fma_f32 v131, v33, v131, v149
	v_mov_b32_e32 v148, v28
	v_mul_f32_e32 v28, 0xbfb8aa3b, v131
	v_exp_f32_e32 v28, v28
	v_mov_b32_e32 v149, v38
	v_mul_f32_e32 v150, v148, v34
	v_mul_f32_e32 v151, v149, v35
	v_mov_b32_dpp v143, v85 row_shr:1 row_mask:0xf bank_mask:0xf
	v_fmac_f32_e32 v150, v96, v36
	v_fmac_f32_e32 v151, v97, v37
	v_add_f32_e32 v28, 1.0, v28
	v_fma_f32 v126, v32, v126, v150
	v_fma_f32 v127, v33, v127, v151
	v_mov_b32_e32 v150, v92
	v_mov_b32_e32 v151, v80
	v_mul_f32_e32 v152, v150, v34
	v_mul_f32_e32 v153, v151, v35
	v_rcp_f32_e32 v28, v28
	v_mul_f32_e32 v38, 0xbfb8aa3b, v127
	v_fmac_f32_e32 v152, v148, v36
	v_fmac_f32_e32 v153, v149, v37
	v_exp_f32_e32 v38, v38
	v_fma_f32 v96, v96, v32, v152
	v_fma_f32 v97, v97, v33, v153
	v_mov_b32_e32 v152, v88
	v_mov_b32_e32 v153, v84
	v_mul_f32_e32 v152, v152, v34
	v_mul_f32_e32 v153, v153, v35
	v_mul_f32_e32 v28, v131, v28
	v_fma_f32 v150, v150, v36, v152
	v_fma_f32 v151, v151, v37, v153
	v_mul_f32_e32 v79, v130, v28
	v_fma_f32 v148, v148, v32, v150
	v_fma_f32 v149, v149, v33, v151
	v_add_f32_e32 v28, 1.0, v38
	v_mul_f32_e32 v38, 0xbfb8aa3b, v97
	v_exp_f32_e32 v38, v38
	v_mul_f32_e32 v40, 0xbfb8aa3b, v149
	v_exp_f32_e32 v40, v40
	v_rcp_f32_e32 v28, v28
	v_add_f32_e32 v38, 1.0, v38
	v_rcp_f32_e32 v38, v38
	v_add_f32_e32 v40, 1.0, v40
	v_rcp_f32_e32 v40, v40
	v_mul_f32_e32 v28, v127, v28
	v_mul_f32_e32 v114, v126, v28
	v_mul_f32_e32 v28, v97, v38
	v_mov_b32_dpp v142, v89 row_shr:1 row_mask:0xf bank_mask:0xf
	v_mov_b32_e32 v106, v119
	v_mul_f32_e32 v118, v96, v28
	v_mul_f32_e32 v28, v149, v40
	v_mov_b32_e32 v40, v43
	v_mov_b32_e32 v110, v123
	v_mul_f32_e32 v42, v106, v142
	v_mul_f32_e32 v43, v107, v143
	v_mov_b32_dpp v145, v81 row_shr:1 row_mask:0xf bank_mask:0xf
	v_mov_b32_dpp v144, v93 row_shr:1 row_mask:0xf bank_mask:0xf
	v_fmac_f32_e32 v42, v40, v110
	v_fmac_f32_e32 v43, v41, v111
	v_mov_b32_e32 v74, v115
	v_fmac_f32_e32 v42, v74, v144
	v_fmac_f32_e32 v43, v75, v145
	v_mov_b32_e32 v38, v29
	v_mul_f32_e32 v84, 0xbfb8aa3b, v43
	v_exp_f32_e32 v88, v84
	v_mul_f32_e32 v122, v148, v28
	v_mul_f32_e32 v28, v38, v110
	v_mul_f32_e32 v29, v39, v111
	v_mov_b32_e32 v84, v89
	v_fmac_f32_e32 v28, v40, v106
	v_fmac_f32_e32 v29, v41, v107
	v_mov_b32_e32 v80, v93
	v_mul_f32_e32 v84, v84, v110
	v_mul_f32_e32 v85, v85, v111
	v_fmac_f32_e32 v28, v74, v142
	v_fmac_f32_e32 v29, v75, v143
	v_mul_f32_e32 v92, v80, v110
	v_mul_f32_e32 v93, v81, v111
	v_fma_f32 v80, v80, v106, v84
	v_fma_f32 v81, v81, v107, v85
	v_add_f32_e32 v84, 1.0, v88
	v_rcp_f32_e32 v84, v84
	v_mul_f32_e32 v85, 0xbfb8aa3b, v29
	v_exp_f32_e32 v85, v85
	v_fmac_f32_e32 v92, v38, v106
	v_fmac_f32_e32 v93, v39, v107
	v_mul_f32_e32 v43, v43, v84
	v_fma_f32 v40, v40, v74, v92
	v_fma_f32 v41, v41, v75, v93
	v_fma_f32 v38, v38, v74, v80
	v_fma_f32 v39, v39, v75, v81
	v_mul_f32_e32 v115, v42, v43
	v_add_f32_e32 v42, 1.0, v85
	v_mul_f32_e32 v43, 0xbfb8aa3b, v41
	v_rcp_f32_e32 v42, v42
	v_exp_f32_e32 v43, v43
	v_mul_f32_e32 v80, 0xbfb8aa3b, v39
	v_exp_f32_e32 v80, v80
	v_mul_f32_e32 v29, v29, v42
	v_add_f32_e32 v42, 1.0, v43
	v_rcp_f32_e32 v42, v42
	v_add_f32_e32 v43, 1.0, v80
	v_rcp_f32_e32 v43, v43
	v_mul_f32_e32 v119, v28, v29
	v_mul_f32_e32 v28, v41, v42
	v_mul_f32_e32 v123, v40, v28
	v_mul_f32_e32 v28, v39, v43
	v_mov_b32_dpp v129, v86 row_shr:1 row_mask:0xf bank_mask:0xf
	v_mov_b32_dpp v128, v90 row_shr:1 row_mask:0xf bank_mask:0xf
	v_mov_b32_e32 v42, v120
	v_mov_b32_e32 v43, v108
	v_mul_f32_e32 v126, v38, v28
	v_mov_b32_e32 v28, v140
	v_mov_b32_e32 v29, v138
	v_mov_b32_e32 v40, v124
	v_mov_b32_e32 v41, v112
	v_mul_f32_e32 v38, v42, v128
	v_mul_f32_e32 v39, v43, v129
	v_mov_b32_dpp v133, v82 row_shr:1 row_mask:0xf bank_mask:0xf
	v_mov_b32_dpp v132, v94 row_shr:1 row_mask:0xf bank_mask:0xf
	v_fma_f32 v80, v28, v40, v38
	v_fma_f32 v81, v29, v41, v39
	v_mov_b32_e32 v38, v116
	v_mov_b32_e32 v39, v76
	v_fmac_f32_e32 v80, v38, v132
	v_fmac_f32_e32 v81, v39, v133
	v_mov_b32_e32 v84, v30
	v_mul_f32_e32 v30, 0xbfb8aa3b, v81
	v_exp_f32_e32 v30, v30
	v_mov_b32_e32 v85, v136
	v_mul_f32_e32 v88, v84, v40
	v_mul_f32_e32 v89, v85, v41
	v_mov_b32_e32 v92, v94
	v_fmac_f32_e32 v88, v28, v42
	v_fmac_f32_e32 v89, v29, v43
	v_mov_b32_e32 v93, v82
	v_fmac_f32_e32 v88, v38, v128
	v_fmac_f32_e32 v89, v39, v129
	v_add_f32_e32 v30, 1.0, v30
	v_mul_f32_e32 v96, v92, v40
	v_mul_f32_e32 v97, v93, v41
	v_rcp_f32_e32 v30, v30
	v_mul_f32_e32 v76, 0xbfb8aa3b, v89
	v_fmac_f32_e32 v96, v84, v42
	v_fmac_f32_e32 v97, v85, v43
	v_exp_f32_e32 v76, v76
	v_fma_f32 v28, v28, v38, v96
	v_fma_f32 v29, v29, v39, v97
	v_mov_b32_e32 v96, v90
	v_mov_b32_e32 v97, v86
	v_mul_f32_e32 v96, v96, v40
	v_mul_f32_e32 v97, v97, v41
	v_mul_f32_e32 v30, v81, v30
	v_fma_f32 v92, v92, v42, v96
	v_fma_f32 v93, v93, v43, v97
	v_mul_f32_e32 v90, v80, v30
	v_fma_f32 v84, v84, v38, v92
	v_fma_f32 v85, v85, v39, v93
	v_add_f32_e32 v30, 1.0, v76
	v_mul_f32_e32 v76, 0xbfb8aa3b, v29
	v_exp_f32_e32 v76, v76
	v_mul_f32_e32 v80, 0xbfb8aa3b, v85
	v_exp_f32_e32 v80, v80
	v_rcp_f32_e32 v30, v30
	v_add_f32_e32 v76, 1.0, v76
	v_rcp_f32_e32 v76, v76
	v_add_f32_e32 v80, 1.0, v80
	v_rcp_f32_e32 v80, v80
	v_mul_f32_e32 v30, v89, v30
	v_mul_f32_e32 v29, v29, v76
	v_mul_f32_e32 v89, v28, v29
	v_mul_f32_e32 v28, v85, v80
	v_mov_b32_dpp v105, v87 row_shr:1 row_mask:0xf bank_mask:0xf
	v_mov_b32_dpp v104, v91 row_shr:1 row_mask:0xf bank_mask:0xf
	v_mov_b32_e32 v108, v121
	v_mul_f32_e32 v92, v84, v28
	v_mov_b32_e32 v138, v141
	v_mov_b32_e32 v112, v125
	v_mul_f32_e32 v28, v108, v104
	v_mul_f32_e32 v29, v109, v105
	v_mov_b32_dpp v135, v83 row_shr:1 row_mask:0xf bank_mask:0xf
	v_mov_b32_dpp v134, v95 row_shr:1 row_mask:0xf bank_mask:0xf
	v_fmac_f32_e32 v28, v138, v112
	v_fmac_f32_e32 v29, v139, v113
	v_mov_b32_e32 v76, v117
	v_fmac_f32_e32 v28, v76, v134
	v_fmac_f32_e32 v29, v77, v135
	v_mov_b32_e32 v136, v31
	v_mul_f32_e32 v84, 0xbfb8aa3b, v29
	v_exp_f32_e32 v93, v84
	v_mul_f32_e32 v88, v88, v30
	v_mul_f32_e32 v30, v136, v112
	v_mul_f32_e32 v31, v137, v113
	v_mov_b32_e32 v86, v91
	v_fmac_f32_e32 v30, v138, v108
	v_fmac_f32_e32 v31, v139, v109
	v_mov_b32_e32 v82, v95
	v_mul_f32_e32 v84, v86, v112
	v_mul_f32_e32 v85, v87, v113
	v_fmac_f32_e32 v30, v76, v104
	v_fmac_f32_e32 v31, v77, v105
	v_mul_f32_e32 v80, v82, v112
	v_mul_f32_e32 v81, v83, v113
	v_fma_f32 v82, v82, v108, v84
	v_fma_f32 v83, v83, v109, v85
	v_add_f32_e32 v84, 1.0, v93
	v_rcp_f32_e32 v84, v84
	v_mul_f32_e32 v85, 0xbfb8aa3b, v31
	v_exp_f32_e32 v85, v85
	v_fmac_f32_e32 v80, v136, v108
	v_fmac_f32_e32 v81, v137, v109
	v_mul_f32_e32 v29, v29, v84
	v_fmac_f32_e32 v80, v138, v76
	v_fmac_f32_e32 v81, v139, v77
	v_fmac_f32_e32 v82, v136, v76
	v_fmac_f32_e32 v83, v137, v77
	v_mul_f32_e32 v28, v28, v29
	v_add_f32_e32 v29, 1.0, v85
	v_mul_f32_e32 v84, 0xbfb8aa3b, v81
	v_rcp_f32_e32 v29, v29
	v_exp_f32_e32 v84, v84
	v_mul_f32_e32 v85, 0xbfb8aa3b, v83
	v_exp_f32_e32 v85, v85
	v_mul_f32_e32 v29, v31, v29
	v_add_f32_e32 v31, 1.0, v84
	v_rcp_f32_e32 v31, v31
	v_add_f32_e32 v84, 1.0, v85
	v_rcp_f32_e32 v84, v84
	v_mul_f32_e32 v85, v30, v29
	v_mul_f32_e32 v29, v81, v31
	v_lshl_or_b32 v72, s56, 7, v210
	v_mul_f32_e32 v80, v80, v29
	v_mul_f32_e32 v29, v83, v84
	v_lshl_add_u32 v146, s57, 8, v209
	v_ashrrev_i32_e32 v73, 31, v72
	v_mul_f32_e32 v81, v82, v29
	v_cvt_pk_bf16_f32 v104, v79, v115
	v_cvt_pk_bf16_f32 v105, v90, v28
	v_mov_b64_e32 v[28:29], s[24:25]
	v_mad_i64_i32 v[30:31], s[28:29], v146, s54, v[28:29]
	v_lshlrev_b64 v[82:83], 1, v[72:73]
	v_lshl_add_u64 v[30:31], v[30:31], 0, v[82:83]
	global_store_dwordx4 v[30:31], v[102:105], off nt
	v_or_b32_e32 v30, 1, v146
	v_mad_i64_i32 v[30:31], s[28:29], v30, s54, v[28:29]
	v_lshl_add_u64 v[30:31], v[30:31], 0, v[82:83]
	v_cvt_pk_bf16_f32 v102, v114, v119
	v_cvt_pk_bf16_f32 v103, v88, v85
	global_store_dwordx4 v[30:31], v[100:103], off nt
	v_or_b32_e32 v30, 2, v146
	v_mad_i64_i32 v[30:31], s[28:29], v30, s54, v[28:29]
	v_lshl_add_u64 v[30:31], v[30:31], 0, v[82:83]
	v_cvt_pk_bf16_f32 v100, v118, v123
	v_cvt_pk_bf16_f32 v101, v89, v80
	global_store_dwordx4 v[30:31], v[98:101], off nt
	v_or_b32_e32 v30, 3, v146
	v_mad_i64_i32 v[28:29], s[28:29], v30, s54, v[28:29]
	v_cvt_pk_bf16_f32 v72, v122, v126
	v_cvt_pk_bf16_f32 v73, v92, v81
	v_lshl_add_u64 v[28:29], v[28:29], 0, v[82:83]
	global_store_dwordx4 v[28:29], v[70:73], off nt
	s_andn2_b64 vcc, exec, s[26:27]
	v_mov_b32_e32 v84, 0
	v_mov_b32_e32 v80, 0
	v_mov_b32_e32 v70, 0
	v_mov_b32_e32 v28, 0
	v_mov_b32_e32 v86, 0
	v_mov_b32_e32 v30, 0
	v_mov_b32_e32 v72, 0
	v_mov_b32_e32 v79, 0
	v_mov_b32_e32 v85, 0
	v_mov_b32_e32 v81, 0
	v_mov_b32_e32 v71, 0
	v_mov_b32_e32 v29, 0
	v_mov_b32_e32 v87, 0
	v_mov_b32_e32 v31, 0
	v_mov_b32_e32 v73, 0
	s_cbranch_vccnz .LBB0_1656
	ds_read_b128 v[78:81], v160 offset:1552
	ds_read_b128 v[28:31], v160 offset:528
	ds_read_b128 v[88:91], v160 offset:16
	ds_read_b128 v[92:95], v160 offset:1040
	s_waitcnt lgkmcnt(0)
	v_mov_b32_e32 v84, v79
	v_mov_b32_e32 v70, v81
	v_mov_b32_e32 v86, v29
	v_mov_b32_e32 v72, v31
	v_mov_b32_e32 v79, v92
	v_mov_b32_e32 v85, v93
	v_mov_b32_e32 v81, v94
	v_mov_b32_e32 v71, v95
	v_mov_b32_e32 v29, v88
	v_mov_b32_e32 v87, v89
	v_mov_b32_e32 v31, v90
	v_mov_b32_e32 v73, v91
.LBB0_1656:
	v_mov_b32_e32 v88, v68
	v_mov_b32_e32 v89, v68
	v_mov_b32_e32 v92, v68
	v_mov_b32_e32 v93, v68
	v_mul_f32_e32 v12, v12, v88
	v_mul_f32_e32 v13, v13, v89
	v_mul_f32_e32 v88, v4, v88
	v_mul_f32_e32 v89, v5, v89
	v_mov_b32_e32 v68, v69
	v_mov_b32_dpp v79, v52 row_shr:1 row_mask:0xf bank_mask:0xf
	v_mov_b32_dpp v78, v56 row_shr:1 row_mask:0xf bank_mask:0xf
	v_mov_b32_e32 v90, v69
	v_mov_b32_e32 v91, v69
	v_mul_f32_e32 v4, v10, v68
	v_mul_f32_e32 v5, v11, v69
	v_mul_f32_e32 v2, v2, v68
	v_mul_f32_e32 v3, v3, v69
	v_mov_b32_e32 v10, v88
	v_mov_b32_e32 v11, v12
	v_mul_f32_e32 v68, v36, v78
	v_mul_f32_e32 v69, v37, v79
	v_mov_b32_dpp v29, v44 row_shr:1 row_mask:0xf bank_mask:0xf
	v_mov_b32_dpp v28, v48 row_shr:1 row_mask:0xf bank_mask:0xf
	v_fmac_f32_e32 v68, v10, v34
	v_fmac_f32_e32 v69, v11, v35
	v_mul_f32_e32 v0, v0, v90
	v_mul_f32_e32 v1, v1, v91
	v_fma_f32 v28, v32, v28, v68
	v_fma_f32 v29, v33, v29, v69
	v_mov_b32_e32 v68, v0
	v_mul_f32_e32 v0, 0xbfb8aa3b, v29
	v_mul_f32_e32 v8, v8, v90
	v_mul_f32_e32 v9, v9, v91
	v_exp_f32_e32 v0, v0
	v_mov_b32_e32 v69, v8
	v_mul_f32_e32 v90, v68, v34
	v_mul_f32_e32 v91, v69, v35
	v_mul_f32_e32 v14, v14, v92
	v_mul_f32_e32 v15, v15, v93
	v_fmac_f32_e32 v90, v10, v36
	v_fmac_f32_e32 v91, v11, v37
	v_add_f32_e32 v0, 1.0, v0
	v_fma_f32 v78, v32, v78, v90
	v_fma_f32 v79, v33, v79, v91
	v_mov_b32_e32 v90, v48
	v_mov_b32_e32 v91, v44
	v_mul_f32_e32 v6, v6, v92
	v_mul_f32_e32 v7, v7, v93
	v_mul_f32_e32 v92, v90, v34
	v_mul_f32_e32 v93, v91, v35
	v_rcp_f32_e32 v0, v0
	v_mul_f32_e32 v8, 0xbfb8aa3b, v79
	v_fmac_f32_e32 v92, v68, v36
	v_fmac_f32_e32 v93, v69, v37
	v_exp_f32_e32 v8, v8
	v_fma_f32 v10, v10, v32, v92
	v_fma_f32 v11, v11, v33, v93
	v_mov_b32_e32 v92, v56
	v_mov_b32_e32 v93, v52
	v_mul_f32_e32 v34, v92, v34
	v_mul_f32_e32 v35, v93, v35
	v_mul_f32_e32 v0, v29, v0
	v_fmac_f32_e32 v34, v90, v36
	v_fmac_f32_e32 v35, v91, v37
	v_mov_b32_dpp v85, v53 row_shr:1 row_mask:0xf bank_mask:0xf
	v_fma_f32 v32, v68, v32, v34
	v_fma_f32 v33, v69, v33, v35
	v_mul_f32_e32 v34, v28, v0
	v_add_f32_e32 v0, 1.0, v8
	v_mul_f32_e32 v8, 0xbfb8aa3b, v11
	v_exp_f32_e32 v8, v8
	v_mul_f32_e32 v12, 0xbfb8aa3b, v33
	v_exp_f32_e32 v12, v12
	v_rcp_f32_e32 v0, v0
	v_add_f32_e32 v8, 1.0, v8
	v_rcp_f32_e32 v8, v8
	v_add_f32_e32 v12, 1.0, v12
	v_rcp_f32_e32 v12, v12
	v_mul_f32_e32 v0, v79, v0
	v_mul_f32_e32 v35, v78, v0
	v_mul_f32_e32 v0, v11, v8
	v_mov_b32_dpp v84, v57 row_shr:1 row_mask:0xf bank_mask:0xf
	v_mul_f32_e32 v36, v10, v0
	v_mul_f32_e32 v0, v33, v12
	v_mov_b32_e32 v12, v89
	v_mul_f32_e32 v10, v106, v84
	v_mul_f32_e32 v11, v107, v85
	v_mov_b32_e32 v44, v49
	v_mov_b32_dpp v87, v45 row_shr:1 row_mask:0xf bank_mask:0xf
	v_mov_b32_dpp v86, v49 row_shr:1 row_mask:0xf bank_mask:0xf
	v_fmac_f32_e32 v10, v12, v110
	v_fmac_f32_e32 v11, v13, v111
	v_mov_b32_e32 v8, v1
	v_mul_f32_e32 v28, v44, v110
	v_mul_f32_e32 v29, v45, v111
	v_mul_f32_e32 v32, v32, v0
	v_fmac_f32_e32 v10, v74, v86
	v_fmac_f32_e32 v11, v75, v87
	v_mul_f32_e32 v0, v8, v110
	v_mul_f32_e32 v1, v9, v111
	v_fmac_f32_e32 v28, v8, v106
	v_fmac_f32_e32 v29, v9, v107
	v_fmac_f32_e32 v0, v12, v106
	v_fmac_f32_e32 v1, v13, v107
	v_fma_f32 v12, v12, v74, v28
	v_fma_f32 v13, v13, v75, v29
	v_mul_f32_e32 v28, 0xbfb8aa3b, v11
	v_exp_f32_e32 v33, v28
	v_fmac_f32_e32 v0, v74, v84
	v_fmac_f32_e32 v1, v75, v85
	v_mov_b32_e32 v52, v57
	v_mul_f32_e32 v37, 0xbfb8aa3b, v1
	v_add_f32_e32 v33, 1.0, v33
	v_rcp_f32_e32 v33, v33
	v_exp_f32_e32 v37, v37
	v_mul_f32_e32 v28, v52, v110
	v_mul_f32_e32 v29, v53, v111
	v_mov_b32_dpp v81, v54 row_shr:1 row_mask:0xf bank_mask:0xf
	v_fmac_f32_e32 v28, v44, v106
	v_fmac_f32_e32 v29, v45, v107
	v_mul_f32_e32 v11, v11, v33
	v_fma_f32 v8, v8, v74, v28
	v_fma_f32 v9, v9, v75, v29
	v_mul_f32_e32 v33, v10, v11
	v_add_f32_e32 v10, 1.0, v37
	v_mul_f32_e32 v11, 0xbfb8aa3b, v13
	v_rcp_f32_e32 v10, v10
	v_exp_f32_e32 v11, v11
	v_mul_f32_e32 v28, 0xbfb8aa3b, v9
	v_exp_f32_e32 v28, v28
	v_mul_f32_e32 v1, v1, v10
	v_add_f32_e32 v10, 1.0, v11
	v_rcp_f32_e32 v10, v10
	v_add_f32_e32 v11, 1.0, v28
	v_rcp_f32_e32 v11, v11
	v_mul_f32_e32 v37, v0, v1
	v_mul_f32_e32 v0, v13, v10
	v_mul_f32_e32 v44, v12, v0
	v_mul_f32_e32 v0, v9, v11
	v_mov_b32_dpp v80, v58 row_shr:1 row_mask:0xf bank_mask:0xf
	v_mul_f32_e32 v45, v8, v0
	v_mov_b32_e32 v0, v6
	v_mov_b32_e32 v1, v14
	v_mul_f32_e32 v8, v42, v80
	v_mul_f32_e32 v9, v43, v81
	v_mov_b32_dpp v31, v46 row_shr:1 row_mask:0xf bank_mask:0xf
	v_mov_b32_dpp v30, v50 row_shr:1 row_mask:0xf bank_mask:0xf
	v_fmac_f32_e32 v8, v0, v40
	v_fmac_f32_e32 v9, v1, v41
	v_mov_b32_e32 v10, v2
	v_fmac_f32_e32 v8, v38, v30
	v_fmac_f32_e32 v9, v39, v31
	v_mov_b32_e32 v11, v4
	v_mul_f32_e32 v2, 0xbfb8aa3b, v9
	v_exp_f32_e32 v2, v2
	v_mul_f32_e32 v12, v10, v40
	v_mul_f32_e32 v13, v11, v41
	v_mov_b32_e32 v28, v50
	v_fmac_f32_e32 v12, v0, v42
	v_fmac_f32_e32 v13, v1, v43
	v_mov_b32_e32 v29, v46
	v_fmac_f32_e32 v12, v38, v80
	v_fmac_f32_e32 v13, v39, v81
	v_add_f32_e32 v2, 1.0, v2
	v_mul_f32_e32 v30, v28, v40
	v_mul_f32_e32 v31, v29, v41
	v_rcp_f32_e32 v2, v2
	v_mul_f32_e32 v4, 0xbfb8aa3b, v13
	v_fmac_f32_e32 v30, v10, v42
	v_fmac_f32_e32 v31, v11, v43
	v_exp_f32_e32 v4, v4
	v_fma_f32 v0, v0, v38, v30
	v_fma_f32 v1, v1, v39, v31
	v_mov_b32_e32 v30, v58
	v_mov_b32_e32 v31, v54
	v_mul_f32_e32 v30, v30, v40
	v_mul_f32_e32 v31, v31, v41
	v_mul_f32_e32 v2, v9, v2
	v_fma_f32 v28, v28, v42, v30
	v_fma_f32 v29, v29, v43, v31
	v_mov_b32_dpp v71, v55 row_shr:1 row_mask:0xf bank_mask:0xf
	v_fma_f32 v10, v10, v38, v28
	v_fma_f32 v11, v11, v39, v29
	v_mul_f32_e32 v28, v8, v2
	v_add_f32_e32 v2, 1.0, v4
	v_mul_f32_e32 v4, 0xbfb8aa3b, v1
	v_exp_f32_e32 v4, v4
	v_mul_f32_e32 v6, 0xbfb8aa3b, v11
	v_exp_f32_e32 v6, v6
	v_rcp_f32_e32 v2, v2
	v_add_f32_e32 v4, 1.0, v4
	v_rcp_f32_e32 v4, v4
	v_add_f32_e32 v6, 1.0, v6
	v_rcp_f32_e32 v6, v6
	v_mul_f32_e32 v2, v13, v2
	v_mul_f32_e32 v1, v1, v4
	v_mul_f32_e32 v13, v0, v1
	v_mul_f32_e32 v0, v11, v6
	v_mov_b32_dpp v70, v59 row_shr:1 row_mask:0xf bank_mask:0xf
	v_mul_f32_e32 v10, v10, v0
	v_mov_b32_e32 v14, v7
	v_mul_f32_e32 v0, v108, v70
	v_mul_f32_e32 v1, v109, v71
	v_mov_b32_dpp v73, v47 row_shr:1 row_mask:0xf bank_mask:0xf
	v_mov_b32_dpp v72, v51 row_shr:1 row_mask:0xf bank_mask:0xf
	v_fmac_f32_e32 v0, v14, v112
	v_fmac_f32_e32 v1, v15, v113
	v_mov_b32_e32 v4, v3
	v_fmac_f32_e32 v0, v76, v72
	v_fmac_f32_e32 v1, v77, v73
	v_mul_f32_e32 v12, v12, v2
	v_mul_f32_e32 v8, 0xbfb8aa3b, v1
	v_exp_f32_e32 v11, v8
	v_mul_f32_e32 v2, v4, v112
	v_mul_f32_e32 v3, v5, v113
	v_mov_b32_e32 v46, v51
	v_fmac_f32_e32 v2, v14, v108
	v_fmac_f32_e32 v3, v15, v109
	v_mul_f32_e32 v6, v46, v112
	v_mul_f32_e32 v7, v47, v113
	v_fmac_f32_e32 v2, v76, v70
	v_fmac_f32_e32 v3, v77, v71
	v_fmac_f32_e32 v6, v4, v108
	v_fmac_f32_e32 v7, v5, v109
	v_add_f32_e32 v11, 1.0, v11
	v_fmac_f32_e32 v6, v14, v76
	v_fmac_f32_e32 v7, v15, v77
	v_rcp_f32_e32 v11, v11
	v_mul_f32_e32 v14, 0xbfb8aa3b, v3
	v_exp_f32_e32 v14, v14
	v_mov_b32_e32 v54, v59
	v_mul_f32_e32 v8, v54, v112
	v_mul_f32_e32 v9, v55, v113
	v_mul_f32_e32 v1, v1, v11
	v_fmac_f32_e32 v8, v46, v108
	v_fmac_f32_e32 v9, v47, v109
	v_mul_f32_e32 v0, v0, v1
	v_fma_f32 v4, v4, v76, v8
	v_fma_f32 v5, v5, v77, v9
	v_add_f32_e32 v1, 1.0, v14
	v_mul_f32_e32 v8, 0xbfb8aa3b, v7
	v_rcp_f32_e32 v1, v1
	v_exp_f32_e32 v8, v8
	v_mul_f32_e32 v9, 0xbfb8aa3b, v5
	v_exp_f32_e32 v9, v9
	v_mul_f32_e32 v1, v3, v1
	v_add_f32_e32 v3, 1.0, v8
	v_rcp_f32_e32 v3, v3
	v_add_f32_e32 v8, 1.0, v9
	v_rcp_f32_e32 v8, v8
	v_mul_f32_e32 v9, v2, v1
	v_mul_f32_e32 v1, v7, v3
	v_mul_f32_e32 v6, v6, v1
	v_mul_f32_e32 v1, v5, v8
	v_add_u32_e32 v94, 0x80, v146
	v_mul_f32_e32 v4, v4, v1
	v_cvt_pk_bf16_f32 v68, v34, v33
	v_cvt_pk_bf16_f32 v69, v28, v0
	v_mov_b64_e32 v[0:1], s[24:25]
	v_mad_i64_i32 v[2:3], s[26:27], v94, s54, v[0:1]
	v_lshl_add_u64 v[2:3], v[2:3], 0, v[82:83]
	global_store_dwordx4 v[2:3], v[66:69], off nt
	v_add_u32_e32 v2, 0x81, v146
	v_mad_i64_i32 v[2:3], s[26:27], v2, s54, v[0:1]
	v_lshl_add_u64 v[2:3], v[2:3], 0, v[82:83]
	v_cvt_pk_bf16_f32 v66, v35, v37
	v_cvt_pk_bf16_f32 v67, v12, v9
	global_store_dwordx4 v[2:3], v[64:67], off nt
	v_add_u32_e32 v2, 0x82, v146
	v_mad_i64_i32 v[2:3], s[26:27], v2, s54, v[0:1]
	v_lshl_add_u64 v[2:3], v[2:3], 0, v[82:83]
	v_cvt_pk_bf16_f32 v64, v36, v44
	v_cvt_pk_bf16_f32 v65, v13, v6
	global_store_dwordx4 v[2:3], v[62:65], off nt
	v_add_u32_e32 v2, 0x83, v146
	v_mad_i64_i32 v[0:1], s[26:27], v2, s54, v[0:1]
	v_lshl_add_u64 v[0:1], v[0:1], 0, v[82:83]
	v_cvt_pk_bf16_f32 v62, v32, v45
	v_cvt_pk_bf16_f32 v63, v10, v4
	global_store_dwordx4 v[0:1], v[60:63], off nt
	s_and_b64 vcc, exec, s[8:9]
	s_mov_b64 s[8:9], -1
	s_cbranch_vccnz .LBB0_1637
	s_xor_b32 s8, s11, 0x1000
	s_add_i32 s11, s8, 0
	s_add_i32 s11, s11, 0x24010
	s_and_saveexec_b64 s[8:9], s[2:3]
	s_cbranch_execz .LBB0_1659
	v_add3_u32 v0, s11, v215, v190
	s_waitcnt vmcnt(8)
	ds_write_b128 v0, v[16:19]

.LBB0_1741:
	ds_read_b128 v[128:131], v190
	ds_read_b128 v[132:135], v190 offset:1024
	ds_read_b128 v[136:139], v190 offset:2048
	ds_read_b128 v[140:143], v190 offset:3072
	s_add_u32 s16, s14, 0x100
	s_addc_u32 s17, s15, 0
	s_cmp_eq_u32 s47, 40
	s_cselect_b32 s21, s1, s17
	s_cselect_b32 s20, s0, s16
	s_cselect_b32 s19, s7, s46
	s_cselect_b32 s18, s6, s45
	v_lshl_add_u64 v[184:185], s[14:15], 0, v[160:161]
	s_add_i32 m0, s28, 0xc000
	ds_read_b128 v[144:147], v191
	ds_read_b128 v[148:151], v191 offset:1024
	ds_read_b128 v[168:171], v191 offset:2048
	ds_read_b128 v[172:175], v191 offset:3072
	ds_read_b128 v[176:179], v191 offset:4096
	ds_read_b128 v[180:183], v191 offset:5120
	ds_read_b128 v[194:197], v191 offset:6144
	ds_read_b128 v[198:201], v191 offset:7168
	global_load_lds_dwordx4 v[184:185], off
	v_lshl_add_u64 v[184:185], s[14:15], 0, v[162:163]
	s_add_i32 m0, s28, 0xe000
	s_nop 0
	global_load_lds_dwordx4 v[184:185], off
	s_waitcnt lgkmcnt(8)
	s_barrier
	s_waitcnt lgkmcnt(0)
	s_setprio 1
	s_waitcnt lgkmcnt(0)
	v_mfma_f32_16x16x32_bf16 v[124:127], v[128:131], v[144:147], v[124:127]
	v_mfma_f32_16x16x32_bf16 v[120:123], v[136:139], v[144:147], v[120:123]
	v_mfma_f32_16x16x32_bf16 v[108:111], v[128:131], v[168:171], v[108:111]
	v_mfma_f32_16x16x32_bf16 v[104:107], v[136:139], v[168:171], v[104:107]
	v_mfma_f32_16x16x32_bf16 v[92:95], v[128:131], v[176:179], v[92:95]
	v_mfma_f32_16x16x32_bf16 v[88:91], v[136:139], v[176:179], v[88:91]
	v_mfma_f32_16x16x32_bf16 v[76:79], v[128:131], v[194:197], v[76:79]
	v_mfma_f32_16x16x32_bf16 v[72:75], v[136:139], v[194:197], v[72:75]
	v_mfma_f32_16x16x32_bf16 v[124:127], v[132:135], v[148:151], v[124:127]
	v_mfma_f32_16x16x32_bf16 v[120:123], v[140:143], v[148:151], v[120:123]
	v_mfma_f32_16x16x32_bf16 v[108:111], v[132:135], v[172:175], v[108:111]
	v_mfma_f32_16x16x32_bf16 v[104:107], v[140:143], v[172:175], v[104:107]
	v_mfma_f32_16x16x32_bf16 v[92:95], v[132:135], v[180:183], v[92:95]
	v_mfma_f32_16x16x32_bf16 v[88:91], v[140:143], v[180:183], v[88:91]
	v_mfma_f32_16x16x32_bf16 v[76:79], v[132:135], v[198:201], v[76:79]
	v_mfma_f32_16x16x32_bf16 v[72:75], v[140:143], v[198:201], v[72:75]
	s_setprio 0
	s_barrier
	s_add_i32 s14, s39, s27
	v_lshl_add_u64 v[184:185], s[18:19], 0, v[154:155]
	s_mov_b32 m0, s14
	ds_read_b128 v[202:205], v192
	ds_read_b128 v[206:209], v192 offset:1024
	ds_read_b128 v[210:213], v192 offset:2048
	ds_read_b128 v[214:217], v192 offset:3072
	global_load_lds_dwordx4 v[184:185], off
	v_lshl_add_u64 v[218:219], s[18:19], 0, v[158:159]
	s_add_i32 m0, s14, 0x2000
	s_nop 0
	global_load_lds_dwordx4 v[218:219], off
	s_barrier
	s_waitcnt lgkmcnt(0)
	s_setprio 1
	s_waitcnt lgkmcnt(0)
	v_mfma_f32_16x16x32_bf16 v[116:119], v[202:205], v[144:147], v[116:119]
	v_mfma_f32_16x16x32_bf16 v[112:115], v[210:213], v[144:147], v[112:115]
	v_mfma_f32_16x16x32_bf16 v[100:103], v[202:205], v[168:171], v[100:103]
	v_mfma_f32_16x16x32_bf16 v[96:99], v[210:213], v[168:171], v[96:99]
	v_mfma_f32_16x16x32_bf16 v[84:87], v[202:205], v[176:179], v[84:87]
	v_mfma_f32_16x16x32_bf16 v[80:83], v[210:213], v[176:179], v[80:83]
	v_mfma_f32_16x16x32_bf16 v[68:71], v[202:205], v[194:197], v[68:71]
	v_mfma_f32_16x16x32_bf16 v[64:67], v[210:213], v[194:197], v[64:67]
	v_mfma_f32_16x16x32_bf16 v[116:119], v[206:209], v[148:151], v[116:119]
	v_mfma_f32_16x16x32_bf16 v[112:115], v[214:217], v[148:151], v[112:115]
	v_mfma_f32_16x16x32_bf16 v[100:103], v[206:209], v[172:175], v[100:103]
	v_mfma_f32_16x16x32_bf16 v[96:99], v[214:217], v[172:175], v[96:99]
	v_mfma_f32_16x16x32_bf16 v[84:87], v[206:209], v[180:183], v[84:87]
	v_mfma_f32_16x16x32_bf16 v[80:83], v[214:217], v[180:183], v[80:83]
	v_mfma_f32_16x16x32_bf16 v[68:71], v[206:209], v[198:201], v[68:71]
	v_mfma_f32_16x16x32_bf16 v[64:67], v[214:217], v[198:201], v[64:67]
	s_setprio 0
	s_mov_b32 m0, s28
	v_lshl_add_u64 v[220:221], s[20:21], 0, v[152:153]
	s_barrier
	ds_read_b128 v[144:147], v191 offset:16384
	ds_read_b128 v[148:151], v191 offset:17408
	ds_read_b128 v[168:171], v191 offset:18432
	ds_read_b128 v[172:175], v191 offset:19456
	ds_read_b128 v[176:179], v191 offset:20480
	ds_read_b128 v[180:183], v191 offset:21504
	ds_read_b128 v[194:197], v191 offset:22528
	ds_read_b128 v[198:201], v191 offset:23552
	global_load_lds_dwordx4 v[220:221], off
	v_lshl_add_u64 v[222:223], s[20:21], 0, v[156:157]
	s_mov_b32 m0, s29
	s_nop 0
	global_load_lds_dwordx4 v[222:223], off
	s_barrier
	s_waitcnt lgkmcnt(0)
	s_setprio 1
	s_waitcnt lgkmcnt(0)
	v_mfma_f32_16x16x32_bf16 v[60:63], v[128:131], v[144:147], v[60:63]
	v_mfma_f32_16x16x32_bf16 v[56:59], v[136:139], v[144:147], v[56:59]
	v_mfma_f32_16x16x32_bf16 v[44:47], v[128:131], v[168:171], v[44:47]
	v_mfma_f32_16x16x32_bf16 v[40:43], v[136:139], v[168:171], v[40:43]
	v_mfma_f32_16x16x32_bf16 v[28:31], v[128:131], v[176:179], v[28:31]
	v_mfma_f32_16x16x32_bf16 v[24:27], v[136:139], v[176:179], v[24:27]
	v_mfma_f32_16x16x32_bf16 v[12:15], v[128:131], v[194:197], v[12:15]
	v_mfma_f32_16x16x32_bf16 v[8:11], v[136:139], v[194:197], v[8:11]
	v_mfma_f32_16x16x32_bf16 v[60:63], v[132:135], v[148:151], v[60:63]
	v_mfma_f32_16x16x32_bf16 v[56:59], v[140:143], v[148:151], v[56:59]
	v_mfma_f32_16x16x32_bf16 v[44:47], v[132:135], v[172:175], v[44:47]
	v_mfma_f32_16x16x32_bf16 v[40:43], v[140:143], v[172:175], v[40:43]
	v_mfma_f32_16x16x32_bf16 v[28:31], v[132:135], v[180:183], v[28:31]
	v_mfma_f32_16x16x32_bf16 v[24:27], v[140:143], v[180:183], v[24:27]
	v_mfma_f32_16x16x32_bf16 v[12:15], v[132:135], v[198:201], v[12:15]
	v_mfma_f32_16x16x32_bf16 v[8:11], v[140:143], v[198:201], v[8:11]
	s_setprio 0
	s_barrier
	s_add_u32 s14, s18, 0xb0000
	s_addc_u32 s15, s19, 0
	s_add_i32 s48, s40, s27
	v_lshl_add_u64 v[128:129], s[14:15], 0, v[154:155]
	s_mov_b32 m0, s48
	s_nop 0
	global_load_lds_dwordx4 v[128:129], off
	v_lshl_add_u64 v[128:129], s[14:15], 0, v[158:159]
	s_add_i32 m0, s48, 0x2000
	s_nop 0
	global_load_lds_dwordx4 v[128:129], off
	s_waitcnt vmcnt(6)
	s_barrier
	s_setprio 1
	v_mfma_f32_16x16x32_bf16 v[52:55], v[202:205], v[144:147], v[52:55]
	v_mfma_f32_16x16x32_bf16 v[48:51], v[210:213], v[144:147], v[48:51]
	v_mfma_f32_16x16x32_bf16 v[36:39], v[202:205], v[168:171], v[36:39]
	v_mfma_f32_16x16x32_bf16 v[32:35], v[210:213], v[168:171], v[32:35]
	v_mfma_f32_16x16x32_bf16 v[20:23], v[202:205], v[176:179], v[20:23]
	v_mfma_f32_16x16x32_bf16 v[16:19], v[210:213], v[176:179], v[16:19]
	v_mfma_f32_16x16x32_bf16 v[4:7], v[202:205], v[194:197], v[4:7]
	v_mfma_f32_16x16x32_bf16 v[0:3], v[210:213], v[194:197], v[0:3]
	v_mfma_f32_16x16x32_bf16 v[52:55], v[206:209], v[148:151], v[52:55]
	v_mfma_f32_16x16x32_bf16 v[48:51], v[214:217], v[148:151], v[48:51]
	v_mfma_f32_16x16x32_bf16 v[36:39], v[206:209], v[172:175], v[36:39]
	v_mfma_f32_16x16x32_bf16 v[32:35], v[214:217], v[172:175], v[32:35]
	v_mfma_f32_16x16x32_bf16 v[20:23], v[206:209], v[180:183], v[20:23]
	v_mfma_f32_16x16x32_bf16 v[16:19], v[214:217], v[180:183], v[16:19]
	v_mfma_f32_16x16x32_bf16 v[4:7], v[206:209], v[198:201], v[4:7]
	v_mfma_f32_16x16x32_bf16 v[0:3], v[214:217], v[198:201], v[0:3]
	s_setprio 0
	s_add_i32 s48, 0, 0x18000
	v_add_u32_e32 v140, s48, v187
	s_barrier
	ds_read_b128 v[128:131], v140
	ds_read_b128 v[132:135], v140 offset:1024
	ds_read_b128 v[136:139], v140 offset:2048
	ds_read_b128 v[140:143], v140 offset:3072
	s_add_u32 s14, s20, 0xb0000
	s_addc_u32 s15, s21, 0
	s_mov_b32 m0, s30
	v_lshl_add_u64 v[202:203], s[14:15], 0, v[152:153]
	ds_read_b128 v[144:147], v191 offset:32768
	ds_read_b128 v[148:151], v191 offset:33792
	ds_read_b128 v[168:171], v191 offset:34816
	ds_read_b128 v[172:175], v191 offset:35840
	ds_read_b128 v[176:179], v191 offset:36864
	ds_read_b128 v[180:183], v191 offset:37888
	ds_read_b128 v[194:197], v191 offset:38912
	ds_read_b128 v[198:201], v191 offset:39936
	global_load_lds_dwordx4 v[202:203], off
	v_lshl_add_u64 v[202:203], s[14:15], 0, v[156:157]
	s_mov_b32 m0, s31
	s_nop 0
	global_load_lds_dwordx4 v[202:203], off
	s_waitcnt lgkmcnt(8)
	s_barrier
	s_waitcnt lgkmcnt(0)
	s_setprio 1
	s_waitcnt lgkmcnt(0)
	v_mfma_f32_16x16x32_bf16 v[124:127], v[128:131], v[144:147], v[124:127]
	v_mfma_f32_16x16x32_bf16 v[120:123], v[136:139], v[144:147], v[120:123]
	v_mfma_f32_16x16x32_bf16 v[108:111], v[128:131], v[168:171], v[108:111]
	v_mfma_f32_16x16x32_bf16 v[104:107], v[136:139], v[168:171], v[104:107]
	v_mfma_f32_16x16x32_bf16 v[92:95], v[128:131], v[176:179], v[92:95]
	v_mfma_f32_16x16x32_bf16 v[88:91], v[136:139], v[176:179], v[88:91]
	v_mfma_f32_16x16x32_bf16 v[76:79], v[128:131], v[194:197], v[76:79]
	v_mfma_f32_16x16x32_bf16 v[72:75], v[136:139], v[194:197], v[72:75]
	v_mfma_f32_16x16x32_bf16 v[124:127], v[132:135], v[148:151], v[124:127]
	v_mfma_f32_16x16x32_bf16 v[120:123], v[140:143], v[148:151], v[120:123]
	v_mfma_f32_16x16x32_bf16 v[108:111], v[132:135], v[172:175], v[108:111]
	v_mfma_f32_16x16x32_bf16 v[104:107], v[140:143], v[172:175], v[104:107]
	v_mfma_f32_16x16x32_bf16 v[92:95], v[132:135], v[180:183], v[92:95]
	v_mfma_f32_16x16x32_bf16 v[88:91], v[140:143], v[180:183], v[88:91]
	v_mfma_f32_16x16x32_bf16 v[76:79], v[132:135], v[198:201], v[76:79]
	v_mfma_f32_16x16x32_bf16 v[72:75], v[140:143], v[198:201], v[72:75]
	s_setprio 0
	s_barrier
	s_add_i32 s20, 0, 0x1c000
	s_add_i32 s14, s48, s27
	v_add_u32_e32 v214, s20, v187
	v_lshl_add_u64 v[184:185], v[184:185], 0, s[12:13]
	s_mov_b32 m0, s14
	ds_read_b128 v[202:205], v214
	ds_read_b128 v[206:209], v214 offset:1024
	ds_read_b128 v[210:213], v214 offset:2048
	ds_read_b128 v[214:217], v214 offset:3072
	global_load_lds_dwordx4 v[184:185], off
	v_lshl_add_u64 v[184:185], v[218:219], 0, s[12:13]
	s_add_i32 m0, s14, 0x2000
	s_nop 0
	global_load_lds_dwordx4 v[184:185], off
	s_barrier
	s_waitcnt lgkmcnt(0)
	s_setprio 1
	s_waitcnt lgkmcnt(0)
	v_mfma_f32_16x16x32_bf16 v[116:119], v[202:205], v[144:147], v[116:119]
	v_mfma_f32_16x16x32_bf16 v[112:115], v[210:213], v[144:147], v[112:115]
	v_mfma_f32_16x16x32_bf16 v[100:103], v[202:205], v[168:171], v[100:103]
	v_mfma_f32_16x16x32_bf16 v[96:99], v[210:213], v[168:171], v[96:99]
	v_mfma_f32_16x16x32_bf16 v[84:87], v[202:205], v[176:179], v[84:87]
	v_mfma_f32_16x16x32_bf16 v[80:83], v[210:213], v[176:179], v[80:83]
	v_mfma_f32_16x16x32_bf16 v[68:71], v[202:205], v[194:197], v[68:71]
	v_mfma_f32_16x16x32_bf16 v[64:67], v[210:213], v[194:197], v[64:67]
	v_mfma_f32_16x16x32_bf16 v[116:119], v[206:209], v[148:151], v[116:119]
	v_mfma_f32_16x16x32_bf16 v[112:115], v[214:217], v[148:151], v[112:115]
	v_mfma_f32_16x16x32_bf16 v[100:103], v[206:209], v[172:175], v[100:103]
	v_mfma_f32_16x16x32_bf16 v[96:99], v[214:217], v[172:175], v[96:99]
	v_mfma_f32_16x16x32_bf16 v[84:87], v[206:209], v[180:183], v[84:87]
	v_mfma_f32_16x16x32_bf16 v[80:83], v[214:217], v[180:183], v[80:83]
	v_mfma_f32_16x16x32_bf16 v[68:71], v[206:209], v[198:201], v[68:71]
	v_mfma_f32_16x16x32_bf16 v[64:67], v[214:217], v[198:201], v[64:67]
	s_setprio 0
	s_mov_b32 m0, s35
	v_lshl_add_u64 v[184:185], v[220:221], 0, s[12:13]
	s_barrier
	ds_read_b128 v[144:147], v191 offset:49152
	ds_read_b128 v[148:151], v191 offset:50176
	ds_read_b128 v[168:171], v191 offset:51200
	ds_read_b128 v[172:175], v191 offset:52224
	ds_read_b128 v[176:179], v191 offset:53248
	ds_read_b128 v[180:183], v191 offset:54272
	ds_read_b128 v[194:197], v191 offset:55296
	ds_read_b128 v[198:201], v191 offset:56320
	global_load_lds_dwordx4 v[184:185], off
	v_lshl_add_u64 v[184:185], v[222:223], 0, s[12:13]
	s_mov_b32 m0, s36
	s_nop 0
	global_load_lds_dwordx4 v[184:185], off
	s_barrier
	s_waitcnt lgkmcnt(0)
	s_setprio 1
	s_waitcnt lgkmcnt(0)
	v_mfma_f32_16x16x32_bf16 v[60:63], v[128:131], v[144:147], v[60:63]
	v_mfma_f32_16x16x32_bf16 v[56:59], v[136:139], v[144:147], v[56:59]
	v_mfma_f32_16x16x32_bf16 v[44:47], v[128:131], v[168:171], v[44:47]
	v_mfma_f32_16x16x32_bf16 v[40:43], v[136:139], v[168:171], v[40:43]
	v_mfma_f32_16x16x32_bf16 v[28:31], v[128:131], v[176:179], v[28:31]
	v_mfma_f32_16x16x32_bf16 v[24:27], v[136:139], v[176:179], v[24:27]
	v_mfma_f32_16x16x32_bf16 v[12:15], v[128:131], v[194:197], v[12:15]
	v_mfma_f32_16x16x32_bf16 v[8:11], v[136:139], v[194:197], v[8:11]
	v_mfma_f32_16x16x32_bf16 v[60:63], v[132:135], v[148:151], v[60:63]
	v_mfma_f32_16x16x32_bf16 v[56:59], v[140:143], v[148:151], v[56:59]
	v_mfma_f32_16x16x32_bf16 v[44:47], v[132:135], v[172:175], v[44:47]
	v_mfma_f32_16x16x32_bf16 v[40:43], v[140:143], v[172:175], v[40:43]
	v_mfma_f32_16x16x32_bf16 v[28:31], v[132:135], v[180:183], v[28:31]
	v_mfma_f32_16x16x32_bf16 v[24:27], v[140:143], v[180:183], v[24:27]
	v_mfma_f32_16x16x32_bf16 v[12:15], v[132:135], v[198:201], v[12:15]
	v_mfma_f32_16x16x32_bf16 v[8:11], v[140:143], v[198:201], v[8:11]
	s_setprio 0
	s_barrier
	s_add_u32 s14, s18, 0xb0080
	s_addc_u32 s15, s19, 0
	s_add_i32 s18, s20, s27
	v_lshl_add_u64 v[128:129], s[14:15], 0, v[154:155]
	s_mov_b32 m0, s18
	s_nop 0
	global_load_lds_dwordx4 v[128:129], off
	v_lshl_add_u64 v[128:129], s[14:15], 0, v[158:159]
	s_add_i32 m0, s18, 0x2000
	s_nop 0
	global_load_lds_dwordx4 v[128:129], off
	s_waitcnt vmcnt(6)
	s_barrier
	s_setprio 1
	v_mfma_f32_16x16x32_bf16 v[52:55], v[202:205], v[144:147], v[52:55]
	v_mfma_f32_16x16x32_bf16 v[48:51], v[210:213], v[144:147], v[48:51]
	v_mfma_f32_16x16x32_bf16 v[36:39], v[202:205], v[168:171], v[36:39]
	v_mfma_f32_16x16x32_bf16 v[32:35], v[210:213], v[168:171], v[32:35]
	v_mfma_f32_16x16x32_bf16 v[20:23], v[202:205], v[176:179], v[20:23]
	v_mfma_f32_16x16x32_bf16 v[16:19], v[210:213], v[176:179], v[16:19]
	v_mfma_f32_16x16x32_bf16 v[4:7], v[202:205], v[194:197], v[4:7]
	v_mfma_f32_16x16x32_bf16 v[0:3], v[210:213], v[194:197], v[0:3]
	v_mfma_f32_16x16x32_bf16 v[52:55], v[206:209], v[148:151], v[52:55]
	v_mfma_f32_16x16x32_bf16 v[48:51], v[214:217], v[148:151], v[48:51]
	v_mfma_f32_16x16x32_bf16 v[36:39], v[206:209], v[172:175], v[36:39]
	v_mfma_f32_16x16x32_bf16 v[32:35], v[214:217], v[172:175], v[32:35]
	v_mfma_f32_16x16x32_bf16 v[20:23], v[206:209], v[180:183], v[20:23]
	v_mfma_f32_16x16x32_bf16 v[16:19], v[214:217], v[180:183], v[16:19]
	v_mfma_f32_16x16x32_bf16 v[4:7], v[206:209], v[198:201], v[4:7]
	v_mfma_f32_16x16x32_bf16 v[0:3], v[214:217], v[198:201], v[0:3]
	s_setprio 0
	s_add_i32 s47, s47, 2
	s_add_u32 s45, s45, 0x100
	s_addc_u32 s46, s46, 0
	s_cmp_gt_u32 s47, 41
	s_mov_b64 s[14:15], s[16:17]
	s_barrier
	s_cbranch_scc0 .LBB0_1741
	v_lshl_or_b32 v168, s10, 8, v189
	v_lshl_add_u32 v170, s44, 8, v186
	v_ashrrev_i32_e32 v169, 31, v168
	v_lshlrev_b64 v[202:203], 1, v[168:169]
	v_ashrrev_i32_e32 v171, 31, v170
	v_or_b32_e32 v182, 16, v170
	v_lshl_add_u64 v[172:173], s[64:65], 0, v[202:203]
	v_lshlrev_b64 v[204:205], 11, v[170:171]
	v_ashrrev_i32_e32 v183, 31, v182
	v_or_b32_e32 v178, 32, v170
	v_lshl_add_u64 v[128:129], v[172:173], 0, v[204:205]
	v_lshlrev_b64 v[184:185], 11, v[182:183]
	v_ashrrev_i32_e32 v179, 31, v178
	v_or_b32_e32 v174, 48, v170
	global_load_dwordx4 v[194:197], v[128:129], off
	global_load_dwordx4 v[198:201], v[128:129], off offset:256
	v_lshl_add_u64 v[128:129], v[172:173], 0, v[184:185]
	v_lshlrev_b64 v[180:181], 11, v[178:179]
	v_ashrrev_i32_e32 v175, 31, v174
	global_load_dwordx4 v[148:151], v[128:129], off
	global_load_dwordx4 v[144:147], v[128:129], off offset:256
	v_lshl_add_u64 v[128:129], v[172:173], 0, v[180:181]
	v_lshlrev_b64 v[176:177], 11, v[174:175]
	global_load_dwordx4 v[140:143], v[128:129], off
	global_load_dwordx4 v[136:139], v[128:129], off offset:256
	v_lshl_add_u64 v[128:129], v[172:173], 0, v[176:177]
	global_load_dwordx4 v[132:135], v[128:129], off
	s_nop 0
	global_load_dwordx4 v[128:131], v[128:129], off offset:256
	s_lshl_b32 s14, s10, 2
	s_ashr_i32 s15, s14, 31
	v_add_u32_e32 v252, 0x80, v170
	v_ashrrev_i32_e32 v253, 31, v252
	v_lshlrev_b64 v[252:253], 11, v[252:253]
	v_lshl_add_u64 v[252:253], v[172:173], 0, v[252:253]
	global_load_dwordx4 v[236:239], v[252:253], off
	global_load_dwordx4 v[240:243], v[252:253], off offset:256
	v_add_u32_e32 v252, 0x90, v170
	v_ashrrev_i32_e32 v253, 31, v252
	v_lshlrev_b64 v[252:253], 11, v[252:253]
	v_lshl_add_u64 v[252:253], v[172:173], 0, v[252:253]
	global_load_dwordx4 v[244:247], v[252:253], off
	global_load_dwordx4 v[248:251], v[252:253], off offset:256
	v_add_u32_e32 v252, 0xa0, v170
	v_ashrrev_i32_e32 v253, 31, v252
	v_lshlrev_b64 v[252:253], 11, v[252:253]
	v_lshl_add_u64 v[252:253], v[172:173], 0, v[252:253]
	global_load_dwordx4 v[210:213], v[252:253], off
	global_load_dwordx4 v[214:217], v[252:253], off offset:256
	s_waitcnt vmcnt(6)
	v_lshlrev_b32_e32 v206, 16, v194
	v_and_b32_e32 v207, 0xffff0000, v194
	v_lshlrev_b32_e32 v194, 16, v195
	v_and_b32_e32 v195, 0xffff0000, v195
	v_lshlrev_b32_e32 v208, 16, v196
	v_and_b32_e32 v209, 0xffff0000, v196
	v_lshlrev_b32_e32 v196, 16, v197
	v_and_b32_e32 v197, 0xffff0000, v197
	v_add_f32_e32 v126, v126, v194
	v_add_f32_e32 v127, v127, v195
	v_add_f32_e32 v124, v124, v206
	v_add_f32_e32 v125, v125, v207
	v_add_f32_e32 v194, v122, v196
	v_add_f32_e32 v195, v123, v197
	v_add_f32_e32 v122, v120, v208
	v_add_f32_e32 v123, v121, v209
	v_mul_f32_e32 v120, v125, v125
	v_mul_f32_e32 v121, v127, v127
	v_fmac_f32_e32 v120, v124, v124
	v_fmac_f32_e32 v121, v126, v126
	v_add_f32_e32 v120, v120, v121
	v_mul_f32_e32 v121, v123, v123
	v_mul_f32_e32 v196, v195, v195
	v_fmac_f32_e32 v121, v122, v122
	v_fmac_f32_e32 v196, v194, v194
	v_add_f32_e32 v121, v121, v196
	v_add_f32_e32 v206, v120, v121
	v_cvt_pk_bf16_f32 v120, v124, v125
	v_cvt_pk_bf16_f32 v121, v126, v127
	v_lshlrev_b32_e32 v124, 16, v198
	v_and_b32_e32 v125, 0xffff0000, v198
	v_lshlrev_b32_e32 v126, 16, v199
	v_and_b32_e32 v127, 0xffff0000, v199
	v_cvt_pk_bf16_f32 v122, v122, v123
	v_cvt_pk_bf16_f32 v123, v194, v195
	v_lshlrev_b32_e32 v194, 16, v200
	v_and_b32_e32 v195, 0xffff0000, v200
	v_add_f32_e32 v118, v118, v126
	v_add_f32_e32 v119, v119, v127
	v_add_f32_e32 v116, v116, v124
	v_add_f32_e32 v117, v117, v125
	v_lshlrev_b32_e32 v196, 16, v201
	v_and_b32_e32 v197, 0xffff0000, v201
	v_add_f32_e32 v126, v112, v194
	v_add_f32_e32 v127, v113, v195
	v_mul_f32_e32 v112, v117, v117
	v_mul_f32_e32 v113, v119, v119
	v_add_f32_e32 v124, v114, v196
	v_add_f32_e32 v125, v115, v197
	v_fmac_f32_e32 v112, v116, v116
	v_fmac_f32_e32 v113, v118, v118
	v_add_f32_e32 v112, v112, v113
	v_mul_f32_e32 v113, v127, v127
	v_mul_f32_e32 v114, v125, v125
	v_fmac_f32_e32 v113, v126, v126
	v_fmac_f32_e32 v114, v124, v124
	v_add_f32_e32 v113, v113, v114
	v_add_f32_e32 v112, v112, v113
	v_and_b32_e32 v114, 64, v193
	v_add_f32_e32 v113, v206, v112
	v_xor_b32_e32 v112, 16, v193
	v_add_u32_e32 v196, 64, v114
	v_cmp_lt_i32_e32 vcc, v112, v196
	v_lshl_add_u64 v[114:115], s[64:65], 0, v[204:205]
	v_lshl_add_u64 v[194:195], v[114:115], 0, v[202:203]
	v_cndmask_b32_e32 v112, v193, v112, vcc
	v_lshlrev_b32_e32 v112, 2, v112
	ds_bpermute_b32 v197, v112, v113
	global_store_dwordx4 v[194:195], v[120:123], off
	v_cvt_pk_bf16_f32 v116, v116, v117
	v_cvt_pk_bf16_f32 v117, v118, v119
	v_cvt_pk_bf16_f32 v118, v126, v127
	s_waitcnt lgkmcnt(0)
	v_add_f32_e32 v114, v113, v197
	v_xor_b32_e32 v113, 32, v193
	v_cmp_lt_i32_e32 vcc, v113, v196
	v_cvt_pk_bf16_f32 v119, v124, v125
	global_store_dwordx4 v[194:195], v[116:119], off offset:256
	s_nop 0
	v_cndmask_b32_e32 v113, v193, v113, vcc
	v_lshlrev_b32_e32 v113, 2, v113
	ds_bpermute_b32 v115, v113, v114
	s_and_saveexec_b64 s[16:17], s[2:3]
	s_cbranch_execz .LBB0_1744
	s_waitcnt lgkmcnt(0)
	v_add_f32_e32 v116, v114, v115
	v_lshlrev_b64 v[114:115], 6, v[170:171]
	v_lshl_add_u64 v[114:115], s[74:75], 0, v[114:115]
	v_lshl_add_u64 v[114:115], s[14:15], 2, v[114:115]
	s_lshl_b32 s10, s34, 2
	v_lshl_add_u64 v[114:115], v[114:115], 0, s[10:11]
	global_store_dword v[114:115], v116, off
.LBB0_1744:
	s_or_b64 exec, exec, s[16:17]
	v_lshlrev_b32_e32 v114, 16, v148
	s_waitcnt lgkmcnt(0)
	v_and_b32_e32 v115, 0xffff0000, v148
	v_lshlrev_b32_e32 v116, 16, v149
	v_and_b32_e32 v117, 0xffff0000, v149
	v_lshlrev_b32_e32 v118, 16, v150
	v_and_b32_e32 v119, 0xffff0000, v150
	v_lshlrev_b32_e32 v120, 16, v151
	v_and_b32_e32 v121, 0xffff0000, v151
	v_add_f32_e32 v110, v110, v116
	v_add_f32_e32 v111, v111, v117
	v_add_f32_e32 v108, v108, v114
	v_add_f32_e32 v109, v109, v115
	v_add_f32_e32 v114, v106, v120
	v_add_f32_e32 v115, v107, v121
	v_add_f32_e32 v106, v104, v118
	v_add_f32_e32 v107, v105, v119
	v_mul_f32_e32 v104, v109, v109
	v_mul_f32_e32 v105, v111, v111
	v_fmac_f32_e32 v104, v108, v108
	v_fmac_f32_e32 v105, v110, v110
	v_add_f32_e32 v104, v104, v105
	v_mul_f32_e32 v105, v107, v107
	v_mul_f32_e32 v116, v115, v115
	v_fmac_f32_e32 v105, v106, v106
	v_fmac_f32_e32 v116, v114, v114
	v_add_f32_e32 v105, v105, v116
	v_add_f32_e32 v118, v104, v105
	v_cvt_pk_bf16_f32 v104, v108, v109
	v_cvt_pk_bf16_f32 v105, v110, v111
	v_lshlrev_b32_e32 v108, 16, v144
	v_and_b32_e32 v109, 0xffff0000, v144
	v_lshlrev_b32_e32 v110, 16, v145
	v_and_b32_e32 v111, 0xffff0000, v145
	v_cvt_pk_bf16_f32 v106, v106, v107
	v_cvt_pk_bf16_f32 v107, v114, v115
	v_lshlrev_b32_e32 v114, 16, v146
	v_and_b32_e32 v115, 0xffff0000, v146
	v_add_f32_e32 v102, v102, v110
	v_add_f32_e32 v103, v103, v111
	v_add_f32_e32 v100, v100, v108
	v_add_f32_e32 v101, v101, v109
	v_lshlrev_b32_e32 v116, 16, v147
	v_and_b32_e32 v117, 0xffff0000, v147
	v_add_f32_e32 v110, v96, v114
	v_add_f32_e32 v111, v97, v115
	v_mul_f32_e32 v96, v101, v101
	v_mul_f32_e32 v97, v103, v103
	v_add_f32_e32 v108, v98, v116
	v_add_f32_e32 v109, v99, v117
	v_fmac_f32_e32 v96, v100, v100
	v_fmac_f32_e32 v97, v102, v102
	v_add_f32_e32 v96, v96, v97
	v_mul_f32_e32 v97, v111, v111
	v_mul_f32_e32 v98, v109, v109
	v_fmac_f32_e32 v97, v110, v110
	v_fmac_f32_e32 v98, v108, v108
	v_add_f32_e32 v97, v97, v98
	v_add_f32_e32 v96, v96, v97
	v_add_f32_e32 v99, v118, v96
	ds_bpermute_b32 v116, v112, v99
	v_lshl_add_u64 v[96:97], s[64:65], 0, v[184:185]
	v_lshl_add_u64 v[114:115], v[168:169], 1, v[96:97]
	global_store_dwordx4 v[114:115], v[104:107], off
	v_cvt_pk_bf16_f32 v98, v100, v101
	s_waitcnt lgkmcnt(0)
	v_add_f32_e32 v96, v99, v116
	ds_bpermute_b32 v97, v113, v96
	v_cvt_pk_bf16_f32 v99, v102, v103
	v_cvt_pk_bf16_f32 v100, v110, v111
	v_cvt_pk_bf16_f32 v101, v108, v109
	global_store_dwordx4 v[114:115], v[98:101], off offset:256
	s_and_saveexec_b64 s[16:17], s[2:3]
	s_cbranch_execz .LBB0_1746
	s_waitcnt lgkmcnt(0)
	v_add_f32_e32 v98, v96, v97
	v_lshlrev_b64 v[96:97], 6, v[182:183]
	v_lshl_add_u64 v[96:97], s[74:75], 0, v[96:97]
	v_lshl_add_u64 v[96:97], s[14:15], 2, v[96:97]
	s_lshl_b32 s10, s34, 2
	v_lshl_add_u64 v[96:97], v[96:97], 0, s[10:11]
	global_store_dword v[96:97], v98, off
.LBB0_1746:
	s_or_b64 exec, exec, s[16:17]
	v_lshlrev_b32_e32 v96, 16, v140
	s_waitcnt lgkmcnt(0)
	v_and_b32_e32 v97, 0xffff0000, v140
	v_lshlrev_b32_e32 v98, 16, v141
	v_and_b32_e32 v99, 0xffff0000, v141
	v_lshlrev_b32_e32 v100, 16, v142
	v_and_b32_e32 v101, 0xffff0000, v142
	v_lshlrev_b32_e32 v102, 16, v143
	v_and_b32_e32 v103, 0xffff0000, v143
	v_add_f32_e32 v94, v94, v98
	v_add_f32_e32 v95, v95, v99
	v_add_f32_e32 v92, v92, v96
	v_add_f32_e32 v93, v93, v97
	v_add_f32_e32 v96, v90, v102
	v_add_f32_e32 v97, v91, v103
	v_add_f32_e32 v90, v88, v100
	v_add_f32_e32 v91, v89, v101
	v_mul_f32_e32 v88, v93, v93
	v_mul_f32_e32 v89, v95, v95
	v_fmac_f32_e32 v88, v92, v92
	v_fmac_f32_e32 v89, v94, v94
	v_add_f32_e32 v88, v88, v89
	v_mul_f32_e32 v89, v91, v91
	v_mul_f32_e32 v98, v97, v97
	v_fmac_f32_e32 v89, v90, v90
	v_fmac_f32_e32 v98, v96, v96
	v_add_f32_e32 v89, v89, v98
	v_add_f32_e32 v100, v88, v89
	v_cvt_pk_bf16_f32 v88, v92, v93
	v_cvt_pk_bf16_f32 v89, v94, v95
	v_lshlrev_b32_e32 v92, 16, v136
	v_and_b32_e32 v93, 0xffff0000, v136
	v_lshlrev_b32_e32 v94, 16, v137
	v_and_b32_e32 v95, 0xffff0000, v137
	v_cvt_pk_bf16_f32 v90, v90, v91
	v_cvt_pk_bf16_f32 v91, v96, v97
	v_lshlrev_b32_e32 v96, 16, v138
	v_and_b32_e32 v97, 0xffff0000, v138
	v_add_f32_e32 v86, v86, v94
	v_add_f32_e32 v87, v87, v95
	v_add_f32_e32 v84, v84, v92
	v_add_f32_e32 v85, v85, v93
	v_lshlrev_b32_e32 v98, 16, v139
	v_and_b32_e32 v99, 0xffff0000, v139
	v_add_f32_e32 v94, v80, v96
	v_add_f32_e32 v95, v81, v97
	v_mul_f32_e32 v80, v85, v85
	v_mul_f32_e32 v81, v87, v87
	v_add_f32_e32 v92, v82, v98
	v_add_f32_e32 v93, v83, v99
	v_fmac_f32_e32 v80, v84, v84
	v_fmac_f32_e32 v81, v86, v86
	v_add_f32_e32 v80, v80, v81
	v_mul_f32_e32 v81, v95, v95
	v_mul_f32_e32 v82, v93, v93
	v_fmac_f32_e32 v81, v94, v94
	v_fmac_f32_e32 v82, v92, v92
	v_add_f32_e32 v81, v81, v82
	v_add_f32_e32 v80, v80, v81
	v_add_f32_e32 v83, v100, v80
	ds_bpermute_b32 v98, v112, v83
	v_lshl_add_u64 v[80:81], s[64:65], 0, v[180:181]
	v_lshl_add_u64 v[96:97], v[168:169], 1, v[80:81]
	global_store_dwordx4 v[96:97], v[88:91], off
	v_cvt_pk_bf16_f32 v82, v84, v85
	s_waitcnt lgkmcnt(0)
	v_add_f32_e32 v80, v83, v98
	ds_bpermute_b32 v81, v113, v80
	v_cvt_pk_bf16_f32 v83, v86, v87
	v_cvt_pk_bf16_f32 v84, v94, v95
	v_cvt_pk_bf16_f32 v85, v92, v93
	global_store_dwordx4 v[96:97], v[82:85], off offset:256
	s_and_saveexec_b64 s[16:17], s[2:3]
	s_cbranch_execz .LBB0_1748
	s_waitcnt lgkmcnt(0)
	v_add_f32_e32 v82, v80, v81
	v_lshlrev_b64 v[80:81], 6, v[178:179]
	v_lshl_add_u64 v[80:81], s[74:75], 0, v[80:81]
	v_lshl_add_u64 v[80:81], s[14:15], 2, v[80:81]
	s_lshl_b32 s10, s34, 2
	v_lshl_add_u64 v[80:81], v[80:81], 0, s[10:11]
	global_store_dword v[80:81], v82, off
.LBB0_1748:
	s_or_b64 exec, exec, s[16:17]
	v_lshlrev_b32_e32 v80, 16, v132
	s_waitcnt lgkmcnt(0)
	v_and_b32_e32 v81, 0xffff0000, v132
	v_lshlrev_b32_e32 v82, 16, v133
	v_and_b32_e32 v83, 0xffff0000, v133
	v_lshlrev_b32_e32 v84, 16, v134
	v_and_b32_e32 v85, 0xffff0000, v134
	v_lshlrev_b32_e32 v86, 16, v135
	v_and_b32_e32 v87, 0xffff0000, v135
	v_add_f32_e32 v78, v78, v82
	v_add_f32_e32 v79, v79, v83
	v_add_f32_e32 v76, v76, v80
	v_add_f32_e32 v77, v77, v81
	v_add_f32_e32 v80, v74, v86
	v_add_f32_e32 v81, v75, v87
	v_add_f32_e32 v74, v72, v84
	v_add_f32_e32 v75, v73, v85
	v_mul_f32_e32 v72, v77, v77
	v_mul_f32_e32 v73, v79, v79
	v_fmac_f32_e32 v72, v76, v76
	v_fmac_f32_e32 v73, v78, v78
	v_add_f32_e32 v72, v72, v73
	v_mul_f32_e32 v73, v75, v75
	v_mul_f32_e32 v82, v81, v81
	v_fmac_f32_e32 v73, v74, v74
	v_fmac_f32_e32 v82, v80, v80
	v_add_f32_e32 v73, v73, v82
	v_add_f32_e32 v84, v72, v73
	v_cvt_pk_bf16_f32 v72, v76, v77
	v_cvt_pk_bf16_f32 v73, v78, v79
	v_lshlrev_b32_e32 v76, 16, v128
	v_and_b32_e32 v77, 0xffff0000, v128
	v_lshlrev_b32_e32 v78, 16, v129
	v_and_b32_e32 v79, 0xffff0000, v129
	v_cvt_pk_bf16_f32 v74, v74, v75
	v_cvt_pk_bf16_f32 v75, v80, v81
	v_lshlrev_b32_e32 v80, 16, v130
	v_and_b32_e32 v81, 0xffff0000, v130
	v_add_f32_e32 v70, v70, v78
	v_add_f32_e32 v71, v71, v79
	v_add_f32_e32 v68, v68, v76
	v_add_f32_e32 v69, v69, v77
	v_lshlrev_b32_e32 v82, 16, v131
	v_and_b32_e32 v83, 0xffff0000, v131
	v_add_f32_e32 v78, v64, v80
	v_add_f32_e32 v79, v65, v81
	v_mul_f32_e32 v64, v69, v69
	v_mul_f32_e32 v65, v71, v71
	v_add_f32_e32 v76, v66, v82
	v_add_f32_e32 v77, v67, v83
	v_fmac_f32_e32 v64, v68, v68
	v_fmac_f32_e32 v65, v70, v70
	v_add_f32_e32 v64, v64, v65
	v_mul_f32_e32 v65, v79, v79
	v_mul_f32_e32 v66, v77, v77
	v_fmac_f32_e32 v65, v78, v78
	v_fmac_f32_e32 v66, v76, v76
	v_add_f32_e32 v65, v65, v66
	v_add_f32_e32 v64, v64, v65
	v_add_f32_e32 v67, v84, v64
	ds_bpermute_b32 v82, v112, v67
	v_lshl_add_u64 v[64:65], s[64:65], 0, v[176:177]
	v_lshl_add_u64 v[80:81], v[168:169], 1, v[64:65]
	global_store_dwordx4 v[80:81], v[72:75], off
	v_cvt_pk_bf16_f32 v66, v68, v69
	s_waitcnt lgkmcnt(0)
	v_add_f32_e32 v64, v67, v82
	ds_bpermute_b32 v65, v113, v64
	v_cvt_pk_bf16_f32 v67, v70, v71
	v_cvt_pk_bf16_f32 v68, v78, v79
	v_cvt_pk_bf16_f32 v69, v76, v77
	global_store_dwordx4 v[80:81], v[66:69], off offset:256
	s_and_saveexec_b64 s[16:17], s[2:3]
	s_cbranch_execz .LBB0_1750
	s_waitcnt lgkmcnt(0)
	v_add_f32_e32 v66, v64, v65
	v_lshlrev_b64 v[64:65], 6, v[174:175]
	v_lshl_add_u64 v[64:65], s[74:75], 0, v[64:65]
	v_lshl_add_u64 v[64:65], s[14:15], 2, v[64:65]
	s_lshl_b32 s10, s34, 2
	v_lshl_add_u64 v[64:65], v[64:65], 0, s[10:11]
	global_store_dword v[64:65], v66, off
.LBB0_1750:
	s_or_b64 exec, exec, s[16:17]
	v_add_u32_e32 v100, 0x80, v170
	v_ashrrev_i32_e32 v101, 31, v100
	v_add_u32_e32 v96, 0x90, v170
	v_lshlrev_b64 v[110:111], 11, v[100:101]
	v_ashrrev_i32_e32 v97, 31, v96
	v_add_u32_e32 v92, 0xa0, v170
	s_waitcnt lgkmcnt(0)
	v_lshl_add_u64 v[64:65], v[172:173], 0, v[110:111]
	v_lshlrev_b64 v[98:99], 11, v[96:97]
	v_ashrrev_i32_e32 v93, 31, v92
	v_add_u32_e32 v88, 0xb0, v170
	v_lshl_add_u64 v[64:65], v[172:173], 0, v[98:99]
	v_lshlrev_b64 v[94:95], 11, v[92:93]
	v_ashrrev_i32_e32 v89, 31, v88
	v_lshl_add_u64 v[64:65], v[172:173], 0, v[94:95]
	v_lshlrev_b64 v[90:91], 11, v[88:89]
	v_lshl_add_u64 v[64:65], v[172:173], 0, v[90:91]
	global_load_dwordx4 v[68:71], v[64:65], off
	s_nop 0
	global_load_dwordx4 v[64:67], v[64:65], off offset:256
	s_waitcnt vmcnt(15)
	v_lshlrev_b32_e32 v114, 16, v236
	v_and_b32_e32 v115, 0xffff0000, v236
	v_lshlrev_b32_e32 v236, 16, v237
	v_and_b32_e32 v237, 0xffff0000, v237
	v_lshlrev_b32_e32 v116, 16, v238
	v_and_b32_e32 v117, 0xffff0000, v238
	v_lshlrev_b32_e32 v238, 16, v239
	v_and_b32_e32 v239, 0xffff0000, v239
	v_add_f32_e32 v62, v62, v236
	v_add_f32_e32 v63, v63, v237
	v_add_f32_e32 v60, v60, v114
	v_add_f32_e32 v61, v61, v115
	v_add_f32_e32 v236, v58, v238
	v_add_f32_e32 v237, v59, v239
	v_add_f32_e32 v58, v56, v116
	v_add_f32_e32 v59, v57, v117
	v_mul_f32_e32 v56, v61, v61
	v_mul_f32_e32 v57, v63, v63
	v_fmac_f32_e32 v56, v60, v60
	v_fmac_f32_e32 v57, v62, v62
	v_add_f32_e32 v56, v56, v57
	v_mul_f32_e32 v57, v59, v59
	v_mul_f32_e32 v238, v237, v237
	v_fmac_f32_e32 v57, v58, v58
	v_fmac_f32_e32 v238, v236, v236
	v_add_f32_e32 v57, v57, v238
	v_add_f32_e32 v114, v56, v57
	v_cvt_pk_bf16_f32 v56, v60, v61
	v_cvt_pk_bf16_f32 v57, v62, v63
	s_waitcnt vmcnt(14)
	v_lshlrev_b32_e32 v60, 16, v240
	v_and_b32_e32 v61, 0xffff0000, v240
	v_lshlrev_b32_e32 v62, 16, v241
	v_and_b32_e32 v63, 0xffff0000, v241
	v_cvt_pk_bf16_f32 v58, v58, v59
	v_cvt_pk_bf16_f32 v59, v236, v237
	v_lshlrev_b32_e32 v236, 16, v242
	v_and_b32_e32 v237, 0xffff0000, v242
	v_add_f32_e32 v54, v54, v62
	v_add_f32_e32 v55, v55, v63
	v_add_f32_e32 v52, v52, v60
	v_add_f32_e32 v53, v53, v61
	v_lshlrev_b32_e32 v238, 16, v243
	v_and_b32_e32 v239, 0xffff0000, v243
	v_add_f32_e32 v62, v48, v236
	v_add_f32_e32 v63, v49, v237
	v_mul_f32_e32 v48, v53, v53
	v_mul_f32_e32 v49, v55, v55
	v_add_f32_e32 v60, v50, v238
	v_add_f32_e32 v61, v51, v239
	v_fmac_f32_e32 v48, v52, v52
	v_fmac_f32_e32 v49, v54, v54
	v_add_f32_e32 v48, v48, v49
	v_mul_f32_e32 v49, v63, v63
	v_mul_f32_e32 v50, v61, v61
	v_fmac_f32_e32 v49, v62, v62
	v_fmac_f32_e32 v50, v60, v60
	v_add_f32_e32 v49, v49, v50
	v_add_f32_e32 v48, v48, v49
	v_add_f32_e32 v51, v114, v48
	ds_bpermute_b32 v238, v112, v51
	v_lshl_add_u64 v[48:49], s[64:65], 0, v[110:111]
	v_lshl_add_u64 v[236:237], v[168:169], 1, v[48:49]
	global_store_dwordx4 v[236:237], v[56:59], off
	v_cvt_pk_bf16_f32 v50, v52, v53
	s_waitcnt lgkmcnt(0)
	v_add_f32_e32 v48, v51, v238
	ds_bpermute_b32 v49, v113, v48
	v_cvt_pk_bf16_f32 v51, v54, v55
	v_cvt_pk_bf16_f32 v52, v62, v63
	v_cvt_pk_bf16_f32 v53, v60, v61
	global_store_dwordx4 v[236:237], v[50:53], off offset:256
	s_and_saveexec_b64 s[16:17], s[2:3]
	s_cbranch_execz .LBB0_1752
	s_waitcnt lgkmcnt(0)
	v_add_f32_e32 v50, v48, v49
	v_lshlrev_b64 v[48:49], 6, v[100:101]
	v_lshl_add_u64 v[48:49], s[74:75], 0, v[48:49]
	v_lshl_add_u64 v[48:49], s[14:15], 2, v[48:49]
	s_lshl_b32 s10, s34, 2
	v_lshl_add_u64 v[48:49], v[48:49], 0, s[10:11]
	global_store_dword v[48:49], v50, off
.LBB0_1752:
	s_or_b64 exec, exec, s[16:17]
	s_waitcnt vmcnt(15)
	v_lshlrev_b32_e32 v48, 16, v244
	s_waitcnt lgkmcnt(0)
	v_and_b32_e32 v49, 0xffff0000, v244
	v_lshlrev_b32_e32 v50, 16, v245
	v_and_b32_e32 v51, 0xffff0000, v245
	v_lshlrev_b32_e32 v52, 16, v246
	v_and_b32_e32 v53, 0xffff0000, v246
	v_lshlrev_b32_e32 v54, 16, v247
	v_and_b32_e32 v55, 0xffff0000, v247
	v_add_f32_e32 v46, v46, v50
	v_add_f32_e32 v47, v47, v51
	v_add_f32_e32 v44, v44, v48
	v_add_f32_e32 v45, v45, v49
	v_add_f32_e32 v48, v42, v54
	v_add_f32_e32 v49, v43, v55
	v_add_f32_e32 v42, v40, v52
	v_add_f32_e32 v43, v41, v53
	v_mul_f32_e32 v40, v45, v45
	v_mul_f32_e32 v41, v47, v47
	v_fmac_f32_e32 v40, v44, v44
	v_fmac_f32_e32 v41, v46, v46
	v_add_f32_e32 v40, v40, v41
	v_mul_f32_e32 v41, v43, v43
	v_mul_f32_e32 v50, v49, v49
	v_fmac_f32_e32 v41, v42, v42
	v_fmac_f32_e32 v50, v48, v48
	v_add_f32_e32 v41, v41, v50
	v_add_f32_e32 v52, v40, v41
	v_cvt_pk_bf16_f32 v40, v44, v45
	v_cvt_pk_bf16_f32 v41, v46, v47
	s_waitcnt vmcnt(14)
	v_lshlrev_b32_e32 v44, 16, v248
	v_and_b32_e32 v45, 0xffff0000, v248
	v_lshlrev_b32_e32 v46, 16, v249
	v_and_b32_e32 v47, 0xffff0000, v249
	v_cvt_pk_bf16_f32 v42, v42, v43
	v_cvt_pk_bf16_f32 v43, v48, v49
	v_lshlrev_b32_e32 v48, 16, v250
	v_and_b32_e32 v49, 0xffff0000, v250
	v_add_f32_e32 v38, v38, v46
	v_add_f32_e32 v39, v39, v47
	v_add_f32_e32 v36, v36, v44
	v_add_f32_e32 v37, v37, v45
	v_lshlrev_b32_e32 v50, 16, v251
	v_and_b32_e32 v51, 0xffff0000, v251
	v_add_f32_e32 v46, v32, v48
	v_add_f32_e32 v47, v33, v49
	v_mul_f32_e32 v32, v37, v37
	v_mul_f32_e32 v33, v39, v39
	v_add_f32_e32 v44, v34, v50
	v_add_f32_e32 v45, v35, v51
	v_fmac_f32_e32 v32, v36, v36
	v_fmac_f32_e32 v33, v38, v38
	v_add_f32_e32 v32, v32, v33
	v_mul_f32_e32 v33, v47, v47
	v_mul_f32_e32 v34, v45, v45
	v_fmac_f32_e32 v33, v46, v46
	v_fmac_f32_e32 v34, v44, v44
	v_add_f32_e32 v33, v33, v34
	v_add_f32_e32 v32, v32, v33
	v_add_f32_e32 v35, v52, v32
	ds_bpermute_b32 v50, v112, v35
	v_lshl_add_u64 v[32:33], s[64:65], 0, v[98:99]
	v_lshl_add_u64 v[48:49], v[168:169], 1, v[32:33]
	global_store_dwordx4 v[48:49], v[40:43], off
	v_cvt_pk_bf16_f32 v34, v36, v37
	s_waitcnt lgkmcnt(0)
	v_add_f32_e32 v32, v35, v50
	ds_bpermute_b32 v33, v113, v32
	v_cvt_pk_bf16_f32 v35, v38, v39
	v_cvt_pk_bf16_f32 v36, v46, v47
	v_cvt_pk_bf16_f32 v37, v44, v45
	global_store_dwordx4 v[48:49], v[34:37], off offset:256
	s_and_saveexec_b64 s[16:17], s[2:3]
	s_cbranch_execz .LBB0_1754
	s_waitcnt lgkmcnt(0)
	v_add_f32_e32 v34, v32, v33
	v_lshlrev_b64 v[32:33], 6, v[96:97]
	v_lshl_add_u64 v[32:33], s[74:75], 0, v[32:33]
	v_lshl_add_u64 v[32:33], s[14:15], 2, v[32:33]
	s_lshl_b32 s10, s34, 2
	v_lshl_add_u64 v[32:33], v[32:33], 0, s[10:11]
	global_store_dword v[32:33], v34, off
.LBB0_1754:
	s_or_b64 exec, exec, s[16:17]
	s_waitcnt vmcnt(15)
	v_lshlrev_b32_e32 v32, 16, v210
	s_waitcnt lgkmcnt(0)
	v_and_b32_e32 v33, 0xffff0000, v210
	v_lshlrev_b32_e32 v34, 16, v211
	v_and_b32_e32 v35, 0xffff0000, v211
	v_lshlrev_b32_e32 v36, 16, v212
	v_and_b32_e32 v37, 0xffff0000, v212
	v_lshlrev_b32_e32 v38, 16, v213
	v_and_b32_e32 v39, 0xffff0000, v213
	v_add_f32_e32 v30, v30, v34
	v_add_f32_e32 v31, v31, v35
	v_add_f32_e32 v28, v28, v32
	v_add_f32_e32 v29, v29, v33
	v_add_f32_e32 v32, v26, v38
	v_add_f32_e32 v33, v27, v39
	v_add_f32_e32 v26, v24, v36
	v_add_f32_e32 v27, v25, v37
	v_mul_f32_e32 v24, v29, v29
	v_mul_f32_e32 v25, v31, v31
	v_fmac_f32_e32 v24, v28, v28
	v_fmac_f32_e32 v25, v30, v30
	v_add_f32_e32 v24, v24, v25
	v_mul_f32_e32 v25, v27, v27
	v_mul_f32_e32 v34, v33, v33
	v_fmac_f32_e32 v25, v26, v26
	v_fmac_f32_e32 v34, v32, v32
	v_add_f32_e32 v25, v25, v34
	v_add_f32_e32 v36, v24, v25
	v_cvt_pk_bf16_f32 v24, v28, v29
	v_cvt_pk_bf16_f32 v25, v30, v31
	s_waitcnt vmcnt(14)
	v_lshlrev_b32_e32 v28, 16, v214
	v_and_b32_e32 v29, 0xffff0000, v214
	v_lshlrev_b32_e32 v30, 16, v215
	v_and_b32_e32 v31, 0xffff0000, v215
	v_cvt_pk_bf16_f32 v26, v26, v27
	v_cvt_pk_bf16_f32 v27, v32, v33
	v_lshlrev_b32_e32 v32, 16, v216
	v_and_b32_e32 v33, 0xffff0000, v216
	v_add_f32_e32 v22, v22, v30
	v_add_f32_e32 v23, v23, v31
	v_add_f32_e32 v20, v20, v28
	v_add_f32_e32 v21, v21, v29
	v_lshlrev_b32_e32 v34, 16, v217
	v_and_b32_e32 v35, 0xffff0000, v217
	v_add_f32_e32 v30, v16, v32
	v_add_f32_e32 v31, v17, v33
	v_mul_f32_e32 v16, v21, v21
	v_mul_f32_e32 v17, v23, v23
	v_add_f32_e32 v28, v18, v34
	v_add_f32_e32 v29, v19, v35
	v_fmac_f32_e32 v16, v20, v20
	v_fmac_f32_e32 v17, v22, v22
	v_add_f32_e32 v16, v16, v17
	v_mul_f32_e32 v17, v31, v31
	v_mul_f32_e32 v18, v29, v29
	v_fmac_f32_e32 v17, v30, v30
	v_fmac_f32_e32 v18, v28, v28
	v_add_f32_e32 v17, v17, v18
	v_add_f32_e32 v16, v16, v17
	v_add_f32_e32 v19, v36, v16
	ds_bpermute_b32 v34, v112, v19
	v_lshl_add_u64 v[16:17], s[64:65], 0, v[94:95]
	v_lshl_add_u64 v[32:33], v[168:169], 1, v[16:17]
	global_store_dwordx4 v[32:33], v[24:27], off
	v_cvt_pk_bf16_f32 v18, v20, v21
	s_waitcnt lgkmcnt(0)
	v_add_f32_e32 v16, v19, v34
	ds_bpermute_b32 v17, v113, v16
	v_cvt_pk_bf16_f32 v19, v22, v23
	v_cvt_pk_bf16_f32 v20, v30, v31
	v_cvt_pk_bf16_f32 v21, v28, v29
	global_store_dwordx4 v[32:33], v[18:21], off offset:256
	s_and_saveexec_b64 s[16:17], s[2:3]
	s_cbranch_execz .LBB0_1756
	s_waitcnt lgkmcnt(0)
	v_add_f32_e32 v18, v16, v17
	v_lshlrev_b64 v[16:17], 6, v[92:93]
	v_lshl_add_u64 v[16:17], s[74:75], 0, v[16:17]
	v_lshl_add_u64 v[16:17], s[14:15], 2, v[16:17]
	s_lshl_b32 s10, s34, 2
	v_lshl_add_u64 v[16:17], v[16:17], 0, s[10:11]
	global_store_dword v[16:17], v18, off
.LBB0_1756:
	s_or_b64 exec, exec, s[16:17]
	s_waitcnt vmcnt(7)
	v_lshlrev_b32_e32 v16, 16, v68
	s_waitcnt lgkmcnt(0)
	v_and_b32_e32 v17, 0xffff0000, v68
	v_lshlrev_b32_e32 v18, 16, v69
	v_and_b32_e32 v19, 0xffff0000, v69
	v_lshlrev_b32_e32 v20, 16, v70
	v_and_b32_e32 v21, 0xffff0000, v70
	v_lshlrev_b32_e32 v22, 16, v71
	v_and_b32_e32 v23, 0xffff0000, v71
	v_add_f32_e32 v14, v14, v18
	v_add_f32_e32 v15, v15, v19
	v_add_f32_e32 v12, v12, v16
	v_add_f32_e32 v13, v13, v17
	v_add_f32_e32 v16, v10, v22
	v_add_f32_e32 v17, v11, v23
	v_add_f32_e32 v10, v8, v20
	v_add_f32_e32 v11, v9, v21
	v_mul_f32_e32 v8, v13, v13
	v_mul_f32_e32 v9, v15, v15
	v_fmac_f32_e32 v8, v12, v12
	v_fmac_f32_e32 v9, v14, v14
	v_add_f32_e32 v8, v8, v9
	v_mul_f32_e32 v9, v11, v11
	v_mul_f32_e32 v18, v17, v17
	v_fmac_f32_e32 v9, v10, v10
	v_fmac_f32_e32 v18, v16, v16
	v_add_f32_e32 v9, v9, v18
	v_add_f32_e32 v20, v8, v9
	v_cvt_pk_bf16_f32 v8, v12, v13
	v_cvt_pk_bf16_f32 v9, v14, v15
	s_waitcnt vmcnt(6)
	v_lshlrev_b32_e32 v12, 16, v64
	v_and_b32_e32 v13, 0xffff0000, v64
	v_lshlrev_b32_e32 v14, 16, v65
	v_and_b32_e32 v15, 0xffff0000, v65
	v_cvt_pk_bf16_f32 v10, v10, v11
	v_cvt_pk_bf16_f32 v11, v16, v17
	v_lshlrev_b32_e32 v16, 16, v66
	v_and_b32_e32 v17, 0xffff0000, v66
	v_add_f32_e32 v6, v6, v14
	v_add_f32_e32 v7, v7, v15
	v_add_f32_e32 v4, v4, v12
	v_add_f32_e32 v5, v5, v13
	v_lshlrev_b32_e32 v18, 16, v67
	v_and_b32_e32 v19, 0xffff0000, v67
	v_add_f32_e32 v14, v0, v16
	v_add_f32_e32 v15, v1, v17
	v_mul_f32_e32 v0, v5, v5
	v_mul_f32_e32 v1, v7, v7
	v_add_f32_e32 v12, v2, v18
	v_add_f32_e32 v13, v3, v19
	v_fmac_f32_e32 v0, v4, v4
	v_fmac_f32_e32 v1, v6, v6
	v_add_f32_e32 v0, v0, v1
	v_mul_f32_e32 v1, v15, v15
	v_mul_f32_e32 v2, v13, v13
	v_fmac_f32_e32 v1, v14, v14
	v_fmac_f32_e32 v2, v12, v12
	v_add_f32_e32 v1, v1, v2
	v_add_f32_e32 v0, v0, v1
	v_add_f32_e32 v3, v20, v0
	ds_bpermute_b32 v18, v112, v3
	v_lshl_add_u64 v[0:1], s[64:65], 0, v[90:91]
	v_lshl_add_u64 v[16:17], v[168:169], 1, v[0:1]
	global_store_dwordx4 v[16:17], v[8:11], off
	v_cvt_pk_bf16_f32 v2, v4, v5
	s_waitcnt lgkmcnt(0)
	v_add_f32_e32 v0, v3, v18
	ds_bpermute_b32 v1, v113, v0
	v_cvt_pk_bf16_f32 v3, v6, v7
	v_cvt_pk_bf16_f32 v4, v14, v15
	v_cvt_pk_bf16_f32 v5, v12, v13
	global_store_dwordx4 v[16:17], v[2:5], off offset:256
	s_and_saveexec_b64 s[16:17], s[2:3]
	s_cbranch_execz .LBB0_1729
	s_waitcnt lgkmcnt(0)
	v_add_f32_e32 v2, v0, v1
	v_lshlrev_b64 v[0:1], 6, v[88:89]
	v_lshl_add_u64 v[0:1], s[74:75], 0, v[0:1]
	v_lshl_add_u64 v[0:1], s[14:15], 2, v[0:1]
	s_lshl_b32 s10, s34, 2
	v_lshl_add_u64 v[0:1], v[0:1], 0, s[10:11]
	global_store_dword v[0:1], v2, off
	s_branch .LBB0_1729

.LBB0_1818:
	s_or_b64 exec, exec, s[0:1]
	v_lshlrev_b64 v[18:19], 11, v[0:1]
	v_lshl_add_u64 v[30:31], v[6:7], 0, v[18:19]
	global_load_dwordx4 v[18:21], v[30:31], off nt
	global_load_dwordx4 v[22:25], v[4:5], off
	global_load_dwordx4 v[26:29], v[4:5], off offset:16
	s_waitcnt vmcnt(3)
	ds_bpermute_b32 v32, v10, v17
	s_waitcnt lgkmcnt(0)
	v_add_f32_e32 v17, v17, v32
	ds_bpermute_b32 v32, v11, v17
	s_waitcnt lgkmcnt(0)
	v_add_f32_e32 v17, v17, v32
	ds_bpermute_b32 v32, v12, v17
	s_waitcnt lgkmcnt(0)
	v_add_f32_e32 v17, v17, v32
	ds_bpermute_b32 v32, v13, v17
	s_waitcnt lgkmcnt(0)
	v_add_f32_e32 v17, v17, v32
	ds_bpermute_b32 v32, v14, v17
	s_waitcnt lgkmcnt(0)
	v_add_f32_e32 v17, v17, v32
	ds_bpermute_b32 v32, v15, v17
	s_waitcnt lgkmcnt(0)
	v_add_f32_e32 v17, v17, v32
	v_fmamk_f32 v17, v17, 0x3a800000, v16
	v_mul_f32_e32 v32, 0x4b800000, v17
	v_cmp_gt_f32_e64 s[0:1], s5, v17
	s_waitcnt vmcnt(2)
	v_and_b32_e32 v37, 0xffff0000, v18
	v_cndmask_b32_e64 v17, v17, v32, s[0:1]
	v_rsq_f32_e32 v17, v17
	v_lshlrev_b64 v[32:33], 12, v[0:1]
	v_lshlrev_b32_e32 v36, 16, v18
	v_and_b32_e32 v39, 0xffff0000, v20
	v_mul_f32_e32 v1, 0x45800000, v17
	v_cndmask_b32_e64 v34, v17, v1, s[0:1]
	v_lshlrev_b32_e32 v38, 16, v20
	v_and_b32_e32 v41, 0xffff0000, v19
	v_lshlrev_b32_e32 v40, 16, v19
	v_and_b32_e32 v19, 0xffff0000, v21
	v_lshlrev_b32_e32 v18, 16, v21
	v_mul_f32_e32 v20, v34, v36
	v_mul_f32_e32 v21, v34, v37
	v_mul_f32_e32 v36, v34, v38
	v_mul_f32_e32 v37, v34, v39
	v_mul_f32_e32 v38, v34, v40
	v_mul_f32_e32 v39, v34, v41
	v_lshl_add_u64 v[32:33], v[8:9], 0, v[32:33]
	v_mul_f32_e32 v40, v34, v18
	v_mul_f32_e32 v41, v34, v19
	s_waitcnt vmcnt(1)
	v_mul_f32_e32 v18, v22, v20
	v_mul_f32_e32 v19, v23, v21
	v_mul_f32_e32 v20, v24, v38
	v_mul_f32_e32 v21, v25, v39
	s_waitcnt vmcnt(0)
	v_mul_f32_e32 v22, v26, v36
	v_mul_f32_e32 v23, v27, v37
	v_mul_f32_e32 v24, v28, v40
	v_mul_f32_e32 v25, v29, v41
	global_store_dwordx4 v[32:33], v[18:21], off nt
	global_store_dwordx4 v[32:33], v[22:25], off offset:16 nt
	global_load_dwordx4 v[18:21], v[30:31], off offset:1024 nt
	s_nop 0
	global_load_dwordx4 v[22:25], v[4:5], off offset:2048
	global_load_dwordx4 v[26:29], v[4:5], off offset:2064
	v_add_u32_e32 v0, s4, v0
	v_cmp_lt_i32_e64 s[0:1], s6, v0
	s_or_b64 s[2:3], s[0:1], s[2:3]
	s_waitcnt vmcnt(2)
	v_and_b32_e32 v31, 0xffff0000, v18
	v_lshlrev_b32_e32 v30, 16, v18
	v_and_b32_e32 v37, 0xffff0000, v20
	v_lshlrev_b32_e32 v36, 16, v20
	v_and_b32_e32 v39, 0xffff0000, v19
	v_lshlrev_b32_e32 v38, 16, v19
	v_and_b32_e32 v19, 0xffff0000, v21
	v_lshlrev_b32_e32 v18, 16, v21
	v_mul_f32_e32 v20, v34, v30
	v_mul_f32_e32 v21, v34, v31
	v_mul_f32_e32 v30, v34, v36
	v_mul_f32_e32 v31, v34, v37
	v_mul_f32_e32 v36, v34, v38
	v_mul_f32_e32 v37, v34, v39
	v_mul_f32_e32 v35, v34, v19
	v_mul_f32_e32 v34, v34, v18
	s_waitcnt vmcnt(1)
	v_mul_f32_e32 v18, v22, v20
	v_mul_f32_e32 v19, v23, v21
	v_mul_f32_e32 v20, v24, v36
	v_mul_f32_e32 v21, v25, v37
	s_waitcnt vmcnt(0)
	v_mul_f32_e32 v22, v26, v30
	v_mul_f32_e32 v23, v27, v31
	v_mul_f32_e32 v24, v28, v34
	v_mul_f32_e32 v25, v29, v35
	global_store_dwordx4 v[32:33], v[18:21], off offset:2048 nt
	global_store_dwordx4 v[32:33], v[22:25], off offset:2064 nt
	s_andn2_b64 exec, exec, s[2:3]
	s_cbranch_execz .LBB0_1821
